# tconv-deserialize + EpiGU fast rcp division + ssq load hoist in GU/ScaleBf epilogues
# speedup vs baseline: 1.0209x; 1.0209x over previous
.LBB0_125:
	s_ashr_i32 s12, s15, 31
	s_lshr_b32 s12, s12, 27
	s_add_i32 s13, s15, s12
	s_ashr_i32 s12, s13, 5
	s_ashr_i32 s38, s13, 6
	s_lshl_b32 s33, s12, 6
	s_lshl_b32 s12, s12, 11
	s_ashr_i32 s39, s38, 31
	s_sub_i32 s12, s14, s12
	s_lshl_b64 s[38:39], s[38:39], 20
	v_and_or_b32 v0, s33, 64, v8
	s_add_u32 s38, s16, s38
	v_add_u32_e32 v12, s12, v3
	s_addc_u32 s39, s17, s39
	v_lshlrev_b32_e32 v0, 2, v0
	v_ashrrev_i32_e32 v13, 31, v12
	v_lshl_add_u64 v[6:7], s[38:39], 0, v[0:1]
	v_lshlrev_b64 v[16:17], 9, v[12:13]
	v_lshl_add_u64 v[16:17], v[6:7], 0, v[16:17]
	s_barrier
	global_load_dword v100, v[16:17], off
	v_add_u32_e32 v16, 8, v12
	v_ashrrev_i32_e32 v17, 31, v16
	v_lshlrev_b64 v[16:17], 9, v[16:17]
	v_lshl_add_u64 v[16:17], v[6:7], 0, v[16:17]
	s_ashr_i32 s13, s12, 31
	s_addk_i32 s14, 0x3800
	global_load_dword v101, v[16:17], off
	v_add_u32_e32 v16, 16, v12
	v_ashrrev_i32_e32 v17, 31, v16
	v_lshlrev_b64 v[16:17], 9, v[16:17]
	v_lshl_add_u64 v[16:17], v[6:7], 0, v[16:17]
	global_load_dword v102, v[16:17], off
	v_add_u32_e32 v16, 24, v12
	v_ashrrev_i32_e32 v17, 31, v16
	v_lshlrev_b64 v[16:17], 9, v[16:17]
	v_lshl_add_u64 v[16:17], v[6:7], 0, v[16:17]
	global_load_dword v103, v[16:17], off
	v_add_u32_e32 v16, 32, v12
	v_ashrrev_i32_e32 v17, 31, v16
	v_lshlrev_b64 v[16:17], 9, v[16:17]
	v_lshl_add_u64 v[16:17], v[6:7], 0, v[16:17]
	global_load_dword v104, v[16:17], off
	v_add_u32_e32 v16, 40, v12
	v_ashrrev_i32_e32 v17, 31, v16
	v_lshlrev_b64 v[16:17], 9, v[16:17]
	v_lshl_add_u64 v[16:17], v[6:7], 0, v[16:17]
	global_load_dword v105, v[16:17], off
	v_add_u32_e32 v16, 48, v12
	v_ashrrev_i32_e32 v17, 31, v16
	v_lshlrev_b64 v[16:17], 9, v[16:17]
	v_lshl_add_u64 v[16:17], v[6:7], 0, v[16:17]
	v_add_u32_e32 v12, 56, v12
	v_ashrrev_i32_e32 v13, 31, v12
	v_lshlrev_b64 v[12:13], 9, v[12:13]
	v_lshl_add_u64 v[6:7], v[6:7], 0, v[12:13]
	global_load_dword v106, v[16:17], off
	global_load_dword v107, v[6:7], off
	v_lshl_add_u64 v[6:7], s[12:13], 1, v[4:5]
	s_waitcnt vmcnt(7)
	ds_write_b32 v11, v100
	s_waitcnt vmcnt(6)
	ds_write_b32 v11, v101 offset:2080
	s_waitcnt vmcnt(5)
	ds_write_b32 v11, v102 offset:4160
	s_waitcnt vmcnt(4)
	ds_write_b32 v11, v103 offset:6240
	s_waitcnt vmcnt(3)
	ds_write_b32 v11, v104 offset:8320
	s_waitcnt vmcnt(2)
	ds_write_b32 v11, v105 offset:10400
	s_waitcnt vmcnt(1)
	ds_write_b32 v11, v106 offset:12480
	s_waitcnt vmcnt(0)
	ds_write_b32 v11, v107 offset:14560
	s_waitcnt lgkmcnt(0)
	s_barrier
	ds_read2_b32 v[12:13], v10 offset1:32
	ds_read2_b32 v[16:17], v10 offset0:65 offset1:97
	ds_read2_b32 v[20:21], v10 offset0:130 offset1:162
	ds_read2_b32 v[22:23], v10 offset0:195 offset1:227
	v_add_u32_e32 v0, s33, v9
	v_mad_i64_i32 v[24:25], s[12:13], v0, s37, v[6:7]
	v_add_u32_e32 v0, 32, v0
	v_mad_i64_i32 v[6:7], s[12:13], v0, s37, v[6:7]
	s_add_i32 s12, s15, 0xe0
	s_waitcnt lgkmcnt(2)
	v_cvt_pk_bf16_f32 v18, v12, v16
	s_waitcnt lgkmcnt(0)
	v_cvt_pk_bf16_f32 v19, v20, v22
	v_cvt_pk_bf16_f32 v12, v13, v17
	v_cvt_pk_bf16_f32 v13, v21, v23
	s_cmpk_lt_i32 s15, 0x720
	s_mov_b32 s15, s12
	global_store_dwordx2 v[24:25], v[18:19], off
	global_store_dwordx2 v[6:7], v[12:13], off
	s_cbranch_scc1 .LBB0_125

.LBB0_136:
	s_ashr_i32 s10, s13, 31
	s_lshr_b32 s10, s10, 30
	s_add_i32 s10, s13, s10
	s_ashr_i32 s11, s10, 2
	s_lshl_b32 s14, s11, 6
	s_lshl_b32 s15, s11, 8
	s_lshl_b32 s11, s11, 4
	s_and_b32 s33, s14, 0xc0
	s_sub_i32 s10, s12, s15
	s_and_b32 s11, s11, 0xffffff00
	v_or_b32_e32 v0, s33, v7
	s_and_b32 s33, s15, 0xc00
	s_add_u32 s36, s22, s33
	s_addc_u32 s37, s23, 0
	s_sub_i32 s11, s11, s15
	s_add_i32 s11, s11, s12
	v_add_u32_e32 v12, s11, v6
	v_lshlrev_b32_e32 v0, 2, v0
	v_ashrrev_i32_e32 v13, 31, v12
	v_lshl_add_u64 v[4:5], s[36:37], 0, v[0:1]
	v_lshlrev_b64 v[14:15], 12, v[12:13]
	v_lshl_add_u64 v[14:15], v[4:5], 0, v[14:15]
	s_barrier
	global_load_dword v100, v[14:15], off
	v_add_u32_e32 v14, 8, v12
	v_ashrrev_i32_e32 v15, 31, v14
	v_lshlrev_b64 v[14:15], 12, v[14:15]
	v_lshl_add_u64 v[14:15], v[4:5], 0, v[14:15]
	v_add_u32_e32 v22, s14, v8
	s_ashr_i32 s11, s10, 31
	v_ashrrev_i32_e32 v23, 31, v22
	v_lshlrev_b64 v[24:25], 9, v[22:23]
	s_addk_i32 s12, 0x3800
	global_load_dword v101, v[14:15], off
	v_add_u32_e32 v14, 16, v12
	v_ashrrev_i32_e32 v15, 31, v14
	v_lshlrev_b64 v[14:15], 12, v[14:15]
	v_lshl_add_u64 v[14:15], v[4:5], 0, v[14:15]
	global_load_dword v102, v[14:15], off
	v_add_u32_e32 v14, 24, v12
	v_ashrrev_i32_e32 v15, 31, v14
	v_lshlrev_b64 v[14:15], 12, v[14:15]
	v_lshl_add_u64 v[14:15], v[4:5], 0, v[14:15]
	global_load_dword v103, v[14:15], off
	v_add_u32_e32 v14, 32, v12
	v_ashrrev_i32_e32 v15, 31, v14
	v_lshlrev_b64 v[14:15], 12, v[14:15]
	v_lshl_add_u64 v[14:15], v[4:5], 0, v[14:15]
	global_load_dword v104, v[14:15], off
	v_add_u32_e32 v14, 40, v12
	v_ashrrev_i32_e32 v15, 31, v14
	v_lshlrev_b64 v[14:15], 12, v[14:15]
	v_lshl_add_u64 v[14:15], v[4:5], 0, v[14:15]
	global_load_dword v105, v[14:15], off
	v_add_u32_e32 v14, 48, v12
	v_ashrrev_i32_e32 v15, 31, v14
	v_lshlrev_b64 v[14:15], 12, v[14:15]
	v_lshl_add_u64 v[14:15], v[4:5], 0, v[14:15]
	v_add_u32_e32 v12, 56, v12
	v_ashrrev_i32_e32 v13, 31, v12
	v_lshlrev_b64 v[12:13], 12, v[12:13]
	v_lshl_add_u64 v[4:5], v[4:5], 0, v[12:13]
	global_load_dword v106, v[14:15], off
	global_load_dword v107, v[4:5], off
	v_lshl_add_u64 v[4:5], s[10:11], 1, v[2:3]
	s_add_i32 s10, s13, 0xe0
	v_lshl_add_u64 v[24:25], v[4:5], 0, v[24:25]
	s_cmpk_gt_i32 s13, 0x71f
	s_mov_b32 s13, s10
	s_waitcnt vmcnt(7)
	ds_write_b32 v10, v100
	s_waitcnt vmcnt(6)
	ds_write_b32 v10, v101 offset:2080
	s_waitcnt vmcnt(5)
	ds_write_b32 v10, v102 offset:4160
	s_waitcnt vmcnt(4)
	ds_write_b32 v10, v103 offset:6240
	s_waitcnt vmcnt(3)
	ds_write_b32 v10, v104 offset:8320
	s_waitcnt vmcnt(2)
	ds_write_b32 v10, v105 offset:10400
	s_waitcnt vmcnt(1)
	ds_write_b32 v10, v106 offset:12480
	s_waitcnt vmcnt(0)
	ds_write_b32 v10, v107 offset:14560
	s_waitcnt lgkmcnt(0)
	s_barrier
	ds_read2_b32 v[12:13], v9 offset1:32
	ds_read2_b32 v[14:15], v9 offset0:65 offset1:97
	ds_read2_b32 v[18:19], v9 offset0:130 offset1:162
	ds_read2_b32 v[20:21], v9 offset0:195 offset1:227
	s_waitcnt lgkmcnt(2)
	v_cvt_pk_bf16_f32 v16, v12, v14
	v_add_u32_e32 v14, 32, v22
	v_cvt_pk_bf16_f32 v12, v13, v15
	v_ashrrev_i32_e32 v15, 31, v14
	v_lshlrev_b64 v[14:15], 9, v[14:15]
	s_waitcnt lgkmcnt(0)
	v_cvt_pk_bf16_f32 v17, v18, v20
	v_cvt_pk_bf16_f32 v13, v19, v21
	v_lshl_add_u64 v[4:5], v[4:5], 0, v[14:15]
	global_store_dwordx2 v[24:25], v[16:17], off
	global_store_dwordx2 v[4:5], v[12:13], off
	s_cbranch_scc0 .LBB0_136

.LBB0_186:
	s_or_b64 exec, exec, s[42:43]
	s_movk_i32 s42, 0x410
	v_lshrrev_b32_e32 v130, 2, v142
	v_lshlrev_b32_e32 v131, 1, v142
	v_and_b32_e32 v0, 15, v142
	v_and_b32_e32 v130, 0xfffffcc, v130
	v_and_b32_e32 v131, 0x180, v131
	v_add_u32_e32 v131, 0, v131
	v_lshlrev_b32_e32 v0, 2, v0
	v_mul_lo_u32 v130, v130, s42
	v_add3_u32 v130, v131, v0, v130
	s_waitcnt vmcnt(0)
	s_barrier
	ds_write2_b32 v130, v114, v126 offset1:16
	v_add_u32_e32 v114, 0x400, v130
	ds_write2_b32 v114, v115, v127 offset0:4 offset1:20
	v_add_u32_e32 v115, 0x800, v130
	ds_write2_b32 v115, v116, v128 offset0:8 offset1:24
	v_add_u32_e32 v116, 0xc00, v130
	ds_write2_b32 v116, v117, v129 offset0:12 offset1:28
	v_add_u32_e32 v117, 0x4000, v130
	ds_write2_b32 v117, v82, v94 offset0:64 offset1:80
	v_add_u32_e32 v94, 0x4400, v130
	ds_write2_b32 v94, v83, v95 offset0:68 offset1:84
	v_add_u32_e32 v95, 0x4800, v130
	ds_write2_b32 v95, v84, v96 offset0:72 offset1:88
	v_add_u32_e32 v96, 0x4c00, v130
	v_add_u32_e32 v133, 0xc000, v130
	ds_write2_b32 v96, v85, v97 offset0:76 offset1:92
	v_add_u32_e32 v132, 0x8000, v130
	v_add_u32_e32 v97, 0x8400, v130
	v_add_u32_e32 v126, 0x8800, v130
	v_add_u32_e32 v127, 0x8c00, v130
	ds_write2_b32 v133, v66, v70 offset0:192 offset1:208
	v_add_u32_e32 v128, 0xc400, v130
	v_add_u32_e32 v129, 0xc800, v130
	v_add_u32_e32 v131, 0xcc00, v130
	v_lshlrev_b32_e32 v0, 3, v142
	v_lshlrev_b32_e32 v66, 2, v142
	ds_write2_b32 v132, v74, v78 offset0:128 offset1:144
	ds_write2_b32 v97, v75, v79 offset0:132 offset1:148
	ds_write2_b32 v126, v76, v80 offset0:136 offset1:152
	ds_write2_b32 v127, v77, v81 offset0:140 offset1:156
	ds_write2_b32 v128, v67, v71 offset0:196 offset1:212
	ds_write2_b32 v129, v68, v72 offset0:200 offset1:216
	ds_write2_b32 v131, v69, v73 offset0:204 offset1:220
	ds_write2_b32 v130, v98, v118 offset0:128 offset1:144
	ds_write2_b32 v114, v99, v119 offset0:132 offset1:148
	ds_write2_b32 v115, v100, v120 offset0:136 offset1:152
	ds_write2_b32 v116, v101, v121 offset0:140 offset1:156
	ds_write2_b32 v117, v102, v122 offset0:192 offset1:208
	ds_write2_b32 v94, v103, v123 offset0:196 offset1:212
	ds_write2_b32 v95, v104, v124 offset0:200 offset1:216
	ds_write2_b32 v96, v105, v125 offset0:204 offset1:220
	ds_write2_b32 v97, v90, v110 offset1:16
	ds_write2_b32 v126, v91, v111 offset0:4 offset1:20
	ds_write2_b32 v127, v92, v112 offset0:8 offset1:24
	v_add_u32_e32 v90, 0x9000, v130
	v_and_b32_e32 v0, 0xe0, v0
	v_and_b32_e32 v68, 12, v66
	ds_write2_b32 v90, v93, v113 offset0:12 offset1:28
	ds_write2_b32 v128, v86, v106 offset0:64 offset1:80
	ds_write2_b32 v129, v87, v107 offset0:68 offset1:84
	ds_write2_b32 v131, v88, v108 offset0:72 offset1:88
	v_lshlrev_b32_e32 v66, 2, v0
	v_lshlrev_b32_e32 v67, 2, v68
	v_or_b32_e32 v0, s38, v0
	v_ashrrev_i32_e32 v88, 5, v142
	v_add3_u32 v74, 0, v66, v67
	v_ashrrev_i32_e32 v66, 1, v0
	v_lshlrev_b32_e32 v0, 1, v68
	v_add_u32_e32 v68, s10, v88
	v_ashrrev_i32_e32 v69, 31, v68
	v_add_u32_e32 v91, 0xd000, v130
	v_lshl_add_u64 v[70:71], v[68:69], 4, s[46:47]
	ds_write2_b32 v91, v89, v109 offset0:76 offset1:92
	s_waitcnt lgkmcnt(0)
	s_barrier
	global_load_dwordx4 v[134:137], v[70:71], off
	global_load_dwordx4 v[138:141], v[70:71], off offset:256
	global_load_dwordx4 v[144:147], v[70:71], off offset:512
	global_load_dwordx4 v[148:151], v[70:71], off offset:768
	global_load_dwordx4 v[152:155], v[70:71], off offset:1024
	global_load_dwordx4 v[156:159], v[70:71], off offset:1280
	global_load_dwordx4 v[160:163], v[70:71], off offset:1536
	global_load_dwordx4 v[164:167], v[70:71], off offset:1792
	v_readlane_b32 s16, v253, 58
	v_ashrrev_i32_e32 v67, 31, v66
	v_readlane_b32 s17, v253, 59
	s_mov_b32 s33, 0x800000
	v_mad_u64_u32 v[82:83], s[36:37], v88, s42, v[74:75]
	v_lshl_add_u64 v[66:67], v[66:67], 1, s[16:17]
	v_lshl_add_u64 v[66:67], v[66:67], 0, v[0:1]
	s_movk_i32 s39, 0x1600
	v_readlane_b32 s16, v254, 61
	v_readlane_b32 s17, v254, 62
	s_waitcnt vmcnt(0)
	v_add_f32_e32 v0, v134, v135
	v_add_f32_e32 v0, v0, v136
	v_add_f32_e32 v0, v0, v137
	v_fmamk_f32 v0, v0, 0x3a800000, v200
	v_cmp_gt_f32_e32 vcc, s33, v0
	v_mul_f32_e32 v69, 0x4b800000, v0
	ds_read_b128 v[70:73], v82
	ds_read_b128 v[76:79], v82 offset:64
	v_cndmask_b32_e32 v0, v0, v69, vcc
	v_rsq_f32_e32 v0, v0
	s_nop 0
	v_mul_f32_e32 v69, 0x45800000, v0
	v_cndmask_b32_e32 v0, v0, v69, vcc
	s_waitcnt lgkmcnt(1)
	v_pk_mul_f32 v[70:71], v[70:71], v[0:1] op_sel_hi:[1,0]
	v_pk_mul_f32 v[72:73], v[72:73], v[0:1] op_sel_hi:[1,0]
	v_mul_f32_e32 v69, 0xbfb8aa3b, v70
	v_exp_f32_e32 v80, v69
	v_mul_f32_e32 v69, 0xbfb8aa3b, v71
	v_exp_f32_e32 v81, v69
	s_waitcnt lgkmcnt(0)
	v_pk_mul_f32 v[76:77], v[76:77], v[0:1] op_sel_hi:[1,0]
	v_pk_mul_f32 v[78:79], v[78:79], v[0:1] op_sel_hi:[1,0]
	v_mul_f32_e32 v0, 0xbfb8aa3b, v73
	v_pk_add_f32 v[80:81], v[80:81], 1.0 op_sel_hi:[1,0]
	s_nop 0
	v_rcp_f32_e32 v75, v81
	s_nop 0
	v_mul_f32_e32 v71, v71, v75
	v_rcp_f32_e32 v75, v80
	s_nop 0
	v_mul_f32_e32 v70, v70, v75
	v_mul_f32_e32 v69, 0xbfb8aa3b, v72
	v_pk_mul_f32 v[70:71], v[76:77], v[70:71]
	v_exp_f32_e32 v76, v69
	v_exp_f32_e32 v77, v0
	v_cvt_pk_bf16_f32 v70, v70, v71
	v_pk_add_f32 v[76:77], v[76:77], 1.0 op_sel_hi:[1,0]
	s_nop 0
	v_rcp_f32_e32 v69, v77
	s_nop 0
	v_mul_f32_e32 v73, v73, v69
	v_rcp_f32_e32 v69, v76
	s_nop 0
	v_mul_f32_e32 v72, v72, v69
	v_pk_mul_f32 v[72:73], v[78:79], v[72:73]
	v_add_u32_e32 v0, 0x200, v142
	v_cvt_pk_bf16_f32 v71, v72, v73
	v_mad_i64_i32 v[68:69], s[36:37], v68, s39, v[66:67]
	v_ashrrev_i32_e32 v83, 5, v0
	global_store_dwordx2 v[68:69], v[70:71], off
	v_add_u32_e32 v68, s10, v83
	v_ashrrev_i32_e32 v69, 31, v68
	v_lshl_add_u64 v[70:71], v[68:69], 4, s[46:47]
	v_mad_u64_u32 v[80:81], s[36:37], v83, s42, v[74:75]
	v_add_f32_e32 v0, v138, v139
	v_add_f32_e32 v0, v0, v140
	v_add_f32_e32 v0, v0, v141
	v_fmamk_f32 v0, v0, 0x3a800000, v200
	v_cmp_gt_f32_e32 vcc, s33, v0
	v_mul_f32_e32 v69, 0x4b800000, v0
	ds_read_b128 v[70:73], v80
	ds_read_b128 v[76:79], v80 offset:64
	v_cndmask_b32_e32 v0, v0, v69, vcc
	v_rsq_f32_e32 v0, v0
	s_nop 0
	v_mul_f32_e32 v69, 0x45800000, v0
	v_cndmask_b32_e32 v0, v0, v69, vcc
	s_waitcnt lgkmcnt(1)
	v_pk_mul_f32 v[70:71], v[70:71], v[0:1] op_sel_hi:[1,0]
	v_pk_mul_f32 v[72:73], v[72:73], v[0:1] op_sel_hi:[1,0]
	v_mul_f32_e32 v69, 0xbfb8aa3b, v70
	v_exp_f32_e32 v84, v69
	v_mul_f32_e32 v69, 0xbfb8aa3b, v71
	v_exp_f32_e32 v85, v69
	s_waitcnt lgkmcnt(0)
	v_pk_mul_f32 v[76:77], v[76:77], v[0:1] op_sel_hi:[1,0]
	v_pk_mul_f32 v[78:79], v[78:79], v[0:1] op_sel_hi:[1,0]
	v_mul_f32_e32 v0, 0xbfb8aa3b, v73
	v_pk_add_f32 v[84:85], v[84:85], 1.0 op_sel_hi:[1,0]
	s_nop 0
	v_rcp_f32_e32 v75, v85
	s_nop 0
	v_mul_f32_e32 v71, v71, v75
	v_rcp_f32_e32 v75, v84
	s_nop 0
	v_mul_f32_e32 v70, v70, v75
	v_mul_f32_e32 v69, 0xbfb8aa3b, v72
	v_pk_mul_f32 v[70:71], v[76:77], v[70:71]
	v_exp_f32_e32 v76, v69
	v_exp_f32_e32 v77, v0
	v_cvt_pk_bf16_f32 v70, v70, v71
	v_pk_add_f32 v[76:77], v[76:77], 1.0 op_sel_hi:[1,0]
	s_nop 0
	v_rcp_f32_e32 v69, v77
	s_nop 0
	v_mul_f32_e32 v73, v73, v69
	v_rcp_f32_e32 v69, v76
	s_nop 0
	v_mul_f32_e32 v72, v72, v69
	v_pk_mul_f32 v[72:73], v[78:79], v[72:73]
	v_add_u32_e32 v0, 0x400, v142
	v_cvt_pk_bf16_f32 v71, v72, v73
	v_mad_i64_i32 v[68:69], s[36:37], v68, s39, v[66:67]
	v_ashrrev_i32_e32 v81, 5, v0
	global_store_dwordx2 v[68:69], v[70:71], off
	v_add_u32_e32 v68, s10, v81
	v_ashrrev_i32_e32 v69, 31, v68
	v_lshl_add_u64 v[70:71], v[68:69], 4, s[46:47]
	v_mad_u64_u32 v[78:79], s[36:37], v81, s42, v[74:75]
	v_add_f32_e32 v0, v144, v145
	v_add_f32_e32 v0, v0, v146
	v_add_f32_e32 v0, v0, v147
	v_fmamk_f32 v0, v0, 0x3a800000, v200
	v_cmp_gt_f32_e32 vcc, s33, v0
	v_mul_f32_e32 v69, 0x4b800000, v0
	ds_read_b128 v[70:73], v78
	ds_read_b128 v[84:87], v78 offset:64
	v_cndmask_b32_e32 v0, v0, v69, vcc
	v_rsq_f32_e32 v0, v0
	s_nop 0
	v_mul_f32_e32 v69, 0x45800000, v0
	v_cndmask_b32_e32 v0, v0, v69, vcc
	s_waitcnt lgkmcnt(1)
	v_pk_mul_f32 v[70:71], v[70:71], v[0:1] op_sel_hi:[1,0]
	v_pk_mul_f32 v[72:73], v[72:73], v[0:1] op_sel_hi:[1,0]
	v_mul_f32_e32 v69, 0xbfb8aa3b, v70
	v_exp_f32_e32 v76, v69
	v_mul_f32_e32 v69, 0xbfb8aa3b, v71
	v_exp_f32_e32 v77, v69
	s_waitcnt lgkmcnt(0)
	v_pk_mul_f32 v[84:85], v[84:85], v[0:1] op_sel_hi:[1,0]
	v_pk_add_f32 v[76:77], v[76:77], 1.0 op_sel_hi:[1,0]
	s_nop 0
	v_rcp_f32_e32 v75, v77
	s_nop 0
	v_mul_f32_e32 v71, v71, v75
	v_rcp_f32_e32 v75, v76
	s_nop 0
	v_mul_f32_e32 v70, v70, v75
	v_mul_f32_e32 v69, 0xbfb8aa3b, v72
	v_pk_mul_f32 v[76:77], v[86:87], v[0:1] op_sel_hi:[1,0]
	v_mul_f32_e32 v0, 0xbfb8aa3b, v73
	v_pk_mul_f32 v[70:71], v[84:85], v[70:71]
	v_exp_f32_e32 v84, v69
	v_exp_f32_e32 v85, v0
	v_cvt_pk_bf16_f32 v70, v70, v71
	v_pk_add_f32 v[84:85], v[84:85], 1.0 op_sel_hi:[1,0]
	s_nop 0
	v_rcp_f32_e32 v69, v85
	s_nop 0
	v_mul_f32_e32 v73, v73, v69
	v_rcp_f32_e32 v69, v84
	s_nop 0
	v_mul_f32_e32 v72, v72, v69
	v_add_u32_e32 v0, 0x600, v142
	v_pk_mul_f32 v[72:73], v[76:77], v[72:73]
	v_ashrrev_i32_e32 v79, 5, v0
	v_cvt_pk_bf16_f32 v71, v72, v73
	v_add_u32_e32 v72, s10, v79
	v_mad_i64_i32 v[68:69], s[36:37], v68, s39, v[66:67]
	v_ashrrev_i32_e32 v73, 31, v72
	global_store_dwordx2 v[68:69], v[70:71], off
	v_lshl_add_u64 v[68:69], v[72:73], 4, s[46:47]
	v_mad_u64_u32 v[76:77], s[36:37], v79, s42, v[74:75]
	v_add_f32_e32 v0, v148, v149
	v_add_f32_e32 v0, v0, v150
	v_add_f32_e32 v0, v0, v151
	v_fmamk_f32 v0, v0, 0x3a800000, v200
	v_cmp_gt_f32_e32 vcc, s33, v0
	v_mul_f32_e32 v68, 0x4b800000, v0
	s_nop 0
	v_cndmask_b32_e32 v0, v0, v68, vcc
	v_rsq_f32_e32 v0, v0
	s_nop 0
	v_mul_f32_e32 v68, 0x45800000, v0
	v_cndmask_b32_e32 v0, v0, v68, vcc
	ds_read_b128 v[68:71], v76
	ds_read_b128 v[84:87], v76 offset:64
	s_waitcnt lgkmcnt(1)
	v_pk_mul_f32 v[68:69], v[68:69], v[0:1] op_sel_hi:[1,0]
	s_nop 0
	v_mul_f32_e32 v73, 0xbfb8aa3b, v68
	v_exp_f32_e32 v92, v73
	v_mul_f32_e32 v73, 0xbfb8aa3b, v69
	v_exp_f32_e32 v93, v73
	v_pk_mul_f32 v[70:71], v[70:71], v[0:1] op_sel_hi:[1,0]
	s_waitcnt lgkmcnt(0)
	v_pk_mul_f32 v[84:85], v[84:85], v[0:1] op_sel_hi:[1,0]
	v_pk_mul_f32 v[86:87], v[86:87], v[0:1] op_sel_hi:[1,0]
	v_pk_add_f32 v[92:93], v[92:93], 1.0 op_sel_hi:[1,0]
	v_mul_f32_e32 v0, 0xbfb8aa3b, v71
	v_rcp_f32_e32 v75, v93
	s_nop 0
	v_mul_f32_e32 v69, v69, v75
	v_rcp_f32_e32 v75, v92
	s_nop 0
	v_mul_f32_e32 v68, v68, v75
	v_mul_f32_e32 v73, 0xbfb8aa3b, v70
	v_pk_mul_f32 v[68:69], v[84:85], v[68:69]
	v_exp_f32_e32 v84, v73
	v_exp_f32_e32 v85, v0
	v_cvt_pk_bf16_f32 v68, v68, v69
	v_pk_add_f32 v[84:85], v[84:85], 1.0 op_sel_hi:[1,0]
	s_nop 0
	v_rcp_f32_e32 v73, v85
	s_nop 0
	v_mul_f32_e32 v71, v71, v73
	v_rcp_f32_e32 v73, v84
	s_nop 0
	v_mul_f32_e32 v70, v70, v73
	v_pk_mul_f32 v[70:71], v[86:87], v[70:71]
	v_add_u32_e32 v0, 0x800, v142
	v_cvt_pk_bf16_f32 v69, v70, v71
	v_mad_i64_i32 v[70:71], s[36:37], v72, s39, v[66:67]
	v_ashrrev_i32_e32 v0, 5, v0
	global_store_dwordx2 v[70:71], v[68:69], off
	v_add_u32_e32 v70, s10, v0
	v_ashrrev_i32_e32 v71, 31, v70
	v_lshl_add_u64 v[72:73], v[70:71], 4, s[46:47]
	v_mad_u64_u32 v[68:69], s[36:37], v0, s42, v[74:75]
	v_add_f32_e32 v69, v152, v153
	v_add_f32_e32 v69, v69, v154
	v_add_f32_e32 v69, v69, v155
	v_fmamk_f32 v69, v69, 0x3a800000, v200
	v_cmp_gt_f32_e32 vcc, s33, v69
	v_mul_f32_e32 v71, 0x4b800000, v69
	ds_read_b128 v[84:87], v68
	ds_read_b128 v[98:101], v68 offset:64
	v_cndmask_b32_e32 v69, v69, v71, vcc
	v_rsq_f32_e32 v69, v69
	s_nop 0
	v_mul_f32_e32 v71, 0x45800000, v69
	v_cndmask_b32_e32 v72, v69, v71, vcc
	s_waitcnt lgkmcnt(1)
	v_pk_mul_f32 v[84:85], v[84:85], v[72:73] op_sel_hi:[1,0]
	s_waitcnt lgkmcnt(0)
	v_pk_mul_f32 v[98:99], v[98:99], v[72:73] op_sel_hi:[1,0]
	v_mul_f32_e32 v69, 0xbfb8aa3b, v84
	v_exp_f32_e32 v92, v69
	v_mul_f32_e32 v69, 0xbfb8aa3b, v85
	v_exp_f32_e32 v93, v69
	s_nop 0
	v_pk_add_f32 v[92:93], v[92:93], 1.0 op_sel_hi:[1,0]
	s_nop 0
	v_rcp_f32_e32 v71, v93
	s_nop 0
	v_mul_f32_e32 v85, v85, v71
	v_div_scale_f32 v69, s[36:37], v92, v92, v84
	v_rcp_f32_e32 v71, v69
	s_nop 0
	v_fma_f32 v73, -v69, v71, 1.0
	v_fmac_f32_e32 v71, v73, v71
	v_div_scale_f32 v73, vcc, v84, v92, v84
	v_mul_f32_e32 v75, v73, v71
	v_fma_f32 v77, -v69, v75, v73
	v_fmac_f32_e32 v75, v77, v71
	v_fma_f32 v69, -v69, v75, v73
	v_div_fmas_f32 v69, v69, v71, v75
	v_pk_mul_f32 v[86:87], v[86:87], v[72:73] op_sel_hi:[1,0]
	v_div_fixup_f32 v84, v69, v92, v84
	v_mul_f32_e32 v69, 0xbfb8aa3b, v86
	v_exp_f32_e32 v92, v69
	v_mul_f32_e32 v69, 0xbfb8aa3b, v87
	v_exp_f32_e32 v93, v69
	v_pk_mul_f32 v[72:73], v[100:101], v[72:73] op_sel_hi:[1,0]
	v_pk_mul_f32 v[84:85], v[98:99], v[84:85]
	v_pk_add_f32 v[92:93], v[92:93], 1.0 op_sel_hi:[1,0]
	s_nop 0
	v_div_scale_f32 v69, s[36:37], v93, v93, v87
	v_rcp_f32_e32 v71, v69
	v_cvt_pk_bf16_f32 v84, v84, v85
	v_fma_f32 v75, -v69, v71, 1.0
	v_fmac_f32_e32 v71, v75, v71
	v_div_scale_f32 v75, vcc, v87, v93, v87
	v_mul_f32_e32 v77, v75, v71
	v_fma_f32 v89, -v69, v77, v75
	v_fmac_f32_e32 v77, v89, v71
	v_fma_f32 v69, -v69, v77, v75
	v_div_fmas_f32 v69, v69, v71, v77
	v_div_fixup_f32 v87, v69, v93, v87
	v_rcp_f32_e32 v71, v92
	s_nop 0
	v_mul_f32_e32 v86, v86, v71
	v_add_u32_e32 v69, 0xa00, v142
	v_pk_mul_f32 v[72:73], v[72:73], v[86:87]
	v_ashrrev_i32_e32 v69, 5, v69
	v_cvt_pk_bf16_f32 v85, v72, v73
	v_add_u32_e32 v72, s10, v69
	v_mad_i64_i32 v[70:71], s[36:37], v70, s39, v[66:67]
	v_ashrrev_i32_e32 v73, 31, v72
	global_store_dwordx2 v[70:71], v[84:85], off
	v_lshl_add_u64 v[84:85], v[72:73], 4, s[46:47]
	v_mad_u64_u32 v[70:71], s[36:37], v69, s42, v[74:75]
	v_add_f32_e32 v71, v156, v157
	v_add_f32_e32 v71, v71, v158
	v_add_f32_e32 v71, v71, v159
	v_fmamk_f32 v71, v71, 0x3a800000, v200
	v_cmp_gt_f32_e32 vcc, s33, v71
	v_mul_f32_e32 v73, 0x4b800000, v71
	ds_read_b128 v[84:87], v70
	ds_read_b128 v[98:101], v70 offset:64
	v_cndmask_b32_e32 v71, v71, v73, vcc
	v_rsq_f32_e32 v71, v71
	s_nop 0
	v_mul_f32_e32 v73, 0x45800000, v71
	v_cndmask_b32_e32 v92, v71, v73, vcc
	s_waitcnt lgkmcnt(1)
	v_pk_mul_f32 v[84:85], v[84:85], v[92:93] op_sel_hi:[1,0]
	v_pk_mul_f32 v[86:87], v[86:87], v[92:93] op_sel_hi:[1,0]
	v_mul_f32_e32 v71, 0xbfb8aa3b, v84
	v_exp_f32_e32 v102, v71
	v_mul_f32_e32 v71, 0xbfb8aa3b, v85
	v_exp_f32_e32 v103, v71
	s_waitcnt lgkmcnt(0)
	v_pk_mul_f32 v[98:99], v[98:99], v[92:93] op_sel_hi:[1,0]
	v_pk_mul_f32 v[92:93], v[100:101], v[92:93] op_sel_hi:[1,0]
	v_pk_add_f32 v[102:103], v[102:103], 1.0 op_sel_hi:[1,0]
	s_nop 0
	v_rcp_f32_e32 v73, v103
	s_nop 0
	v_mul_f32_e32 v85, v85, v73
	v_rcp_f32_e32 v73, v102
	s_nop 0
	v_mul_f32_e32 v84, v84, v73
	v_mul_f32_e32 v71, 0xbfb8aa3b, v86
	v_pk_mul_f32 v[84:85], v[98:99], v[84:85]
	v_exp_f32_e32 v98, v71
	v_mul_f32_e32 v71, 0xbfb8aa3b, v87
	v_exp_f32_e32 v99, v71
	v_cvt_pk_bf16_f32 v84, v84, v85
	v_pk_add_f32 v[98:99], v[98:99], 1.0 op_sel_hi:[1,0]
	s_nop 0
	v_rcp_f32_e32 v73, v99
	s_nop 0
	v_mul_f32_e32 v87, v87, v73
	v_rcp_f32_e32 v73, v98
	s_nop 0
	v_mul_f32_e32 v86, v86, v73
	v_pk_mul_f32 v[86:87], v[92:93], v[86:87]
	v_add_u32_e32 v71, 0xc00, v142
	v_cvt_pk_bf16_f32 v85, v86, v87
	v_mad_i64_i32 v[72:73], s[36:37], v72, s39, v[66:67]
	v_ashrrev_i32_e32 v71, 5, v71
	global_store_dwordx2 v[72:73], v[84:85], off
	v_add_u32_e32 v84, s10, v71
	v_ashrrev_i32_e32 v85, 31, v84
	v_lshl_add_u64 v[86:87], v[84:85], 4, s[46:47]
	v_mad_u64_u32 v[72:73], s[36:37], v71, s42, v[74:75]
	v_add_f32_e32 v73, v160, v161
	v_add_f32_e32 v73, v73, v162
	v_add_f32_e32 v73, v73, v163
	v_fmamk_f32 v73, v73, 0x3a800000, v200
	v_cmp_gt_f32_e32 vcc, s33, v73
	v_mul_f32_e32 v75, 0x4b800000, v73
	ds_read_b128 v[98:101], v72
	ds_read_b128 v[102:105], v72 offset:64
	v_cndmask_b32_e32 v73, v73, v75, vcc
	v_rsq_f32_e32 v73, v73
	s_nop 0
	v_mul_f32_e32 v75, 0x45800000, v73
	v_cndmask_b32_e32 v86, v73, v75, vcc
	s_waitcnt lgkmcnt(1)
	v_pk_mul_f32 v[92:93], v[98:99], v[86:87] op_sel_hi:[1,0]
	s_waitcnt lgkmcnt(0)
	v_pk_mul_f32 v[102:103], v[102:103], v[86:87] op_sel_hi:[1,0]
	v_mul_f32_e32 v73, 0xbfb8aa3b, v92
	v_exp_f32_e32 v98, v73
	v_mul_f32_e32 v73, 0xbfb8aa3b, v93
	v_exp_f32_e32 v99, v73
	s_nop 0
	v_pk_add_f32 v[98:99], v[98:99], 1.0 op_sel_hi:[1,0]
	s_nop 0
	v_rcp_f32_e32 v75, v99
	s_nop 0
	v_mul_f32_e32 v93, v93, v75
	v_rcp_f32_e32 v75, v98
	s_nop 0
	v_mul_f32_e32 v92, v92, v75
	v_pk_mul_f32 v[98:99], v[100:101], v[86:87] op_sel_hi:[1,0]
	v_pk_mul_f32 v[86:87], v[104:105], v[86:87] op_sel_hi:[1,0]
	v_mul_f32_e32 v73, 0xbfb8aa3b, v98
	v_exp_f32_e32 v100, v73
	v_mul_f32_e32 v73, 0xbfb8aa3b, v99
	v_exp_f32_e32 v101, v73
	v_pk_mul_f32 v[92:93], v[102:103], v[92:93]
	v_pk_add_f32 v[100:101], v[100:101], 1.0 op_sel_hi:[1,0]
	s_nop 0
	v_div_scale_f32 v73, s[36:37], v101, v101, v99
	v_rcp_f32_e32 v75, v73
	v_cvt_pk_bf16_f32 v92, v92, v93
	v_fma_f32 v77, -v73, v75, 1.0
	v_fmac_f32_e32 v75, v77, v75
	v_div_scale_f32 v77, vcc, v99, v101, v99
	v_mul_f32_e32 v85, v77, v75
	v_fma_f32 v89, -v73, v85, v77
	v_fmac_f32_e32 v85, v89, v75
	v_fma_f32 v73, -v73, v85, v77
	v_div_fmas_f32 v73, v73, v75, v85
	v_div_fixup_f32 v99, v73, v101, v99
	v_rcp_f32_e32 v75, v100
	s_nop 0
	v_mul_f32_e32 v98, v98, v75
	v_pk_mul_f32 v[86:87], v[86:87], v[98:99]
	v_add_u32_e32 v73, 0xe00, v142
	v_cvt_pk_bf16_f32 v93, v86, v87
	v_mad_i64_i32 v[84:85], s[36:37], v84, s39, v[66:67]
	v_ashrrev_i32_e32 v73, 5, v73
	global_store_dwordx2 v[84:85], v[92:93], off
	v_add_u32_e32 v84, s10, v73
	v_ashrrev_i32_e32 v85, 31, v84
	v_lshl_add_u64 v[86:87], v[84:85], 4, s[46:47]
	v_mad_u64_u32 v[74:75], s[36:37], v73, s42, v[74:75]
	v_mov_b32_e32 v142, v201
	s_or_b32 s42, s38, 0x100
	s_ashr_i32 s43, s42, 31
	s_lshl_b64 s[70:71], s[42:43], 11
	v_add_f32_e32 v75, v164, v165
	v_add_f32_e32 v75, v75, v166
	v_add_f32_e32 v75, v75, v167
	v_fmamk_f32 v75, v75, 0x3a800000, v200
	v_cmp_gt_f32_e32 vcc, s33, v75
	v_mul_f32_e32 v77, 0x4b800000, v75
	ds_read_b128 v[98:101], v74
	ds_read_b128 v[102:105], v74 offset:64
	v_cndmask_b32_e32 v75, v75, v77, vcc
	v_rsq_f32_e32 v75, v75
	s_nop 0
	v_mul_f32_e32 v77, 0x45800000, v75
	v_cndmask_b32_e32 v86, v75, v77, vcc
	s_waitcnt lgkmcnt(1)
	v_pk_mul_f32 v[92:93], v[98:99], v[86:87] op_sel_hi:[1,0]
	s_waitcnt lgkmcnt(0)
	v_pk_mul_f32 v[102:103], v[102:103], v[86:87] op_sel_hi:[1,0]
	v_mul_f32_e32 v75, 0xbfb8aa3b, v92
	v_exp_f32_e32 v98, v75
	v_mul_f32_e32 v75, 0xbfb8aa3b, v93
	v_exp_f32_e32 v99, v75
	s_nop 0
	v_pk_add_f32 v[98:99], v[98:99], 1.0 op_sel_hi:[1,0]
	s_nop 0
	v_rcp_f32_e32 v77, v99
	s_nop 0
	v_mul_f32_e32 v93, v93, v77
	v_rcp_f32_e32 v77, v98
	s_nop 0
	v_mul_f32_e32 v92, v92, v77
	v_pk_mul_f32 v[98:99], v[100:101], v[86:87] op_sel_hi:[1,0]
	v_pk_mul_f32 v[92:93], v[102:103], v[92:93]
	v_mul_f32_e32 v75, 0xbfb8aa3b, v98
	v_exp_f32_e32 v100, v75
	v_mul_f32_e32 v75, 0xbfb8aa3b, v99
	v_exp_f32_e32 v101, v75
	v_pk_mul_f32 v[86:87], v[104:105], v[86:87] op_sel_hi:[1,0]
	v_cvt_pk_bf16_f32 v92, v92, v93
	v_pk_add_f32 v[100:101], v[100:101], 1.0 op_sel_hi:[1,0]
	s_nop 0
	v_rcp_f32_e32 v77, v101
	s_nop 0
	v_mul_f32_e32 v99, v99, v77
	v_rcp_f32_e32 v77, v100
	s_nop 0
	v_mul_f32_e32 v98, v98, v77
	v_pk_mul_f32 v[86:87], v[86:87], v[98:99]
	v_mad_i64_i32 v[84:85], s[36:37], v84, s39, v[66:67]
	v_cvt_pk_bf16_f32 v93, v86, v87
	global_store_dwordx2 v[84:85], v[92:93], off
	s_barrier
	ds_write2_b32 v130, v2, v18 offset1:16
	ds_write2_b32 v114, v3, v19 offset0:4 offset1:20
	ds_write2_b32 v115, v4, v20 offset0:8 offset1:24
	ds_write2_b32 v116, v5, v21 offset0:12 offset1:28
	ds_write2_b32 v117, v6, v22 offset0:64 offset1:80
	ds_write2_b32 v94, v7, v23 offset0:68 offset1:84
	ds_write2_b32 v95, v8, v24 offset0:72 offset1:88
	ds_write2_b32 v96, v9, v25 offset0:76 offset1:92
	ds_write2_b32 v132, v10, v26 offset0:128 offset1:144
	ds_write2_b32 v97, v11, v27 offset0:132 offset1:148
	ds_write2_b32 v126, v12, v28 offset0:136 offset1:152
	ds_write2_b32 v127, v13, v29 offset0:140 offset1:156
	ds_write2_b32 v133, v14, v30 offset0:192 offset1:208
	ds_write2_b32 v128, v15, v31 offset0:196 offset1:212
	ds_write2_b32 v129, v16, v32 offset0:200 offset1:216
	ds_write2_b32 v131, v17, v33 offset0:204 offset1:220
	ds_write2_b32 v130, v34, v50 offset0:128 offset1:144
	ds_write2_b32 v114, v35, v51 offset0:132 offset1:148
	ds_write2_b32 v115, v36, v52 offset0:136 offset1:152
	ds_write2_b32 v116, v37, v53 offset0:140 offset1:156
	ds_write2_b32 v117, v38, v54 offset0:192 offset1:208
	ds_write2_b32 v94, v39, v55 offset0:196 offset1:212
	ds_write2_b32 v95, v40, v56 offset0:200 offset1:216
	ds_write2_b32 v96, v41, v57 offset0:204 offset1:220
	ds_write2_b32 v97, v42, v58 offset1:16
	ds_write2_b32 v126, v43, v59 offset0:4 offset1:20
	ds_write2_b32 v127, v44, v60 offset0:8 offset1:24
	ds_write2_b32 v90, v45, v61 offset0:12 offset1:28
	ds_write2_b32 v128, v46, v62 offset0:64 offset1:80
	ds_write2_b32 v129, v47, v63 offset0:68 offset1:84
	ds_write2_b32 v131, v48, v64 offset0:72 offset1:88
	ds_write2_b32 v91, v49, v65 offset0:76 offset1:92
	v_add_u32_e32 v2, s8, v88
	v_ashrrev_i32_e32 v3, 31, v2
	v_lshl_add_u64 v[4:5], v[2:3], 4, s[46:47]
	s_waitcnt lgkmcnt(0)
	s_barrier
	global_load_dwordx4 v[134:137], v[4:5], off
	global_load_dwordx4 v[138:141], v[4:5], off offset:256
	global_load_dwordx4 v[144:147], v[4:5], off offset:512
	global_load_dwordx4 v[148:151], v[4:5], off offset:768
	global_load_dwordx4 v[152:155], v[4:5], off offset:1024
	global_load_dwordx4 v[156:159], v[4:5], off offset:1280
	global_load_dwordx4 v[160:163], v[4:5], off offset:1536
	global_load_dwordx4 v[164:167], v[4:5], off offset:1792
	s_waitcnt vmcnt(0)
	v_add_f32_e32 v3, v134, v135
	v_add_f32_e32 v3, v3, v136
	v_add_f32_e32 v3, v3, v137
	v_fmamk_f32 v3, v3, 0x3a800000, v200
	v_cmp_gt_f32_e32 vcc, s33, v3
	v_mul_f32_e32 v4, 0x4b800000, v3
	s_nop 0
	v_cndmask_b32_e32 v3, v3, v4, vcc
	v_rsq_f32_e32 v3, v3
	s_nop 0
	v_mul_f32_e32 v4, 0x45800000, v3
	v_cndmask_b32_e32 v12, v3, v4, vcc
	ds_read_b128 v[4:7], v82
	ds_read_b128 v[8:11], v82 offset:64
	s_waitcnt lgkmcnt(1)
	v_pk_mul_f32 v[4:5], v[4:5], v[12:13] op_sel_hi:[1,0]
	s_nop 0
	v_mul_f32_e32 v3, 0xbfb8aa3b, v4
	v_exp_f32_e32 v14, v3
	v_mul_f32_e32 v3, 0xbfb8aa3b, v5
	v_exp_f32_e32 v15, v3
	s_waitcnt lgkmcnt(0)
	v_pk_mul_f32 v[8:9], v[8:9], v[12:13] op_sel_hi:[1,0]
	v_pk_add_f32 v[14:15], v[14:15], 1.0 op_sel_hi:[1,0]
	s_nop 0
	v_rcp_f32_e32 v13, v15
	s_nop 0
	v_mul_f32_e32 v5, v5, v13
	v_div_scale_f32 v3, s[36:37], v14, v14, v4
	v_rcp_f32_e32 v13, v3
	s_nop 0
	v_fma_f32 v15, -v3, v13, 1.0
	v_fmac_f32_e32 v13, v15, v13
	v_div_scale_f32 v15, vcc, v4, v14, v4
	v_mul_f32_e32 v16, v15, v13
	v_fma_f32 v17, -v3, v16, v15
	v_fmac_f32_e32 v16, v17, v13
	v_fma_f32 v3, -v3, v16, v15
	v_div_fmas_f32 v3, v3, v13, v16
	v_pk_mul_f32 v[6:7], v[6:7], v[12:13] op_sel_hi:[1,0]
	v_div_fixup_f32 v4, v3, v14, v4
	v_mul_f32_e32 v3, 0xbfb8aa3b, v6
	v_pk_mul_f32 v[4:5], v[8:9], v[4:5]
	v_exp_f32_e32 v8, v3
	v_mul_f32_e32 v3, 0xbfb8aa3b, v7
	v_exp_f32_e32 v9, v3
	v_pk_mul_f32 v[10:11], v[10:11], v[12:13] op_sel_hi:[1,0]
	v_cvt_pk_bf16_f32 v4, v4, v5
	v_pk_add_f32 v[8:9], v[8:9], 1.0 op_sel_hi:[1,0]
	s_nop 0
	v_rcp_f32_e32 v12, v9
	s_nop 0
	v_mul_f32_e32 v7, v7, v12
	v_rcp_f32_e32 v9, v8
	s_nop 0
	v_mul_f32_e32 v6, v6, v9
	v_pk_mul_f32 v[6:7], v[10:11], v[6:7]
	v_mad_i64_i32 v[2:3], s[36:37], v2, s39, v[66:67]
	v_cvt_pk_bf16_f32 v5, v6, v7
	global_store_dwordx2 v[2:3], v[4:5], off
	v_add_u32_e32 v2, s8, v83
	v_ashrrev_i32_e32 v3, 31, v2
	v_lshl_add_u64 v[4:5], v[2:3], 4, s[46:47]
	v_add_f32_e32 v3, v138, v139
	v_add_f32_e32 v3, v3, v140
	v_add_f32_e32 v3, v3, v141
	v_fmamk_f32 v3, v3, 0x3a800000, v200
	v_cmp_gt_f32_e32 vcc, s33, v3
	v_mul_f32_e32 v4, 0x4b800000, v3
	s_nop 0
	v_cndmask_b32_e32 v3, v3, v4, vcc
	v_rsq_f32_e32 v3, v3
	s_nop 0
	v_mul_f32_e32 v4, 0x45800000, v3
	v_cndmask_b32_e32 v12, v3, v4, vcc
	ds_read_b128 v[4:7], v80
	ds_read_b128 v[8:11], v80 offset:64
	s_waitcnt lgkmcnt(1)
	v_pk_mul_f32 v[4:5], v[4:5], v[12:13] op_sel_hi:[1,0]
	s_nop 0
	v_mul_f32_e32 v3, 0xbfb8aa3b, v4
	v_exp_f32_e32 v14, v3
	v_mul_f32_e32 v3, 0xbfb8aa3b, v5
	v_exp_f32_e32 v15, v3
	s_waitcnt lgkmcnt(0)
	v_pk_mul_f32 v[8:9], v[8:9], v[12:13] op_sel_hi:[1,0]
	v_pk_add_f32 v[14:15], v[14:15], 1.0 op_sel_hi:[1,0]
	s_nop 0
	v_rcp_f32_e32 v13, v15
	s_nop 0
	v_mul_f32_e32 v5, v5, v13
	v_div_scale_f32 v3, s[36:37], v14, v14, v4
	v_rcp_f32_e32 v13, v3
	s_nop 0
	v_fma_f32 v15, -v3, v13, 1.0
	v_fmac_f32_e32 v13, v15, v13
	v_div_scale_f32 v15, vcc, v4, v14, v4
	v_mul_f32_e32 v16, v15, v13
	v_fma_f32 v17, -v3, v16, v15
	v_fmac_f32_e32 v16, v17, v13
	v_fma_f32 v3, -v3, v16, v15
	v_div_fmas_f32 v3, v3, v13, v16
	v_pk_mul_f32 v[6:7], v[6:7], v[12:13] op_sel_hi:[1,0]
	v_div_fixup_f32 v4, v3, v14, v4
	v_mul_f32_e32 v3, 0xbfb8aa3b, v6
	v_pk_mul_f32 v[4:5], v[8:9], v[4:5]
	v_exp_f32_e32 v8, v3
	v_mul_f32_e32 v3, 0xbfb8aa3b, v7
	v_exp_f32_e32 v9, v3
	v_pk_mul_f32 v[10:11], v[10:11], v[12:13] op_sel_hi:[1,0]
	v_cvt_pk_bf16_f32 v4, v4, v5
	v_pk_add_f32 v[8:9], v[8:9], 1.0 op_sel_hi:[1,0]
	s_nop 0
	v_rcp_f32_e32 v12, v9
	s_nop 0
	v_mul_f32_e32 v7, v7, v12
	v_rcp_f32_e32 v9, v8
	s_nop 0
	v_mul_f32_e32 v6, v6, v9
	v_pk_mul_f32 v[6:7], v[10:11], v[6:7]
	v_mad_i64_i32 v[2:3], s[36:37], v2, s39, v[66:67]
	v_cvt_pk_bf16_f32 v5, v6, v7
	global_store_dwordx2 v[2:3], v[4:5], off
	v_add_u32_e32 v2, s8, v81
	v_ashrrev_i32_e32 v3, 31, v2
	v_lshl_add_u64 v[4:5], v[2:3], 4, s[46:47]
	v_add_f32_e32 v3, v144, v145
	v_add_f32_e32 v3, v3, v146
	v_add_f32_e32 v3, v3, v147
	v_fmamk_f32 v3, v3, 0x3a800000, v200
	v_cmp_gt_f32_e32 vcc, s33, v3
	v_mul_f32_e32 v4, 0x4b800000, v3
	s_nop 0
	v_cndmask_b32_e32 v3, v3, v4, vcc
	v_rsq_f32_e32 v3, v3
	s_nop 0
	v_mul_f32_e32 v4, 0x45800000, v3
	v_cndmask_b32_e32 v12, v3, v4, vcc
	ds_read_b128 v[4:7], v78
	ds_read_b128 v[8:11], v78 offset:64
	s_waitcnt lgkmcnt(1)
	v_pk_mul_f32 v[4:5], v[4:5], v[12:13] op_sel_hi:[1,0]
	s_nop 0
	v_mul_f32_e32 v3, 0xbfb8aa3b, v4
	v_exp_f32_e32 v14, v3
	v_mul_f32_e32 v3, 0xbfb8aa3b, v5
	v_exp_f32_e32 v15, v3
	s_waitcnt lgkmcnt(0)
	v_pk_mul_f32 v[8:9], v[8:9], v[12:13] op_sel_hi:[1,0]
	v_pk_add_f32 v[14:15], v[14:15], 1.0 op_sel_hi:[1,0]
	s_nop 0
	v_rcp_f32_e32 v13, v15
	s_nop 0
	v_mul_f32_e32 v5, v5, v13
	v_div_scale_f32 v3, s[36:37], v14, v14, v4
	v_rcp_f32_e32 v13, v3
	s_nop 0
	v_fma_f32 v15, -v3, v13, 1.0
	v_fmac_f32_e32 v13, v15, v13
	v_div_scale_f32 v15, vcc, v4, v14, v4
	v_mul_f32_e32 v16, v15, v13
	v_fma_f32 v17, -v3, v16, v15
	v_fmac_f32_e32 v16, v17, v13
	v_fma_f32 v3, -v3, v16, v15
	v_div_fmas_f32 v3, v3, v13, v16
	v_pk_mul_f32 v[6:7], v[6:7], v[12:13] op_sel_hi:[1,0]
	v_div_fixup_f32 v4, v3, v14, v4
	v_mul_f32_e32 v3, 0xbfb8aa3b, v6
	v_pk_mul_f32 v[4:5], v[8:9], v[4:5]
	v_exp_f32_e32 v8, v3
	v_mul_f32_e32 v3, 0xbfb8aa3b, v7
	v_exp_f32_e32 v9, v3
	v_pk_mul_f32 v[10:11], v[10:11], v[12:13] op_sel_hi:[1,0]
	v_cvt_pk_bf16_f32 v4, v4, v5
	v_pk_add_f32 v[8:9], v[8:9], 1.0 op_sel_hi:[1,0]
	s_nop 0
	v_rcp_f32_e32 v12, v9
	s_nop 0
	v_mul_f32_e32 v7, v7, v12
	v_rcp_f32_e32 v9, v8
	s_nop 0
	v_mul_f32_e32 v6, v6, v9
	v_pk_mul_f32 v[6:7], v[10:11], v[6:7]
	v_mad_i64_i32 v[2:3], s[36:37], v2, s39, v[66:67]
	v_cvt_pk_bf16_f32 v5, v6, v7
	global_store_dwordx2 v[2:3], v[4:5], off
	v_add_u32_e32 v2, s8, v79
	v_ashrrev_i32_e32 v3, 31, v2
	v_lshl_add_u64 v[4:5], v[2:3], 4, s[46:47]
	v_add_f32_e32 v3, v148, v149
	v_add_f32_e32 v3, v3, v150
	v_add_f32_e32 v3, v3, v151
	v_fmamk_f32 v3, v3, 0x3a800000, v200
	v_cmp_gt_f32_e32 vcc, s33, v3
	v_mul_f32_e32 v4, 0x4b800000, v3
	s_nop 0
	v_cndmask_b32_e32 v3, v3, v4, vcc
	v_rsq_f32_e32 v3, v3
	s_nop 0
	v_mul_f32_e32 v4, 0x45800000, v3
	v_cndmask_b32_e32 v12, v3, v4, vcc
	ds_read_b128 v[4:7], v76
	ds_read_b128 v[8:11], v76 offset:64
	s_waitcnt lgkmcnt(1)
	v_pk_mul_f32 v[4:5], v[4:5], v[12:13] op_sel_hi:[1,0]
	s_nop 0
	v_mul_f32_e32 v3, 0xbfb8aa3b, v4
	v_exp_f32_e32 v14, v3
	v_mul_f32_e32 v3, 0xbfb8aa3b, v5
	v_exp_f32_e32 v15, v3
	s_waitcnt lgkmcnt(0)
	v_pk_mul_f32 v[8:9], v[8:9], v[12:13] op_sel_hi:[1,0]
	v_pk_add_f32 v[14:15], v[14:15], 1.0 op_sel_hi:[1,0]
	s_nop 0
	v_rcp_f32_e32 v13, v15
	s_nop 0
	v_mul_f32_e32 v5, v5, v13
	v_div_scale_f32 v3, s[36:37], v14, v14, v4
	v_rcp_f32_e32 v13, v3
	s_nop 0
	v_fma_f32 v15, -v3, v13, 1.0
	v_fmac_f32_e32 v13, v15, v13
	v_div_scale_f32 v15, vcc, v4, v14, v4
	v_mul_f32_e32 v16, v15, v13
	v_fma_f32 v17, -v3, v16, v15
	v_fmac_f32_e32 v16, v17, v13
	v_fma_f32 v3, -v3, v16, v15
	v_div_fmas_f32 v3, v3, v13, v16
	v_pk_mul_f32 v[6:7], v[6:7], v[12:13] op_sel_hi:[1,0]
	v_div_fixup_f32 v4, v3, v14, v4
	v_mul_f32_e32 v3, 0xbfb8aa3b, v6
	v_pk_mul_f32 v[4:5], v[8:9], v[4:5]
	v_exp_f32_e32 v8, v3
	v_mul_f32_e32 v3, 0xbfb8aa3b, v7
	v_exp_f32_e32 v9, v3
	v_pk_mul_f32 v[10:11], v[10:11], v[12:13] op_sel_hi:[1,0]
	v_cvt_pk_bf16_f32 v4, v4, v5
	v_pk_add_f32 v[8:9], v[8:9], 1.0 op_sel_hi:[1,0]
	s_nop 0
	v_rcp_f32_e32 v12, v9
	s_nop 0
	v_mul_f32_e32 v7, v7, v12
	v_rcp_f32_e32 v9, v8
	s_nop 0
	v_mul_f32_e32 v6, v6, v9
	v_pk_mul_f32 v[6:7], v[10:11], v[6:7]
	v_mad_i64_i32 v[2:3], s[36:37], v2, s39, v[66:67]
	v_cvt_pk_bf16_f32 v5, v6, v7
	global_store_dwordx2 v[2:3], v[4:5], off
	v_add_u32_e32 v2, s8, v0
	v_ashrrev_i32_e32 v3, 31, v2
	v_lshl_add_u64 v[4:5], v[2:3], 4, s[46:47]
	v_add_f32_e32 v0, v152, v153
	v_add_f32_e32 v0, v0, v154
	v_add_f32_e32 v0, v0, v155
	v_fmamk_f32 v0, v0, 0x3a800000, v200
	v_cmp_gt_f32_e32 vcc, s33, v0
	v_mul_f32_e32 v3, 0x4b800000, v0
	ds_read_b128 v[4:7], v68
	ds_read_b128 v[8:11], v68 offset:64
	v_cndmask_b32_e32 v0, v0, v3, vcc
	v_rsq_f32_e32 v0, v0
	s_nop 0
	v_mul_f32_e32 v3, 0x45800000, v0
	v_cndmask_b32_e32 v0, v0, v3, vcc
	s_waitcnt lgkmcnt(1)
	v_pk_mul_f32 v[4:5], v[4:5], v[0:1] op_sel_hi:[1,0]
	v_pk_mul_f32 v[6:7], v[6:7], v[0:1] op_sel_hi:[1,0]
	v_mul_f32_e32 v3, 0xbfb8aa3b, v4
	v_exp_f32_e32 v12, v3
	v_mul_f32_e32 v3, 0xbfb8aa3b, v5
	v_exp_f32_e32 v13, v3
	s_waitcnt lgkmcnt(0)
	v_pk_mul_f32 v[8:9], v[8:9], v[0:1] op_sel_hi:[1,0]
	v_pk_mul_f32 v[10:11], v[10:11], v[0:1] op_sel_hi:[1,0]
	v_mul_f32_e32 v0, 0xbfb8aa3b, v7
	v_pk_add_f32 v[12:13], v[12:13], 1.0 op_sel_hi:[1,0]
	s_nop 0
	v_rcp_f32_e32 v14, v13
	s_nop 0
	v_mul_f32_e32 v5, v5, v14
	v_rcp_f32_e32 v13, v12
	s_nop 0
	v_mul_f32_e32 v4, v4, v13
	v_mul_f32_e32 v3, 0xbfb8aa3b, v6
	v_pk_mul_f32 v[4:5], v[8:9], v[4:5]
	v_exp_f32_e32 v8, v3
	v_exp_f32_e32 v9, v0
	v_cvt_pk_bf16_f32 v4, v4, v5
	v_pk_add_f32 v[8:9], v[8:9], 1.0 op_sel_hi:[1,0]
	s_nop 0
	v_rcp_f32_e32 v3, v9
	s_nop 0
	v_mul_f32_e32 v7, v7, v3
	v_rcp_f32_e32 v3, v8
	s_nop 0
	v_mul_f32_e32 v6, v6, v3
	v_pk_mul_f32 v[6:7], v[10:11], v[6:7]
	v_mad_i64_i32 v[2:3], s[36:37], v2, s39, v[66:67]
	v_cvt_pk_bf16_f32 v5, v6, v7
	global_store_dwordx2 v[2:3], v[4:5], off
	v_add_u32_e32 v2, s8, v69
	v_ashrrev_i32_e32 v3, 31, v2
	v_lshl_add_u64 v[4:5], v[2:3], 4, s[46:47]
	v_add_f32_e32 v0, v156, v157
	v_add_f32_e32 v0, v0, v158
	v_add_f32_e32 v0, v0, v159
	v_fmamk_f32 v0, v0, 0x3a800000, v200
	v_cmp_gt_f32_e32 vcc, s33, v0
	v_mul_f32_e32 v3, 0x4b800000, v0
	ds_read_b128 v[4:7], v70
	ds_read_b128 v[8:11], v70 offset:64
	v_cndmask_b32_e32 v0, v0, v3, vcc
	v_rsq_f32_e32 v0, v0
	s_nop 0
	v_mul_f32_e32 v3, 0x45800000, v0
	v_cndmask_b32_e32 v0, v0, v3, vcc
	s_waitcnt lgkmcnt(1)
	v_pk_mul_f32 v[4:5], v[4:5], v[0:1] op_sel_hi:[1,0]
	v_pk_mul_f32 v[6:7], v[6:7], v[0:1] op_sel_hi:[1,0]
	v_mul_f32_e32 v3, 0xbfb8aa3b, v4
	v_exp_f32_e32 v12, v3
	v_mul_f32_e32 v3, 0xbfb8aa3b, v5
	v_exp_f32_e32 v13, v3
	s_waitcnt lgkmcnt(0)
	v_pk_mul_f32 v[8:9], v[8:9], v[0:1] op_sel_hi:[1,0]
	v_pk_mul_f32 v[10:11], v[10:11], v[0:1] op_sel_hi:[1,0]
	v_mul_f32_e32 v0, 0xbfb8aa3b, v7
	v_pk_add_f32 v[12:13], v[12:13], 1.0 op_sel_hi:[1,0]
	s_nop 0
	v_rcp_f32_e32 v14, v13
	s_nop 0
	v_mul_f32_e32 v5, v5, v14
	v_rcp_f32_e32 v13, v12
	s_nop 0
	v_mul_f32_e32 v4, v4, v13
	v_mul_f32_e32 v3, 0xbfb8aa3b, v6
	v_pk_mul_f32 v[4:5], v[8:9], v[4:5]
	v_exp_f32_e32 v8, v3
	v_exp_f32_e32 v9, v0
	v_cvt_pk_bf16_f32 v4, v4, v5
	v_pk_add_f32 v[8:9], v[8:9], 1.0 op_sel_hi:[1,0]
	s_nop 0
	v_rcp_f32_e32 v3, v9
	s_nop 0
	v_mul_f32_e32 v7, v7, v3
	v_rcp_f32_e32 v3, v8
	s_nop 0
	v_mul_f32_e32 v6, v6, v3
	v_pk_mul_f32 v[6:7], v[10:11], v[6:7]
	v_mad_i64_i32 v[2:3], s[36:37], v2, s39, v[66:67]
	v_cvt_pk_bf16_f32 v5, v6, v7
	global_store_dwordx2 v[2:3], v[4:5], off
	v_add_u32_e32 v2, s8, v71
	v_ashrrev_i32_e32 v3, 31, v2
	v_lshl_add_u64 v[4:5], v[2:3], 4, s[46:47]
	v_add_f32_e32 v0, v160, v161
	v_add_f32_e32 v0, v0, v162
	v_add_f32_e32 v0, v0, v163
	v_fmamk_f32 v0, v0, 0x3a800000, v200
	v_cmp_gt_f32_e32 vcc, s33, v0
	v_mul_f32_e32 v3, 0x4b800000, v0
	ds_read_b128 v[4:7], v72
	ds_read_b128 v[8:11], v72 offset:64
	v_cndmask_b32_e32 v0, v0, v3, vcc
	v_rsq_f32_e32 v0, v0
	s_nop 0
	v_mul_f32_e32 v3, 0x45800000, v0
	v_cndmask_b32_e32 v0, v0, v3, vcc
	s_waitcnt lgkmcnt(1)
	v_pk_mul_f32 v[4:5], v[4:5], v[0:1] op_sel_hi:[1,0]
	v_pk_mul_f32 v[6:7], v[6:7], v[0:1] op_sel_hi:[1,0]
	v_mul_f32_e32 v3, 0xbfb8aa3b, v4
	v_exp_f32_e32 v12, v3
	v_mul_f32_e32 v3, 0xbfb8aa3b, v5
	v_exp_f32_e32 v13, v3
	s_waitcnt lgkmcnt(0)
	v_pk_mul_f32 v[8:9], v[8:9], v[0:1] op_sel_hi:[1,0]
	v_pk_mul_f32 v[10:11], v[10:11], v[0:1] op_sel_hi:[1,0]
	v_mul_f32_e32 v0, 0xbfb8aa3b, v7
	v_pk_add_f32 v[12:13], v[12:13], 1.0 op_sel_hi:[1,0]
	s_nop 0
	v_rcp_f32_e32 v14, v13
	s_nop 0
	v_mul_f32_e32 v5, v5, v14
	v_rcp_f32_e32 v13, v12
	s_nop 0
	v_mul_f32_e32 v4, v4, v13
	v_mul_f32_e32 v3, 0xbfb8aa3b, v6
	v_pk_mul_f32 v[4:5], v[8:9], v[4:5]
	v_exp_f32_e32 v8, v3
	v_exp_f32_e32 v9, v0
	v_cvt_pk_bf16_f32 v4, v4, v5
	v_pk_add_f32 v[8:9], v[8:9], 1.0 op_sel_hi:[1,0]
	s_nop 0
	v_rcp_f32_e32 v3, v9
	s_nop 0
	v_mul_f32_e32 v7, v7, v3
	v_rcp_f32_e32 v3, v8
	s_nop 0
	v_mul_f32_e32 v6, v6, v3
	v_pk_mul_f32 v[6:7], v[10:11], v[6:7]
	v_mad_i64_i32 v[2:3], s[36:37], v2, s39, v[66:67]
	v_cvt_pk_bf16_f32 v5, v6, v7
	global_store_dwordx2 v[2:3], v[4:5], off
	v_add_u32_e32 v2, s8, v73
	v_ashrrev_i32_e32 v3, 31, v2
	v_lshl_add_u64 v[4:5], v[2:3], 4, s[46:47]
	v_add_f32_e32 v0, v164, v165
	v_add_f32_e32 v0, v0, v166
	v_add_f32_e32 v0, v0, v167
	v_fmamk_f32 v0, v0, 0x3a800000, v200
	v_cmp_gt_f32_e32 vcc, s33, v0
	v_mul_f32_e32 v3, 0x4b800000, v0
	ds_read_b128 v[4:7], v74
	ds_read_b128 v[8:11], v74 offset:64
	v_cndmask_b32_e32 v0, v0, v3, vcc
	v_rsq_f32_e32 v0, v0
	s_nop 0
	v_mul_f32_e32 v3, 0x45800000, v0
	v_cndmask_b32_e32 v0, v0, v3, vcc
	s_waitcnt lgkmcnt(1)
	v_pk_mul_f32 v[4:5], v[4:5], v[0:1] op_sel_hi:[1,0]
	v_pk_mul_f32 v[6:7], v[6:7], v[0:1] op_sel_hi:[1,0]
	v_mul_f32_e32 v3, 0xbfb8aa3b, v4
	v_exp_f32_e32 v12, v3
	v_mul_f32_e32 v3, 0xbfb8aa3b, v5
	v_exp_f32_e32 v13, v3
	s_waitcnt lgkmcnt(0)
	v_pk_mul_f32 v[8:9], v[8:9], v[0:1] op_sel_hi:[1,0]
	v_pk_mul_f32 v[10:11], v[10:11], v[0:1] op_sel_hi:[1,0]
	v_mul_f32_e32 v0, 0xbfb8aa3b, v7
	v_pk_add_f32 v[12:13], v[12:13], 1.0 op_sel_hi:[1,0]
	s_nop 0
	v_rcp_f32_e32 v14, v13
	s_nop 0
	v_mul_f32_e32 v5, v5, v14
	v_rcp_f32_e32 v13, v12
	s_nop 0
	v_mul_f32_e32 v4, v4, v13
	v_mul_f32_e32 v3, 0xbfb8aa3b, v6
	v_pk_mul_f32 v[4:5], v[8:9], v[4:5]
	v_exp_f32_e32 v8, v3
	v_exp_f32_e32 v9, v0
	v_cvt_pk_bf16_f32 v4, v4, v5
	v_pk_add_f32 v[8:9], v[8:9], 1.0 op_sel_hi:[1,0]
	s_nop 0
	v_rcp_f32_e32 v3, v9
	s_nop 0
	v_mul_f32_e32 v7, v7, v3
	v_rcp_f32_e32 v3, v8
	s_nop 0
	v_mul_f32_e32 v6, v6, v3
	v_pk_mul_f32 v[6:7], v[10:11], v[6:7]
	v_mad_i64_i32 v[2:3], s[36:37], v2, s39, v[66:67]
	v_cvt_pk_bf16_f32 v5, v6, v7
	global_store_dwordx2 v[2:3], v[4:5], off
	s_barrier
	s_nop 0
	v_ashrrev_i32_e32 v0, 31, v142
	v_lshrrev_b32_e32 v0, 26, v0
	v_add_u32_e32 v0, v142, v0
	v_ashrrev_i32_e32 v16, 6, v0
	v_bfe_i32 v0, v142, 27, 1
	v_lshlrev_b32_e32 v2, 4, v142
	v_lshrrev_b32_e32 v0, 22, v0
	v_add_u32_e32 v0, v2, v0
	v_and_b32_e32 v0, 0xfffffc00, v0
	v_sub_u32_e32 v0, v2, v0
	v_lshrrev_b32_e32 v3, 4, v0
	v_bitop3_b32 v3, v3, v0, 32 bitop3:0x6c
	v_ashrrev_i32_e32 v0, 31, v0
	v_lshrrev_b32_e32 v0, 26, v0
	v_add_u32_e32 v0, v3, v0
	v_ashrrev_i32_e32 v18, 6, v0
	v_mul_i32_i24_e32 v5, 64, v18
	v_sub_u32_e32 v3, v3, v5
	v_lshlrev_b32_e32 v4, 3, v16
	v_lshlrev_b32_e32 v0, 5, v16
	v_ashrrev_i16_sdwa v3, v217, sext(v3) dst_sel:DWORD dst_unused:UNUSED_PAD src0_sel:DWORD src1_sel:BYTE_0
	v_and_b32_e32 v4, 0x1ffff0, v4
	v_and_b32_e32 v0, 32, v0
	v_bfe_i32 v19, v3, 0, 16
	v_add_u32_e32 v0, v0, v19
	v_add_lshl_u32 v3, v18, v4, 11
	v_add_u32_e32 v2, 0x2000, v2
	v_lshl_add_u32 v0, v0, 1, v3
	v_ashrrev_i32_e32 v3, 31, v2
	v_lshrrev_b32_e32 v3, 22, v3
	v_add_u32_e32 v3, v2, v3
	v_ashrrev_i32_e32 v21, 10, v3
	v_mul_i32_i24_e32 v3, 0x400, v21
	v_sub_u32_e32 v2, v2, v3
	v_lshrrev_b32_e32 v3, 4, v2
	v_bitop3_b32 v2, v3, v2, 32 bitop3:0x6c
	v_ashrrev_i32_e32 v4, 31, v2
	v_ashrrev_i32_e32 v20, 6, v142
	v_lshrrev_b32_e32 v4, 26, v4
	v_readfirstlane_b32 s33, v20
	v_add_u32_e32 v4, v2, v4
	s_lshl_b32 s73, s33, 10
	v_ashrrev_i32_e32 v22, 6, v4
	v_and_b32_e32 v4, 0xc0, v4
	v_sub_u32_e32 v2, v2, v4
	s_add_u32 s70, s16, s70
	v_lshlrev_b32_e32 v3, 3, v21
	v_lshlrev_b32_e32 v5, 5, v21
	v_ashrrev_i16_sdwa v2, v217, sext(v2) dst_sel:DWORD dst_unused:UNUSED_PAD src0_sel:DWORD src1_sel:BYTE_0
	s_addc_u32 s71, s17, s71
	s_add_i32 s36, s73, 0
	v_and_b32_e32 v3, 0x1ffff0, v3
	v_and_b32_e32 v5, 32, v5
	v_bfe_i32 v23, v2, 0, 16
	s_add_i32 s37, s36, 0x10000
	v_add_u32_e32 v2, v5, v23
	v_add_lshl_u32 v3, v22, v3, 11
	s_mov_b32 m0, s37
	s_add_i32 s43, s36, 0x12000
	s_or_b32 s38, s38, 0x180
	v_lshl_add_u32 v2, v2, 1, v3
	global_load_lds_dwordx4 v0, s[70:71]
	v_mov_b32_e32 v3, v1
	s_mov_b32 m0, s43
	s_ashr_i32 s39, s38, 31
	v_lshl_add_u64 v[4:5], s[70:71], 0, v[0:1]
	v_lshl_add_u64 v[8:9], s[70:71], 0, v[2:3]
	global_load_lds_dwordx4 v2, s[70:71]
	s_mov_b32 m0, s36
	s_add_i32 s70, s36, 0x2000
	s_lshl_b64 s[38:39], s[38:39], 11
	global_load_lds_dwordx4 v0, s[54:55]
	s_mov_b32 m0, s70
	s_add_u32 s38, s16, s38
	v_lshl_add_u64 v[10:11], s[54:55], 0, v[0:1]
	v_lshl_add_u64 v[6:7], s[54:55], 0, v[2:3]
	global_load_lds_dwordx4 v2, s[54:55]
	s_addc_u32 s39, s17, s39
	s_add_i32 s54, s36, 0x14000
	s_mov_b32 m0, s54
	s_add_i32 s55, s36, 0x16000
	global_load_lds_dwordx4 v0, s[38:39]
	s_mov_b32 m0, s55
	s_add_i32 s71, s36, 0x4000
	global_load_lds_dwordx4 v2, s[38:39]
	s_mov_b32 m0, s71
	s_add_i32 s72, s36, 0x6000
	global_load_lds_dwordx4 v0, s[60:61]
	s_mov_b32 m0, s72
	v_ashrrev_i32_e32 v17, 8, v142
	global_load_lds_dwordx4 v2, s[60:61]
	v_lshl_add_u64 v[12:13], s[38:39], 0, v[0:1]
	v_lshl_add_u64 v[14:15], s[38:39], 0, v[2:3]
	v_cmp_eq_u32_e32 vcc, 1, v17
	s_and_saveexec_b64 s[38:39], vcc
	v_readlane_b32 s62, v253, 50
	s_cbranch_execz .LBB0_188
	s_barrier

.LBB0_192:
	s_or_b64 exec, exec, s[12:13]
	s_movk_i32 s11, 0x410
	v_lshrrev_b32_e32 v130, 2, v142
	v_lshlrev_b32_e32 v131, 1, v142
	v_and_b32_e32 v0, 15, v142
	v_and_b32_e32 v130, 0xfffffcc, v130
	v_and_b32_e32 v131, 0x180, v131
	v_add_u32_e32 v131, 0, v131
	v_lshlrev_b32_e32 v0, 2, v0
	v_mul_lo_u32 v130, v130, s11
	v_add3_u32 v130, v131, v0, v130
	s_waitcnt vmcnt(0)
	s_barrier
	ds_write2_b32 v130, v114, v126 offset1:16
	v_add_u32_e32 v114, 0x400, v130
	ds_write2_b32 v114, v115, v127 offset0:4 offset1:20
	v_add_u32_e32 v115, 0x800, v130
	ds_write2_b32 v115, v116, v128 offset0:8 offset1:24
	v_add_u32_e32 v116, 0xc00, v130
	ds_write2_b32 v116, v117, v129 offset0:12 offset1:28
	v_add_u32_e32 v117, 0x4000, v130
	ds_write2_b32 v117, v82, v94 offset0:64 offset1:80
	v_add_u32_e32 v94, 0x4400, v130
	ds_write2_b32 v94, v83, v95 offset0:68 offset1:84
	v_add_u32_e32 v95, 0x4800, v130
	ds_write2_b32 v95, v84, v96 offset0:72 offset1:88
	v_add_u32_e32 v96, 0x4c00, v130
	ds_write2_b32 v96, v85, v97 offset0:76 offset1:92
	v_add_u32_e32 v132, 0x8000, v130
	v_add_u32_e32 v97, 0x8400, v130
	v_add_u32_e32 v126, 0x8800, v130
	v_add_u32_e32 v127, 0x8c00, v130
	v_add_u32_e32 v133, 0xc000, v130
	v_add_u32_e32 v128, 0xc400, v130
	v_add_u32_e32 v129, 0xc800, v130
	v_add_u32_e32 v131, 0xcc00, v130
	ds_write2_b32 v132, v74, v78 offset0:128 offset1:144
	ds_write2_b32 v97, v75, v79 offset0:132 offset1:148
	ds_write2_b32 v126, v76, v80 offset0:136 offset1:152
	ds_write2_b32 v127, v77, v81 offset0:140 offset1:156
	ds_write2_b32 v133, v66, v70 offset0:192 offset1:208
	ds_write2_b32 v128, v67, v71 offset0:196 offset1:212
	ds_write2_b32 v129, v68, v72 offset0:200 offset1:216
	ds_write2_b32 v131, v69, v73 offset0:204 offset1:220
	ds_write2_b32 v130, v98, v118 offset0:128 offset1:144
	ds_write2_b32 v114, v99, v119 offset0:132 offset1:148
	ds_write2_b32 v115, v100, v120 offset0:136 offset1:152
	ds_write2_b32 v116, v101, v121 offset0:140 offset1:156
	ds_write2_b32 v117, v102, v122 offset0:192 offset1:208
	ds_write2_b32 v94, v103, v123 offset0:196 offset1:212
	ds_write2_b32 v95, v104, v124 offset0:200 offset1:216
	ds_write2_b32 v96, v105, v125 offset0:204 offset1:220
	ds_write2_b32 v97, v90, v110 offset1:16
	ds_write2_b32 v126, v91, v111 offset0:4 offset1:20
	ds_write2_b32 v127, v92, v112 offset0:8 offset1:24
	v_add_u32_e32 v90, 0x9000, v130
	ds_write2_b32 v90, v93, v113 offset0:12 offset1:28
	ds_write2_b32 v128, v86, v106 offset0:64 offset1:80
	ds_write2_b32 v129, v87, v107 offset0:68 offset1:84
	ds_write2_b32 v131, v88, v108 offset0:72 offset1:88
	v_ashrrev_i32_e32 v88, 5, v142
	v_add_u32_e32 v70, s10, v88
	v_ashrrev_i32_e32 v71, 31, v70
	v_add_u32_e32 v91, 0xd000, v130
	v_lshl_add_u64 v[72:73], v[70:71], 4, s[46:47]
	ds_write2_b32 v91, v89, v109 offset0:76 offset1:92
	s_waitcnt lgkmcnt(0)
	s_barrier
	global_load_dwordx4 v[134:137], v[72:73], off
	global_load_dwordx4 v[138:141], v[72:73], off offset:256
	global_load_dwordx4 v[144:147], v[72:73], off offset:512
	global_load_dwordx4 v[148:151], v[72:73], off offset:768
	global_load_dwordx4 v[152:155], v[72:73], off offset:1024
	global_load_dwordx4 v[156:159], v[72:73], off offset:1280
	global_load_dwordx4 v[160:163], v[72:73], off offset:1536
	global_load_dwordx4 v[164:167], v[72:73], off offset:1792
	v_lshlrev_b32_e32 v0, 3, v142
	v_lshlrev_b32_e32 v66, 2, v142
	v_and_b32_e32 v0, 0xe0, v0
	v_and_b32_e32 v69, 12, v66
	v_lshlrev_b32_e32 v66, 2, v0
	v_lshlrev_b32_e32 v67, 2, v69
	v_or_b32_e32 v0, s42, v0
	v_add3_u32 v68, 0, v66, v67
	v_ashrrev_i32_e32 v66, 1, v0
	v_readlane_b32 s12, v253, 58
	v_ashrrev_i32_e32 v67, 31, v66
	v_readlane_b32 s13, v253, 59
	v_lshlrev_b32_e32 v0, 1, v69
	s_mov_b32 s9, 0x800000
	v_lshl_add_u64 v[66:67], v[66:67], 1, s[12:13]
	v_lshl_add_u64 v[66:67], v[66:67], 0, v[0:1]
	v_mad_u64_u32 v[82:83], s[12:13], v88, s11, v[68:69]
	s_movk_i32 s14, 0x1600
	s_mov_b64 s[38:39], -1
	s_waitcnt vmcnt(0)
	v_add_f32_e32 v0, v134, v135
	v_add_f32_e32 v0, v0, v136
	v_add_f32_e32 v0, v0, v137
	v_fmamk_f32 v0, v0, 0x3a800000, v200
	v_cmp_gt_f32_e32 vcc, s9, v0
	v_mul_f32_e32 v69, 0x4b800000, v0
	ds_read_b128 v[72:75], v82
	ds_read_b128 v[76:79], v82 offset:64
	v_cndmask_b32_e32 v0, v0, v69, vcc
	v_rsq_f32_e32 v0, v0
	s_nop 0
	v_mul_f32_e32 v69, 0x45800000, v0
	v_cndmask_b32_e32 v0, v0, v69, vcc
	s_waitcnt lgkmcnt(1)
	v_pk_mul_f32 v[72:73], v[72:73], v[0:1] op_sel_hi:[1,0]
	v_pk_mul_f32 v[74:75], v[74:75], v[0:1] op_sel_hi:[1,0]
	v_mul_f32_e32 v69, 0xbfb8aa3b, v72
	v_exp_f32_e32 v80, v69
	v_mul_f32_e32 v69, 0xbfb8aa3b, v73
	v_exp_f32_e32 v81, v69
	s_waitcnt lgkmcnt(0)
	v_pk_mul_f32 v[76:77], v[76:77], v[0:1] op_sel_hi:[1,0]
	v_pk_mul_f32 v[78:79], v[78:79], v[0:1] op_sel_hi:[1,0]
	v_mul_f32_e32 v0, 0xbfb8aa3b, v75
	v_pk_add_f32 v[80:81], v[80:81], 1.0 op_sel_hi:[1,0]
	s_nop 0
	v_rcp_f32_e32 v71, v81
	s_nop 0
	v_mul_f32_e32 v73, v73, v71
	v_rcp_f32_e32 v71, v80
	s_nop 0
	v_mul_f32_e32 v72, v72, v71
	v_mul_f32_e32 v69, 0xbfb8aa3b, v74
	v_pk_mul_f32 v[72:73], v[76:77], v[72:73]
	v_exp_f32_e32 v76, v69
	v_exp_f32_e32 v77, v0
	v_cvt_pk_bf16_f32 v72, v72, v73
	v_pk_add_f32 v[76:77], v[76:77], 1.0 op_sel_hi:[1,0]
	s_nop 0
	v_rcp_f32_e32 v69, v77
	s_nop 0
	v_mul_f32_e32 v75, v75, v69
	v_rcp_f32_e32 v69, v76
	s_nop 0
	v_mul_f32_e32 v74, v74, v69
	v_pk_mul_f32 v[74:75], v[78:79], v[74:75]
	v_add_u32_e32 v0, 0x200, v142
	v_cvt_pk_bf16_f32 v73, v74, v75
	v_mad_i64_i32 v[70:71], s[12:13], v70, s14, v[66:67]
	v_ashrrev_i32_e32 v83, 5, v0
	global_store_dwordx2 v[70:71], v[72:73], off
	v_add_u32_e32 v70, s10, v83
	v_ashrrev_i32_e32 v71, 31, v70
	v_lshl_add_u64 v[72:73], v[70:71], 4, s[46:47]
	v_mad_u64_u32 v[80:81], s[12:13], v83, s11, v[68:69]
	v_add_f32_e32 v0, v138, v139
	v_add_f32_e32 v0, v0, v140
	v_add_f32_e32 v0, v0, v141
	v_fmamk_f32 v0, v0, 0x3a800000, v200
	v_cmp_gt_f32_e32 vcc, s9, v0
	v_mul_f32_e32 v69, 0x4b800000, v0
	ds_read_b128 v[72:75], v80
	ds_read_b128 v[76:79], v80 offset:64
	v_cndmask_b32_e32 v0, v0, v69, vcc
	v_rsq_f32_e32 v0, v0
	s_nop 0
	v_mul_f32_e32 v69, 0x45800000, v0
	v_cndmask_b32_e32 v0, v0, v69, vcc
	s_waitcnt lgkmcnt(1)
	v_pk_mul_f32 v[72:73], v[72:73], v[0:1] op_sel_hi:[1,0]
	v_pk_mul_f32 v[74:75], v[74:75], v[0:1] op_sel_hi:[1,0]
	v_mul_f32_e32 v69, 0xbfb8aa3b, v72
	v_exp_f32_e32 v84, v69
	v_mul_f32_e32 v69, 0xbfb8aa3b, v73
	v_exp_f32_e32 v85, v69
	s_waitcnt lgkmcnt(0)
	v_pk_mul_f32 v[76:77], v[76:77], v[0:1] op_sel_hi:[1,0]
	v_pk_mul_f32 v[78:79], v[78:79], v[0:1] op_sel_hi:[1,0]
	v_mul_f32_e32 v0, 0xbfb8aa3b, v75
	v_pk_add_f32 v[84:85], v[84:85], 1.0 op_sel_hi:[1,0]
	s_nop 0
	v_rcp_f32_e32 v71, v85
	s_nop 0
	v_mul_f32_e32 v73, v73, v71
	v_rcp_f32_e32 v71, v84
	s_nop 0
	v_mul_f32_e32 v72, v72, v71
	v_mul_f32_e32 v69, 0xbfb8aa3b, v74
	v_pk_mul_f32 v[72:73], v[76:77], v[72:73]
	v_exp_f32_e32 v76, v69
	v_exp_f32_e32 v77, v0
	v_cvt_pk_bf16_f32 v72, v72, v73
	v_pk_add_f32 v[76:77], v[76:77], 1.0 op_sel_hi:[1,0]
	s_nop 0
	v_rcp_f32_e32 v69, v77
	s_nop 0
	v_mul_f32_e32 v75, v75, v69
	v_rcp_f32_e32 v69, v76
	s_nop 0
	v_mul_f32_e32 v74, v74, v69
	v_pk_mul_f32 v[74:75], v[78:79], v[74:75]
	v_add_u32_e32 v0, 0x400, v142
	v_cvt_pk_bf16_f32 v73, v74, v75
	v_mad_i64_i32 v[70:71], s[12:13], v70, s14, v[66:67]
	v_ashrrev_i32_e32 v81, 5, v0
	global_store_dwordx2 v[70:71], v[72:73], off
	v_add_u32_e32 v70, s10, v81
	v_ashrrev_i32_e32 v71, 31, v70
	v_lshl_add_u64 v[72:73], v[70:71], 4, s[46:47]
	v_mad_u64_u32 v[78:79], s[12:13], v81, s11, v[68:69]
	v_add_f32_e32 v0, v144, v145
	v_add_f32_e32 v0, v0, v146
	v_add_f32_e32 v0, v0, v147
	v_fmamk_f32 v0, v0, 0x3a800000, v200
	v_cmp_gt_f32_e32 vcc, s9, v0
	v_mul_f32_e32 v69, 0x4b800000, v0
	ds_read_b128 v[72:75], v78
	ds_read_b128 v[84:87], v78 offset:64
	v_cndmask_b32_e32 v0, v0, v69, vcc
	v_rsq_f32_e32 v0, v0
	s_nop 0
	v_mul_f32_e32 v69, 0x45800000, v0
	v_cndmask_b32_e32 v0, v0, v69, vcc
	s_waitcnt lgkmcnt(1)
	v_pk_mul_f32 v[72:73], v[72:73], v[0:1] op_sel_hi:[1,0]
	v_pk_mul_f32 v[74:75], v[74:75], v[0:1] op_sel_hi:[1,0]
	v_mul_f32_e32 v69, 0xbfb8aa3b, v72
	v_exp_f32_e32 v76, v69
	v_mul_f32_e32 v69, 0xbfb8aa3b, v73
	v_exp_f32_e32 v77, v69
	s_waitcnt lgkmcnt(0)
	v_pk_mul_f32 v[84:85], v[84:85], v[0:1] op_sel_hi:[1,0]
	v_pk_add_f32 v[76:77], v[76:77], 1.0 op_sel_hi:[1,0]
	s_nop 0
	v_rcp_f32_e32 v71, v77
	s_nop 0
	v_mul_f32_e32 v73, v73, v71
	v_rcp_f32_e32 v71, v76
	s_nop 0
	v_mul_f32_e32 v72, v72, v71
	v_mul_f32_e32 v69, 0xbfb8aa3b, v74
	v_pk_mul_f32 v[76:77], v[86:87], v[0:1] op_sel_hi:[1,0]
	v_mul_f32_e32 v0, 0xbfb8aa3b, v75
	v_pk_mul_f32 v[72:73], v[84:85], v[72:73]
	v_exp_f32_e32 v84, v69
	v_exp_f32_e32 v85, v0
	v_cvt_pk_bf16_f32 v72, v72, v73
	v_pk_add_f32 v[84:85], v[84:85], 1.0 op_sel_hi:[1,0]
	s_nop 0
	v_rcp_f32_e32 v69, v85
	s_nop 0
	v_mul_f32_e32 v75, v75, v69
	v_rcp_f32_e32 v69, v84
	s_nop 0
	v_mul_f32_e32 v74, v74, v69
	v_add_u32_e32 v0, 0x600, v142
	v_pk_mul_f32 v[74:75], v[76:77], v[74:75]
	v_ashrrev_i32_e32 v79, 5, v0
	v_cvt_pk_bf16_f32 v73, v74, v75
	v_add_u32_e32 v74, s10, v79
	v_mad_i64_i32 v[70:71], s[12:13], v70, s14, v[66:67]
	v_ashrrev_i32_e32 v75, 31, v74
	global_store_dwordx2 v[70:71], v[72:73], off
	v_lshl_add_u64 v[70:71], v[74:75], 4, s[46:47]
	v_mad_u64_u32 v[76:77], s[12:13], v79, s11, v[68:69]
	v_add_f32_e32 v0, v148, v149
	v_add_f32_e32 v0, v0, v150
	v_add_f32_e32 v0, v0, v151
	v_fmamk_f32 v0, v0, 0x3a800000, v200
	v_cmp_gt_f32_e32 vcc, s9, v0
	v_mul_f32_e32 v69, 0x4b800000, v0
	ds_read_b128 v[70:73], v76
	ds_read_b128 v[84:87], v76 offset:64
	v_cndmask_b32_e32 v0, v0, v69, vcc
	v_rsq_f32_e32 v0, v0
	s_nop 0
	v_mul_f32_e32 v69, 0x45800000, v0
	v_cndmask_b32_e32 v0, v0, v69, vcc
	s_waitcnt lgkmcnt(1)
	v_pk_mul_f32 v[70:71], v[70:71], v[0:1] op_sel_hi:[1,0]
	v_pk_mul_f32 v[72:73], v[72:73], v[0:1] op_sel_hi:[1,0]
	v_mul_f32_e32 v69, 0xbfb8aa3b, v70
	v_exp_f32_e32 v92, v69
	v_mul_f32_e32 v69, 0xbfb8aa3b, v71
	v_exp_f32_e32 v93, v69
	s_waitcnt lgkmcnt(0)
	v_pk_mul_f32 v[84:85], v[84:85], v[0:1] op_sel_hi:[1,0]
	v_pk_mul_f32 v[86:87], v[86:87], v[0:1] op_sel_hi:[1,0]
	v_mul_f32_e32 v0, 0xbfb8aa3b, v73
	v_pk_add_f32 v[92:93], v[92:93], 1.0 op_sel_hi:[1,0]
	s_nop 0
	v_rcp_f32_e32 v75, v93
	s_nop 0
	v_mul_f32_e32 v71, v71, v75
	v_rcp_f32_e32 v75, v92
	s_nop 0
	v_mul_f32_e32 v70, v70, v75
	v_mul_f32_e32 v69, 0xbfb8aa3b, v72
	v_pk_mul_f32 v[70:71], v[84:85], v[70:71]
	v_exp_f32_e32 v84, v69
	v_exp_f32_e32 v85, v0
	v_cvt_pk_bf16_f32 v70, v70, v71
	v_pk_add_f32 v[84:85], v[84:85], 1.0 op_sel_hi:[1,0]
	s_nop 0
	v_rcp_f32_e32 v69, v85
	s_nop 0
	v_mul_f32_e32 v73, v73, v69
	v_rcp_f32_e32 v69, v84
	s_nop 0
	v_mul_f32_e32 v72, v72, v69
	v_pk_mul_f32 v[72:73], v[86:87], v[72:73]
	v_add_u32_e32 v0, 0x800, v142
	v_cvt_pk_bf16_f32 v71, v72, v73
	v_mad_i64_i32 v[72:73], s[12:13], v74, s14, v[66:67]
	v_ashrrev_i32_e32 v0, 5, v0
	global_store_dwordx2 v[72:73], v[70:71], off
	v_add_u32_e32 v72, s10, v0
	v_ashrrev_i32_e32 v73, 31, v72
	v_lshl_add_u64 v[74:75], v[72:73], 4, s[46:47]
	v_mad_u64_u32 v[70:71], s[12:13], v0, s11, v[68:69]
	v_add_f32_e32 v69, v152, v153
	v_add_f32_e32 v69, v69, v154
	v_add_f32_e32 v69, v69, v155
	v_fmamk_f32 v69, v69, 0x3a800000, v200
	v_cmp_gt_f32_e32 vcc, s9, v69
	v_mul_f32_e32 v71, 0x4b800000, v69
	ds_read_b128 v[84:87], v70
	ds_read_b128 v[98:101], v70 offset:64
	v_cndmask_b32_e32 v69, v69, v71, vcc
	v_rsq_f32_e32 v69, v69
	s_nop 0
	v_mul_f32_e32 v71, 0x45800000, v69
	v_cndmask_b32_e32 v74, v69, v71, vcc
	s_waitcnt lgkmcnt(1)
	v_pk_mul_f32 v[84:85], v[84:85], v[74:75] op_sel_hi:[1,0]
	s_waitcnt lgkmcnt(0)
	v_pk_mul_f32 v[98:99], v[98:99], v[74:75] op_sel_hi:[1,0]
	v_mul_f32_e32 v69, 0xbfb8aa3b, v84
	v_exp_f32_e32 v92, v69
	v_mul_f32_e32 v69, 0xbfb8aa3b, v85
	v_exp_f32_e32 v93, v69
	s_nop 0
	v_pk_add_f32 v[92:93], v[92:93], 1.0 op_sel_hi:[1,0]
	s_nop 0
	v_rcp_f32_e32 v71, v93
	s_nop 0
	v_mul_f32_e32 v85, v85, v71
	v_div_scale_f32 v69, s[12:13], v92, v92, v84
	v_rcp_f32_e32 v71, v69
	s_nop 0
	v_fma_f32 v73, -v69, v71, 1.0
	v_fmac_f32_e32 v71, v73, v71
	v_div_scale_f32 v73, vcc, v84, v92, v84
	v_mul_f32_e32 v75, v73, v71
	v_fma_f32 v77, -v69, v75, v73
	v_fmac_f32_e32 v75, v77, v71
	v_fma_f32 v69, -v69, v75, v73
	v_div_fmas_f32 v69, v69, v71, v75
	v_pk_mul_f32 v[86:87], v[86:87], v[74:75] op_sel_hi:[1,0]
	v_div_fixup_f32 v84, v69, v92, v84
	v_mul_f32_e32 v69, 0xbfb8aa3b, v86
	v_exp_f32_e32 v92, v69
	v_mul_f32_e32 v69, 0xbfb8aa3b, v87
	v_exp_f32_e32 v93, v69
	v_pk_mul_f32 v[74:75], v[100:101], v[74:75] op_sel_hi:[1,0]
	v_pk_mul_f32 v[84:85], v[98:99], v[84:85]
	v_pk_add_f32 v[92:93], v[92:93], 1.0 op_sel_hi:[1,0]
	s_nop 0
	v_div_scale_f32 v69, s[12:13], v93, v93, v87
	v_rcp_f32_e32 v71, v69
	v_cvt_pk_bf16_f32 v84, v84, v85
	v_fma_f32 v73, -v69, v71, 1.0
	v_fmac_f32_e32 v71, v73, v71
	v_div_scale_f32 v73, vcc, v87, v93, v87
	v_mul_f32_e32 v77, v73, v71
	v_fma_f32 v89, -v69, v77, v73
	v_fmac_f32_e32 v77, v89, v71
	v_fma_f32 v69, -v69, v77, v73
	v_div_fmas_f32 v69, v69, v71, v77
	v_div_fixup_f32 v87, v69, v93, v87
	v_rcp_f32_e32 v71, v92
	s_nop 0
	v_mul_f32_e32 v86, v86, v71
	v_add_u32_e32 v69, 0xa00, v142
	v_pk_mul_f32 v[74:75], v[74:75], v[86:87]
	v_ashrrev_i32_e32 v71, 5, v69
	v_cvt_pk_bf16_f32 v85, v74, v75
	v_add_u32_e32 v74, s10, v71
	v_mad_i64_i32 v[72:73], s[12:13], v72, s14, v[66:67]
	v_ashrrev_i32_e32 v75, 31, v74
	global_store_dwordx2 v[72:73], v[84:85], off
	v_lshl_add_u64 v[84:85], v[74:75], 4, s[46:47]
	v_mad_u64_u32 v[72:73], s[12:13], v71, s11, v[68:69]
	v_add_f32_e32 v69, v156, v157
	v_add_f32_e32 v69, v69, v158
	v_add_f32_e32 v69, v69, v159
	v_fmamk_f32 v69, v69, 0x3a800000, v200
	v_cmp_gt_f32_e32 vcc, s9, v69
	v_mul_f32_e32 v73, 0x4b800000, v69
	ds_read_b128 v[84:87], v72
	ds_read_b128 v[98:101], v72 offset:64
	v_cndmask_b32_e32 v69, v69, v73, vcc
	v_rsq_f32_e32 v69, v69
	s_nop 0
	v_mul_f32_e32 v73, 0x45800000, v69
	v_cndmask_b32_e32 v92, v69, v73, vcc
	s_waitcnt lgkmcnt(1)
	v_pk_mul_f32 v[84:85], v[84:85], v[92:93] op_sel_hi:[1,0]
	v_pk_mul_f32 v[86:87], v[86:87], v[92:93] op_sel_hi:[1,0]
	v_mul_f32_e32 v69, 0xbfb8aa3b, v84
	v_exp_f32_e32 v102, v69
	v_mul_f32_e32 v69, 0xbfb8aa3b, v85
	v_exp_f32_e32 v103, v69
	s_waitcnt lgkmcnt(0)
	v_pk_mul_f32 v[98:99], v[98:99], v[92:93] op_sel_hi:[1,0]
	v_pk_mul_f32 v[92:93], v[100:101], v[92:93] op_sel_hi:[1,0]
	v_pk_add_f32 v[102:103], v[102:103], 1.0 op_sel_hi:[1,0]
	s_nop 0
	v_rcp_f32_e32 v73, v103
	s_nop 0
	v_mul_f32_e32 v85, v85, v73
	v_rcp_f32_e32 v73, v102
	s_nop 0
	v_mul_f32_e32 v84, v84, v73
	v_mul_f32_e32 v69, 0xbfb8aa3b, v86
	v_pk_mul_f32 v[84:85], v[98:99], v[84:85]
	v_exp_f32_e32 v98, v69
	v_mul_f32_e32 v69, 0xbfb8aa3b, v87
	v_exp_f32_e32 v99, v69
	v_cvt_pk_bf16_f32 v84, v84, v85
	v_pk_add_f32 v[98:99], v[98:99], 1.0 op_sel_hi:[1,0]
	s_nop 0
	v_rcp_f32_e32 v73, v99
	s_nop 0
	v_mul_f32_e32 v87, v87, v73
	v_rcp_f32_e32 v73, v98
	s_nop 0
	v_mul_f32_e32 v86, v86, v73
	v_pk_mul_f32 v[86:87], v[92:93], v[86:87]
	v_add_u32_e32 v69, 0xc00, v142
	v_cvt_pk_bf16_f32 v85, v86, v87
	v_mad_i64_i32 v[74:75], s[12:13], v74, s14, v[66:67]
	v_ashrrev_i32_e32 v73, 5, v69
	global_store_dwordx2 v[74:75], v[84:85], off
	v_add_u32_e32 v84, s10, v73
	v_ashrrev_i32_e32 v85, 31, v84
	v_lshl_add_u64 v[86:87], v[84:85], 4, s[46:47]
	v_mad_u64_u32 v[74:75], s[12:13], v73, s11, v[68:69]
	v_add_f32_e32 v69, v160, v161
	v_add_f32_e32 v69, v69, v162
	v_add_f32_e32 v69, v69, v163
	v_fmamk_f32 v69, v69, 0x3a800000, v200
	v_cmp_gt_f32_e32 vcc, s9, v69
	v_mul_f32_e32 v75, 0x4b800000, v69
	ds_read_b128 v[98:101], v74
	ds_read_b128 v[102:105], v74 offset:64
	v_cndmask_b32_e32 v69, v69, v75, vcc
	v_rsq_f32_e32 v69, v69
	s_nop 0
	v_mul_f32_e32 v75, 0x45800000, v69
	v_cndmask_b32_e32 v86, v69, v75, vcc
	s_waitcnt lgkmcnt(1)
	v_pk_mul_f32 v[92:93], v[98:99], v[86:87] op_sel_hi:[1,0]
	s_waitcnt lgkmcnt(0)
	v_pk_mul_f32 v[102:103], v[102:103], v[86:87] op_sel_hi:[1,0]
	v_mul_f32_e32 v69, 0xbfb8aa3b, v92
	v_exp_f32_e32 v98, v69
	v_mul_f32_e32 v69, 0xbfb8aa3b, v93
	v_exp_f32_e32 v99, v69
	s_nop 0
	v_pk_add_f32 v[98:99], v[98:99], 1.0 op_sel_hi:[1,0]
	s_nop 0
	v_rcp_f32_e32 v75, v99
	s_nop 0
	v_mul_f32_e32 v93, v93, v75
	v_rcp_f32_e32 v75, v98
	s_nop 0
	v_mul_f32_e32 v92, v92, v75
	v_pk_mul_f32 v[98:99], v[100:101], v[86:87] op_sel_hi:[1,0]
	v_pk_mul_f32 v[86:87], v[104:105], v[86:87] op_sel_hi:[1,0]
	v_mul_f32_e32 v69, 0xbfb8aa3b, v98
	v_exp_f32_e32 v100, v69
	v_mul_f32_e32 v69, 0xbfb8aa3b, v99
	v_exp_f32_e32 v101, v69
	v_pk_mul_f32 v[92:93], v[102:103], v[92:93]
	v_pk_add_f32 v[100:101], v[100:101], 1.0 op_sel_hi:[1,0]
	s_nop 0
	v_div_scale_f32 v69, s[12:13], v101, v101, v99
	v_rcp_f32_e32 v75, v69
	v_cvt_pk_bf16_f32 v92, v92, v93
	v_fma_f32 v77, -v69, v75, 1.0
	v_fmac_f32_e32 v75, v77, v75
	v_div_scale_f32 v77, vcc, v99, v101, v99
	v_mul_f32_e32 v85, v77, v75
	v_fma_f32 v89, -v69, v85, v77
	v_fmac_f32_e32 v85, v89, v75
	v_fma_f32 v69, -v69, v85, v77
	v_div_fmas_f32 v69, v69, v75, v85
	v_div_fixup_f32 v99, v69, v101, v99
	v_rcp_f32_e32 v75, v100
	s_nop 0
	v_mul_f32_e32 v98, v98, v75
	v_pk_mul_f32 v[86:87], v[86:87], v[98:99]
	v_add_u32_e32 v69, 0xe00, v142
	v_cvt_pk_bf16_f32 v93, v86, v87
	v_mad_i64_i32 v[84:85], s[12:13], v84, s14, v[66:67]
	v_ashrrev_i32_e32 v75, 5, v69
	global_store_dwordx2 v[84:85], v[92:93], off
	v_add_u32_e32 v84, s10, v75
	v_ashrrev_i32_e32 v85, 31, v84
	v_lshl_add_u64 v[86:87], v[84:85], 4, s[46:47]
	v_mad_u64_u32 v[68:69], s[12:13], v75, s11, v[68:69]
	v_add_f32_e32 v69, v164, v165
	v_add_f32_e32 v69, v69, v166
	v_add_f32_e32 v69, v69, v167
	v_fmamk_f32 v69, v69, 0x3a800000, v200
	v_cmp_gt_f32_e32 vcc, s9, v69
	v_mul_f32_e32 v77, 0x4b800000, v69
	ds_read_b128 v[98:101], v68
	ds_read_b128 v[102:105], v68 offset:64
	v_cndmask_b32_e32 v69, v69, v77, vcc
	v_rsq_f32_e32 v69, v69
	s_nop 0
	v_mul_f32_e32 v77, 0x45800000, v69
	v_cndmask_b32_e32 v86, v69, v77, vcc
	s_waitcnt lgkmcnt(1)
	v_pk_mul_f32 v[92:93], v[98:99], v[86:87] op_sel_hi:[1,0]
	s_waitcnt lgkmcnt(0)
	v_pk_mul_f32 v[102:103], v[102:103], v[86:87] op_sel_hi:[1,0]
	v_mul_f32_e32 v69, 0xbfb8aa3b, v92
	v_exp_f32_e32 v98, v69
	v_mul_f32_e32 v69, 0xbfb8aa3b, v93
	v_exp_f32_e32 v99, v69
	s_nop 0
	v_pk_add_f32 v[98:99], v[98:99], 1.0 op_sel_hi:[1,0]
	s_nop 0
	v_rcp_f32_e32 v77, v99
	s_nop 0
	v_mul_f32_e32 v93, v93, v77
	v_rcp_f32_e32 v77, v98
	s_nop 0
	v_mul_f32_e32 v92, v92, v77
	v_pk_mul_f32 v[98:99], v[100:101], v[86:87] op_sel_hi:[1,0]
	v_pk_mul_f32 v[92:93], v[102:103], v[92:93]
	v_mul_f32_e32 v69, 0xbfb8aa3b, v98
	v_exp_f32_e32 v100, v69
	v_mul_f32_e32 v69, 0xbfb8aa3b, v99
	v_exp_f32_e32 v101, v69
	v_pk_mul_f32 v[86:87], v[104:105], v[86:87] op_sel_hi:[1,0]
	v_cvt_pk_bf16_f32 v92, v92, v93
	v_pk_add_f32 v[100:101], v[100:101], 1.0 op_sel_hi:[1,0]
	s_nop 0
	v_rcp_f32_e32 v77, v101
	s_nop 0
	v_mul_f32_e32 v99, v99, v77
	v_rcp_f32_e32 v77, v100
	s_nop 0
	v_mul_f32_e32 v98, v98, v77
	v_pk_mul_f32 v[86:87], v[86:87], v[98:99]
	v_mad_i64_i32 v[84:85], s[10:11], v84, s14, v[66:67]
	v_cvt_pk_bf16_f32 v93, v86, v87
	global_store_dwordx2 v[84:85], v[92:93], off
	s_barrier
	ds_write2_b32 v130, v2, v18 offset1:16
	ds_write2_b32 v114, v3, v19 offset0:4 offset1:20
	ds_write2_b32 v115, v4, v20 offset0:8 offset1:24
	ds_write2_b32 v116, v5, v21 offset0:12 offset1:28
	ds_write2_b32 v117, v6, v22 offset0:64 offset1:80
	ds_write2_b32 v94, v7, v23 offset0:68 offset1:84
	ds_write2_b32 v95, v8, v24 offset0:72 offset1:88
	ds_write2_b32 v96, v9, v25 offset0:76 offset1:92
	ds_write2_b32 v132, v10, v26 offset0:128 offset1:144
	ds_write2_b32 v97, v11, v27 offset0:132 offset1:148
	ds_write2_b32 v126, v12, v28 offset0:136 offset1:152
	ds_write2_b32 v127, v13, v29 offset0:140 offset1:156
	ds_write2_b32 v133, v14, v30 offset0:192 offset1:208
	ds_write2_b32 v128, v15, v31 offset0:196 offset1:212
	ds_write2_b32 v129, v16, v32 offset0:200 offset1:216
	ds_write2_b32 v131, v17, v33 offset0:204 offset1:220
	ds_write2_b32 v130, v34, v50 offset0:128 offset1:144
	ds_write2_b32 v114, v35, v51 offset0:132 offset1:148
	ds_write2_b32 v115, v36, v52 offset0:136 offset1:152
	ds_write2_b32 v116, v37, v53 offset0:140 offset1:156
	ds_write2_b32 v117, v38, v54 offset0:192 offset1:208
	ds_write2_b32 v94, v39, v55 offset0:196 offset1:212
	ds_write2_b32 v95, v40, v56 offset0:200 offset1:216
	ds_write2_b32 v96, v41, v57 offset0:204 offset1:220
	ds_write2_b32 v97, v42, v58 offset1:16
	ds_write2_b32 v126, v43, v59 offset0:4 offset1:20
	ds_write2_b32 v127, v44, v60 offset0:8 offset1:24
	ds_write2_b32 v90, v45, v61 offset0:12 offset1:28
	ds_write2_b32 v128, v46, v62 offset0:64 offset1:80
	ds_write2_b32 v129, v47, v63 offset0:68 offset1:84
	ds_write2_b32 v131, v48, v64 offset0:72 offset1:88
	ds_write2_b32 v91, v49, v65 offset0:76 offset1:92
	v_add_u32_e32 v2, s8, v88
	v_ashrrev_i32_e32 v3, 31, v2
	v_lshl_add_u64 v[4:5], v[2:3], 4, s[46:47]
	s_waitcnt lgkmcnt(0)
	s_barrier
	global_load_dwordx4 v[134:137], v[4:5], off
	global_load_dwordx4 v[138:141], v[4:5], off offset:256
	global_load_dwordx4 v[144:147], v[4:5], off offset:512
	global_load_dwordx4 v[148:151], v[4:5], off offset:768
	global_load_dwordx4 v[152:155], v[4:5], off offset:1024
	global_load_dwordx4 v[156:159], v[4:5], off offset:1280
	global_load_dwordx4 v[160:163], v[4:5], off offset:1536
	global_load_dwordx4 v[164:167], v[4:5], off offset:1792
	s_waitcnt vmcnt(0)
	v_add_f32_e32 v3, v134, v135
	v_add_f32_e32 v3, v3, v136
	v_add_f32_e32 v3, v3, v137
	v_fmamk_f32 v3, v3, 0x3a800000, v200
	v_cmp_gt_f32_e32 vcc, s9, v3
	v_mul_f32_e32 v4, 0x4b800000, v3
	s_nop 0
	v_cndmask_b32_e32 v3, v3, v4, vcc
	v_rsq_f32_e32 v3, v3
	s_nop 0
	v_mul_f32_e32 v4, 0x45800000, v3
	v_cndmask_b32_e32 v12, v3, v4, vcc
	ds_read_b128 v[4:7], v82
	ds_read_b128 v[8:11], v82 offset:64
	s_waitcnt lgkmcnt(1)
	v_pk_mul_f32 v[4:5], v[4:5], v[12:13] op_sel_hi:[1,0]
	s_nop 0
	v_mul_f32_e32 v3, 0xbfb8aa3b, v4
	v_exp_f32_e32 v14, v3
	v_mul_f32_e32 v3, 0xbfb8aa3b, v5
	v_exp_f32_e32 v15, v3
	s_waitcnt lgkmcnt(0)
	v_pk_mul_f32 v[8:9], v[8:9], v[12:13] op_sel_hi:[1,0]
	v_pk_add_f32 v[14:15], v[14:15], 1.0 op_sel_hi:[1,0]
	s_nop 0
	v_rcp_f32_e32 v13, v15
	s_nop 0
	v_mul_f32_e32 v5, v5, v13
	v_div_scale_f32 v3, s[10:11], v14, v14, v4
	v_rcp_f32_e32 v13, v3
	s_nop 0
	v_fma_f32 v15, -v3, v13, 1.0
	v_fmac_f32_e32 v13, v15, v13
	v_div_scale_f32 v15, vcc, v4, v14, v4
	v_mul_f32_e32 v16, v15, v13
	v_fma_f32 v17, -v3, v16, v15
	v_fmac_f32_e32 v16, v17, v13
	v_fma_f32 v3, -v3, v16, v15
	v_div_fmas_f32 v3, v3, v13, v16
	v_pk_mul_f32 v[6:7], v[6:7], v[12:13] op_sel_hi:[1,0]
	v_div_fixup_f32 v4, v3, v14, v4
	v_mul_f32_e32 v3, 0xbfb8aa3b, v6
	v_pk_mul_f32 v[4:5], v[8:9], v[4:5]
	v_exp_f32_e32 v8, v3
	v_mul_f32_e32 v3, 0xbfb8aa3b, v7
	v_exp_f32_e32 v9, v3
	v_pk_mul_f32 v[10:11], v[10:11], v[12:13] op_sel_hi:[1,0]
	v_cvt_pk_bf16_f32 v4, v4, v5
	v_pk_add_f32 v[8:9], v[8:9], 1.0 op_sel_hi:[1,0]
	s_nop 0
	v_rcp_f32_e32 v12, v9
	s_nop 0
	v_mul_f32_e32 v7, v7, v12
	v_rcp_f32_e32 v9, v8
	s_nop 0
	v_mul_f32_e32 v6, v6, v9
	v_pk_mul_f32 v[6:7], v[10:11], v[6:7]
	v_mad_i64_i32 v[2:3], s[10:11], v2, s14, v[66:67]
	v_cvt_pk_bf16_f32 v5, v6, v7
	global_store_dwordx2 v[2:3], v[4:5], off
	v_add_u32_e32 v2, s8, v83
	v_ashrrev_i32_e32 v3, 31, v2
	v_lshl_add_u64 v[4:5], v[2:3], 4, s[46:47]
	v_add_f32_e32 v3, v138, v139
	v_add_f32_e32 v3, v3, v140
	v_add_f32_e32 v3, v3, v141
	v_fmamk_f32 v3, v3, 0x3a800000, v200
	v_cmp_gt_f32_e32 vcc, s9, v3
	v_mul_f32_e32 v4, 0x4b800000, v3
	s_nop 0
	v_cndmask_b32_e32 v3, v3, v4, vcc
	v_rsq_f32_e32 v3, v3
	s_nop 0
	v_mul_f32_e32 v4, 0x45800000, v3
	v_cndmask_b32_e32 v12, v3, v4, vcc
	ds_read_b128 v[4:7], v80
	ds_read_b128 v[8:11], v80 offset:64
	s_waitcnt lgkmcnt(1)
	v_pk_mul_f32 v[4:5], v[4:5], v[12:13] op_sel_hi:[1,0]
	s_nop 0
	v_mul_f32_e32 v3, 0xbfb8aa3b, v4
	v_exp_f32_e32 v14, v3
	v_mul_f32_e32 v3, 0xbfb8aa3b, v5
	v_exp_f32_e32 v15, v3
	s_waitcnt lgkmcnt(0)
	v_pk_mul_f32 v[8:9], v[8:9], v[12:13] op_sel_hi:[1,0]
	v_pk_add_f32 v[14:15], v[14:15], 1.0 op_sel_hi:[1,0]
	s_nop 0
	v_rcp_f32_e32 v13, v15
	s_nop 0
	v_mul_f32_e32 v5, v5, v13
	v_div_scale_f32 v3, s[10:11], v14, v14, v4
	v_rcp_f32_e32 v13, v3
	s_nop 0
	v_fma_f32 v15, -v3, v13, 1.0
	v_fmac_f32_e32 v13, v15, v13
	v_div_scale_f32 v15, vcc, v4, v14, v4
	v_mul_f32_e32 v16, v15, v13
	v_fma_f32 v17, -v3, v16, v15
	v_fmac_f32_e32 v16, v17, v13
	v_fma_f32 v3, -v3, v16, v15
	v_div_fmas_f32 v3, v3, v13, v16
	v_pk_mul_f32 v[6:7], v[6:7], v[12:13] op_sel_hi:[1,0]
	v_div_fixup_f32 v4, v3, v14, v4
	v_mul_f32_e32 v3, 0xbfb8aa3b, v6
	v_pk_mul_f32 v[4:5], v[8:9], v[4:5]
	v_exp_f32_e32 v8, v3
	v_mul_f32_e32 v3, 0xbfb8aa3b, v7
	v_exp_f32_e32 v9, v3
	v_pk_mul_f32 v[10:11], v[10:11], v[12:13] op_sel_hi:[1,0]
	v_cvt_pk_bf16_f32 v4, v4, v5
	v_pk_add_f32 v[8:9], v[8:9], 1.0 op_sel_hi:[1,0]
	s_nop 0
	v_rcp_f32_e32 v12, v9
	s_nop 0
	v_mul_f32_e32 v7, v7, v12
	v_rcp_f32_e32 v9, v8
	s_nop 0
	v_mul_f32_e32 v6, v6, v9
	v_pk_mul_f32 v[6:7], v[10:11], v[6:7]
	v_mad_i64_i32 v[2:3], s[10:11], v2, s14, v[66:67]
	v_cvt_pk_bf16_f32 v5, v6, v7
	global_store_dwordx2 v[2:3], v[4:5], off
	v_add_u32_e32 v2, s8, v81
	v_ashrrev_i32_e32 v3, 31, v2
	v_lshl_add_u64 v[4:5], v[2:3], 4, s[46:47]
	v_add_f32_e32 v3, v144, v145
	v_add_f32_e32 v3, v3, v146
	v_add_f32_e32 v3, v3, v147
	v_fmamk_f32 v3, v3, 0x3a800000, v200
	v_cmp_gt_f32_e32 vcc, s9, v3
	v_mul_f32_e32 v4, 0x4b800000, v3
	s_nop 0
	v_cndmask_b32_e32 v3, v3, v4, vcc
	v_rsq_f32_e32 v3, v3
	s_nop 0
	v_mul_f32_e32 v4, 0x45800000, v3
	v_cndmask_b32_e32 v12, v3, v4, vcc
	ds_read_b128 v[4:7], v78
	ds_read_b128 v[8:11], v78 offset:64
	s_waitcnt lgkmcnt(1)
	v_pk_mul_f32 v[4:5], v[4:5], v[12:13] op_sel_hi:[1,0]
	s_nop 0
	v_mul_f32_e32 v3, 0xbfb8aa3b, v4
	v_exp_f32_e32 v14, v3
	v_mul_f32_e32 v3, 0xbfb8aa3b, v5
	v_exp_f32_e32 v15, v3
	s_waitcnt lgkmcnt(0)
	v_pk_mul_f32 v[8:9], v[8:9], v[12:13] op_sel_hi:[1,0]
	v_pk_add_f32 v[14:15], v[14:15], 1.0 op_sel_hi:[1,0]
	s_nop 0
	v_rcp_f32_e32 v13, v15
	s_nop 0
	v_mul_f32_e32 v5, v5, v13
	v_div_scale_f32 v3, s[10:11], v14, v14, v4
	v_rcp_f32_e32 v13, v3
	s_nop 0
	v_fma_f32 v15, -v3, v13, 1.0
	v_fmac_f32_e32 v13, v15, v13
	v_div_scale_f32 v15, vcc, v4, v14, v4
	v_mul_f32_e32 v16, v15, v13
	v_fma_f32 v17, -v3, v16, v15
	v_fmac_f32_e32 v16, v17, v13
	v_fma_f32 v3, -v3, v16, v15
	v_div_fmas_f32 v3, v3, v13, v16
	v_pk_mul_f32 v[6:7], v[6:7], v[12:13] op_sel_hi:[1,0]
	v_div_fixup_f32 v4, v3, v14, v4
	v_mul_f32_e32 v3, 0xbfb8aa3b, v6
	v_pk_mul_f32 v[4:5], v[8:9], v[4:5]
	v_exp_f32_e32 v8, v3
	v_mul_f32_e32 v3, 0xbfb8aa3b, v7
	v_exp_f32_e32 v9, v3
	v_pk_mul_f32 v[10:11], v[10:11], v[12:13] op_sel_hi:[1,0]
	v_cvt_pk_bf16_f32 v4, v4, v5
	v_pk_add_f32 v[8:9], v[8:9], 1.0 op_sel_hi:[1,0]
	s_nop 0
	v_rcp_f32_e32 v12, v9
	s_nop 0
	v_mul_f32_e32 v7, v7, v12
	v_rcp_f32_e32 v9, v8
	s_nop 0
	v_mul_f32_e32 v6, v6, v9
	v_pk_mul_f32 v[6:7], v[10:11], v[6:7]
	v_mad_i64_i32 v[2:3], s[10:11], v2, s14, v[66:67]
	v_cvt_pk_bf16_f32 v5, v6, v7
	global_store_dwordx2 v[2:3], v[4:5], off
	v_add_u32_e32 v2, s8, v79
	v_ashrrev_i32_e32 v3, 31, v2
	v_lshl_add_u64 v[4:5], v[2:3], 4, s[46:47]
	v_add_f32_e32 v3, v148, v149
	v_add_f32_e32 v3, v3, v150
	v_add_f32_e32 v3, v3, v151
	v_fmamk_f32 v3, v3, 0x3a800000, v200
	v_cmp_gt_f32_e32 vcc, s9, v3
	v_mul_f32_e32 v4, 0x4b800000, v3
	s_nop 0
	v_cndmask_b32_e32 v3, v3, v4, vcc
	v_rsq_f32_e32 v3, v3
	s_nop 0
	v_mul_f32_e32 v4, 0x45800000, v3
	v_cndmask_b32_e32 v12, v3, v4, vcc
	ds_read_b128 v[4:7], v76
	ds_read_b128 v[8:11], v76 offset:64
	s_waitcnt lgkmcnt(1)
	v_pk_mul_f32 v[4:5], v[4:5], v[12:13] op_sel_hi:[1,0]
	s_nop 0
	v_mul_f32_e32 v3, 0xbfb8aa3b, v4
	v_exp_f32_e32 v14, v3
	v_mul_f32_e32 v3, 0xbfb8aa3b, v5
	v_exp_f32_e32 v15, v3
	s_waitcnt lgkmcnt(0)
	v_pk_mul_f32 v[8:9], v[8:9], v[12:13] op_sel_hi:[1,0]
	v_pk_add_f32 v[14:15], v[14:15], 1.0 op_sel_hi:[1,0]
	s_nop 0
	v_rcp_f32_e32 v13, v15
	s_nop 0
	v_mul_f32_e32 v5, v5, v13
	v_div_scale_f32 v3, s[10:11], v14, v14, v4
	v_rcp_f32_e32 v13, v3
	s_nop 0
	v_fma_f32 v15, -v3, v13, 1.0
	v_fmac_f32_e32 v13, v15, v13
	v_div_scale_f32 v15, vcc, v4, v14, v4
	v_mul_f32_e32 v16, v15, v13
	v_fma_f32 v17, -v3, v16, v15
	v_fmac_f32_e32 v16, v17, v13
	v_fma_f32 v3, -v3, v16, v15
	v_div_fmas_f32 v3, v3, v13, v16
	v_pk_mul_f32 v[6:7], v[6:7], v[12:13] op_sel_hi:[1,0]
	v_div_fixup_f32 v4, v3, v14, v4
	v_mul_f32_e32 v3, 0xbfb8aa3b, v6
	v_pk_mul_f32 v[4:5], v[8:9], v[4:5]
	v_exp_f32_e32 v8, v3
	v_mul_f32_e32 v3, 0xbfb8aa3b, v7
	v_exp_f32_e32 v9, v3
	v_pk_mul_f32 v[10:11], v[10:11], v[12:13] op_sel_hi:[1,0]
	v_cvt_pk_bf16_f32 v4, v4, v5
	v_pk_add_f32 v[8:9], v[8:9], 1.0 op_sel_hi:[1,0]
	s_nop 0
	v_rcp_f32_e32 v12, v9
	s_nop 0
	v_mul_f32_e32 v7, v7, v12
	v_rcp_f32_e32 v9, v8
	s_nop 0
	v_mul_f32_e32 v6, v6, v9
	v_pk_mul_f32 v[6:7], v[10:11], v[6:7]
	v_mad_i64_i32 v[2:3], s[10:11], v2, s14, v[66:67]
	v_cvt_pk_bf16_f32 v5, v6, v7
	global_store_dwordx2 v[2:3], v[4:5], off
	v_add_u32_e32 v2, s8, v0
	v_ashrrev_i32_e32 v3, 31, v2
	v_lshl_add_u64 v[4:5], v[2:3], 4, s[46:47]
	v_add_f32_e32 v0, v152, v153
	v_add_f32_e32 v0, v0, v154
	v_add_f32_e32 v0, v0, v155
	v_fmamk_f32 v0, v0, 0x3a800000, v200
	v_cmp_gt_f32_e32 vcc, s9, v0
	v_mul_f32_e32 v3, 0x4b800000, v0
	ds_read_b128 v[4:7], v70
	ds_read_b128 v[8:11], v70 offset:64
	v_cndmask_b32_e32 v0, v0, v3, vcc
	v_rsq_f32_e32 v0, v0
	s_nop 0
	v_mul_f32_e32 v3, 0x45800000, v0
	v_cndmask_b32_e32 v0, v0, v3, vcc
	s_waitcnt lgkmcnt(1)
	v_pk_mul_f32 v[4:5], v[4:5], v[0:1] op_sel_hi:[1,0]
	v_pk_mul_f32 v[6:7], v[6:7], v[0:1] op_sel_hi:[1,0]
	v_mul_f32_e32 v3, 0xbfb8aa3b, v4
	v_exp_f32_e32 v12, v3
	v_mul_f32_e32 v3, 0xbfb8aa3b, v5
	v_exp_f32_e32 v13, v3
	s_waitcnt lgkmcnt(0)
	v_pk_mul_f32 v[8:9], v[8:9], v[0:1] op_sel_hi:[1,0]
	v_pk_mul_f32 v[10:11], v[10:11], v[0:1] op_sel_hi:[1,0]
	v_mul_f32_e32 v0, 0xbfb8aa3b, v7
	v_pk_add_f32 v[12:13], v[12:13], 1.0 op_sel_hi:[1,0]
	s_nop 0
	v_rcp_f32_e32 v14, v13
	s_nop 0
	v_mul_f32_e32 v5, v5, v14
	v_rcp_f32_e32 v13, v12
	s_nop 0
	v_mul_f32_e32 v4, v4, v13
	v_mul_f32_e32 v3, 0xbfb8aa3b, v6
	v_pk_mul_f32 v[4:5], v[8:9], v[4:5]
	v_exp_f32_e32 v8, v3
	v_exp_f32_e32 v9, v0
	v_cvt_pk_bf16_f32 v4, v4, v5
	v_pk_add_f32 v[8:9], v[8:9], 1.0 op_sel_hi:[1,0]
	s_nop 0
	v_rcp_f32_e32 v3, v9
	s_nop 0
	v_mul_f32_e32 v7, v7, v3
	v_rcp_f32_e32 v3, v8
	s_nop 0
	v_mul_f32_e32 v6, v6, v3
	v_pk_mul_f32 v[6:7], v[10:11], v[6:7]
	v_mad_i64_i32 v[2:3], s[10:11], v2, s14, v[66:67]
	v_cvt_pk_bf16_f32 v5, v6, v7
	global_store_dwordx2 v[2:3], v[4:5], off
	v_add_u32_e32 v2, s8, v71
	v_ashrrev_i32_e32 v3, 31, v2
	v_lshl_add_u64 v[4:5], v[2:3], 4, s[46:47]
	v_add_f32_e32 v0, v156, v157
	v_add_f32_e32 v0, v0, v158
	v_add_f32_e32 v0, v0, v159
	v_fmamk_f32 v0, v0, 0x3a800000, v200
	v_cmp_gt_f32_e32 vcc, s9, v0
	v_mul_f32_e32 v3, 0x4b800000, v0
	ds_read_b128 v[4:7], v72
	ds_read_b128 v[8:11], v72 offset:64
	v_cndmask_b32_e32 v0, v0, v3, vcc
	v_rsq_f32_e32 v0, v0
	s_nop 0
	v_mul_f32_e32 v3, 0x45800000, v0
	v_cndmask_b32_e32 v0, v0, v3, vcc
	s_waitcnt lgkmcnt(1)
	v_pk_mul_f32 v[4:5], v[4:5], v[0:1] op_sel_hi:[1,0]
	v_pk_mul_f32 v[6:7], v[6:7], v[0:1] op_sel_hi:[1,0]
	v_mul_f32_e32 v3, 0xbfb8aa3b, v4
	v_exp_f32_e32 v12, v3
	v_mul_f32_e32 v3, 0xbfb8aa3b, v5
	v_exp_f32_e32 v13, v3
	s_waitcnt lgkmcnt(0)
	v_pk_mul_f32 v[8:9], v[8:9], v[0:1] op_sel_hi:[1,0]
	v_pk_mul_f32 v[10:11], v[10:11], v[0:1] op_sel_hi:[1,0]
	v_mul_f32_e32 v0, 0xbfb8aa3b, v7
	v_pk_add_f32 v[12:13], v[12:13], 1.0 op_sel_hi:[1,0]
	s_nop 0
	v_rcp_f32_e32 v14, v13
	s_nop 0
	v_mul_f32_e32 v5, v5, v14
	v_rcp_f32_e32 v13, v12
	s_nop 0
	v_mul_f32_e32 v4, v4, v13
	v_mul_f32_e32 v3, 0xbfb8aa3b, v6
	v_pk_mul_f32 v[4:5], v[8:9], v[4:5]
	v_exp_f32_e32 v8, v3
	v_exp_f32_e32 v9, v0
	v_cvt_pk_bf16_f32 v4, v4, v5
	v_pk_add_f32 v[8:9], v[8:9], 1.0 op_sel_hi:[1,0]
	s_nop 0
	v_rcp_f32_e32 v3, v9
	s_nop 0
	v_mul_f32_e32 v7, v7, v3
	v_rcp_f32_e32 v3, v8
	s_nop 0
	v_mul_f32_e32 v6, v6, v3
	v_pk_mul_f32 v[6:7], v[10:11], v[6:7]
	v_mad_i64_i32 v[2:3], s[10:11], v2, s14, v[66:67]
	v_cvt_pk_bf16_f32 v5, v6, v7
	global_store_dwordx2 v[2:3], v[4:5], off
	v_add_u32_e32 v2, s8, v73
	v_ashrrev_i32_e32 v3, 31, v2
	v_lshl_add_u64 v[4:5], v[2:3], 4, s[46:47]
	v_add_f32_e32 v0, v160, v161
	v_add_f32_e32 v0, v0, v162
	v_add_f32_e32 v0, v0, v163
	v_fmamk_f32 v0, v0, 0x3a800000, v200
	v_cmp_gt_f32_e32 vcc, s9, v0
	v_mul_f32_e32 v3, 0x4b800000, v0
	ds_read_b128 v[4:7], v74
	ds_read_b128 v[8:11], v74 offset:64
	v_cndmask_b32_e32 v0, v0, v3, vcc
	v_rsq_f32_e32 v0, v0
	s_nop 0
	v_mul_f32_e32 v3, 0x45800000, v0
	v_cndmask_b32_e32 v0, v0, v3, vcc
	s_waitcnt lgkmcnt(1)
	v_pk_mul_f32 v[4:5], v[4:5], v[0:1] op_sel_hi:[1,0]
	v_pk_mul_f32 v[6:7], v[6:7], v[0:1] op_sel_hi:[1,0]
	v_mul_f32_e32 v3, 0xbfb8aa3b, v4
	v_exp_f32_e32 v12, v3
	v_mul_f32_e32 v3, 0xbfb8aa3b, v5
	v_exp_f32_e32 v13, v3
	s_waitcnt lgkmcnt(0)
	v_pk_mul_f32 v[8:9], v[8:9], v[0:1] op_sel_hi:[1,0]
	v_pk_mul_f32 v[10:11], v[10:11], v[0:1] op_sel_hi:[1,0]
	v_mul_f32_e32 v0, 0xbfb8aa3b, v7
	v_pk_add_f32 v[12:13], v[12:13], 1.0 op_sel_hi:[1,0]
	s_nop 0
	v_rcp_f32_e32 v14, v13
	s_nop 0
	v_mul_f32_e32 v5, v5, v14
	v_rcp_f32_e32 v13, v12
	s_nop 0
	v_mul_f32_e32 v4, v4, v13
	v_mul_f32_e32 v3, 0xbfb8aa3b, v6
	v_pk_mul_f32 v[4:5], v[8:9], v[4:5]
	v_exp_f32_e32 v8, v3
	v_exp_f32_e32 v9, v0
	v_cvt_pk_bf16_f32 v4, v4, v5
	v_pk_add_f32 v[8:9], v[8:9], 1.0 op_sel_hi:[1,0]
	s_nop 0
	v_rcp_f32_e32 v3, v9
	s_nop 0
	v_mul_f32_e32 v7, v7, v3
	v_rcp_f32_e32 v3, v8
	s_nop 0
	v_mul_f32_e32 v6, v6, v3
	v_pk_mul_f32 v[6:7], v[10:11], v[6:7]
	v_mad_i64_i32 v[2:3], s[10:11], v2, s14, v[66:67]
	v_cvt_pk_bf16_f32 v5, v6, v7
	global_store_dwordx2 v[2:3], v[4:5], off
	v_add_u32_e32 v2, s8, v75
	v_ashrrev_i32_e32 v3, 31, v2
	v_lshl_add_u64 v[4:5], v[2:3], 4, s[46:47]
	v_add_f32_e32 v0, v164, v165
	v_add_f32_e32 v0, v0, v166
	v_add_f32_e32 v0, v0, v167
	v_fmamk_f32 v0, v0, 0x3a800000, v200
	v_cmp_gt_f32_e32 vcc, s9, v0
	v_mul_f32_e32 v3, 0x4b800000, v0
	ds_read_b128 v[4:7], v68
	ds_read_b128 v[8:11], v68 offset:64
	v_cndmask_b32_e32 v0, v0, v3, vcc
	v_rsq_f32_e32 v0, v0
	s_nop 0
	v_mul_f32_e32 v3, 0x45800000, v0
	v_cndmask_b32_e32 v0, v0, v3, vcc
	s_waitcnt lgkmcnt(1)
	v_pk_mul_f32 v[4:5], v[4:5], v[0:1] op_sel_hi:[1,0]
	v_pk_mul_f32 v[6:7], v[6:7], v[0:1] op_sel_hi:[1,0]
	v_mul_f32_e32 v3, 0xbfb8aa3b, v4
	v_exp_f32_e32 v12, v3
	v_mul_f32_e32 v3, 0xbfb8aa3b, v5
	v_exp_f32_e32 v13, v3
	s_waitcnt lgkmcnt(0)
	v_pk_mul_f32 v[8:9], v[8:9], v[0:1] op_sel_hi:[1,0]
	v_pk_mul_f32 v[10:11], v[10:11], v[0:1] op_sel_hi:[1,0]
	v_mul_f32_e32 v0, 0xbfb8aa3b, v7
	v_pk_add_f32 v[12:13], v[12:13], 1.0 op_sel_hi:[1,0]
	s_nop 0
	v_rcp_f32_e32 v14, v13
	s_nop 0
	v_mul_f32_e32 v5, v5, v14
	v_rcp_f32_e32 v13, v12
	s_nop 0
	v_mul_f32_e32 v4, v4, v13
	v_mul_f32_e32 v3, 0xbfb8aa3b, v6
	v_pk_mul_f32 v[4:5], v[8:9], v[4:5]
	v_exp_f32_e32 v8, v3
	v_exp_f32_e32 v9, v0
	v_cvt_pk_bf16_f32 v4, v4, v5
	v_pk_add_f32 v[8:9], v[8:9], 1.0 op_sel_hi:[1,0]
	s_nop 0
	v_rcp_f32_e32 v3, v9
	s_nop 0
	v_mul_f32_e32 v7, v7, v3
	v_rcp_f32_e32 v3, v8
	s_nop 0
	v_mul_f32_e32 v6, v6, v3
	v_pk_mul_f32 v[6:7], v[10:11], v[6:7]
	v_mad_i64_i32 v[2:3], s[8:9], v2, s14, v[66:67]
	v_cvt_pk_bf16_f32 v5, v6, v7
	global_store_dwordx2 v[2:3], v[4:5], off
	s_barrier

.LBB0_242:
	s_or_b64 exec, exec, s[42:43]
	s_movk_i32 s42, 0x410
	v_lshrrev_b32_e32 v130, 2, v142
	v_lshlrev_b32_e32 v131, 1, v142
	v_and_b32_e32 v0, 15, v142
	v_and_b32_e32 v130, 0xfffffcc, v130
	v_and_b32_e32 v131, 0x180, v131
	v_add_u32_e32 v131, 0, v131
	v_lshlrev_b32_e32 v0, 2, v0
	v_mul_lo_u32 v130, v130, s42
	v_add3_u32 v130, v131, v0, v130
	s_waitcnt vmcnt(0)
	s_barrier
	ds_write2_b32 v130, v114, v126 offset1:16
	v_add_u32_e32 v114, 0x400, v130
	ds_write2_b32 v114, v115, v127 offset0:4 offset1:20
	v_add_u32_e32 v115, 0x800, v130
	ds_write2_b32 v115, v116, v128 offset0:8 offset1:24
	v_add_u32_e32 v116, 0xc00, v130
	ds_write2_b32 v116, v117, v129 offset0:12 offset1:28
	v_add_u32_e32 v117, 0x4000, v130
	ds_write2_b32 v117, v82, v94 offset0:64 offset1:80
	v_add_u32_e32 v94, 0x4400, v130
	ds_write2_b32 v94, v83, v95 offset0:68 offset1:84
	v_add_u32_e32 v95, 0x4800, v130
	ds_write2_b32 v95, v84, v96 offset0:72 offset1:88
	v_add_u32_e32 v96, 0x4c00, v130
	v_add_u32_e32 v133, 0xc000, v130
	ds_write2_b32 v96, v85, v97 offset0:76 offset1:92
	v_add_u32_e32 v132, 0x8000, v130
	v_add_u32_e32 v97, 0x8400, v130
	v_add_u32_e32 v126, 0x8800, v130
	v_add_u32_e32 v127, 0x8c00, v130
	ds_write2_b32 v133, v66, v70 offset0:192 offset1:208
	v_add_u32_e32 v128, 0xc400, v130
	v_add_u32_e32 v129, 0xc800, v130
	v_add_u32_e32 v131, 0xcc00, v130
	v_lshlrev_b32_e32 v0, 3, v142
	v_lshlrev_b32_e32 v66, 2, v142
	ds_write2_b32 v132, v74, v78 offset0:128 offset1:144
	ds_write2_b32 v97, v75, v79 offset0:132 offset1:148
	ds_write2_b32 v126, v76, v80 offset0:136 offset1:152
	ds_write2_b32 v127, v77, v81 offset0:140 offset1:156
	ds_write2_b32 v128, v67, v71 offset0:196 offset1:212
	ds_write2_b32 v129, v68, v72 offset0:200 offset1:216
	ds_write2_b32 v131, v69, v73 offset0:204 offset1:220
	ds_write2_b32 v130, v98, v118 offset0:128 offset1:144
	ds_write2_b32 v114, v99, v119 offset0:132 offset1:148
	ds_write2_b32 v115, v100, v120 offset0:136 offset1:152
	ds_write2_b32 v116, v101, v121 offset0:140 offset1:156
	ds_write2_b32 v117, v102, v122 offset0:192 offset1:208
	ds_write2_b32 v94, v103, v123 offset0:196 offset1:212
	ds_write2_b32 v95, v104, v124 offset0:200 offset1:216
	ds_write2_b32 v96, v105, v125 offset0:204 offset1:220
	ds_write2_b32 v97, v90, v110 offset1:16
	ds_write2_b32 v126, v91, v111 offset0:4 offset1:20
	ds_write2_b32 v127, v92, v112 offset0:8 offset1:24
	v_add_u32_e32 v90, 0x9000, v130
	v_and_b32_e32 v0, 0xe0, v0
	v_and_b32_e32 v68, 12, v66
	ds_write2_b32 v90, v93, v113 offset0:12 offset1:28
	ds_write2_b32 v128, v86, v106 offset0:64 offset1:80
	ds_write2_b32 v129, v87, v107 offset0:68 offset1:84
	ds_write2_b32 v131, v88, v108 offset0:72 offset1:88
	v_lshlrev_b32_e32 v66, 2, v0
	v_lshlrev_b32_e32 v67, 2, v68
	v_or_b32_e32 v0, s38, v0
	v_ashrrev_i32_e32 v88, 5, v142
	v_add3_u32 v74, 0, v66, v67
	v_ashrrev_i32_e32 v66, 1, v0
	v_lshlrev_b32_e32 v0, 1, v68
	v_add_u32_e32 v68, s10, v88
	v_ashrrev_i32_e32 v69, 31, v68
	v_add_u32_e32 v91, 0xd000, v130
	v_lshl_add_u64 v[70:71], v[68:69], 4, s[46:47]
	ds_write2_b32 v91, v89, v109 offset0:76 offset1:92
	s_waitcnt lgkmcnt(0)
	s_barrier
	global_load_dwordx4 v[134:137], v[70:71], off
	global_load_dwordx4 v[138:141], v[70:71], off offset:256
	global_load_dwordx4 v[144:147], v[70:71], off offset:512
	global_load_dwordx4 v[148:151], v[70:71], off offset:768
	global_load_dwordx4 v[152:155], v[70:71], off offset:1024
	global_load_dwordx4 v[156:159], v[70:71], off offset:1280
	global_load_dwordx4 v[160:163], v[70:71], off offset:1536
	global_load_dwordx4 v[164:167], v[70:71], off offset:1792
	v_readlane_b32 s16, v253, 58
	v_ashrrev_i32_e32 v67, 31, v66
	v_readlane_b32 s17, v253, 59
	s_mov_b32 s33, 0x800000
	v_mad_u64_u32 v[82:83], s[36:37], v88, s42, v[74:75]
	v_lshl_add_u64 v[66:67], v[66:67], 1, s[16:17]
	v_lshl_add_u64 v[66:67], v[66:67], 0, v[0:1]
	s_movk_i32 s39, 0x1600
	v_readlane_b32 s16, v255, 10
	v_readlane_b32 s17, v255, 11
	s_waitcnt vmcnt(0)
	v_add_f32_e32 v0, v134, v135
	v_add_f32_e32 v0, v0, v136
	v_add_f32_e32 v0, v0, v137
	v_fmamk_f32 v0, v0, 0x3a800000, v200
	v_cmp_gt_f32_e32 vcc, s33, v0
	v_mul_f32_e32 v69, 0x4b800000, v0
	ds_read_b128 v[70:73], v82
	ds_read_b128 v[76:79], v82 offset:64
	v_cndmask_b32_e32 v0, v0, v69, vcc
	v_rsq_f32_e32 v0, v0
	s_nop 0
	v_mul_f32_e32 v69, 0x45800000, v0
	v_cndmask_b32_e32 v0, v0, v69, vcc
	s_waitcnt lgkmcnt(1)
	v_pk_mul_f32 v[70:71], v[70:71], v[0:1] op_sel_hi:[1,0]
	v_pk_mul_f32 v[72:73], v[72:73], v[0:1] op_sel_hi:[1,0]
	v_mul_f32_e32 v69, 0xbfb8aa3b, v70
	v_exp_f32_e32 v80, v69
	v_mul_f32_e32 v69, 0xbfb8aa3b, v71
	v_exp_f32_e32 v81, v69
	s_waitcnt lgkmcnt(0)
	v_pk_mul_f32 v[76:77], v[76:77], v[0:1] op_sel_hi:[1,0]
	v_pk_mul_f32 v[78:79], v[78:79], v[0:1] op_sel_hi:[1,0]
	v_mul_f32_e32 v0, 0xbfb8aa3b, v73
	v_pk_add_f32 v[80:81], v[80:81], 1.0 op_sel_hi:[1,0]
	s_nop 0
	v_rcp_f32_e32 v75, v81
	s_nop 0
	v_mul_f32_e32 v71, v71, v75
	v_rcp_f32_e32 v75, v80
	s_nop 0
	v_mul_f32_e32 v70, v70, v75
	v_mul_f32_e32 v69, 0xbfb8aa3b, v72
	v_pk_mul_f32 v[70:71], v[76:77], v[70:71]
	v_exp_f32_e32 v76, v69
	v_exp_f32_e32 v77, v0
	v_cvt_pk_bf16_f32 v70, v70, v71
	v_pk_add_f32 v[76:77], v[76:77], 1.0 op_sel_hi:[1,0]
	s_nop 0
	v_rcp_f32_e32 v69, v77
	s_nop 0
	v_mul_f32_e32 v73, v73, v69
	v_rcp_f32_e32 v69, v76
	s_nop 0
	v_mul_f32_e32 v72, v72, v69
	v_pk_mul_f32 v[72:73], v[78:79], v[72:73]
	v_add_u32_e32 v0, 0x200, v142
	v_cvt_pk_bf16_f32 v71, v72, v73
	v_mad_i64_i32 v[68:69], s[36:37], v68, s39, v[66:67]
	v_ashrrev_i32_e32 v83, 5, v0
	global_store_dwordx2 v[68:69], v[70:71], off
	v_add_u32_e32 v68, s10, v83
	v_ashrrev_i32_e32 v69, 31, v68
	v_lshl_add_u64 v[70:71], v[68:69], 4, s[46:47]
	v_mad_u64_u32 v[80:81], s[36:37], v83, s42, v[74:75]
	v_add_f32_e32 v0, v138, v139
	v_add_f32_e32 v0, v0, v140
	v_add_f32_e32 v0, v0, v141
	v_fmamk_f32 v0, v0, 0x3a800000, v200
	v_cmp_gt_f32_e32 vcc, s33, v0
	v_mul_f32_e32 v69, 0x4b800000, v0
	ds_read_b128 v[70:73], v80
	ds_read_b128 v[76:79], v80 offset:64
	v_cndmask_b32_e32 v0, v0, v69, vcc
	v_rsq_f32_e32 v0, v0
	s_nop 0
	v_mul_f32_e32 v69, 0x45800000, v0
	v_cndmask_b32_e32 v0, v0, v69, vcc
	s_waitcnt lgkmcnt(1)
	v_pk_mul_f32 v[70:71], v[70:71], v[0:1] op_sel_hi:[1,0]
	v_pk_mul_f32 v[72:73], v[72:73], v[0:1] op_sel_hi:[1,0]
	v_mul_f32_e32 v69, 0xbfb8aa3b, v70
	v_exp_f32_e32 v84, v69
	v_mul_f32_e32 v69, 0xbfb8aa3b, v71
	v_exp_f32_e32 v85, v69
	s_waitcnt lgkmcnt(0)
	v_pk_mul_f32 v[76:77], v[76:77], v[0:1] op_sel_hi:[1,0]
	v_pk_mul_f32 v[78:79], v[78:79], v[0:1] op_sel_hi:[1,0]
	v_mul_f32_e32 v0, 0xbfb8aa3b, v73
	v_pk_add_f32 v[84:85], v[84:85], 1.0 op_sel_hi:[1,0]
	s_nop 0
	v_rcp_f32_e32 v75, v85
	s_nop 0
	v_mul_f32_e32 v71, v71, v75
	v_rcp_f32_e32 v75, v84
	s_nop 0
	v_mul_f32_e32 v70, v70, v75
	v_mul_f32_e32 v69, 0xbfb8aa3b, v72
	v_pk_mul_f32 v[70:71], v[76:77], v[70:71]
	v_exp_f32_e32 v76, v69
	v_exp_f32_e32 v77, v0
	v_cvt_pk_bf16_f32 v70, v70, v71
	v_pk_add_f32 v[76:77], v[76:77], 1.0 op_sel_hi:[1,0]
	s_nop 0
	v_rcp_f32_e32 v69, v77
	s_nop 0
	v_mul_f32_e32 v73, v73, v69
	v_rcp_f32_e32 v69, v76
	s_nop 0
	v_mul_f32_e32 v72, v72, v69
	v_pk_mul_f32 v[72:73], v[78:79], v[72:73]
	v_add_u32_e32 v0, 0x400, v142
	v_cvt_pk_bf16_f32 v71, v72, v73
	v_mad_i64_i32 v[68:69], s[36:37], v68, s39, v[66:67]
	v_ashrrev_i32_e32 v81, 5, v0
	global_store_dwordx2 v[68:69], v[70:71], off
	v_add_u32_e32 v68, s10, v81
	v_ashrrev_i32_e32 v69, 31, v68
	v_lshl_add_u64 v[70:71], v[68:69], 4, s[46:47]
	v_mad_u64_u32 v[78:79], s[36:37], v81, s42, v[74:75]
	v_add_f32_e32 v0, v144, v145
	v_add_f32_e32 v0, v0, v146
	v_add_f32_e32 v0, v0, v147
	v_fmamk_f32 v0, v0, 0x3a800000, v200
	v_cmp_gt_f32_e32 vcc, s33, v0
	v_mul_f32_e32 v69, 0x4b800000, v0
	ds_read_b128 v[70:73], v78
	ds_read_b128 v[84:87], v78 offset:64
	v_cndmask_b32_e32 v0, v0, v69, vcc
	v_rsq_f32_e32 v0, v0
	s_nop 0
	v_mul_f32_e32 v69, 0x45800000, v0
	v_cndmask_b32_e32 v0, v0, v69, vcc
	s_waitcnt lgkmcnt(1)
	v_pk_mul_f32 v[70:71], v[70:71], v[0:1] op_sel_hi:[1,0]
	v_pk_mul_f32 v[72:73], v[72:73], v[0:1] op_sel_hi:[1,0]
	v_mul_f32_e32 v69, 0xbfb8aa3b, v70
	v_exp_f32_e32 v76, v69
	v_mul_f32_e32 v69, 0xbfb8aa3b, v71
	v_exp_f32_e32 v77, v69
	s_waitcnt lgkmcnt(0)
	v_pk_mul_f32 v[84:85], v[84:85], v[0:1] op_sel_hi:[1,0]
	v_pk_add_f32 v[76:77], v[76:77], 1.0 op_sel_hi:[1,0]
	s_nop 0
	v_rcp_f32_e32 v75, v77
	s_nop 0
	v_mul_f32_e32 v71, v71, v75
	v_rcp_f32_e32 v75, v76
	s_nop 0
	v_mul_f32_e32 v70, v70, v75
	v_mul_f32_e32 v69, 0xbfb8aa3b, v72
	v_pk_mul_f32 v[76:77], v[86:87], v[0:1] op_sel_hi:[1,0]
	v_mul_f32_e32 v0, 0xbfb8aa3b, v73
	v_pk_mul_f32 v[70:71], v[84:85], v[70:71]
	v_exp_f32_e32 v84, v69
	v_exp_f32_e32 v85, v0
	v_cvt_pk_bf16_f32 v70, v70, v71
	v_pk_add_f32 v[84:85], v[84:85], 1.0 op_sel_hi:[1,0]
	s_nop 0
	v_rcp_f32_e32 v69, v85
	s_nop 0
	v_mul_f32_e32 v73, v73, v69
	v_rcp_f32_e32 v69, v84
	s_nop 0
	v_mul_f32_e32 v72, v72, v69
	v_add_u32_e32 v0, 0x600, v142
	v_pk_mul_f32 v[72:73], v[76:77], v[72:73]
	v_ashrrev_i32_e32 v79, 5, v0
	v_cvt_pk_bf16_f32 v71, v72, v73
	v_add_u32_e32 v72, s10, v79
	v_mad_i64_i32 v[68:69], s[36:37], v68, s39, v[66:67]
	v_ashrrev_i32_e32 v73, 31, v72
	global_store_dwordx2 v[68:69], v[70:71], off
	v_lshl_add_u64 v[68:69], v[72:73], 4, s[46:47]
	v_mad_u64_u32 v[76:77], s[36:37], v79, s42, v[74:75]
	v_add_f32_e32 v0, v148, v149
	v_add_f32_e32 v0, v0, v150
	v_add_f32_e32 v0, v0, v151
	v_fmamk_f32 v0, v0, 0x3a800000, v200
	v_cmp_gt_f32_e32 vcc, s33, v0
	v_mul_f32_e32 v68, 0x4b800000, v0
	s_nop 0
	v_cndmask_b32_e32 v0, v0, v68, vcc
	v_rsq_f32_e32 v0, v0
	s_nop 0
	v_mul_f32_e32 v68, 0x45800000, v0
	v_cndmask_b32_e32 v0, v0, v68, vcc
	ds_read_b128 v[68:71], v76
	ds_read_b128 v[84:87], v76 offset:64
	s_waitcnt lgkmcnt(1)
	v_pk_mul_f32 v[68:69], v[68:69], v[0:1] op_sel_hi:[1,0]
	s_nop 0
	v_mul_f32_e32 v73, 0xbfb8aa3b, v68
	v_exp_f32_e32 v92, v73
	v_mul_f32_e32 v73, 0xbfb8aa3b, v69
	v_exp_f32_e32 v93, v73
	v_pk_mul_f32 v[70:71], v[70:71], v[0:1] op_sel_hi:[1,0]
	s_waitcnt lgkmcnt(0)
	v_pk_mul_f32 v[84:85], v[84:85], v[0:1] op_sel_hi:[1,0]
	v_pk_mul_f32 v[86:87], v[86:87], v[0:1] op_sel_hi:[1,0]
	v_pk_add_f32 v[92:93], v[92:93], 1.0 op_sel_hi:[1,0]
	v_mul_f32_e32 v0, 0xbfb8aa3b, v71
	v_rcp_f32_e32 v75, v93
	s_nop 0
	v_mul_f32_e32 v69, v69, v75
	v_rcp_f32_e32 v75, v92
	s_nop 0
	v_mul_f32_e32 v68, v68, v75
	v_mul_f32_e32 v73, 0xbfb8aa3b, v70
	v_pk_mul_f32 v[68:69], v[84:85], v[68:69]
	v_exp_f32_e32 v84, v73
	v_exp_f32_e32 v85, v0
	v_cvt_pk_bf16_f32 v68, v68, v69
	v_pk_add_f32 v[84:85], v[84:85], 1.0 op_sel_hi:[1,0]
	s_nop 0
	v_rcp_f32_e32 v73, v85
	s_nop 0
	v_mul_f32_e32 v71, v71, v73
	v_rcp_f32_e32 v73, v84
	s_nop 0
	v_mul_f32_e32 v70, v70, v73
	v_pk_mul_f32 v[70:71], v[86:87], v[70:71]
	v_add_u32_e32 v0, 0x800, v142
	v_cvt_pk_bf16_f32 v69, v70, v71
	v_mad_i64_i32 v[70:71], s[36:37], v72, s39, v[66:67]
	v_ashrrev_i32_e32 v0, 5, v0
	global_store_dwordx2 v[70:71], v[68:69], off
	v_add_u32_e32 v70, s10, v0
	v_ashrrev_i32_e32 v71, 31, v70
	v_lshl_add_u64 v[72:73], v[70:71], 4, s[46:47]
	v_mad_u64_u32 v[68:69], s[36:37], v0, s42, v[74:75]
	v_add_f32_e32 v69, v152, v153
	v_add_f32_e32 v69, v69, v154
	v_add_f32_e32 v69, v69, v155
	v_fmamk_f32 v69, v69, 0x3a800000, v200
	v_cmp_gt_f32_e32 vcc, s33, v69
	v_mul_f32_e32 v71, 0x4b800000, v69
	ds_read_b128 v[84:87], v68
	ds_read_b128 v[98:101], v68 offset:64
	v_cndmask_b32_e32 v69, v69, v71, vcc
	v_rsq_f32_e32 v69, v69
	s_nop 0
	v_mul_f32_e32 v71, 0x45800000, v69
	v_cndmask_b32_e32 v72, v69, v71, vcc
	s_waitcnt lgkmcnt(1)
	v_pk_mul_f32 v[84:85], v[84:85], v[72:73] op_sel_hi:[1,0]
	s_waitcnt lgkmcnt(0)
	v_pk_mul_f32 v[98:99], v[98:99], v[72:73] op_sel_hi:[1,0]
	v_mul_f32_e32 v69, 0xbfb8aa3b, v84
	v_exp_f32_e32 v92, v69
	v_mul_f32_e32 v69, 0xbfb8aa3b, v85
	v_exp_f32_e32 v93, v69
	s_nop 0
	v_pk_add_f32 v[92:93], v[92:93], 1.0 op_sel_hi:[1,0]
	s_nop 0
	v_rcp_f32_e32 v71, v93
	s_nop 0
	v_mul_f32_e32 v85, v85, v71
	v_div_scale_f32 v69, s[36:37], v92, v92, v84
	v_rcp_f32_e32 v71, v69
	s_nop 0
	v_fma_f32 v73, -v69, v71, 1.0
	v_fmac_f32_e32 v71, v73, v71
	v_div_scale_f32 v73, vcc, v84, v92, v84
	v_mul_f32_e32 v75, v73, v71
	v_fma_f32 v77, -v69, v75, v73
	v_fmac_f32_e32 v75, v77, v71
	v_fma_f32 v69, -v69, v75, v73
	v_div_fmas_f32 v69, v69, v71, v75
	v_pk_mul_f32 v[86:87], v[86:87], v[72:73] op_sel_hi:[1,0]
	v_div_fixup_f32 v84, v69, v92, v84
	v_mul_f32_e32 v69, 0xbfb8aa3b, v86
	v_exp_f32_e32 v92, v69
	v_mul_f32_e32 v69, 0xbfb8aa3b, v87
	v_exp_f32_e32 v93, v69
	v_pk_mul_f32 v[72:73], v[100:101], v[72:73] op_sel_hi:[1,0]
	v_pk_mul_f32 v[84:85], v[98:99], v[84:85]
	v_pk_add_f32 v[92:93], v[92:93], 1.0 op_sel_hi:[1,0]
	s_nop 0
	v_div_scale_f32 v69, s[36:37], v93, v93, v87
	v_rcp_f32_e32 v71, v69
	v_cvt_pk_bf16_f32 v84, v84, v85
	v_fma_f32 v75, -v69, v71, 1.0
	v_fmac_f32_e32 v71, v75, v71
	v_div_scale_f32 v75, vcc, v87, v93, v87
	v_mul_f32_e32 v77, v75, v71
	v_fma_f32 v89, -v69, v77, v75
	v_fmac_f32_e32 v77, v89, v71
	v_fma_f32 v69, -v69, v77, v75
	v_div_fmas_f32 v69, v69, v71, v77
	v_div_fixup_f32 v87, v69, v93, v87
	v_rcp_f32_e32 v71, v92
	s_nop 0
	v_mul_f32_e32 v86, v86, v71
	v_add_u32_e32 v69, 0xa00, v142
	v_pk_mul_f32 v[72:73], v[72:73], v[86:87]
	v_ashrrev_i32_e32 v69, 5, v69
	v_cvt_pk_bf16_f32 v85, v72, v73
	v_add_u32_e32 v72, s10, v69
	v_mad_i64_i32 v[70:71], s[36:37], v70, s39, v[66:67]
	v_ashrrev_i32_e32 v73, 31, v72
	global_store_dwordx2 v[70:71], v[84:85], off
	v_lshl_add_u64 v[84:85], v[72:73], 4, s[46:47]
	v_mad_u64_u32 v[70:71], s[36:37], v69, s42, v[74:75]
	v_add_f32_e32 v71, v156, v157
	v_add_f32_e32 v71, v71, v158
	v_add_f32_e32 v71, v71, v159
	v_fmamk_f32 v71, v71, 0x3a800000, v200
	v_cmp_gt_f32_e32 vcc, s33, v71
	v_mul_f32_e32 v73, 0x4b800000, v71
	ds_read_b128 v[84:87], v70
	ds_read_b128 v[98:101], v70 offset:64
	v_cndmask_b32_e32 v71, v71, v73, vcc
	v_rsq_f32_e32 v71, v71
	s_nop 0
	v_mul_f32_e32 v73, 0x45800000, v71
	v_cndmask_b32_e32 v92, v71, v73, vcc
	s_waitcnt lgkmcnt(1)
	v_pk_mul_f32 v[84:85], v[84:85], v[92:93] op_sel_hi:[1,0]
	v_pk_mul_f32 v[86:87], v[86:87], v[92:93] op_sel_hi:[1,0]
	v_mul_f32_e32 v71, 0xbfb8aa3b, v84
	v_exp_f32_e32 v102, v71
	v_mul_f32_e32 v71, 0xbfb8aa3b, v85
	v_exp_f32_e32 v103, v71
	s_waitcnt lgkmcnt(0)
	v_pk_mul_f32 v[98:99], v[98:99], v[92:93] op_sel_hi:[1,0]
	v_pk_mul_f32 v[92:93], v[100:101], v[92:93] op_sel_hi:[1,0]
	v_pk_add_f32 v[102:103], v[102:103], 1.0 op_sel_hi:[1,0]
	s_nop 0
	v_rcp_f32_e32 v73, v103
	s_nop 0
	v_mul_f32_e32 v85, v85, v73
	v_rcp_f32_e32 v73, v102
	s_nop 0
	v_mul_f32_e32 v84, v84, v73
	v_mul_f32_e32 v71, 0xbfb8aa3b, v86
	v_pk_mul_f32 v[84:85], v[98:99], v[84:85]
	v_exp_f32_e32 v98, v71
	v_mul_f32_e32 v71, 0xbfb8aa3b, v87
	v_exp_f32_e32 v99, v71
	v_cvt_pk_bf16_f32 v84, v84, v85
	v_pk_add_f32 v[98:99], v[98:99], 1.0 op_sel_hi:[1,0]
	s_nop 0
	v_rcp_f32_e32 v73, v99
	s_nop 0
	v_mul_f32_e32 v87, v87, v73
	v_rcp_f32_e32 v73, v98
	s_nop 0
	v_mul_f32_e32 v86, v86, v73
	v_pk_mul_f32 v[86:87], v[92:93], v[86:87]
	v_add_u32_e32 v71, 0xc00, v142
	v_cvt_pk_bf16_f32 v85, v86, v87
	v_mad_i64_i32 v[72:73], s[36:37], v72, s39, v[66:67]
	v_ashrrev_i32_e32 v71, 5, v71
	global_store_dwordx2 v[72:73], v[84:85], off
	v_add_u32_e32 v84, s10, v71
	v_ashrrev_i32_e32 v85, 31, v84
	v_lshl_add_u64 v[86:87], v[84:85], 4, s[46:47]
	v_mad_u64_u32 v[72:73], s[36:37], v71, s42, v[74:75]
	v_add_f32_e32 v73, v160, v161
	v_add_f32_e32 v73, v73, v162
	v_add_f32_e32 v73, v73, v163
	v_fmamk_f32 v73, v73, 0x3a800000, v200
	v_cmp_gt_f32_e32 vcc, s33, v73
	v_mul_f32_e32 v75, 0x4b800000, v73
	ds_read_b128 v[98:101], v72
	ds_read_b128 v[102:105], v72 offset:64
	v_cndmask_b32_e32 v73, v73, v75, vcc
	v_rsq_f32_e32 v73, v73
	s_nop 0
	v_mul_f32_e32 v75, 0x45800000, v73
	v_cndmask_b32_e32 v86, v73, v75, vcc
	s_waitcnt lgkmcnt(1)
	v_pk_mul_f32 v[92:93], v[98:99], v[86:87] op_sel_hi:[1,0]
	s_waitcnt lgkmcnt(0)
	v_pk_mul_f32 v[102:103], v[102:103], v[86:87] op_sel_hi:[1,0]
	v_mul_f32_e32 v73, 0xbfb8aa3b, v92
	v_exp_f32_e32 v98, v73
	v_mul_f32_e32 v73, 0xbfb8aa3b, v93
	v_exp_f32_e32 v99, v73
	s_nop 0
	v_pk_add_f32 v[98:99], v[98:99], 1.0 op_sel_hi:[1,0]
	s_nop 0
	v_rcp_f32_e32 v75, v99
	s_nop 0
	v_mul_f32_e32 v93, v93, v75
	v_rcp_f32_e32 v75, v98
	s_nop 0
	v_mul_f32_e32 v92, v92, v75
	v_pk_mul_f32 v[98:99], v[100:101], v[86:87] op_sel_hi:[1,0]
	v_pk_mul_f32 v[86:87], v[104:105], v[86:87] op_sel_hi:[1,0]
	v_mul_f32_e32 v73, 0xbfb8aa3b, v98
	v_exp_f32_e32 v100, v73
	v_mul_f32_e32 v73, 0xbfb8aa3b, v99
	v_exp_f32_e32 v101, v73
	v_pk_mul_f32 v[92:93], v[102:103], v[92:93]
	v_pk_add_f32 v[100:101], v[100:101], 1.0 op_sel_hi:[1,0]
	s_nop 0
	v_div_scale_f32 v73, s[36:37], v101, v101, v99
	v_rcp_f32_e32 v75, v73
	v_cvt_pk_bf16_f32 v92, v92, v93
	v_fma_f32 v77, -v73, v75, 1.0
	v_fmac_f32_e32 v75, v77, v75
	v_div_scale_f32 v77, vcc, v99, v101, v99
	v_mul_f32_e32 v85, v77, v75
	v_fma_f32 v89, -v73, v85, v77
	v_fmac_f32_e32 v85, v89, v75
	v_fma_f32 v73, -v73, v85, v77
	v_div_fmas_f32 v73, v73, v75, v85
	v_div_fixup_f32 v99, v73, v101, v99
	v_rcp_f32_e32 v75, v100
	s_nop 0
	v_mul_f32_e32 v98, v98, v75
	v_pk_mul_f32 v[86:87], v[86:87], v[98:99]
	v_add_u32_e32 v73, 0xe00, v142
	v_cvt_pk_bf16_f32 v93, v86, v87
	v_mad_i64_i32 v[84:85], s[36:37], v84, s39, v[66:67]
	v_ashrrev_i32_e32 v73, 5, v73
	global_store_dwordx2 v[84:85], v[92:93], off
	v_add_u32_e32 v84, s10, v73
	v_ashrrev_i32_e32 v85, 31, v84
	v_lshl_add_u64 v[86:87], v[84:85], 4, s[46:47]
	v_mad_u64_u32 v[74:75], s[36:37], v73, s42, v[74:75]
	v_mov_b32_e32 v142, v201
	s_or_b32 s42, s38, 0x100
	s_ashr_i32 s43, s42, 31
	s_lshl_b64 s[70:71], s[42:43], 11
	v_add_f32_e32 v75, v164, v165
	v_add_f32_e32 v75, v75, v166
	v_add_f32_e32 v75, v75, v167
	v_fmamk_f32 v75, v75, 0x3a800000, v200
	v_cmp_gt_f32_e32 vcc, s33, v75
	v_mul_f32_e32 v77, 0x4b800000, v75
	ds_read_b128 v[98:101], v74
	ds_read_b128 v[102:105], v74 offset:64
	v_cndmask_b32_e32 v75, v75, v77, vcc
	v_rsq_f32_e32 v75, v75
	s_nop 0
	v_mul_f32_e32 v77, 0x45800000, v75
	v_cndmask_b32_e32 v86, v75, v77, vcc
	s_waitcnt lgkmcnt(1)
	v_pk_mul_f32 v[92:93], v[98:99], v[86:87] op_sel_hi:[1,0]
	s_waitcnt lgkmcnt(0)
	v_pk_mul_f32 v[102:103], v[102:103], v[86:87] op_sel_hi:[1,0]
	v_mul_f32_e32 v75, 0xbfb8aa3b, v92
	v_exp_f32_e32 v98, v75
	v_mul_f32_e32 v75, 0xbfb8aa3b, v93
	v_exp_f32_e32 v99, v75
	s_nop 0
	v_pk_add_f32 v[98:99], v[98:99], 1.0 op_sel_hi:[1,0]
	s_nop 0
	v_rcp_f32_e32 v77, v99
	s_nop 0
	v_mul_f32_e32 v93, v93, v77
	v_rcp_f32_e32 v77, v98
	s_nop 0
	v_mul_f32_e32 v92, v92, v77
	v_pk_mul_f32 v[98:99], v[100:101], v[86:87] op_sel_hi:[1,0]
	v_pk_mul_f32 v[92:93], v[102:103], v[92:93]
	v_mul_f32_e32 v75, 0xbfb8aa3b, v98
	v_exp_f32_e32 v100, v75
	v_mul_f32_e32 v75, 0xbfb8aa3b, v99
	v_exp_f32_e32 v101, v75
	v_pk_mul_f32 v[86:87], v[104:105], v[86:87] op_sel_hi:[1,0]
	v_cvt_pk_bf16_f32 v92, v92, v93
	v_pk_add_f32 v[100:101], v[100:101], 1.0 op_sel_hi:[1,0]
	s_nop 0
	v_rcp_f32_e32 v77, v101
	s_nop 0
	v_mul_f32_e32 v99, v99, v77
	v_rcp_f32_e32 v77, v100
	s_nop 0
	v_mul_f32_e32 v98, v98, v77
	v_pk_mul_f32 v[86:87], v[86:87], v[98:99]
	v_mad_i64_i32 v[84:85], s[36:37], v84, s39, v[66:67]
	v_cvt_pk_bf16_f32 v93, v86, v87
	global_store_dwordx2 v[84:85], v[92:93], off
	s_barrier
	ds_write2_b32 v130, v2, v18 offset1:16
	ds_write2_b32 v114, v3, v19 offset0:4 offset1:20
	ds_write2_b32 v115, v4, v20 offset0:8 offset1:24
	ds_write2_b32 v116, v5, v21 offset0:12 offset1:28
	ds_write2_b32 v117, v6, v22 offset0:64 offset1:80
	ds_write2_b32 v94, v7, v23 offset0:68 offset1:84
	ds_write2_b32 v95, v8, v24 offset0:72 offset1:88
	ds_write2_b32 v96, v9, v25 offset0:76 offset1:92
	ds_write2_b32 v132, v10, v26 offset0:128 offset1:144
	ds_write2_b32 v97, v11, v27 offset0:132 offset1:148
	ds_write2_b32 v126, v12, v28 offset0:136 offset1:152
	ds_write2_b32 v127, v13, v29 offset0:140 offset1:156
	ds_write2_b32 v133, v14, v30 offset0:192 offset1:208
	ds_write2_b32 v128, v15, v31 offset0:196 offset1:212
	ds_write2_b32 v129, v16, v32 offset0:200 offset1:216
	ds_write2_b32 v131, v17, v33 offset0:204 offset1:220
	ds_write2_b32 v130, v34, v50 offset0:128 offset1:144
	ds_write2_b32 v114, v35, v51 offset0:132 offset1:148
	ds_write2_b32 v115, v36, v52 offset0:136 offset1:152
	ds_write2_b32 v116, v37, v53 offset0:140 offset1:156
	ds_write2_b32 v117, v38, v54 offset0:192 offset1:208
	ds_write2_b32 v94, v39, v55 offset0:196 offset1:212
	ds_write2_b32 v95, v40, v56 offset0:200 offset1:216
	ds_write2_b32 v96, v41, v57 offset0:204 offset1:220
	ds_write2_b32 v97, v42, v58 offset1:16
	ds_write2_b32 v126, v43, v59 offset0:4 offset1:20
	ds_write2_b32 v127, v44, v60 offset0:8 offset1:24
	ds_write2_b32 v90, v45, v61 offset0:12 offset1:28
	ds_write2_b32 v128, v46, v62 offset0:64 offset1:80
	ds_write2_b32 v129, v47, v63 offset0:68 offset1:84
	ds_write2_b32 v131, v48, v64 offset0:72 offset1:88
	ds_write2_b32 v91, v49, v65 offset0:76 offset1:92
	v_add_u32_e32 v2, s8, v88
	v_ashrrev_i32_e32 v3, 31, v2
	v_lshl_add_u64 v[4:5], v[2:3], 4, s[46:47]
	s_waitcnt lgkmcnt(0)
	s_barrier
	global_load_dwordx4 v[134:137], v[4:5], off
	global_load_dwordx4 v[138:141], v[4:5], off offset:256
	global_load_dwordx4 v[144:147], v[4:5], off offset:512
	global_load_dwordx4 v[148:151], v[4:5], off offset:768
	global_load_dwordx4 v[152:155], v[4:5], off offset:1024
	global_load_dwordx4 v[156:159], v[4:5], off offset:1280
	global_load_dwordx4 v[160:163], v[4:5], off offset:1536
	global_load_dwordx4 v[164:167], v[4:5], off offset:1792
	s_waitcnt vmcnt(0)
	v_add_f32_e32 v3, v134, v135
	v_add_f32_e32 v3, v3, v136
	v_add_f32_e32 v3, v3, v137
	v_fmamk_f32 v3, v3, 0x3a800000, v200
	v_cmp_gt_f32_e32 vcc, s33, v3
	v_mul_f32_e32 v4, 0x4b800000, v3
	s_nop 0
	v_cndmask_b32_e32 v3, v3, v4, vcc
	v_rsq_f32_e32 v3, v3
	s_nop 0
	v_mul_f32_e32 v4, 0x45800000, v3
	v_cndmask_b32_e32 v12, v3, v4, vcc
	ds_read_b128 v[4:7], v82
	ds_read_b128 v[8:11], v82 offset:64
	s_waitcnt lgkmcnt(1)
	v_pk_mul_f32 v[4:5], v[4:5], v[12:13] op_sel_hi:[1,0]
	s_nop 0
	v_mul_f32_e32 v3, 0xbfb8aa3b, v4
	v_exp_f32_e32 v14, v3
	v_mul_f32_e32 v3, 0xbfb8aa3b, v5
	v_exp_f32_e32 v15, v3
	s_waitcnt lgkmcnt(0)
	v_pk_mul_f32 v[8:9], v[8:9], v[12:13] op_sel_hi:[1,0]
	v_pk_add_f32 v[14:15], v[14:15], 1.0 op_sel_hi:[1,0]
	s_nop 0
	v_rcp_f32_e32 v13, v15
	s_nop 0
	v_mul_f32_e32 v5, v5, v13
	v_div_scale_f32 v3, s[36:37], v14, v14, v4
	v_rcp_f32_e32 v13, v3
	s_nop 0
	v_fma_f32 v15, -v3, v13, 1.0
	v_fmac_f32_e32 v13, v15, v13
	v_div_scale_f32 v15, vcc, v4, v14, v4
	v_mul_f32_e32 v16, v15, v13
	v_fma_f32 v17, -v3, v16, v15
	v_fmac_f32_e32 v16, v17, v13
	v_fma_f32 v3, -v3, v16, v15
	v_div_fmas_f32 v3, v3, v13, v16
	v_pk_mul_f32 v[6:7], v[6:7], v[12:13] op_sel_hi:[1,0]
	v_div_fixup_f32 v4, v3, v14, v4
	v_mul_f32_e32 v3, 0xbfb8aa3b, v6
	v_pk_mul_f32 v[4:5], v[8:9], v[4:5]
	v_exp_f32_e32 v8, v3
	v_mul_f32_e32 v3, 0xbfb8aa3b, v7
	v_exp_f32_e32 v9, v3
	v_pk_mul_f32 v[10:11], v[10:11], v[12:13] op_sel_hi:[1,0]
	v_cvt_pk_bf16_f32 v4, v4, v5
	v_pk_add_f32 v[8:9], v[8:9], 1.0 op_sel_hi:[1,0]
	s_nop 0
	v_rcp_f32_e32 v12, v9
	s_nop 0
	v_mul_f32_e32 v7, v7, v12
	v_rcp_f32_e32 v9, v8
	s_nop 0
	v_mul_f32_e32 v6, v6, v9
	v_pk_mul_f32 v[6:7], v[10:11], v[6:7]
	v_mad_i64_i32 v[2:3], s[36:37], v2, s39, v[66:67]
	v_cvt_pk_bf16_f32 v5, v6, v7
	global_store_dwordx2 v[2:3], v[4:5], off
	v_add_u32_e32 v2, s8, v83
	v_ashrrev_i32_e32 v3, 31, v2
	v_lshl_add_u64 v[4:5], v[2:3], 4, s[46:47]
	v_add_f32_e32 v3, v138, v139
	v_add_f32_e32 v3, v3, v140
	v_add_f32_e32 v3, v3, v141
	v_fmamk_f32 v3, v3, 0x3a800000, v200
	v_cmp_gt_f32_e32 vcc, s33, v3
	v_mul_f32_e32 v4, 0x4b800000, v3
	s_nop 0
	v_cndmask_b32_e32 v3, v3, v4, vcc
	v_rsq_f32_e32 v3, v3
	s_nop 0
	v_mul_f32_e32 v4, 0x45800000, v3
	v_cndmask_b32_e32 v12, v3, v4, vcc
	ds_read_b128 v[4:7], v80
	ds_read_b128 v[8:11], v80 offset:64
	s_waitcnt lgkmcnt(1)
	v_pk_mul_f32 v[4:5], v[4:5], v[12:13] op_sel_hi:[1,0]
	s_nop 0
	v_mul_f32_e32 v3, 0xbfb8aa3b, v4
	v_exp_f32_e32 v14, v3
	v_mul_f32_e32 v3, 0xbfb8aa3b, v5
	v_exp_f32_e32 v15, v3
	s_waitcnt lgkmcnt(0)
	v_pk_mul_f32 v[8:9], v[8:9], v[12:13] op_sel_hi:[1,0]
	v_pk_add_f32 v[14:15], v[14:15], 1.0 op_sel_hi:[1,0]
	s_nop 0
	v_rcp_f32_e32 v13, v15
	s_nop 0
	v_mul_f32_e32 v5, v5, v13
	v_div_scale_f32 v3, s[36:37], v14, v14, v4
	v_rcp_f32_e32 v13, v3
	s_nop 0
	v_fma_f32 v15, -v3, v13, 1.0
	v_fmac_f32_e32 v13, v15, v13
	v_div_scale_f32 v15, vcc, v4, v14, v4
	v_mul_f32_e32 v16, v15, v13
	v_fma_f32 v17, -v3, v16, v15
	v_fmac_f32_e32 v16, v17, v13
	v_fma_f32 v3, -v3, v16, v15
	v_div_fmas_f32 v3, v3, v13, v16
	v_pk_mul_f32 v[6:7], v[6:7], v[12:13] op_sel_hi:[1,0]
	v_div_fixup_f32 v4, v3, v14, v4
	v_mul_f32_e32 v3, 0xbfb8aa3b, v6
	v_pk_mul_f32 v[4:5], v[8:9], v[4:5]
	v_exp_f32_e32 v8, v3
	v_mul_f32_e32 v3, 0xbfb8aa3b, v7
	v_exp_f32_e32 v9, v3
	v_pk_mul_f32 v[10:11], v[10:11], v[12:13] op_sel_hi:[1,0]
	v_cvt_pk_bf16_f32 v4, v4, v5
	v_pk_add_f32 v[8:9], v[8:9], 1.0 op_sel_hi:[1,0]
	s_nop 0
	v_rcp_f32_e32 v12, v9
	s_nop 0
	v_mul_f32_e32 v7, v7, v12
	v_rcp_f32_e32 v9, v8
	s_nop 0
	v_mul_f32_e32 v6, v6, v9
	v_pk_mul_f32 v[6:7], v[10:11], v[6:7]
	v_mad_i64_i32 v[2:3], s[36:37], v2, s39, v[66:67]
	v_cvt_pk_bf16_f32 v5, v6, v7
	global_store_dwordx2 v[2:3], v[4:5], off
	v_add_u32_e32 v2, s8, v81
	v_ashrrev_i32_e32 v3, 31, v2
	v_lshl_add_u64 v[4:5], v[2:3], 4, s[46:47]
	v_add_f32_e32 v3, v144, v145
	v_add_f32_e32 v3, v3, v146
	v_add_f32_e32 v3, v3, v147
	v_fmamk_f32 v3, v3, 0x3a800000, v200
	v_cmp_gt_f32_e32 vcc, s33, v3
	v_mul_f32_e32 v4, 0x4b800000, v3
	s_nop 0
	v_cndmask_b32_e32 v3, v3, v4, vcc
	v_rsq_f32_e32 v3, v3
	s_nop 0
	v_mul_f32_e32 v4, 0x45800000, v3
	v_cndmask_b32_e32 v12, v3, v4, vcc
	ds_read_b128 v[4:7], v78
	ds_read_b128 v[8:11], v78 offset:64
	s_waitcnt lgkmcnt(1)
	v_pk_mul_f32 v[4:5], v[4:5], v[12:13] op_sel_hi:[1,0]
	s_nop 0
	v_mul_f32_e32 v3, 0xbfb8aa3b, v4
	v_exp_f32_e32 v14, v3
	v_mul_f32_e32 v3, 0xbfb8aa3b, v5
	v_exp_f32_e32 v15, v3
	s_waitcnt lgkmcnt(0)
	v_pk_mul_f32 v[8:9], v[8:9], v[12:13] op_sel_hi:[1,0]
	v_pk_add_f32 v[14:15], v[14:15], 1.0 op_sel_hi:[1,0]
	s_nop 0
	v_rcp_f32_e32 v13, v15
	s_nop 0
	v_mul_f32_e32 v5, v5, v13
	v_div_scale_f32 v3, s[36:37], v14, v14, v4
	v_rcp_f32_e32 v13, v3
	s_nop 0
	v_fma_f32 v15, -v3, v13, 1.0
	v_fmac_f32_e32 v13, v15, v13
	v_div_scale_f32 v15, vcc, v4, v14, v4
	v_mul_f32_e32 v16, v15, v13
	v_fma_f32 v17, -v3, v16, v15
	v_fmac_f32_e32 v16, v17, v13
	v_fma_f32 v3, -v3, v16, v15
	v_div_fmas_f32 v3, v3, v13, v16
	v_pk_mul_f32 v[6:7], v[6:7], v[12:13] op_sel_hi:[1,0]
	v_div_fixup_f32 v4, v3, v14, v4
	v_mul_f32_e32 v3, 0xbfb8aa3b, v6
	v_pk_mul_f32 v[4:5], v[8:9], v[4:5]
	v_exp_f32_e32 v8, v3
	v_mul_f32_e32 v3, 0xbfb8aa3b, v7
	v_exp_f32_e32 v9, v3
	v_pk_mul_f32 v[10:11], v[10:11], v[12:13] op_sel_hi:[1,0]
	v_cvt_pk_bf16_f32 v4, v4, v5
	v_pk_add_f32 v[8:9], v[8:9], 1.0 op_sel_hi:[1,0]
	s_nop 0
	v_rcp_f32_e32 v12, v9
	s_nop 0
	v_mul_f32_e32 v7, v7, v12
	v_rcp_f32_e32 v9, v8
	s_nop 0
	v_mul_f32_e32 v6, v6, v9
	v_pk_mul_f32 v[6:7], v[10:11], v[6:7]
	v_mad_i64_i32 v[2:3], s[36:37], v2, s39, v[66:67]
	v_cvt_pk_bf16_f32 v5, v6, v7
	global_store_dwordx2 v[2:3], v[4:5], off
	v_add_u32_e32 v2, s8, v79
	v_ashrrev_i32_e32 v3, 31, v2
	v_lshl_add_u64 v[4:5], v[2:3], 4, s[46:47]
	v_add_f32_e32 v3, v148, v149
	v_add_f32_e32 v3, v3, v150
	v_add_f32_e32 v3, v3, v151
	v_fmamk_f32 v3, v3, 0x3a800000, v200
	v_cmp_gt_f32_e32 vcc, s33, v3
	v_mul_f32_e32 v4, 0x4b800000, v3
	s_nop 0
	v_cndmask_b32_e32 v3, v3, v4, vcc
	v_rsq_f32_e32 v3, v3
	s_nop 0
	v_mul_f32_e32 v4, 0x45800000, v3
	v_cndmask_b32_e32 v12, v3, v4, vcc
	ds_read_b128 v[4:7], v76
	ds_read_b128 v[8:11], v76 offset:64
	s_waitcnt lgkmcnt(1)
	v_pk_mul_f32 v[4:5], v[4:5], v[12:13] op_sel_hi:[1,0]
	s_nop 0
	v_mul_f32_e32 v3, 0xbfb8aa3b, v4
	v_exp_f32_e32 v14, v3
	v_mul_f32_e32 v3, 0xbfb8aa3b, v5
	v_exp_f32_e32 v15, v3
	s_waitcnt lgkmcnt(0)
	v_pk_mul_f32 v[8:9], v[8:9], v[12:13] op_sel_hi:[1,0]
	v_pk_add_f32 v[14:15], v[14:15], 1.0 op_sel_hi:[1,0]
	s_nop 0
	v_rcp_f32_e32 v13, v15
	s_nop 0
	v_mul_f32_e32 v5, v5, v13
	v_div_scale_f32 v3, s[36:37], v14, v14, v4
	v_rcp_f32_e32 v13, v3
	s_nop 0
	v_fma_f32 v15, -v3, v13, 1.0
	v_fmac_f32_e32 v13, v15, v13
	v_div_scale_f32 v15, vcc, v4, v14, v4
	v_mul_f32_e32 v16, v15, v13
	v_fma_f32 v17, -v3, v16, v15
	v_fmac_f32_e32 v16, v17, v13
	v_fma_f32 v3, -v3, v16, v15
	v_div_fmas_f32 v3, v3, v13, v16
	v_pk_mul_f32 v[6:7], v[6:7], v[12:13] op_sel_hi:[1,0]
	v_div_fixup_f32 v4, v3, v14, v4
	v_mul_f32_e32 v3, 0xbfb8aa3b, v6
	v_pk_mul_f32 v[4:5], v[8:9], v[4:5]
	v_exp_f32_e32 v8, v3
	v_mul_f32_e32 v3, 0xbfb8aa3b, v7
	v_exp_f32_e32 v9, v3
	v_pk_mul_f32 v[10:11], v[10:11], v[12:13] op_sel_hi:[1,0]
	v_cvt_pk_bf16_f32 v4, v4, v5
	v_pk_add_f32 v[8:9], v[8:9], 1.0 op_sel_hi:[1,0]
	s_nop 0
	v_rcp_f32_e32 v12, v9
	s_nop 0
	v_mul_f32_e32 v7, v7, v12
	v_rcp_f32_e32 v9, v8
	s_nop 0
	v_mul_f32_e32 v6, v6, v9
	v_pk_mul_f32 v[6:7], v[10:11], v[6:7]
	v_mad_i64_i32 v[2:3], s[36:37], v2, s39, v[66:67]
	v_cvt_pk_bf16_f32 v5, v6, v7
	global_store_dwordx2 v[2:3], v[4:5], off
	v_add_u32_e32 v2, s8, v0
	v_ashrrev_i32_e32 v3, 31, v2
	v_lshl_add_u64 v[4:5], v[2:3], 4, s[46:47]
	v_add_f32_e32 v0, v152, v153
	v_add_f32_e32 v0, v0, v154
	v_add_f32_e32 v0, v0, v155
	v_fmamk_f32 v0, v0, 0x3a800000, v200
	v_cmp_gt_f32_e32 vcc, s33, v0
	v_mul_f32_e32 v3, 0x4b800000, v0
	ds_read_b128 v[4:7], v68
	ds_read_b128 v[8:11], v68 offset:64
	v_cndmask_b32_e32 v0, v0, v3, vcc
	v_rsq_f32_e32 v0, v0
	s_nop 0
	v_mul_f32_e32 v3, 0x45800000, v0
	v_cndmask_b32_e32 v0, v0, v3, vcc
	s_waitcnt lgkmcnt(1)
	v_pk_mul_f32 v[4:5], v[4:5], v[0:1] op_sel_hi:[1,0]
	v_pk_mul_f32 v[6:7], v[6:7], v[0:1] op_sel_hi:[1,0]
	v_mul_f32_e32 v3, 0xbfb8aa3b, v4
	v_exp_f32_e32 v12, v3
	v_mul_f32_e32 v3, 0xbfb8aa3b, v5
	v_exp_f32_e32 v13, v3
	s_waitcnt lgkmcnt(0)
	v_pk_mul_f32 v[8:9], v[8:9], v[0:1] op_sel_hi:[1,0]
	v_pk_mul_f32 v[10:11], v[10:11], v[0:1] op_sel_hi:[1,0]
	v_mul_f32_e32 v0, 0xbfb8aa3b, v7
	v_pk_add_f32 v[12:13], v[12:13], 1.0 op_sel_hi:[1,0]
	s_nop 0
	v_rcp_f32_e32 v14, v13
	s_nop 0
	v_mul_f32_e32 v5, v5, v14
	v_rcp_f32_e32 v13, v12
	s_nop 0
	v_mul_f32_e32 v4, v4, v13
	v_mul_f32_e32 v3, 0xbfb8aa3b, v6
	v_pk_mul_f32 v[4:5], v[8:9], v[4:5]
	v_exp_f32_e32 v8, v3
	v_exp_f32_e32 v9, v0
	v_cvt_pk_bf16_f32 v4, v4, v5
	v_pk_add_f32 v[8:9], v[8:9], 1.0 op_sel_hi:[1,0]
	s_nop 0
	v_rcp_f32_e32 v3, v9
	s_nop 0
	v_mul_f32_e32 v7, v7, v3
	v_rcp_f32_e32 v3, v8
	s_nop 0
	v_mul_f32_e32 v6, v6, v3
	v_pk_mul_f32 v[6:7], v[10:11], v[6:7]
	v_mad_i64_i32 v[2:3], s[36:37], v2, s39, v[66:67]
	v_cvt_pk_bf16_f32 v5, v6, v7
	global_store_dwordx2 v[2:3], v[4:5], off
	v_add_u32_e32 v2, s8, v69
	v_ashrrev_i32_e32 v3, 31, v2
	v_lshl_add_u64 v[4:5], v[2:3], 4, s[46:47]
	v_add_f32_e32 v0, v156, v157
	v_add_f32_e32 v0, v0, v158
	v_add_f32_e32 v0, v0, v159
	v_fmamk_f32 v0, v0, 0x3a800000, v200
	v_cmp_gt_f32_e32 vcc, s33, v0
	v_mul_f32_e32 v3, 0x4b800000, v0
	ds_read_b128 v[4:7], v70
	ds_read_b128 v[8:11], v70 offset:64
	v_cndmask_b32_e32 v0, v0, v3, vcc
	v_rsq_f32_e32 v0, v0
	s_nop 0
	v_mul_f32_e32 v3, 0x45800000, v0
	v_cndmask_b32_e32 v0, v0, v3, vcc
	s_waitcnt lgkmcnt(1)
	v_pk_mul_f32 v[4:5], v[4:5], v[0:1] op_sel_hi:[1,0]
	v_pk_mul_f32 v[6:7], v[6:7], v[0:1] op_sel_hi:[1,0]
	v_mul_f32_e32 v3, 0xbfb8aa3b, v4
	v_exp_f32_e32 v12, v3
	v_mul_f32_e32 v3, 0xbfb8aa3b, v5
	v_exp_f32_e32 v13, v3
	s_waitcnt lgkmcnt(0)
	v_pk_mul_f32 v[8:9], v[8:9], v[0:1] op_sel_hi:[1,0]
	v_pk_mul_f32 v[10:11], v[10:11], v[0:1] op_sel_hi:[1,0]
	v_mul_f32_e32 v0, 0xbfb8aa3b, v7
	v_pk_add_f32 v[12:13], v[12:13], 1.0 op_sel_hi:[1,0]
	s_nop 0
	v_rcp_f32_e32 v14, v13
	s_nop 0
	v_mul_f32_e32 v5, v5, v14
	v_rcp_f32_e32 v13, v12
	s_nop 0
	v_mul_f32_e32 v4, v4, v13
	v_mul_f32_e32 v3, 0xbfb8aa3b, v6
	v_pk_mul_f32 v[4:5], v[8:9], v[4:5]
	v_exp_f32_e32 v8, v3
	v_exp_f32_e32 v9, v0
	v_cvt_pk_bf16_f32 v4, v4, v5
	v_pk_add_f32 v[8:9], v[8:9], 1.0 op_sel_hi:[1,0]
	s_nop 0
	v_rcp_f32_e32 v3, v9
	s_nop 0
	v_mul_f32_e32 v7, v7, v3
	v_rcp_f32_e32 v3, v8
	s_nop 0
	v_mul_f32_e32 v6, v6, v3
	v_pk_mul_f32 v[6:7], v[10:11], v[6:7]
	v_mad_i64_i32 v[2:3], s[36:37], v2, s39, v[66:67]
	v_cvt_pk_bf16_f32 v5, v6, v7
	global_store_dwordx2 v[2:3], v[4:5], off
	v_add_u32_e32 v2, s8, v71
	v_ashrrev_i32_e32 v3, 31, v2
	v_lshl_add_u64 v[4:5], v[2:3], 4, s[46:47]
	v_add_f32_e32 v0, v160, v161
	v_add_f32_e32 v0, v0, v162
	v_add_f32_e32 v0, v0, v163
	v_fmamk_f32 v0, v0, 0x3a800000, v200
	v_cmp_gt_f32_e32 vcc, s33, v0
	v_mul_f32_e32 v3, 0x4b800000, v0
	ds_read_b128 v[4:7], v72
	ds_read_b128 v[8:11], v72 offset:64
	v_cndmask_b32_e32 v0, v0, v3, vcc
	v_rsq_f32_e32 v0, v0
	s_nop 0
	v_mul_f32_e32 v3, 0x45800000, v0
	v_cndmask_b32_e32 v0, v0, v3, vcc
	s_waitcnt lgkmcnt(1)
	v_pk_mul_f32 v[4:5], v[4:5], v[0:1] op_sel_hi:[1,0]
	v_pk_mul_f32 v[6:7], v[6:7], v[0:1] op_sel_hi:[1,0]
	v_mul_f32_e32 v3, 0xbfb8aa3b, v4
	v_exp_f32_e32 v12, v3
	v_mul_f32_e32 v3, 0xbfb8aa3b, v5
	v_exp_f32_e32 v13, v3
	s_waitcnt lgkmcnt(0)
	v_pk_mul_f32 v[8:9], v[8:9], v[0:1] op_sel_hi:[1,0]
	v_pk_mul_f32 v[10:11], v[10:11], v[0:1] op_sel_hi:[1,0]
	v_mul_f32_e32 v0, 0xbfb8aa3b, v7
	v_pk_add_f32 v[12:13], v[12:13], 1.0 op_sel_hi:[1,0]
	s_nop 0
	v_rcp_f32_e32 v14, v13
	s_nop 0
	v_mul_f32_e32 v5, v5, v14
	v_rcp_f32_e32 v13, v12
	s_nop 0
	v_mul_f32_e32 v4, v4, v13
	v_mul_f32_e32 v3, 0xbfb8aa3b, v6
	v_pk_mul_f32 v[4:5], v[8:9], v[4:5]
	v_exp_f32_e32 v8, v3
	v_exp_f32_e32 v9, v0
	v_cvt_pk_bf16_f32 v4, v4, v5
	v_pk_add_f32 v[8:9], v[8:9], 1.0 op_sel_hi:[1,0]
	s_nop 0
	v_rcp_f32_e32 v3, v9
	s_nop 0
	v_mul_f32_e32 v7, v7, v3
	v_rcp_f32_e32 v3, v8
	s_nop 0
	v_mul_f32_e32 v6, v6, v3
	v_pk_mul_f32 v[6:7], v[10:11], v[6:7]
	v_mad_i64_i32 v[2:3], s[36:37], v2, s39, v[66:67]
	v_cvt_pk_bf16_f32 v5, v6, v7
	global_store_dwordx2 v[2:3], v[4:5], off
	v_add_u32_e32 v2, s8, v73
	v_ashrrev_i32_e32 v3, 31, v2
	v_lshl_add_u64 v[4:5], v[2:3], 4, s[46:47]
	v_add_f32_e32 v0, v164, v165
	v_add_f32_e32 v0, v0, v166
	v_add_f32_e32 v0, v0, v167
	v_fmamk_f32 v0, v0, 0x3a800000, v200
	v_cmp_gt_f32_e32 vcc, s33, v0
	v_mul_f32_e32 v3, 0x4b800000, v0
	ds_read_b128 v[4:7], v74
	ds_read_b128 v[8:11], v74 offset:64
	v_cndmask_b32_e32 v0, v0, v3, vcc
	v_rsq_f32_e32 v0, v0
	s_nop 0
	v_mul_f32_e32 v3, 0x45800000, v0
	v_cndmask_b32_e32 v0, v0, v3, vcc
	s_waitcnt lgkmcnt(1)
	v_pk_mul_f32 v[4:5], v[4:5], v[0:1] op_sel_hi:[1,0]
	v_pk_mul_f32 v[6:7], v[6:7], v[0:1] op_sel_hi:[1,0]
	v_mul_f32_e32 v3, 0xbfb8aa3b, v4
	v_exp_f32_e32 v12, v3
	v_mul_f32_e32 v3, 0xbfb8aa3b, v5
	v_exp_f32_e32 v13, v3
	s_waitcnt lgkmcnt(0)
	v_pk_mul_f32 v[8:9], v[8:9], v[0:1] op_sel_hi:[1,0]
	v_pk_mul_f32 v[10:11], v[10:11], v[0:1] op_sel_hi:[1,0]
	v_mul_f32_e32 v0, 0xbfb8aa3b, v7
	v_pk_add_f32 v[12:13], v[12:13], 1.0 op_sel_hi:[1,0]
	s_nop 0
	v_rcp_f32_e32 v14, v13
	s_nop 0
	v_mul_f32_e32 v5, v5, v14
	v_rcp_f32_e32 v13, v12
	s_nop 0
	v_mul_f32_e32 v4, v4, v13
	v_mul_f32_e32 v3, 0xbfb8aa3b, v6
	v_pk_mul_f32 v[4:5], v[8:9], v[4:5]
	v_exp_f32_e32 v8, v3
	v_exp_f32_e32 v9, v0
	v_cvt_pk_bf16_f32 v4, v4, v5
	v_pk_add_f32 v[8:9], v[8:9], 1.0 op_sel_hi:[1,0]
	s_nop 0
	v_rcp_f32_e32 v3, v9
	s_nop 0
	v_mul_f32_e32 v7, v7, v3
	v_rcp_f32_e32 v3, v8
	s_nop 0
	v_mul_f32_e32 v6, v6, v3
	v_pk_mul_f32 v[6:7], v[10:11], v[6:7]
	v_mad_i64_i32 v[2:3], s[36:37], v2, s39, v[66:67]
	v_cvt_pk_bf16_f32 v5, v6, v7
	global_store_dwordx2 v[2:3], v[4:5], off
	s_barrier
	s_nop 0
	v_ashrrev_i32_e32 v0, 31, v142
	v_lshrrev_b32_e32 v0, 26, v0
	v_add_u32_e32 v0, v142, v0
	v_ashrrev_i32_e32 v16, 6, v0
	v_bfe_i32 v0, v142, 27, 1
	v_lshlrev_b32_e32 v2, 4, v142
	v_lshrrev_b32_e32 v0, 22, v0
	v_add_u32_e32 v0, v2, v0
	v_and_b32_e32 v0, 0xfffffc00, v0
	v_sub_u32_e32 v0, v2, v0
	v_lshrrev_b32_e32 v3, 4, v0
	v_bitop3_b32 v3, v3, v0, 32 bitop3:0x6c
	v_ashrrev_i32_e32 v0, 31, v0
	v_lshrrev_b32_e32 v0, 26, v0
	v_add_u32_e32 v0, v3, v0
	v_ashrrev_i32_e32 v18, 6, v0
	v_mul_i32_i24_e32 v5, 64, v18
	v_sub_u32_e32 v3, v3, v5
	v_lshlrev_b32_e32 v4, 3, v16
	v_lshlrev_b32_e32 v0, 5, v16
	v_ashrrev_i16_sdwa v3, v217, sext(v3) dst_sel:DWORD dst_unused:UNUSED_PAD src0_sel:DWORD src1_sel:BYTE_0
	v_and_b32_e32 v4, 0x1ffff0, v4
	v_and_b32_e32 v0, 32, v0
	v_bfe_i32 v19, v3, 0, 16
	v_add_u32_e32 v0, v0, v19
	v_add_lshl_u32 v3, v18, v4, 11
	v_add_u32_e32 v2, 0x2000, v2
	v_lshl_add_u32 v0, v0, 1, v3
	v_ashrrev_i32_e32 v3, 31, v2
	v_lshrrev_b32_e32 v3, 22, v3
	v_add_u32_e32 v3, v2, v3
	v_ashrrev_i32_e32 v21, 10, v3
	v_mul_i32_i24_e32 v3, 0x400, v21
	v_sub_u32_e32 v2, v2, v3
	v_lshrrev_b32_e32 v3, 4, v2
	v_bitop3_b32 v2, v3, v2, 32 bitop3:0x6c
	v_ashrrev_i32_e32 v4, 31, v2
	v_ashrrev_i32_e32 v20, 6, v142
	v_lshrrev_b32_e32 v4, 26, v4
	v_readfirstlane_b32 s33, v20
	v_add_u32_e32 v4, v2, v4
	s_lshl_b32 s73, s33, 10
	v_ashrrev_i32_e32 v22, 6, v4
	v_and_b32_e32 v4, 0xc0, v4
	v_sub_u32_e32 v2, v2, v4
	s_add_u32 s70, s16, s70
	v_lshlrev_b32_e32 v3, 3, v21
	v_lshlrev_b32_e32 v5, 5, v21
	v_ashrrev_i16_sdwa v2, v217, sext(v2) dst_sel:DWORD dst_unused:UNUSED_PAD src0_sel:DWORD src1_sel:BYTE_0
	s_addc_u32 s71, s17, s71
	s_add_i32 s36, s73, 0
	v_and_b32_e32 v3, 0x1ffff0, v3
	v_and_b32_e32 v5, 32, v5
	v_bfe_i32 v23, v2, 0, 16
	s_add_i32 s37, s36, 0x10000
	v_add_u32_e32 v2, v5, v23
	v_add_lshl_u32 v3, v22, v3, 11
	s_mov_b32 m0, s37
	s_add_i32 s43, s36, 0x12000
	s_or_b32 s38, s38, 0x180
	v_lshl_add_u32 v2, v2, 1, v3
	global_load_lds_dwordx4 v0, s[70:71]
	v_mov_b32_e32 v3, v1
	s_mov_b32 m0, s43
	s_ashr_i32 s39, s38, 31
	v_lshl_add_u64 v[4:5], s[70:71], 0, v[0:1]
	v_lshl_add_u64 v[8:9], s[70:71], 0, v[2:3]
	global_load_lds_dwordx4 v2, s[70:71]
	s_mov_b32 m0, s36
	s_add_i32 s70, s36, 0x2000
	s_lshl_b64 s[38:39], s[38:39], 11
	global_load_lds_dwordx4 v0, s[54:55]
	s_mov_b32 m0, s70
	s_add_u32 s38, s16, s38
	v_lshl_add_u64 v[10:11], s[54:55], 0, v[0:1]
	v_lshl_add_u64 v[6:7], s[54:55], 0, v[2:3]
	global_load_lds_dwordx4 v2, s[54:55]
	s_addc_u32 s39, s17, s39
	s_add_i32 s54, s36, 0x14000
	s_mov_b32 m0, s54
	s_add_i32 s55, s36, 0x16000
	global_load_lds_dwordx4 v0, s[38:39]
	s_mov_b32 m0, s55
	s_add_i32 s71, s36, 0x4000
	global_load_lds_dwordx4 v2, s[38:39]
	s_mov_b32 m0, s71
	s_add_i32 s72, s36, 0x6000
	global_load_lds_dwordx4 v0, s[60:61]
	s_mov_b32 m0, s72
	v_ashrrev_i32_e32 v17, 8, v142
	global_load_lds_dwordx4 v2, s[60:61]
	v_lshl_add_u64 v[12:13], s[38:39], 0, v[0:1]
	v_lshl_add_u64 v[14:15], s[38:39], 0, v[2:3]
	v_cmp_eq_u32_e32 vcc, 1, v17
	s_and_saveexec_b64 s[38:39], vcc
	v_readlane_b32 s62, v253, 50
	s_cbranch_execz .LBB0_244
	s_barrier

.LBB0_248:
	s_or_b64 exec, exec, s[12:13]
	s_movk_i32 s11, 0x410
	v_lshrrev_b32_e32 v130, 2, v142
	v_lshlrev_b32_e32 v131, 1, v142
	v_and_b32_e32 v0, 15, v142
	v_and_b32_e32 v130, 0xfffffcc, v130
	v_and_b32_e32 v131, 0x180, v131
	v_add_u32_e32 v131, 0, v131
	v_lshlrev_b32_e32 v0, 2, v0
	v_mul_lo_u32 v130, v130, s11
	v_add3_u32 v130, v131, v0, v130
	s_waitcnt vmcnt(0)
	s_barrier
	ds_write2_b32 v130, v114, v126 offset1:16
	v_add_u32_e32 v114, 0x400, v130
	ds_write2_b32 v114, v115, v127 offset0:4 offset1:20
	v_add_u32_e32 v115, 0x800, v130
	ds_write2_b32 v115, v116, v128 offset0:8 offset1:24
	v_add_u32_e32 v116, 0xc00, v130
	ds_write2_b32 v116, v117, v129 offset0:12 offset1:28
	v_add_u32_e32 v117, 0x4000, v130
	ds_write2_b32 v117, v82, v94 offset0:64 offset1:80
	v_add_u32_e32 v94, 0x4400, v130
	ds_write2_b32 v94, v83, v95 offset0:68 offset1:84
	v_add_u32_e32 v95, 0x4800, v130
	ds_write2_b32 v95, v84, v96 offset0:72 offset1:88
	v_add_u32_e32 v96, 0x4c00, v130
	ds_write2_b32 v96, v85, v97 offset0:76 offset1:92
	v_add_u32_e32 v132, 0x8000, v130
	v_add_u32_e32 v97, 0x8400, v130
	v_add_u32_e32 v126, 0x8800, v130
	v_add_u32_e32 v127, 0x8c00, v130
	v_add_u32_e32 v133, 0xc000, v130
	v_add_u32_e32 v128, 0xc400, v130
	v_add_u32_e32 v129, 0xc800, v130
	v_add_u32_e32 v131, 0xcc00, v130
	ds_write2_b32 v132, v74, v78 offset0:128 offset1:144
	ds_write2_b32 v97, v75, v79 offset0:132 offset1:148
	ds_write2_b32 v126, v76, v80 offset0:136 offset1:152
	ds_write2_b32 v127, v77, v81 offset0:140 offset1:156
	ds_write2_b32 v133, v66, v70 offset0:192 offset1:208
	ds_write2_b32 v128, v67, v71 offset0:196 offset1:212
	ds_write2_b32 v129, v68, v72 offset0:200 offset1:216
	ds_write2_b32 v131, v69, v73 offset0:204 offset1:220
	ds_write2_b32 v130, v98, v118 offset0:128 offset1:144
	ds_write2_b32 v114, v99, v119 offset0:132 offset1:148
	ds_write2_b32 v115, v100, v120 offset0:136 offset1:152
	ds_write2_b32 v116, v101, v121 offset0:140 offset1:156
	ds_write2_b32 v117, v102, v122 offset0:192 offset1:208
	ds_write2_b32 v94, v103, v123 offset0:196 offset1:212
	ds_write2_b32 v95, v104, v124 offset0:200 offset1:216
	ds_write2_b32 v96, v105, v125 offset0:204 offset1:220
	ds_write2_b32 v97, v90, v110 offset1:16
	ds_write2_b32 v126, v91, v111 offset0:4 offset1:20
	ds_write2_b32 v127, v92, v112 offset0:8 offset1:24
	v_add_u32_e32 v90, 0x9000, v130
	ds_write2_b32 v90, v93, v113 offset0:12 offset1:28
	ds_write2_b32 v128, v86, v106 offset0:64 offset1:80
	ds_write2_b32 v129, v87, v107 offset0:68 offset1:84
	ds_write2_b32 v131, v88, v108 offset0:72 offset1:88
	v_ashrrev_i32_e32 v88, 5, v142
	v_add_u32_e32 v70, s10, v88
	v_ashrrev_i32_e32 v71, 31, v70
	v_add_u32_e32 v91, 0xd000, v130
	v_lshl_add_u64 v[72:73], v[70:71], 4, s[46:47]
	ds_write2_b32 v91, v89, v109 offset0:76 offset1:92
	s_waitcnt lgkmcnt(0)
	s_barrier
	global_load_dwordx4 v[134:137], v[72:73], off
	global_load_dwordx4 v[138:141], v[72:73], off offset:256
	global_load_dwordx4 v[144:147], v[72:73], off offset:512
	global_load_dwordx4 v[148:151], v[72:73], off offset:768
	global_load_dwordx4 v[152:155], v[72:73], off offset:1024
	global_load_dwordx4 v[156:159], v[72:73], off offset:1280
	global_load_dwordx4 v[160:163], v[72:73], off offset:1536
	global_load_dwordx4 v[164:167], v[72:73], off offset:1792
	v_lshlrev_b32_e32 v0, 3, v142
	v_lshlrev_b32_e32 v66, 2, v142
	v_and_b32_e32 v0, 0xe0, v0
	v_and_b32_e32 v69, 12, v66
	v_lshlrev_b32_e32 v66, 2, v0
	v_lshlrev_b32_e32 v67, 2, v69
	v_or_b32_e32 v0, s42, v0
	v_add3_u32 v68, 0, v66, v67
	v_ashrrev_i32_e32 v66, 1, v0
	v_readlane_b32 s12, v253, 58
	v_ashrrev_i32_e32 v67, 31, v66
	v_readlane_b32 s13, v253, 59
	v_lshlrev_b32_e32 v0, 1, v69
	s_mov_b32 s9, 0x800000
	v_lshl_add_u64 v[66:67], v[66:67], 1, s[12:13]
	v_lshl_add_u64 v[66:67], v[66:67], 0, v[0:1]
	v_mad_u64_u32 v[82:83], s[12:13], v88, s11, v[68:69]
	s_movk_i32 s14, 0x1600
	s_waitcnt vmcnt(0)
	v_add_f32_e32 v0, v134, v135
	v_add_f32_e32 v0, v0, v136
	v_add_f32_e32 v0, v0, v137
	v_fmamk_f32 v0, v0, 0x3a800000, v200
	v_cmp_gt_f32_e32 vcc, s9, v0
	v_mul_f32_e32 v69, 0x4b800000, v0
	ds_read_b128 v[72:75], v82
	ds_read_b128 v[76:79], v82 offset:64
	v_cndmask_b32_e32 v0, v0, v69, vcc
	v_rsq_f32_e32 v0, v0
	s_nop 0
	v_mul_f32_e32 v69, 0x45800000, v0
	v_cndmask_b32_e32 v0, v0, v69, vcc
	s_waitcnt lgkmcnt(1)
	v_pk_mul_f32 v[72:73], v[72:73], v[0:1] op_sel_hi:[1,0]
	v_pk_mul_f32 v[74:75], v[74:75], v[0:1] op_sel_hi:[1,0]
	v_mul_f32_e32 v69, 0xbfb8aa3b, v72
	v_exp_f32_e32 v80, v69
	v_mul_f32_e32 v69, 0xbfb8aa3b, v73
	v_exp_f32_e32 v81, v69
	s_waitcnt lgkmcnt(0)
	v_pk_mul_f32 v[76:77], v[76:77], v[0:1] op_sel_hi:[1,0]
	v_pk_mul_f32 v[78:79], v[78:79], v[0:1] op_sel_hi:[1,0]
	v_mul_f32_e32 v0, 0xbfb8aa3b, v75
	v_pk_add_f32 v[80:81], v[80:81], 1.0 op_sel_hi:[1,0]
	s_nop 0
	v_rcp_f32_e32 v71, v81
	s_nop 0
	v_mul_f32_e32 v73, v73, v71
	v_rcp_f32_e32 v71, v80
	s_nop 0
	v_mul_f32_e32 v72, v72, v71
	v_mul_f32_e32 v69, 0xbfb8aa3b, v74
	v_pk_mul_f32 v[72:73], v[76:77], v[72:73]
	v_exp_f32_e32 v76, v69
	v_exp_f32_e32 v77, v0
	v_cvt_pk_bf16_f32 v72, v72, v73
	v_pk_add_f32 v[76:77], v[76:77], 1.0 op_sel_hi:[1,0]
	s_nop 0
	v_rcp_f32_e32 v69, v77
	s_nop 0
	v_mul_f32_e32 v75, v75, v69
	v_rcp_f32_e32 v69, v76
	s_nop 0
	v_mul_f32_e32 v74, v74, v69
	v_pk_mul_f32 v[74:75], v[78:79], v[74:75]
	v_add_u32_e32 v0, 0x200, v142
	v_cvt_pk_bf16_f32 v73, v74, v75
	v_mad_i64_i32 v[70:71], s[12:13], v70, s14, v[66:67]
	v_ashrrev_i32_e32 v83, 5, v0
	global_store_dwordx2 v[70:71], v[72:73], off
	v_add_u32_e32 v70, s10, v83
	v_ashrrev_i32_e32 v71, 31, v70
	v_lshl_add_u64 v[72:73], v[70:71], 4, s[46:47]
	v_mad_u64_u32 v[80:81], s[12:13], v83, s11, v[68:69]
	v_add_f32_e32 v0, v138, v139
	v_add_f32_e32 v0, v0, v140
	v_add_f32_e32 v0, v0, v141
	v_fmamk_f32 v0, v0, 0x3a800000, v200
	v_cmp_gt_f32_e32 vcc, s9, v0
	v_mul_f32_e32 v69, 0x4b800000, v0
	ds_read_b128 v[72:75], v80
	ds_read_b128 v[76:79], v80 offset:64
	v_cndmask_b32_e32 v0, v0, v69, vcc
	v_rsq_f32_e32 v0, v0
	s_nop 0
	v_mul_f32_e32 v69, 0x45800000, v0
	v_cndmask_b32_e32 v0, v0, v69, vcc
	s_waitcnt lgkmcnt(1)
	v_pk_mul_f32 v[72:73], v[72:73], v[0:1] op_sel_hi:[1,0]
	v_pk_mul_f32 v[74:75], v[74:75], v[0:1] op_sel_hi:[1,0]
	v_mul_f32_e32 v69, 0xbfb8aa3b, v72
	v_exp_f32_e32 v84, v69
	v_mul_f32_e32 v69, 0xbfb8aa3b, v73
	v_exp_f32_e32 v85, v69
	s_waitcnt lgkmcnt(0)
	v_pk_mul_f32 v[76:77], v[76:77], v[0:1] op_sel_hi:[1,0]
	v_pk_mul_f32 v[78:79], v[78:79], v[0:1] op_sel_hi:[1,0]
	v_mul_f32_e32 v0, 0xbfb8aa3b, v75
	v_pk_add_f32 v[84:85], v[84:85], 1.0 op_sel_hi:[1,0]
	s_nop 0
	v_rcp_f32_e32 v71, v85
	s_nop 0
	v_mul_f32_e32 v73, v73, v71
	v_rcp_f32_e32 v71, v84
	s_nop 0
	v_mul_f32_e32 v72, v72, v71
	v_mul_f32_e32 v69, 0xbfb8aa3b, v74
	v_pk_mul_f32 v[72:73], v[76:77], v[72:73]
	v_exp_f32_e32 v76, v69
	v_exp_f32_e32 v77, v0
	v_cvt_pk_bf16_f32 v72, v72, v73
	v_pk_add_f32 v[76:77], v[76:77], 1.0 op_sel_hi:[1,0]
	s_nop 0
	v_rcp_f32_e32 v69, v77
	s_nop 0
	v_mul_f32_e32 v75, v75, v69
	v_rcp_f32_e32 v69, v76
	s_nop 0
	v_mul_f32_e32 v74, v74, v69
	v_pk_mul_f32 v[74:75], v[78:79], v[74:75]
	v_add_u32_e32 v0, 0x400, v142
	v_cvt_pk_bf16_f32 v73, v74, v75
	v_mad_i64_i32 v[70:71], s[12:13], v70, s14, v[66:67]
	v_ashrrev_i32_e32 v81, 5, v0
	global_store_dwordx2 v[70:71], v[72:73], off
	v_add_u32_e32 v70, s10, v81
	v_ashrrev_i32_e32 v71, 31, v70
	v_lshl_add_u64 v[72:73], v[70:71], 4, s[46:47]
	v_mad_u64_u32 v[78:79], s[12:13], v81, s11, v[68:69]
	v_add_f32_e32 v0, v144, v145
	v_add_f32_e32 v0, v0, v146
	v_add_f32_e32 v0, v0, v147
	v_fmamk_f32 v0, v0, 0x3a800000, v200
	v_cmp_gt_f32_e32 vcc, s9, v0
	v_mul_f32_e32 v69, 0x4b800000, v0
	ds_read_b128 v[72:75], v78
	ds_read_b128 v[84:87], v78 offset:64
	v_cndmask_b32_e32 v0, v0, v69, vcc
	v_rsq_f32_e32 v0, v0
	s_nop 0
	v_mul_f32_e32 v69, 0x45800000, v0
	v_cndmask_b32_e32 v0, v0, v69, vcc
	s_waitcnt lgkmcnt(1)
	v_pk_mul_f32 v[72:73], v[72:73], v[0:1] op_sel_hi:[1,0]
	v_pk_mul_f32 v[74:75], v[74:75], v[0:1] op_sel_hi:[1,0]
	v_mul_f32_e32 v69, 0xbfb8aa3b, v72
	v_exp_f32_e32 v76, v69
	v_mul_f32_e32 v69, 0xbfb8aa3b, v73
	v_exp_f32_e32 v77, v69
	s_waitcnt lgkmcnt(0)
	v_pk_mul_f32 v[84:85], v[84:85], v[0:1] op_sel_hi:[1,0]
	v_pk_add_f32 v[76:77], v[76:77], 1.0 op_sel_hi:[1,0]
	s_nop 0
	v_rcp_f32_e32 v71, v77
	s_nop 0
	v_mul_f32_e32 v73, v73, v71
	v_rcp_f32_e32 v71, v76
	s_nop 0
	v_mul_f32_e32 v72, v72, v71
	v_mul_f32_e32 v69, 0xbfb8aa3b, v74
	v_pk_mul_f32 v[76:77], v[86:87], v[0:1] op_sel_hi:[1,0]
	v_mul_f32_e32 v0, 0xbfb8aa3b, v75
	v_pk_mul_f32 v[72:73], v[84:85], v[72:73]
	v_exp_f32_e32 v84, v69
	v_exp_f32_e32 v85, v0
	v_cvt_pk_bf16_f32 v72, v72, v73
	v_pk_add_f32 v[84:85], v[84:85], 1.0 op_sel_hi:[1,0]
	s_nop 0
	v_rcp_f32_e32 v69, v85
	s_nop 0
	v_mul_f32_e32 v75, v75, v69
	v_rcp_f32_e32 v69, v84
	s_nop 0
	v_mul_f32_e32 v74, v74, v69
	v_add_u32_e32 v0, 0x600, v142
	v_pk_mul_f32 v[74:75], v[76:77], v[74:75]
	v_ashrrev_i32_e32 v79, 5, v0
	v_cvt_pk_bf16_f32 v73, v74, v75
	v_add_u32_e32 v74, s10, v79
	v_mad_i64_i32 v[70:71], s[12:13], v70, s14, v[66:67]
	v_ashrrev_i32_e32 v75, 31, v74
	global_store_dwordx2 v[70:71], v[72:73], off
	v_lshl_add_u64 v[70:71], v[74:75], 4, s[46:47]
	v_mad_u64_u32 v[76:77], s[12:13], v79, s11, v[68:69]
	v_add_f32_e32 v0, v148, v149
	v_add_f32_e32 v0, v0, v150
	v_add_f32_e32 v0, v0, v151
	v_fmamk_f32 v0, v0, 0x3a800000, v200
	v_cmp_gt_f32_e32 vcc, s9, v0
	v_mul_f32_e32 v69, 0x4b800000, v0
	ds_read_b128 v[70:73], v76
	ds_read_b128 v[84:87], v76 offset:64
	v_cndmask_b32_e32 v0, v0, v69, vcc
	v_rsq_f32_e32 v0, v0
	s_nop 0
	v_mul_f32_e32 v69, 0x45800000, v0
	v_cndmask_b32_e32 v0, v0, v69, vcc
	s_waitcnt lgkmcnt(1)
	v_pk_mul_f32 v[70:71], v[70:71], v[0:1] op_sel_hi:[1,0]
	v_pk_mul_f32 v[72:73], v[72:73], v[0:1] op_sel_hi:[1,0]
	v_mul_f32_e32 v69, 0xbfb8aa3b, v70
	v_exp_f32_e32 v92, v69
	v_mul_f32_e32 v69, 0xbfb8aa3b, v71
	v_exp_f32_e32 v93, v69
	s_waitcnt lgkmcnt(0)
	v_pk_mul_f32 v[84:85], v[84:85], v[0:1] op_sel_hi:[1,0]
	v_pk_mul_f32 v[86:87], v[86:87], v[0:1] op_sel_hi:[1,0]
	v_mul_f32_e32 v0, 0xbfb8aa3b, v73
	v_pk_add_f32 v[92:93], v[92:93], 1.0 op_sel_hi:[1,0]
	s_nop 0
	v_rcp_f32_e32 v75, v93
	s_nop 0
	v_mul_f32_e32 v71, v71, v75
	v_rcp_f32_e32 v75, v92
	s_nop 0
	v_mul_f32_e32 v70, v70, v75
	v_mul_f32_e32 v69, 0xbfb8aa3b, v72
	v_pk_mul_f32 v[70:71], v[84:85], v[70:71]
	v_exp_f32_e32 v84, v69
	v_exp_f32_e32 v85, v0
	v_cvt_pk_bf16_f32 v70, v70, v71
	v_pk_add_f32 v[84:85], v[84:85], 1.0 op_sel_hi:[1,0]
	s_nop 0
	v_rcp_f32_e32 v69, v85
	s_nop 0
	v_mul_f32_e32 v73, v73, v69
	v_rcp_f32_e32 v69, v84
	s_nop 0
	v_mul_f32_e32 v72, v72, v69
	v_pk_mul_f32 v[72:73], v[86:87], v[72:73]
	v_add_u32_e32 v0, 0x800, v142
	v_cvt_pk_bf16_f32 v71, v72, v73
	v_mad_i64_i32 v[72:73], s[12:13], v74, s14, v[66:67]
	v_ashrrev_i32_e32 v0, 5, v0
	global_store_dwordx2 v[72:73], v[70:71], off
	v_add_u32_e32 v72, s10, v0
	v_ashrrev_i32_e32 v73, 31, v72
	v_lshl_add_u64 v[74:75], v[72:73], 4, s[46:47]
	v_mad_u64_u32 v[70:71], s[12:13], v0, s11, v[68:69]
	v_add_f32_e32 v69, v152, v153
	v_add_f32_e32 v69, v69, v154
	v_add_f32_e32 v69, v69, v155
	v_fmamk_f32 v69, v69, 0x3a800000, v200
	v_cmp_gt_f32_e32 vcc, s9, v69
	v_mul_f32_e32 v71, 0x4b800000, v69
	ds_read_b128 v[84:87], v70
	ds_read_b128 v[98:101], v70 offset:64
	v_cndmask_b32_e32 v69, v69, v71, vcc
	v_rsq_f32_e32 v69, v69
	s_nop 0
	v_mul_f32_e32 v71, 0x45800000, v69
	v_cndmask_b32_e32 v74, v69, v71, vcc
	s_waitcnt lgkmcnt(1)
	v_pk_mul_f32 v[84:85], v[84:85], v[74:75] op_sel_hi:[1,0]
	s_waitcnt lgkmcnt(0)
	v_pk_mul_f32 v[98:99], v[98:99], v[74:75] op_sel_hi:[1,0]
	v_mul_f32_e32 v69, 0xbfb8aa3b, v84
	v_exp_f32_e32 v92, v69
	v_mul_f32_e32 v69, 0xbfb8aa3b, v85
	v_exp_f32_e32 v93, v69
	s_nop 0
	v_pk_add_f32 v[92:93], v[92:93], 1.0 op_sel_hi:[1,0]
	s_nop 0
	v_rcp_f32_e32 v71, v93
	s_nop 0
	v_mul_f32_e32 v85, v85, v71
	v_div_scale_f32 v69, s[12:13], v92, v92, v84
	v_rcp_f32_e32 v71, v69
	s_nop 0
	v_fma_f32 v73, -v69, v71, 1.0
	v_fmac_f32_e32 v71, v73, v71
	v_div_scale_f32 v73, vcc, v84, v92, v84
	v_mul_f32_e32 v75, v73, v71
	v_fma_f32 v77, -v69, v75, v73
	v_fmac_f32_e32 v75, v77, v71
	v_fma_f32 v69, -v69, v75, v73
	v_div_fmas_f32 v69, v69, v71, v75
	v_pk_mul_f32 v[86:87], v[86:87], v[74:75] op_sel_hi:[1,0]
	v_div_fixup_f32 v84, v69, v92, v84
	v_mul_f32_e32 v69, 0xbfb8aa3b, v86
	v_exp_f32_e32 v92, v69
	v_mul_f32_e32 v69, 0xbfb8aa3b, v87
	v_exp_f32_e32 v93, v69
	v_pk_mul_f32 v[74:75], v[100:101], v[74:75] op_sel_hi:[1,0]
	v_pk_mul_f32 v[84:85], v[98:99], v[84:85]
	v_pk_add_f32 v[92:93], v[92:93], 1.0 op_sel_hi:[1,0]
	s_nop 0
	v_div_scale_f32 v69, s[12:13], v93, v93, v87
	v_rcp_f32_e32 v71, v69
	v_cvt_pk_bf16_f32 v84, v84, v85
	v_fma_f32 v73, -v69, v71, 1.0
	v_fmac_f32_e32 v71, v73, v71
	v_div_scale_f32 v73, vcc, v87, v93, v87
	v_mul_f32_e32 v77, v73, v71
	v_fma_f32 v89, -v69, v77, v73
	v_fmac_f32_e32 v77, v89, v71
	v_fma_f32 v69, -v69, v77, v73
	v_div_fmas_f32 v69, v69, v71, v77
	v_div_fixup_f32 v87, v69, v93, v87
	v_rcp_f32_e32 v71, v92
	s_nop 0
	v_mul_f32_e32 v86, v86, v71
	v_add_u32_e32 v69, 0xa00, v142
	v_pk_mul_f32 v[74:75], v[74:75], v[86:87]
	v_ashrrev_i32_e32 v71, 5, v69
	v_cvt_pk_bf16_f32 v85, v74, v75
	v_add_u32_e32 v74, s10, v71
	v_mad_i64_i32 v[72:73], s[12:13], v72, s14, v[66:67]
	v_ashrrev_i32_e32 v75, 31, v74
	global_store_dwordx2 v[72:73], v[84:85], off
	v_lshl_add_u64 v[84:85], v[74:75], 4, s[46:47]
	v_mad_u64_u32 v[72:73], s[12:13], v71, s11, v[68:69]
	v_add_f32_e32 v69, v156, v157
	v_add_f32_e32 v69, v69, v158
	v_add_f32_e32 v69, v69, v159
	v_fmamk_f32 v69, v69, 0x3a800000, v200
	v_cmp_gt_f32_e32 vcc, s9, v69
	v_mul_f32_e32 v73, 0x4b800000, v69
	ds_read_b128 v[84:87], v72
	ds_read_b128 v[98:101], v72 offset:64
	v_cndmask_b32_e32 v69, v69, v73, vcc
	v_rsq_f32_e32 v69, v69
	s_nop 0
	v_mul_f32_e32 v73, 0x45800000, v69
	v_cndmask_b32_e32 v92, v69, v73, vcc
	s_waitcnt lgkmcnt(1)
	v_pk_mul_f32 v[84:85], v[84:85], v[92:93] op_sel_hi:[1,0]
	v_pk_mul_f32 v[86:87], v[86:87], v[92:93] op_sel_hi:[1,0]
	v_mul_f32_e32 v69, 0xbfb8aa3b, v84
	v_exp_f32_e32 v102, v69
	v_mul_f32_e32 v69, 0xbfb8aa3b, v85
	v_exp_f32_e32 v103, v69
	s_waitcnt lgkmcnt(0)
	v_pk_mul_f32 v[98:99], v[98:99], v[92:93] op_sel_hi:[1,0]
	v_pk_mul_f32 v[92:93], v[100:101], v[92:93] op_sel_hi:[1,0]
	v_pk_add_f32 v[102:103], v[102:103], 1.0 op_sel_hi:[1,0]
	s_nop 0
	v_rcp_f32_e32 v73, v103
	s_nop 0
	v_mul_f32_e32 v85, v85, v73
	v_rcp_f32_e32 v73, v102
	s_nop 0
	v_mul_f32_e32 v84, v84, v73
	v_mul_f32_e32 v69, 0xbfb8aa3b, v86
	v_pk_mul_f32 v[84:85], v[98:99], v[84:85]
	v_exp_f32_e32 v98, v69
	v_mul_f32_e32 v69, 0xbfb8aa3b, v87
	v_exp_f32_e32 v99, v69
	v_cvt_pk_bf16_f32 v84, v84, v85
	v_pk_add_f32 v[98:99], v[98:99], 1.0 op_sel_hi:[1,0]
	s_nop 0
	v_rcp_f32_e32 v73, v99
	s_nop 0
	v_mul_f32_e32 v87, v87, v73
	v_rcp_f32_e32 v73, v98
	s_nop 0
	v_mul_f32_e32 v86, v86, v73
	v_pk_mul_f32 v[86:87], v[92:93], v[86:87]
	v_add_u32_e32 v69, 0xc00, v142
	v_cvt_pk_bf16_f32 v85, v86, v87
	v_mad_i64_i32 v[74:75], s[12:13], v74, s14, v[66:67]
	v_ashrrev_i32_e32 v73, 5, v69
	global_store_dwordx2 v[74:75], v[84:85], off
	v_add_u32_e32 v84, s10, v73
	v_ashrrev_i32_e32 v85, 31, v84
	v_lshl_add_u64 v[86:87], v[84:85], 4, s[46:47]
	v_mad_u64_u32 v[74:75], s[12:13], v73, s11, v[68:69]
	v_add_f32_e32 v69, v160, v161
	v_add_f32_e32 v69, v69, v162
	v_add_f32_e32 v69, v69, v163
	v_fmamk_f32 v69, v69, 0x3a800000, v200
	v_cmp_gt_f32_e32 vcc, s9, v69
	v_mul_f32_e32 v75, 0x4b800000, v69
	ds_read_b128 v[98:101], v74
	ds_read_b128 v[102:105], v74 offset:64
	v_cndmask_b32_e32 v69, v69, v75, vcc
	v_rsq_f32_e32 v69, v69
	s_nop 0
	v_mul_f32_e32 v75, 0x45800000, v69
	v_cndmask_b32_e32 v86, v69, v75, vcc
	s_waitcnt lgkmcnt(1)
	v_pk_mul_f32 v[92:93], v[98:99], v[86:87] op_sel_hi:[1,0]
	s_waitcnt lgkmcnt(0)
	v_pk_mul_f32 v[102:103], v[102:103], v[86:87] op_sel_hi:[1,0]
	v_mul_f32_e32 v69, 0xbfb8aa3b, v92
	v_exp_f32_e32 v98, v69
	v_mul_f32_e32 v69, 0xbfb8aa3b, v93
	v_exp_f32_e32 v99, v69
	s_nop 0
	v_pk_add_f32 v[98:99], v[98:99], 1.0 op_sel_hi:[1,0]
	s_nop 0
	v_rcp_f32_e32 v75, v99
	s_nop 0
	v_mul_f32_e32 v93, v93, v75
	v_rcp_f32_e32 v75, v98
	s_nop 0
	v_mul_f32_e32 v92, v92, v75
	v_pk_mul_f32 v[98:99], v[100:101], v[86:87] op_sel_hi:[1,0]
	v_pk_mul_f32 v[86:87], v[104:105], v[86:87] op_sel_hi:[1,0]
	v_mul_f32_e32 v69, 0xbfb8aa3b, v98
	v_exp_f32_e32 v100, v69
	v_mul_f32_e32 v69, 0xbfb8aa3b, v99
	v_exp_f32_e32 v101, v69
	v_pk_mul_f32 v[92:93], v[102:103], v[92:93]
	v_pk_add_f32 v[100:101], v[100:101], 1.0 op_sel_hi:[1,0]
	s_nop 0
	v_div_scale_f32 v69, s[12:13], v101, v101, v99
	v_rcp_f32_e32 v75, v69
	v_cvt_pk_bf16_f32 v92, v92, v93
	v_fma_f32 v77, -v69, v75, 1.0
	v_fmac_f32_e32 v75, v77, v75
	v_div_scale_f32 v77, vcc, v99, v101, v99
	v_mul_f32_e32 v85, v77, v75
	v_fma_f32 v89, -v69, v85, v77
	v_fmac_f32_e32 v85, v89, v75
	v_fma_f32 v69, -v69, v85, v77
	v_div_fmas_f32 v69, v69, v75, v85
	v_div_fixup_f32 v99, v69, v101, v99
	v_rcp_f32_e32 v75, v100
	s_nop 0
	v_mul_f32_e32 v98, v98, v75
	v_pk_mul_f32 v[86:87], v[86:87], v[98:99]
	v_add_u32_e32 v69, 0xe00, v142
	v_cvt_pk_bf16_f32 v93, v86, v87
	v_mad_i64_i32 v[84:85], s[12:13], v84, s14, v[66:67]
	v_ashrrev_i32_e32 v75, 5, v69
	global_store_dwordx2 v[84:85], v[92:93], off
	v_add_u32_e32 v84, s10, v75
	v_ashrrev_i32_e32 v85, 31, v84
	v_lshl_add_u64 v[86:87], v[84:85], 4, s[46:47]
	v_mad_u64_u32 v[68:69], s[12:13], v75, s11, v[68:69]
	v_add_f32_e32 v69, v164, v165
	v_add_f32_e32 v69, v69, v166
	v_add_f32_e32 v69, v69, v167
	v_fmamk_f32 v69, v69, 0x3a800000, v200
	v_cmp_gt_f32_e32 vcc, s9, v69
	v_mul_f32_e32 v77, 0x4b800000, v69
	ds_read_b128 v[98:101], v68
	ds_read_b128 v[102:105], v68 offset:64
	v_cndmask_b32_e32 v69, v69, v77, vcc
	v_rsq_f32_e32 v69, v69
	s_nop 0
	v_mul_f32_e32 v77, 0x45800000, v69
	v_cndmask_b32_e32 v86, v69, v77, vcc
	s_waitcnt lgkmcnt(1)
	v_pk_mul_f32 v[92:93], v[98:99], v[86:87] op_sel_hi:[1,0]
	s_waitcnt lgkmcnt(0)
	v_pk_mul_f32 v[102:103], v[102:103], v[86:87] op_sel_hi:[1,0]
	v_mul_f32_e32 v69, 0xbfb8aa3b, v92
	v_exp_f32_e32 v98, v69
	v_mul_f32_e32 v69, 0xbfb8aa3b, v93
	v_exp_f32_e32 v99, v69
	s_nop 0
	v_pk_add_f32 v[98:99], v[98:99], 1.0 op_sel_hi:[1,0]
	s_nop 0
	v_rcp_f32_e32 v77, v99
	s_nop 0
	v_mul_f32_e32 v93, v93, v77
	v_rcp_f32_e32 v77, v98
	s_nop 0
	v_mul_f32_e32 v92, v92, v77
	v_pk_mul_f32 v[98:99], v[100:101], v[86:87] op_sel_hi:[1,0]
	v_pk_mul_f32 v[92:93], v[102:103], v[92:93]
	v_mul_f32_e32 v69, 0xbfb8aa3b, v98
	v_exp_f32_e32 v100, v69
	v_mul_f32_e32 v69, 0xbfb8aa3b, v99
	v_exp_f32_e32 v101, v69
	v_pk_mul_f32 v[86:87], v[104:105], v[86:87] op_sel_hi:[1,0]
	v_cvt_pk_bf16_f32 v92, v92, v93
	v_pk_add_f32 v[100:101], v[100:101], 1.0 op_sel_hi:[1,0]
	s_nop 0
	v_rcp_f32_e32 v77, v101
	s_nop 0
	v_mul_f32_e32 v99, v99, v77
	v_rcp_f32_e32 v77, v100
	s_nop 0
	v_mul_f32_e32 v98, v98, v77
	v_pk_mul_f32 v[86:87], v[86:87], v[98:99]
	v_mad_i64_i32 v[84:85], s[10:11], v84, s14, v[66:67]
	v_cvt_pk_bf16_f32 v93, v86, v87
	global_store_dwordx2 v[84:85], v[92:93], off
	s_barrier
	ds_write2_b32 v130, v2, v18 offset1:16
	ds_write2_b32 v114, v3, v19 offset0:4 offset1:20
	ds_write2_b32 v115, v4, v20 offset0:8 offset1:24
	ds_write2_b32 v116, v5, v21 offset0:12 offset1:28
	ds_write2_b32 v117, v6, v22 offset0:64 offset1:80
	ds_write2_b32 v94, v7, v23 offset0:68 offset1:84
	ds_write2_b32 v95, v8, v24 offset0:72 offset1:88
	ds_write2_b32 v96, v9, v25 offset0:76 offset1:92
	ds_write2_b32 v132, v10, v26 offset0:128 offset1:144
	ds_write2_b32 v97, v11, v27 offset0:132 offset1:148
	ds_write2_b32 v126, v12, v28 offset0:136 offset1:152
	ds_write2_b32 v127, v13, v29 offset0:140 offset1:156
	ds_write2_b32 v133, v14, v30 offset0:192 offset1:208
	ds_write2_b32 v128, v15, v31 offset0:196 offset1:212
	ds_write2_b32 v129, v16, v32 offset0:200 offset1:216
	ds_write2_b32 v131, v17, v33 offset0:204 offset1:220
	ds_write2_b32 v130, v34, v50 offset0:128 offset1:144
	ds_write2_b32 v114, v35, v51 offset0:132 offset1:148
	ds_write2_b32 v115, v36, v52 offset0:136 offset1:152
	ds_write2_b32 v116, v37, v53 offset0:140 offset1:156
	ds_write2_b32 v117, v38, v54 offset0:192 offset1:208
	ds_write2_b32 v94, v39, v55 offset0:196 offset1:212
	ds_write2_b32 v95, v40, v56 offset0:200 offset1:216
	ds_write2_b32 v96, v41, v57 offset0:204 offset1:220
	ds_write2_b32 v97, v42, v58 offset1:16
	ds_write2_b32 v126, v43, v59 offset0:4 offset1:20
	ds_write2_b32 v127, v44, v60 offset0:8 offset1:24
	ds_write2_b32 v90, v45, v61 offset0:12 offset1:28
	ds_write2_b32 v128, v46, v62 offset0:64 offset1:80
	ds_write2_b32 v129, v47, v63 offset0:68 offset1:84
	ds_write2_b32 v131, v48, v64 offset0:72 offset1:88
	ds_write2_b32 v91, v49, v65 offset0:76 offset1:92
	v_add_u32_e32 v2, s8, v88
	v_ashrrev_i32_e32 v3, 31, v2
	v_lshl_add_u64 v[4:5], v[2:3], 4, s[46:47]
	s_waitcnt lgkmcnt(0)
	s_barrier
	global_load_dwordx4 v[134:137], v[4:5], off
	global_load_dwordx4 v[138:141], v[4:5], off offset:256
	global_load_dwordx4 v[144:147], v[4:5], off offset:512
	global_load_dwordx4 v[148:151], v[4:5], off offset:768
	global_load_dwordx4 v[152:155], v[4:5], off offset:1024
	global_load_dwordx4 v[156:159], v[4:5], off offset:1280
	global_load_dwordx4 v[160:163], v[4:5], off offset:1536
	global_load_dwordx4 v[164:167], v[4:5], off offset:1792
	s_waitcnt vmcnt(0)
	v_add_f32_e32 v3, v134, v135
	v_add_f32_e32 v3, v3, v136
	v_add_f32_e32 v3, v3, v137
	v_fmamk_f32 v3, v3, 0x3a800000, v200
	v_cmp_gt_f32_e32 vcc, s9, v3
	v_mul_f32_e32 v4, 0x4b800000, v3
	s_nop 0
	v_cndmask_b32_e32 v3, v3, v4, vcc
	v_rsq_f32_e32 v3, v3
	s_nop 0
	v_mul_f32_e32 v4, 0x45800000, v3
	v_cndmask_b32_e32 v12, v3, v4, vcc
	ds_read_b128 v[4:7], v82
	ds_read_b128 v[8:11], v82 offset:64
	s_waitcnt lgkmcnt(1)
	v_pk_mul_f32 v[4:5], v[4:5], v[12:13] op_sel_hi:[1,0]
	s_nop 0
	v_mul_f32_e32 v3, 0xbfb8aa3b, v4
	v_exp_f32_e32 v14, v3
	v_mul_f32_e32 v3, 0xbfb8aa3b, v5
	v_exp_f32_e32 v15, v3
	s_waitcnt lgkmcnt(0)
	v_pk_mul_f32 v[8:9], v[8:9], v[12:13] op_sel_hi:[1,0]
	v_pk_add_f32 v[14:15], v[14:15], 1.0 op_sel_hi:[1,0]
	s_nop 0
	v_rcp_f32_e32 v13, v15
	s_nop 0
	v_mul_f32_e32 v5, v5, v13
	v_div_scale_f32 v3, s[10:11], v14, v14, v4
	v_rcp_f32_e32 v13, v3
	s_nop 0
	v_fma_f32 v15, -v3, v13, 1.0
	v_fmac_f32_e32 v13, v15, v13
	v_div_scale_f32 v15, vcc, v4, v14, v4
	v_mul_f32_e32 v16, v15, v13
	v_fma_f32 v17, -v3, v16, v15
	v_fmac_f32_e32 v16, v17, v13
	v_fma_f32 v3, -v3, v16, v15
	v_div_fmas_f32 v3, v3, v13, v16
	v_pk_mul_f32 v[6:7], v[6:7], v[12:13] op_sel_hi:[1,0]
	v_div_fixup_f32 v4, v3, v14, v4
	v_mul_f32_e32 v3, 0xbfb8aa3b, v6
	v_pk_mul_f32 v[4:5], v[8:9], v[4:5]
	v_exp_f32_e32 v8, v3
	v_mul_f32_e32 v3, 0xbfb8aa3b, v7
	v_exp_f32_e32 v9, v3
	v_pk_mul_f32 v[10:11], v[10:11], v[12:13] op_sel_hi:[1,0]
	v_cvt_pk_bf16_f32 v4, v4, v5
	v_pk_add_f32 v[8:9], v[8:9], 1.0 op_sel_hi:[1,0]
	s_nop 0
	v_rcp_f32_e32 v12, v9
	s_nop 0
	v_mul_f32_e32 v7, v7, v12
	v_rcp_f32_e32 v9, v8
	s_nop 0
	v_mul_f32_e32 v6, v6, v9
	v_pk_mul_f32 v[6:7], v[10:11], v[6:7]
	v_mad_i64_i32 v[2:3], s[10:11], v2, s14, v[66:67]
	v_cvt_pk_bf16_f32 v5, v6, v7
	global_store_dwordx2 v[2:3], v[4:5], off
	v_add_u32_e32 v2, s8, v83
	v_ashrrev_i32_e32 v3, 31, v2
	v_lshl_add_u64 v[4:5], v[2:3], 4, s[46:47]
	v_add_f32_e32 v3, v138, v139
	v_add_f32_e32 v3, v3, v140
	v_add_f32_e32 v3, v3, v141
	v_fmamk_f32 v3, v3, 0x3a800000, v200
	v_cmp_gt_f32_e32 vcc, s9, v3
	v_mul_f32_e32 v4, 0x4b800000, v3
	s_nop 0
	v_cndmask_b32_e32 v3, v3, v4, vcc
	v_rsq_f32_e32 v3, v3
	s_nop 0
	v_mul_f32_e32 v4, 0x45800000, v3
	v_cndmask_b32_e32 v12, v3, v4, vcc
	ds_read_b128 v[4:7], v80
	ds_read_b128 v[8:11], v80 offset:64
	s_waitcnt lgkmcnt(1)
	v_pk_mul_f32 v[4:5], v[4:5], v[12:13] op_sel_hi:[1,0]
	s_nop 0
	v_mul_f32_e32 v3, 0xbfb8aa3b, v4
	v_exp_f32_e32 v14, v3
	v_mul_f32_e32 v3, 0xbfb8aa3b, v5
	v_exp_f32_e32 v15, v3
	s_waitcnt lgkmcnt(0)
	v_pk_mul_f32 v[8:9], v[8:9], v[12:13] op_sel_hi:[1,0]
	v_pk_add_f32 v[14:15], v[14:15], 1.0 op_sel_hi:[1,0]
	s_nop 0
	v_rcp_f32_e32 v13, v15
	s_nop 0
	v_mul_f32_e32 v5, v5, v13
	v_div_scale_f32 v3, s[10:11], v14, v14, v4
	v_rcp_f32_e32 v13, v3
	s_nop 0
	v_fma_f32 v15, -v3, v13, 1.0
	v_fmac_f32_e32 v13, v15, v13
	v_div_scale_f32 v15, vcc, v4, v14, v4
	v_mul_f32_e32 v16, v15, v13
	v_fma_f32 v17, -v3, v16, v15
	v_fmac_f32_e32 v16, v17, v13
	v_fma_f32 v3, -v3, v16, v15
	v_div_fmas_f32 v3, v3, v13, v16
	v_pk_mul_f32 v[6:7], v[6:7], v[12:13] op_sel_hi:[1,0]
	v_div_fixup_f32 v4, v3, v14, v4
	v_mul_f32_e32 v3, 0xbfb8aa3b, v6
	v_pk_mul_f32 v[4:5], v[8:9], v[4:5]
	v_exp_f32_e32 v8, v3
	v_mul_f32_e32 v3, 0xbfb8aa3b, v7
	v_exp_f32_e32 v9, v3
	v_pk_mul_f32 v[10:11], v[10:11], v[12:13] op_sel_hi:[1,0]
	v_cvt_pk_bf16_f32 v4, v4, v5
	v_pk_add_f32 v[8:9], v[8:9], 1.0 op_sel_hi:[1,0]
	s_nop 0
	v_rcp_f32_e32 v12, v9
	s_nop 0
	v_mul_f32_e32 v7, v7, v12
	v_rcp_f32_e32 v9, v8
	s_nop 0
	v_mul_f32_e32 v6, v6, v9
	v_pk_mul_f32 v[6:7], v[10:11], v[6:7]
	v_mad_i64_i32 v[2:3], s[10:11], v2, s14, v[66:67]
	v_cvt_pk_bf16_f32 v5, v6, v7
	global_store_dwordx2 v[2:3], v[4:5], off
	v_add_u32_e32 v2, s8, v81
	v_ashrrev_i32_e32 v3, 31, v2
	v_lshl_add_u64 v[4:5], v[2:3], 4, s[46:47]
	v_add_f32_e32 v3, v144, v145
	v_add_f32_e32 v3, v3, v146
	v_add_f32_e32 v3, v3, v147
	v_fmamk_f32 v3, v3, 0x3a800000, v200
	v_cmp_gt_f32_e32 vcc, s9, v3
	v_mul_f32_e32 v4, 0x4b800000, v3
	s_nop 0
	v_cndmask_b32_e32 v3, v3, v4, vcc
	v_rsq_f32_e32 v3, v3
	s_nop 0
	v_mul_f32_e32 v4, 0x45800000, v3
	v_cndmask_b32_e32 v12, v3, v4, vcc
	ds_read_b128 v[4:7], v78
	ds_read_b128 v[8:11], v78 offset:64
	s_waitcnt lgkmcnt(1)
	v_pk_mul_f32 v[4:5], v[4:5], v[12:13] op_sel_hi:[1,0]
	s_nop 0
	v_mul_f32_e32 v3, 0xbfb8aa3b, v4
	v_exp_f32_e32 v14, v3
	v_mul_f32_e32 v3, 0xbfb8aa3b, v5
	v_exp_f32_e32 v15, v3
	s_waitcnt lgkmcnt(0)
	v_pk_mul_f32 v[8:9], v[8:9], v[12:13] op_sel_hi:[1,0]
	v_pk_add_f32 v[14:15], v[14:15], 1.0 op_sel_hi:[1,0]
	s_nop 0
	v_rcp_f32_e32 v13, v15
	s_nop 0
	v_mul_f32_e32 v5, v5, v13
	v_div_scale_f32 v3, s[10:11], v14, v14, v4
	v_rcp_f32_e32 v13, v3
	s_nop 0
	v_fma_f32 v15, -v3, v13, 1.0
	v_fmac_f32_e32 v13, v15, v13
	v_div_scale_f32 v15, vcc, v4, v14, v4
	v_mul_f32_e32 v16, v15, v13
	v_fma_f32 v17, -v3, v16, v15
	v_fmac_f32_e32 v16, v17, v13
	v_fma_f32 v3, -v3, v16, v15
	v_div_fmas_f32 v3, v3, v13, v16
	v_pk_mul_f32 v[6:7], v[6:7], v[12:13] op_sel_hi:[1,0]
	v_div_fixup_f32 v4, v3, v14, v4
	v_mul_f32_e32 v3, 0xbfb8aa3b, v6
	v_pk_mul_f32 v[4:5], v[8:9], v[4:5]
	v_exp_f32_e32 v8, v3
	v_mul_f32_e32 v3, 0xbfb8aa3b, v7
	v_exp_f32_e32 v9, v3
	v_pk_mul_f32 v[10:11], v[10:11], v[12:13] op_sel_hi:[1,0]
	v_cvt_pk_bf16_f32 v4, v4, v5
	v_pk_add_f32 v[8:9], v[8:9], 1.0 op_sel_hi:[1,0]
	s_nop 0
	v_rcp_f32_e32 v12, v9
	s_nop 0
	v_mul_f32_e32 v7, v7, v12
	v_rcp_f32_e32 v9, v8
	s_nop 0
	v_mul_f32_e32 v6, v6, v9
	v_pk_mul_f32 v[6:7], v[10:11], v[6:7]
	v_mad_i64_i32 v[2:3], s[10:11], v2, s14, v[66:67]
	v_cvt_pk_bf16_f32 v5, v6, v7
	global_store_dwordx2 v[2:3], v[4:5], off
	v_add_u32_e32 v2, s8, v79
	v_ashrrev_i32_e32 v3, 31, v2
	v_lshl_add_u64 v[4:5], v[2:3], 4, s[46:47]
	v_add_f32_e32 v3, v148, v149
	v_add_f32_e32 v3, v3, v150
	v_add_f32_e32 v3, v3, v151
	v_fmamk_f32 v3, v3, 0x3a800000, v200
	v_cmp_gt_f32_e32 vcc, s9, v3
	v_mul_f32_e32 v4, 0x4b800000, v3
	s_nop 0
	v_cndmask_b32_e32 v3, v3, v4, vcc
	v_rsq_f32_e32 v3, v3
	s_nop 0
	v_mul_f32_e32 v4, 0x45800000, v3
	v_cndmask_b32_e32 v12, v3, v4, vcc
	ds_read_b128 v[4:7], v76
	ds_read_b128 v[8:11], v76 offset:64
	s_waitcnt lgkmcnt(1)
	v_pk_mul_f32 v[4:5], v[4:5], v[12:13] op_sel_hi:[1,0]
	s_nop 0
	v_mul_f32_e32 v3, 0xbfb8aa3b, v4
	v_exp_f32_e32 v14, v3
	v_mul_f32_e32 v3, 0xbfb8aa3b, v5
	v_exp_f32_e32 v15, v3
	s_waitcnt lgkmcnt(0)
	v_pk_mul_f32 v[8:9], v[8:9], v[12:13] op_sel_hi:[1,0]
	v_pk_add_f32 v[14:15], v[14:15], 1.0 op_sel_hi:[1,0]
	s_nop 0
	v_rcp_f32_e32 v13, v15
	s_nop 0
	v_mul_f32_e32 v5, v5, v13
	v_div_scale_f32 v3, s[10:11], v14, v14, v4
	v_rcp_f32_e32 v13, v3
	s_nop 0
	v_fma_f32 v15, -v3, v13, 1.0
	v_fmac_f32_e32 v13, v15, v13
	v_div_scale_f32 v15, vcc, v4, v14, v4
	v_mul_f32_e32 v16, v15, v13
	v_fma_f32 v17, -v3, v16, v15
	v_fmac_f32_e32 v16, v17, v13
	v_fma_f32 v3, -v3, v16, v15
	v_div_fmas_f32 v3, v3, v13, v16
	v_pk_mul_f32 v[6:7], v[6:7], v[12:13] op_sel_hi:[1,0]
	v_div_fixup_f32 v4, v3, v14, v4
	v_mul_f32_e32 v3, 0xbfb8aa3b, v6
	v_pk_mul_f32 v[4:5], v[8:9], v[4:5]
	v_exp_f32_e32 v8, v3
	v_mul_f32_e32 v3, 0xbfb8aa3b, v7
	v_exp_f32_e32 v9, v3
	v_pk_mul_f32 v[10:11], v[10:11], v[12:13] op_sel_hi:[1,0]
	v_cvt_pk_bf16_f32 v4, v4, v5
	v_pk_add_f32 v[8:9], v[8:9], 1.0 op_sel_hi:[1,0]
	s_nop 0
	v_rcp_f32_e32 v12, v9
	s_nop 0
	v_mul_f32_e32 v7, v7, v12
	v_rcp_f32_e32 v9, v8
	s_nop 0
	v_mul_f32_e32 v6, v6, v9
	v_pk_mul_f32 v[6:7], v[10:11], v[6:7]
	v_mad_i64_i32 v[2:3], s[10:11], v2, s14, v[66:67]
	v_cvt_pk_bf16_f32 v5, v6, v7
	global_store_dwordx2 v[2:3], v[4:5], off
	v_add_u32_e32 v2, s8, v0
	v_ashrrev_i32_e32 v3, 31, v2
	v_lshl_add_u64 v[4:5], v[2:3], 4, s[46:47]
	v_add_f32_e32 v0, v152, v153
	v_add_f32_e32 v0, v0, v154
	v_add_f32_e32 v0, v0, v155
	v_fmamk_f32 v0, v0, 0x3a800000, v200
	v_cmp_gt_f32_e32 vcc, s9, v0
	v_mul_f32_e32 v3, 0x4b800000, v0
	ds_read_b128 v[4:7], v70
	ds_read_b128 v[8:11], v70 offset:64
	v_cndmask_b32_e32 v0, v0, v3, vcc
	v_rsq_f32_e32 v0, v0
	s_nop 0
	v_mul_f32_e32 v3, 0x45800000, v0
	v_cndmask_b32_e32 v0, v0, v3, vcc
	s_waitcnt lgkmcnt(1)
	v_pk_mul_f32 v[4:5], v[4:5], v[0:1] op_sel_hi:[1,0]
	v_pk_mul_f32 v[6:7], v[6:7], v[0:1] op_sel_hi:[1,0]
	v_mul_f32_e32 v3, 0xbfb8aa3b, v4
	v_exp_f32_e32 v12, v3
	v_mul_f32_e32 v3, 0xbfb8aa3b, v5
	v_exp_f32_e32 v13, v3
	s_waitcnt lgkmcnt(0)
	v_pk_mul_f32 v[8:9], v[8:9], v[0:1] op_sel_hi:[1,0]
	v_pk_mul_f32 v[10:11], v[10:11], v[0:1] op_sel_hi:[1,0]
	v_mul_f32_e32 v0, 0xbfb8aa3b, v7
	v_pk_add_f32 v[12:13], v[12:13], 1.0 op_sel_hi:[1,0]
	s_nop 0
	v_rcp_f32_e32 v14, v13
	s_nop 0
	v_mul_f32_e32 v5, v5, v14
	v_rcp_f32_e32 v13, v12
	s_nop 0
	v_mul_f32_e32 v4, v4, v13
	v_mul_f32_e32 v3, 0xbfb8aa3b, v6
	v_pk_mul_f32 v[4:5], v[8:9], v[4:5]
	v_exp_f32_e32 v8, v3
	v_exp_f32_e32 v9, v0
	v_cvt_pk_bf16_f32 v4, v4, v5
	v_pk_add_f32 v[8:9], v[8:9], 1.0 op_sel_hi:[1,0]
	s_nop 0
	v_rcp_f32_e32 v3, v9
	s_nop 0
	v_mul_f32_e32 v7, v7, v3
	v_rcp_f32_e32 v3, v8
	s_nop 0
	v_mul_f32_e32 v6, v6, v3
	v_pk_mul_f32 v[6:7], v[10:11], v[6:7]
	v_mad_i64_i32 v[2:3], s[10:11], v2, s14, v[66:67]
	v_cvt_pk_bf16_f32 v5, v6, v7
	global_store_dwordx2 v[2:3], v[4:5], off
	v_add_u32_e32 v2, s8, v71
	v_ashrrev_i32_e32 v3, 31, v2
	v_lshl_add_u64 v[4:5], v[2:3], 4, s[46:47]
	v_add_f32_e32 v0, v156, v157
	v_add_f32_e32 v0, v0, v158
	v_add_f32_e32 v0, v0, v159
	v_fmamk_f32 v0, v0, 0x3a800000, v200
	v_cmp_gt_f32_e32 vcc, s9, v0
	v_mul_f32_e32 v3, 0x4b800000, v0
	ds_read_b128 v[4:7], v72
	ds_read_b128 v[8:11], v72 offset:64
	v_cndmask_b32_e32 v0, v0, v3, vcc
	v_rsq_f32_e32 v0, v0
	s_nop 0
	v_mul_f32_e32 v3, 0x45800000, v0
	v_cndmask_b32_e32 v0, v0, v3, vcc
	s_waitcnt lgkmcnt(1)
	v_pk_mul_f32 v[4:5], v[4:5], v[0:1] op_sel_hi:[1,0]
	v_pk_mul_f32 v[6:7], v[6:7], v[0:1] op_sel_hi:[1,0]
	v_mul_f32_e32 v3, 0xbfb8aa3b, v4
	v_exp_f32_e32 v12, v3
	v_mul_f32_e32 v3, 0xbfb8aa3b, v5
	v_exp_f32_e32 v13, v3
	s_waitcnt lgkmcnt(0)
	v_pk_mul_f32 v[8:9], v[8:9], v[0:1] op_sel_hi:[1,0]
	v_pk_mul_f32 v[10:11], v[10:11], v[0:1] op_sel_hi:[1,0]
	v_mul_f32_e32 v0, 0xbfb8aa3b, v7
	v_pk_add_f32 v[12:13], v[12:13], 1.0 op_sel_hi:[1,0]
	s_nop 0
	v_rcp_f32_e32 v14, v13
	s_nop 0
	v_mul_f32_e32 v5, v5, v14
	v_rcp_f32_e32 v13, v12
	s_nop 0
	v_mul_f32_e32 v4, v4, v13
	v_mul_f32_e32 v3, 0xbfb8aa3b, v6
	v_pk_mul_f32 v[4:5], v[8:9], v[4:5]
	v_exp_f32_e32 v8, v3
	v_exp_f32_e32 v9, v0
	v_cvt_pk_bf16_f32 v4, v4, v5
	v_pk_add_f32 v[8:9], v[8:9], 1.0 op_sel_hi:[1,0]
	s_nop 0
	v_rcp_f32_e32 v3, v9
	s_nop 0
	v_mul_f32_e32 v7, v7, v3
	v_rcp_f32_e32 v3, v8
	s_nop 0
	v_mul_f32_e32 v6, v6, v3
	v_pk_mul_f32 v[6:7], v[10:11], v[6:7]
	v_mad_i64_i32 v[2:3], s[10:11], v2, s14, v[66:67]
	v_cvt_pk_bf16_f32 v5, v6, v7
	global_store_dwordx2 v[2:3], v[4:5], off
	v_add_u32_e32 v2, s8, v73
	v_ashrrev_i32_e32 v3, 31, v2
	v_lshl_add_u64 v[4:5], v[2:3], 4, s[46:47]
	v_add_f32_e32 v0, v160, v161
	v_add_f32_e32 v0, v0, v162
	v_add_f32_e32 v0, v0, v163
	v_fmamk_f32 v0, v0, 0x3a800000, v200
	v_cmp_gt_f32_e32 vcc, s9, v0
	v_mul_f32_e32 v3, 0x4b800000, v0
	ds_read_b128 v[4:7], v74
	ds_read_b128 v[8:11], v74 offset:64
	v_cndmask_b32_e32 v0, v0, v3, vcc
	v_rsq_f32_e32 v0, v0
	s_nop 0
	v_mul_f32_e32 v3, 0x45800000, v0
	v_cndmask_b32_e32 v0, v0, v3, vcc
	s_waitcnt lgkmcnt(1)
	v_pk_mul_f32 v[4:5], v[4:5], v[0:1] op_sel_hi:[1,0]
	v_pk_mul_f32 v[6:7], v[6:7], v[0:1] op_sel_hi:[1,0]
	v_mul_f32_e32 v3, 0xbfb8aa3b, v4
	v_exp_f32_e32 v12, v3
	v_mul_f32_e32 v3, 0xbfb8aa3b, v5
	v_exp_f32_e32 v13, v3
	s_waitcnt lgkmcnt(0)
	v_pk_mul_f32 v[8:9], v[8:9], v[0:1] op_sel_hi:[1,0]
	v_pk_mul_f32 v[10:11], v[10:11], v[0:1] op_sel_hi:[1,0]
	v_mul_f32_e32 v0, 0xbfb8aa3b, v7
	v_pk_add_f32 v[12:13], v[12:13], 1.0 op_sel_hi:[1,0]
	s_nop 0
	v_rcp_f32_e32 v14, v13
	s_nop 0
	v_mul_f32_e32 v5, v5, v14
	v_rcp_f32_e32 v13, v12
	s_nop 0
	v_mul_f32_e32 v4, v4, v13
	v_mul_f32_e32 v3, 0xbfb8aa3b, v6
	v_pk_mul_f32 v[4:5], v[8:9], v[4:5]
	v_exp_f32_e32 v8, v3
	v_exp_f32_e32 v9, v0
	v_cvt_pk_bf16_f32 v4, v4, v5
	v_pk_add_f32 v[8:9], v[8:9], 1.0 op_sel_hi:[1,0]
	s_nop 0
	v_rcp_f32_e32 v3, v9
	s_nop 0
	v_mul_f32_e32 v7, v7, v3
	v_rcp_f32_e32 v3, v8
	s_nop 0
	v_mul_f32_e32 v6, v6, v3
	v_pk_mul_f32 v[6:7], v[10:11], v[6:7]
	v_mad_i64_i32 v[2:3], s[10:11], v2, s14, v[66:67]
	v_cvt_pk_bf16_f32 v5, v6, v7
	global_store_dwordx2 v[2:3], v[4:5], off
	v_add_u32_e32 v2, s8, v75
	v_ashrrev_i32_e32 v3, 31, v2
	v_lshl_add_u64 v[4:5], v[2:3], 4, s[46:47]
	v_add_f32_e32 v0, v164, v165
	v_add_f32_e32 v0, v0, v166
	v_add_f32_e32 v0, v0, v167
	v_fmamk_f32 v0, v0, 0x3a800000, v200
	v_cmp_gt_f32_e32 vcc, s9, v0
	v_mul_f32_e32 v3, 0x4b800000, v0
	ds_read_b128 v[4:7], v68
	ds_read_b128 v[8:11], v68 offset:64
	v_cndmask_b32_e32 v0, v0, v3, vcc
	v_rsq_f32_e32 v0, v0
	s_nop 0
	v_mul_f32_e32 v3, 0x45800000, v0
	v_cndmask_b32_e32 v0, v0, v3, vcc
	s_waitcnt lgkmcnt(1)
	v_pk_mul_f32 v[4:5], v[4:5], v[0:1] op_sel_hi:[1,0]
	v_pk_mul_f32 v[6:7], v[6:7], v[0:1] op_sel_hi:[1,0]
	v_mul_f32_e32 v3, 0xbfb8aa3b, v4
	v_exp_f32_e32 v12, v3
	v_mul_f32_e32 v3, 0xbfb8aa3b, v5
	v_exp_f32_e32 v13, v3
	s_waitcnt lgkmcnt(0)
	v_pk_mul_f32 v[8:9], v[8:9], v[0:1] op_sel_hi:[1,0]
	v_pk_mul_f32 v[10:11], v[10:11], v[0:1] op_sel_hi:[1,0]
	v_mul_f32_e32 v0, 0xbfb8aa3b, v7
	v_pk_add_f32 v[12:13], v[12:13], 1.0 op_sel_hi:[1,0]
	s_nop 0
	v_rcp_f32_e32 v14, v13
	s_nop 0
	v_mul_f32_e32 v5, v5, v14
	v_rcp_f32_e32 v13, v12
	s_nop 0
	v_mul_f32_e32 v4, v4, v13
	v_mul_f32_e32 v3, 0xbfb8aa3b, v6
	v_pk_mul_f32 v[4:5], v[8:9], v[4:5]
	v_exp_f32_e32 v8, v3
	v_exp_f32_e32 v9, v0
	v_cvt_pk_bf16_f32 v4, v4, v5
	v_pk_add_f32 v[8:9], v[8:9], 1.0 op_sel_hi:[1,0]
	s_nop 0
	v_rcp_f32_e32 v3, v9
	s_nop 0
	v_mul_f32_e32 v7, v7, v3
	v_rcp_f32_e32 v3, v8
	s_nop 0
	v_mul_f32_e32 v6, v6, v3
	v_pk_mul_f32 v[6:7], v[10:11], v[6:7]
	v_mad_i64_i32 v[2:3], s[8:9], v2, s14, v[66:67]
	v_cvt_pk_bf16_f32 v5, v6, v7
	global_store_dwordx2 v[2:3], v[4:5], off
	s_barrier

.LBB0_410:
	s_or_b64 exec, exec, s[12:13]
	s_movk_i32 s9, 0x410
	v_lshrrev_b32_e32 v130, 2, v142
	v_lshlrev_b32_e32 v131, 1, v142
	v_and_b32_e32 v0, 15, v142
	v_and_b32_e32 v130, 0xfffffcc, v130
	v_and_b32_e32 v131, 0x180, v131
	v_add_u32_e32 v131, 0, v131
	v_lshlrev_b32_e32 v0, 2, v0
	v_mul_lo_u32 v130, v130, s9
	v_add3_u32 v130, v131, v0, v130
	s_waitcnt vmcnt(0)
	s_barrier
	ds_write2_b32 v130, v114, v126 offset1:16
	v_add_u32_e32 v114, 0x400, v130
	ds_write2_b32 v114, v115, v127 offset0:4 offset1:20
	v_add_u32_e32 v115, 0x800, v130
	ds_write2_b32 v115, v116, v128 offset0:8 offset1:24
	v_add_u32_e32 v116, 0xc00, v130
	ds_write2_b32 v116, v117, v129 offset0:12 offset1:28
	v_add_u32_e32 v117, 0x4000, v130
	ds_write2_b32 v117, v82, v94 offset0:64 offset1:80
	v_add_u32_e32 v94, 0x4400, v130
	ds_write2_b32 v94, v83, v95 offset0:68 offset1:84
	v_add_u32_e32 v95, 0x4800, v130
	ds_write2_b32 v95, v84, v96 offset0:72 offset1:88
	v_add_u32_e32 v96, 0x4c00, v130
	v_add_u32_e32 v128, 0xc800, v130
	v_ashrrev_i32_e32 v84, 5, v142
	ds_write2_b32 v96, v85, v97 offset0:76 offset1:92
	v_add_u32_e32 v131, 0x8000, v130
	v_add_u32_e32 v85, 0x8400, v130
	v_add_u32_e32 v97, 0x8800, v130
	v_add_u32_e32 v126, 0x8c00, v130
	v_add_u32_e32 v132, 0xc000, v130
	v_add_u32_e32 v127, 0xc400, v130
	ds_write2_b32 v128, v68, v72 offset0:200 offset1:216
	v_add_u32_e32 v129, 0xcc00, v130
	v_add_u32_e32 v72, s8, v84
	ds_write2_b32 v131, v74, v78 offset0:128 offset1:144
	ds_write2_b32 v85, v75, v79 offset0:132 offset1:148
	ds_write2_b32 v97, v76, v80 offset0:136 offset1:152
	ds_write2_b32 v126, v77, v81 offset0:140 offset1:156
	ds_write2_b32 v132, v66, v70 offset0:192 offset1:208
	ds_write2_b32 v127, v67, v71 offset0:196 offset1:212
	ds_write2_b32 v129, v69, v73 offset0:204 offset1:220
	ds_write2_b32 v130, v98, v118 offset0:128 offset1:144
	ds_write2_b32 v114, v99, v119 offset0:132 offset1:148
	ds_write2_b32 v115, v100, v120 offset0:136 offset1:152
	ds_write2_b32 v116, v101, v121 offset0:140 offset1:156
	ds_write2_b32 v117, v102, v122 offset0:192 offset1:208
	ds_write2_b32 v94, v103, v123 offset0:196 offset1:212
	ds_write2_b32 v95, v104, v124 offset0:200 offset1:216
	ds_write2_b32 v96, v105, v125 offset0:204 offset1:220
	ds_write2_b32 v85, v90, v110 offset1:16
	ds_write2_b32 v97, v91, v111 offset0:4 offset1:20
	ds_write2_b32 v126, v92, v112 offset0:8 offset1:24
	v_add_u32_e32 v90, 0x9000, v130
	v_ashrrev_i32_e32 v73, 31, v72
	ds_write2_b32 v90, v93, v113 offset0:12 offset1:28
	ds_write2_b32 v127, v86, v106 offset0:64 offset1:80
	ds_write2_b32 v128, v87, v107 offset0:68 offset1:84
	ds_write2_b32 v129, v88, v108 offset0:72 offset1:88
	v_add_u32_e32 v86, 0xd000, v130
	v_lshl_add_u64 v[68:69], v[72:73], 4, s[46:47]
	ds_write2_b32 v86, v89, v109 offset0:76 offset1:92
	s_waitcnt lgkmcnt(0)
	s_barrier
	global_load_dwordx4 v[134:137], v[68:69], off
	global_load_dwordx4 v[138:141], v[68:69], off offset:256
	global_load_dwordx4 v[144:147], v[68:69], off offset:512
	global_load_dwordx4 v[148:151], v[68:69], off offset:768
	global_load_dwordx4 v[152:155], v[68:69], off offset:1024
	global_load_dwordx4 v[156:159], v[68:69], off offset:1280
	global_load_dwordx4 v[160:163], v[68:69], off offset:1536
	global_load_dwordx4 v[164:167], v[68:69], off offset:1792
	v_lshlrev_b32_e32 v66, 2, v142
	v_lshlrev_b32_e32 v0, 3, v142
	v_and_b32_e32 v66, 12, v66
	s_movk_i32 s7, 0xe0
	v_and_or_b32 v66, v0, s7, v66
	s_mov_b32 s7, 0x800000
	v_lshl_add_u32 v0, v66, 2, 0
	v_or_b32_e32 v66, s10, v66
	v_mad_u64_u32 v[82:83], s[10:11], v84, s9, v[0:1]
	v_ashrrev_i32_e32 v67, 31, v66
	v_lshl_add_u64 v[66:67], v[66:67], 1, s[30:31]
	s_movk_i32 s12, 0x1200
	v_mad_i64_i32 v[72:73], s[10:11], v72, s12, v[66:67]
	s_mov_b64 s[38:39], -1
	s_waitcnt vmcnt(0)
	v_add_f32_e32 v68, v134, v135
	v_add_f32_e32 v68, v68, v136
	v_add_f32_e32 v68, v68, v137
	v_fmamk_f32 v68, v68, 0x3a800000, v200
	v_cmp_gt_f32_e32 vcc, s7, v68
	v_mul_f32_e32 v69, 0x4b800000, v68
	s_nop 0
	v_cndmask_b32_e32 v68, v68, v69, vcc
	v_rsq_f32_e32 v68, v68
	s_nop 0
	v_mul_f32_e32 v69, 0x45800000, v68
	v_cndmask_b32_e32 v74, v68, v69, vcc
	ds_read_b128 v[68:71], v82
	s_waitcnt lgkmcnt(0)
	v_pk_mul_f32 v[68:69], v[68:69], v[74:75] op_sel_hi:[1,0]
	v_pk_mul_f32 v[70:71], v[70:71], v[74:75] op_sel_hi:[1,0]
	v_cvt_pk_bf16_f32 v68, v68, v69
	v_cvt_pk_bf16_f32 v69, v70, v71
	global_store_dwordx2 v[72:73], v[68:69], off
	ds_read_b128 v[68:71], v82 offset:64
	s_waitcnt lgkmcnt(0)
	v_pk_mul_f32 v[68:69], v[68:69], v[74:75] op_sel_hi:[1,0]
	v_pk_mul_f32 v[70:71], v[70:71], v[74:75] op_sel_hi:[1,0]
	v_cvt_pk_bf16_f32 v68, v68, v69
	v_cvt_pk_bf16_f32 v69, v70, v71
	global_store_dwordx2 v[72:73], v[68:69], off offset:32
	v_add_u32_e32 v68, 0x200, v142
	v_ashrrev_i32_e32 v83, 5, v68
	v_add_u32_e32 v72, s8, v83
	v_ashrrev_i32_e32 v73, 31, v72
	v_lshl_add_u64 v[68:69], v[72:73], 4, s[46:47]
	v_mad_u64_u32 v[80:81], s[10:11], v83, s9, v[0:1]
	v_mad_i64_i32 v[72:73], s[10:11], v72, s12, v[66:67]
	v_add_f32_e32 v68, v138, v139
	v_add_f32_e32 v68, v68, v140
	v_add_f32_e32 v68, v68, v141
	v_fmamk_f32 v68, v68, 0x3a800000, v200
	v_cmp_gt_f32_e32 vcc, s7, v68
	v_mul_f32_e32 v69, 0x4b800000, v68
	s_nop 0
	v_cndmask_b32_e32 v68, v68, v69, vcc
	v_rsq_f32_e32 v68, v68
	s_nop 0
	v_mul_f32_e32 v69, 0x45800000, v68
	v_cndmask_b32_e32 v74, v68, v69, vcc
	ds_read_b128 v[68:71], v80
	s_waitcnt lgkmcnt(0)
	v_pk_mul_f32 v[68:69], v[68:69], v[74:75] op_sel_hi:[1,0]
	v_pk_mul_f32 v[70:71], v[70:71], v[74:75] op_sel_hi:[1,0]
	v_cvt_pk_bf16_f32 v68, v68, v69
	v_cvt_pk_bf16_f32 v69, v70, v71
	global_store_dwordx2 v[72:73], v[68:69], off
	ds_read_b128 v[68:71], v80 offset:64
	s_waitcnt lgkmcnt(0)
	v_pk_mul_f32 v[68:69], v[68:69], v[74:75] op_sel_hi:[1,0]
	v_pk_mul_f32 v[70:71], v[70:71], v[74:75] op_sel_hi:[1,0]
	v_cvt_pk_bf16_f32 v68, v68, v69
	v_cvt_pk_bf16_f32 v69, v70, v71
	global_store_dwordx2 v[72:73], v[68:69], off offset:32
	v_add_u32_e32 v68, 0x400, v142
	v_ashrrev_i32_e32 v81, 5, v68
	v_add_u32_e32 v74, s8, v81
	v_ashrrev_i32_e32 v75, 31, v74
	v_lshl_add_u64 v[70:71], v[74:75], 4, s[46:47]
	v_mad_u64_u32 v[68:69], s[10:11], v81, s9, v[0:1]
	v_mad_i64_i32 v[74:75], s[10:11], v74, s12, v[66:67]
	v_add_f32_e32 v69, v144, v145
	v_add_f32_e32 v69, v69, v146
	v_add_f32_e32 v69, v69, v147
	v_fmamk_f32 v69, v69, 0x3a800000, v200
	v_cmp_gt_f32_e32 vcc, s7, v69
	v_mul_f32_e32 v70, 0x4b800000, v69
	s_nop 0
	v_cndmask_b32_e32 v69, v69, v70, vcc
	v_rsq_f32_e32 v69, v69
	s_nop 0
	v_mul_f32_e32 v70, 0x45800000, v69
	v_cndmask_b32_e32 v76, v69, v70, vcc
	ds_read_b128 v[70:73], v68
	v_add_u32_e32 v69, 0x600, v142
	v_ashrrev_i32_e32 v69, 5, v69
	s_waitcnt lgkmcnt(0)
	v_pk_mul_f32 v[70:71], v[70:71], v[76:77] op_sel_hi:[1,0]
	v_pk_mul_f32 v[72:73], v[72:73], v[76:77] op_sel_hi:[1,0]
	v_cvt_pk_bf16_f32 v70, v70, v71
	v_cvt_pk_bf16_f32 v71, v72, v73
	global_store_dwordx2 v[74:75], v[70:71], off
	ds_read_b128 v[70:73], v68 offset:64
	s_waitcnt lgkmcnt(0)
	v_pk_mul_f32 v[70:71], v[70:71], v[76:77] op_sel_hi:[1,0]
	v_pk_mul_f32 v[72:73], v[72:73], v[76:77] op_sel_hi:[1,0]
	v_add_u32_e32 v76, s8, v69
	v_cvt_pk_bf16_f32 v70, v70, v71
	v_cvt_pk_bf16_f32 v71, v72, v73
	v_ashrrev_i32_e32 v77, 31, v76
	global_store_dwordx2 v[74:75], v[70:71], off offset:32
	v_lshl_add_u64 v[72:73], v[76:77], 4, s[46:47]
	v_mad_u64_u32 v[70:71], s[10:11], v69, s9, v[0:1]
	v_mad_i64_i32 v[76:77], s[10:11], v76, s12, v[66:67]
	v_add_f32_e32 v71, v148, v149
	v_add_f32_e32 v71, v71, v150
	v_add_f32_e32 v71, v71, v151
	v_fmamk_f32 v71, v71, 0x3a800000, v200
	v_cmp_gt_f32_e32 vcc, s7, v71
	v_mul_f32_e32 v72, 0x4b800000, v71
	s_nop 0
	v_cndmask_b32_e32 v71, v71, v72, vcc
	v_rsq_f32_e32 v71, v71
	s_nop 0
	v_mul_f32_e32 v72, 0x45800000, v71
	v_cndmask_b32_e32 v78, v71, v72, vcc
	ds_read_b128 v[72:75], v70
	v_add_u32_e32 v71, 0x800, v142
	v_ashrrev_i32_e32 v71, 5, v71
	s_waitcnt lgkmcnt(0)
	v_pk_mul_f32 v[72:73], v[72:73], v[78:79] op_sel_hi:[1,0]
	v_pk_mul_f32 v[74:75], v[74:75], v[78:79] op_sel_hi:[1,0]
	v_cvt_pk_bf16_f32 v72, v72, v73
	v_cvt_pk_bf16_f32 v73, v74, v75
	global_store_dwordx2 v[76:77], v[72:73], off
	ds_read_b128 v[72:75], v70 offset:64
	s_waitcnt lgkmcnt(0)
	v_pk_mul_f32 v[72:73], v[72:73], v[78:79] op_sel_hi:[1,0]
	v_pk_mul_f32 v[74:75], v[74:75], v[78:79] op_sel_hi:[1,0]
	v_add_u32_e32 v78, s8, v71
	v_cvt_pk_bf16_f32 v72, v72, v73
	v_cvt_pk_bf16_f32 v73, v74, v75
	v_ashrrev_i32_e32 v79, 31, v78
	global_store_dwordx2 v[76:77], v[72:73], off offset:32
	v_lshl_add_u64 v[74:75], v[78:79], 4, s[46:47]
	v_mad_u64_u32 v[72:73], s[10:11], v71, s9, v[0:1]
	v_mad_i64_i32 v[78:79], s[10:11], v78, s12, v[66:67]
	v_add_f32_e32 v73, v152, v153
	v_add_f32_e32 v73, v73, v154
	v_add_f32_e32 v73, v73, v155
	v_fmamk_f32 v73, v73, 0x3a800000, v200
	v_cmp_gt_f32_e32 vcc, s7, v73
	v_mul_f32_e32 v74, 0x4b800000, v73
	s_nop 0
	v_cndmask_b32_e32 v73, v73, v74, vcc
	v_rsq_f32_e32 v73, v73
	s_nop 0
	v_mul_f32_e32 v74, 0x45800000, v73
	v_cndmask_b32_e32 v88, v73, v74, vcc
	ds_read_b128 v[74:77], v72
	v_add_u32_e32 v73, 0xa00, v142
	v_ashrrev_i32_e32 v73, 5, v73
	s_waitcnt lgkmcnt(0)
	v_pk_mul_f32 v[74:75], v[74:75], v[88:89] op_sel_hi:[1,0]
	v_pk_mul_f32 v[76:77], v[76:77], v[88:89] op_sel_hi:[1,0]
	v_cvt_pk_bf16_f32 v74, v74, v75
	v_cvt_pk_bf16_f32 v75, v76, v77
	global_store_dwordx2 v[78:79], v[74:75], off
	ds_read_b128 v[74:77], v72 offset:64
	s_waitcnt lgkmcnt(0)
	v_pk_mul_f32 v[74:75], v[74:75], v[88:89] op_sel_hi:[1,0]
	v_pk_mul_f32 v[76:77], v[76:77], v[88:89] op_sel_hi:[1,0]
	v_add_u32_e32 v88, s8, v73
	v_cvt_pk_bf16_f32 v74, v74, v75
	v_cvt_pk_bf16_f32 v75, v76, v77
	v_ashrrev_i32_e32 v89, 31, v88
	global_store_dwordx2 v[78:79], v[74:75], off offset:32
	v_lshl_add_u64 v[76:77], v[88:89], 4, s[46:47]
	v_mad_u64_u32 v[74:75], s[10:11], v73, s9, v[0:1]
	v_mad_i64_i32 v[88:89], s[10:11], v88, s12, v[66:67]
	v_add_f32_e32 v75, v156, v157
	v_add_f32_e32 v75, v75, v158
	v_add_f32_e32 v75, v75, v159
	v_fmamk_f32 v75, v75, 0x3a800000, v200
	v_cmp_gt_f32_e32 vcc, s7, v75
	v_mul_f32_e32 v76, 0x4b800000, v75
	s_nop 0
	v_cndmask_b32_e32 v75, v75, v76, vcc
	v_rsq_f32_e32 v75, v75
	s_nop 0
	v_mul_f32_e32 v76, 0x45800000, v75
	v_cndmask_b32_e32 v92, v75, v76, vcc
	ds_read_b128 v[76:79], v74
	v_add_u32_e32 v75, 0xc00, v142
	v_ashrrev_i32_e32 v75, 5, v75
	s_waitcnt lgkmcnt(0)
	v_pk_mul_f32 v[76:77], v[76:77], v[92:93] op_sel_hi:[1,0]
	v_pk_mul_f32 v[78:79], v[78:79], v[92:93] op_sel_hi:[1,0]
	v_cvt_pk_bf16_f32 v76, v76, v77
	v_cvt_pk_bf16_f32 v77, v78, v79
	global_store_dwordx2 v[88:89], v[76:77], off
	ds_read_b128 v[76:79], v74 offset:64
	s_waitcnt lgkmcnt(0)
	v_pk_mul_f32 v[76:77], v[76:77], v[92:93] op_sel_hi:[1,0]
	v_pk_mul_f32 v[78:79], v[78:79], v[92:93] op_sel_hi:[1,0]
	v_cvt_pk_bf16_f32 v76, v76, v77
	v_cvt_pk_bf16_f32 v77, v78, v79
	v_add_u32_e32 v78, s8, v75
	v_ashrrev_i32_e32 v79, 31, v78
	global_store_dwordx2 v[88:89], v[76:77], off offset:32
	v_lshl_add_u64 v[88:89], v[78:79], 4, s[46:47]
	v_mad_u64_u32 v[76:77], s[10:11], v75, s9, v[0:1]
	v_add_f32_e32 v77, v160, v161
	v_add_f32_e32 v77, v77, v162
	v_add_f32_e32 v77, v77, v163
	v_fmamk_f32 v77, v77, 0x3a800000, v200
	v_cmp_gt_f32_e32 vcc, s7, v77
	v_mul_f32_e32 v79, 0x4b800000, v77
	ds_read_b128 v[98:101], v76
	v_cndmask_b32_e32 v77, v77, v79, vcc
	v_rsq_f32_e32 v77, v77
	s_nop 0
	v_mul_f32_e32 v79, 0x45800000, v77
	v_cndmask_b32_e32 v88, v77, v79, vcc
	s_waitcnt lgkmcnt(0)
	v_pk_mul_f32 v[92:93], v[98:99], v[88:89] op_sel_hi:[1,0]
	v_pk_mul_f32 v[98:99], v[100:101], v[88:89] op_sel_hi:[1,0]
	v_cvt_pk_bf16_f32 v92, v92, v93
	v_cvt_pk_bf16_f32 v93, v98, v99
	ds_read_b128 v[98:101], v76 offset:64
	v_mad_i64_i32 v[78:79], s[10:11], v78, s12, v[66:67]
	v_add_u32_e32 v77, 0xe00, v142
	global_store_dwordx2 v[78:79], v[92:93], off
	s_waitcnt lgkmcnt(0)
	v_pk_mul_f32 v[92:93], v[98:99], v[88:89] op_sel_hi:[1,0]
	v_pk_mul_f32 v[88:89], v[100:101], v[88:89] op_sel_hi:[1,0]
	v_ashrrev_i32_e32 v77, 5, v77
	v_cvt_pk_bf16_f32 v92, v92, v93
	v_cvt_pk_bf16_f32 v93, v88, v89
	v_add_u32_e32 v88, s8, v77
	v_ashrrev_i32_e32 v89, 31, v88
	global_store_dwordx2 v[78:79], v[92:93], off offset:32
	v_lshl_add_u64 v[92:93], v[88:89], 4, s[46:47]
	v_mad_u64_u32 v[78:79], s[10:11], v77, s9, v[0:1]
	v_mad_i64_i32 v[88:89], s[8:9], v88, s12, v[66:67]
	v_add_f32_e32 v0, v164, v165
	v_add_f32_e32 v0, v0, v166
	v_add_f32_e32 v0, v0, v167
	v_fmamk_f32 v0, v0, 0x3a800000, v200
	v_cmp_gt_f32_e32 vcc, s7, v0
	v_mul_f32_e32 v79, 0x4b800000, v0
	ds_read_b128 v[98:101], v78
	v_cndmask_b32_e32 v0, v0, v79, vcc
	v_rsq_f32_e32 v0, v0
	s_nop 0
	v_mul_f32_e32 v79, 0x45800000, v0
	v_cndmask_b32_e32 v0, v0, v79, vcc
	s_waitcnt lgkmcnt(0)
	v_pk_mul_f32 v[92:93], v[98:99], v[0:1] op_sel_hi:[1,0]
	v_pk_mul_f32 v[98:99], v[100:101], v[0:1] op_sel_hi:[1,0]
	v_cvt_pk_bf16_f32 v92, v92, v93
	v_cvt_pk_bf16_f32 v93, v98, v99
	ds_read_b128 v[98:101], v78 offset:64
	global_store_dwordx2 v[88:89], v[92:93], off
	s_waitcnt lgkmcnt(0)
	v_pk_mul_f32 v[92:93], v[98:99], v[0:1] op_sel_hi:[1,0]
	v_pk_mul_f32 v[98:99], v[100:101], v[0:1] op_sel_hi:[1,0]
	v_cvt_pk_bf16_f32 v92, v92, v93
	v_cvt_pk_bf16_f32 v93, v98, v99
	global_store_dwordx2 v[88:89], v[92:93], off offset:32
	s_barrier
	ds_write2_b32 v130, v2, v18 offset1:16
	ds_write2_b32 v114, v3, v19 offset0:4 offset1:20
	ds_write2_b32 v115, v4, v20 offset0:8 offset1:24
	ds_write2_b32 v116, v5, v21 offset0:12 offset1:28
	ds_write2_b32 v117, v6, v22 offset0:64 offset1:80
	ds_write2_b32 v94, v7, v23 offset0:68 offset1:84
	ds_write2_b32 v95, v8, v24 offset0:72 offset1:88
	ds_write2_b32 v96, v9, v25 offset0:76 offset1:92
	ds_write2_b32 v131, v10, v26 offset0:128 offset1:144
	ds_write2_b32 v85, v11, v27 offset0:132 offset1:148
	ds_write2_b32 v97, v12, v28 offset0:136 offset1:152
	ds_write2_b32 v126, v13, v29 offset0:140 offset1:156
	ds_write2_b32 v132, v14, v30 offset0:192 offset1:208
	ds_write2_b32 v127, v15, v31 offset0:196 offset1:212
	ds_write2_b32 v128, v16, v32 offset0:200 offset1:216
	ds_write2_b32 v129, v17, v33 offset0:204 offset1:220
	ds_write2_b32 v130, v34, v50 offset0:128 offset1:144
	ds_write2_b32 v114, v35, v51 offset0:132 offset1:148
	ds_write2_b32 v115, v36, v52 offset0:136 offset1:152
	ds_write2_b32 v116, v37, v53 offset0:140 offset1:156
	ds_write2_b32 v117, v38, v54 offset0:192 offset1:208
	ds_write2_b32 v94, v39, v55 offset0:196 offset1:212
	ds_write2_b32 v95, v40, v56 offset0:200 offset1:216
	ds_write2_b32 v96, v41, v57 offset0:204 offset1:220
	ds_write2_b32 v85, v42, v58 offset1:16
	ds_write2_b32 v97, v43, v59 offset0:4 offset1:20
	ds_write2_b32 v126, v44, v60 offset0:8 offset1:24
	ds_write2_b32 v90, v45, v61 offset0:12 offset1:28
	ds_write2_b32 v127, v46, v62 offset0:64 offset1:80
	ds_write2_b32 v128, v47, v63 offset0:68 offset1:84
	ds_write2_b32 v129, v48, v64 offset0:72 offset1:88
	ds_write2_b32 v86, v49, v65 offset0:76 offset1:92
	v_add_u32_e32 v2, s6, v84
	v_ashrrev_i32_e32 v3, 31, v2
	v_lshl_add_u64 v[4:5], v[2:3], 4, s[46:47]
	s_waitcnt lgkmcnt(0)
	s_barrier
	global_load_dwordx4 v[134:137], v[4:5], off
	global_load_dwordx4 v[138:141], v[4:5], off offset:256
	global_load_dwordx4 v[144:147], v[4:5], off offset:512
	global_load_dwordx4 v[148:151], v[4:5], off offset:768
	global_load_dwordx4 v[152:155], v[4:5], off offset:1024
	global_load_dwordx4 v[156:159], v[4:5], off offset:1280
	global_load_dwordx4 v[160:163], v[4:5], off offset:1536
	global_load_dwordx4 v[164:167], v[4:5], off offset:1792
	s_waitcnt vmcnt(0)
	v_add_f32_e32 v0, v134, v135
	v_add_f32_e32 v0, v0, v136
	v_add_f32_e32 v0, v0, v137
	v_fmamk_f32 v0, v0, 0x3a800000, v200
	v_cmp_gt_f32_e32 vcc, s7, v0
	v_mul_f32_e32 v3, 0x4b800000, v0
	ds_read_b128 v[4:7], v82
	v_cndmask_b32_e32 v0, v0, v3, vcc
	v_rsq_f32_e32 v0, v0
	s_nop 0
	v_mul_f32_e32 v3, 0x45800000, v0
	v_cndmask_b32_e32 v0, v0, v3, vcc
	s_waitcnt lgkmcnt(0)
	v_pk_mul_f32 v[4:5], v[4:5], v[0:1] op_sel_hi:[1,0]
	v_pk_mul_f32 v[6:7], v[6:7], v[0:1] op_sel_hi:[1,0]
	v_cvt_pk_bf16_f32 v4, v4, v5
	v_cvt_pk_bf16_f32 v5, v6, v7
	v_mad_i64_i32 v[6:7], s[8:9], v2, s12, v[66:67]
	global_store_dwordx2 v[6:7], v[4:5], off
	ds_read_b128 v[2:5], v82 offset:64
	s_waitcnt lgkmcnt(0)
	v_pk_mul_f32 v[2:3], v[2:3], v[0:1] op_sel_hi:[1,0]
	v_pk_mul_f32 v[4:5], v[4:5], v[0:1] op_sel_hi:[1,0]
	v_cvt_pk_bf16_f32 v2, v2, v3
	v_cvt_pk_bf16_f32 v3, v4, v5
	global_store_dwordx2 v[6:7], v[2:3], off offset:32
	v_add_u32_e32 v6, s6, v83
	v_ashrrev_i32_e32 v7, 31, v6
	v_lshl_add_u64 v[2:3], v[6:7], 4, s[46:47]
	v_mad_i64_i32 v[6:7], s[8:9], v6, s12, v[66:67]
	v_add_f32_e32 v0, v138, v139
	v_add_f32_e32 v0, v0, v140
	v_add_f32_e32 v0, v0, v141
	v_fmamk_f32 v0, v0, 0x3a800000, v200
	v_cmp_gt_f32_e32 vcc, s7, v0
	v_mul_f32_e32 v2, 0x4b800000, v0
	s_nop 0
	v_cndmask_b32_e32 v0, v0, v2, vcc
	v_rsq_f32_e32 v0, v0
	s_nop 0
	v_mul_f32_e32 v2, 0x45800000, v0
	v_cndmask_b32_e32 v0, v0, v2, vcc
	ds_read_b128 v[2:5], v80
	s_waitcnt lgkmcnt(0)
	v_pk_mul_f32 v[2:3], v[2:3], v[0:1] op_sel_hi:[1,0]
	v_pk_mul_f32 v[4:5], v[4:5], v[0:1] op_sel_hi:[1,0]
	v_cvt_pk_bf16_f32 v2, v2, v3
	v_cvt_pk_bf16_f32 v3, v4, v5
	global_store_dwordx2 v[6:7], v[2:3], off
	ds_read_b128 v[2:5], v80 offset:64
	s_waitcnt lgkmcnt(0)
	v_pk_mul_f32 v[2:3], v[2:3], v[0:1] op_sel_hi:[1,0]
	v_pk_mul_f32 v[4:5], v[4:5], v[0:1] op_sel_hi:[1,0]
	v_cvt_pk_bf16_f32 v2, v2, v3
	v_cvt_pk_bf16_f32 v3, v4, v5
	global_store_dwordx2 v[6:7], v[2:3], off offset:32
	v_add_u32_e32 v6, s6, v81
	v_ashrrev_i32_e32 v7, 31, v6
	v_lshl_add_u64 v[2:3], v[6:7], 4, s[46:47]
	v_mad_i64_i32 v[6:7], s[8:9], v6, s12, v[66:67]
	v_add_f32_e32 v0, v144, v145
	v_add_f32_e32 v0, v0, v146
	v_add_f32_e32 v0, v0, v147
	v_fmamk_f32 v0, v0, 0x3a800000, v200
	v_cmp_gt_f32_e32 vcc, s7, v0
	v_mul_f32_e32 v2, 0x4b800000, v0
	s_nop 0
	v_cndmask_b32_e32 v0, v0, v2, vcc
	v_rsq_f32_e32 v0, v0
	s_nop 0
	v_mul_f32_e32 v2, 0x45800000, v0
	v_cndmask_b32_e32 v0, v0, v2, vcc
	ds_read_b128 v[2:5], v68
	s_waitcnt lgkmcnt(0)
	v_pk_mul_f32 v[2:3], v[2:3], v[0:1] op_sel_hi:[1,0]
	v_pk_mul_f32 v[4:5], v[4:5], v[0:1] op_sel_hi:[1,0]
	v_cvt_pk_bf16_f32 v2, v2, v3
	v_cvt_pk_bf16_f32 v3, v4, v5
	global_store_dwordx2 v[6:7], v[2:3], off
	ds_read_b128 v[2:5], v68 offset:64
	s_waitcnt lgkmcnt(0)
	v_pk_mul_f32 v[2:3], v[2:3], v[0:1] op_sel_hi:[1,0]
	v_pk_mul_f32 v[4:5], v[4:5], v[0:1] op_sel_hi:[1,0]
	v_cvt_pk_bf16_f32 v2, v2, v3
	v_cvt_pk_bf16_f32 v3, v4, v5
	global_store_dwordx2 v[6:7], v[2:3], off offset:32
	v_add_u32_e32 v6, s6, v69
	v_ashrrev_i32_e32 v7, 31, v6
	v_lshl_add_u64 v[2:3], v[6:7], 4, s[46:47]
	v_mad_i64_i32 v[6:7], s[8:9], v6, s12, v[66:67]
	v_add_f32_e32 v0, v148, v149
	v_add_f32_e32 v0, v0, v150
	v_add_f32_e32 v0, v0, v151
	v_fmamk_f32 v0, v0, 0x3a800000, v200
	v_cmp_gt_f32_e32 vcc, s7, v0
	v_mul_f32_e32 v2, 0x4b800000, v0
	s_nop 0
	v_cndmask_b32_e32 v0, v0, v2, vcc
	v_rsq_f32_e32 v0, v0
	s_nop 0
	v_mul_f32_e32 v2, 0x45800000, v0
	v_cndmask_b32_e32 v0, v0, v2, vcc
	ds_read_b128 v[2:5], v70
	s_waitcnt lgkmcnt(0)
	v_pk_mul_f32 v[2:3], v[2:3], v[0:1] op_sel_hi:[1,0]
	v_pk_mul_f32 v[4:5], v[4:5], v[0:1] op_sel_hi:[1,0]
	v_cvt_pk_bf16_f32 v2, v2, v3
	v_cvt_pk_bf16_f32 v3, v4, v5
	global_store_dwordx2 v[6:7], v[2:3], off
	ds_read_b128 v[2:5], v70 offset:64
	s_waitcnt lgkmcnt(0)
	v_pk_mul_f32 v[2:3], v[2:3], v[0:1] op_sel_hi:[1,0]
	v_pk_mul_f32 v[4:5], v[4:5], v[0:1] op_sel_hi:[1,0]
	v_cvt_pk_bf16_f32 v2, v2, v3
	v_cvt_pk_bf16_f32 v3, v4, v5
	global_store_dwordx2 v[6:7], v[2:3], off offset:32
	v_add_u32_e32 v6, s6, v71
	v_ashrrev_i32_e32 v7, 31, v6
	v_lshl_add_u64 v[2:3], v[6:7], 4, s[46:47]
	v_mad_i64_i32 v[6:7], s[8:9], v6, s12, v[66:67]
	v_add_f32_e32 v0, v152, v153
	v_add_f32_e32 v0, v0, v154
	v_add_f32_e32 v0, v0, v155
	v_fmamk_f32 v0, v0, 0x3a800000, v200
	v_cmp_gt_f32_e32 vcc, s7, v0
	v_mul_f32_e32 v2, 0x4b800000, v0
	s_nop 0
	v_cndmask_b32_e32 v0, v0, v2, vcc
	v_rsq_f32_e32 v0, v0
	s_nop 0
	v_mul_f32_e32 v2, 0x45800000, v0
	v_cndmask_b32_e32 v0, v0, v2, vcc
	ds_read_b128 v[2:5], v72
	s_waitcnt lgkmcnt(0)
	v_pk_mul_f32 v[2:3], v[2:3], v[0:1] op_sel_hi:[1,0]
	v_pk_mul_f32 v[4:5], v[4:5], v[0:1] op_sel_hi:[1,0]
	v_cvt_pk_bf16_f32 v2, v2, v3
	v_cvt_pk_bf16_f32 v3, v4, v5
	global_store_dwordx2 v[6:7], v[2:3], off
	ds_read_b128 v[2:5], v72 offset:64
	s_waitcnt lgkmcnt(0)
	v_pk_mul_f32 v[2:3], v[2:3], v[0:1] op_sel_hi:[1,0]
	v_pk_mul_f32 v[4:5], v[4:5], v[0:1] op_sel_hi:[1,0]
	v_cvt_pk_bf16_f32 v2, v2, v3
	v_cvt_pk_bf16_f32 v3, v4, v5
	global_store_dwordx2 v[6:7], v[2:3], off offset:32
	v_add_u32_e32 v6, s6, v73
	v_ashrrev_i32_e32 v7, 31, v6
	v_lshl_add_u64 v[2:3], v[6:7], 4, s[46:47]
	v_mad_i64_i32 v[6:7], s[8:9], v6, s12, v[66:67]
	v_add_f32_e32 v0, v156, v157
	v_add_f32_e32 v0, v0, v158
	v_add_f32_e32 v0, v0, v159
	v_fmamk_f32 v0, v0, 0x3a800000, v200
	v_cmp_gt_f32_e32 vcc, s7, v0
	v_mul_f32_e32 v2, 0x4b800000, v0
	s_nop 0
	v_cndmask_b32_e32 v0, v0, v2, vcc
	v_rsq_f32_e32 v0, v0
	s_nop 0
	v_mul_f32_e32 v2, 0x45800000, v0
	v_cndmask_b32_e32 v0, v0, v2, vcc
	ds_read_b128 v[2:5], v74
	s_waitcnt lgkmcnt(0)
	v_pk_mul_f32 v[2:3], v[2:3], v[0:1] op_sel_hi:[1,0]
	v_pk_mul_f32 v[4:5], v[4:5], v[0:1] op_sel_hi:[1,0]
	v_cvt_pk_bf16_f32 v2, v2, v3
	v_cvt_pk_bf16_f32 v3, v4, v5
	global_store_dwordx2 v[6:7], v[2:3], off
	ds_read_b128 v[2:5], v74 offset:64
	s_waitcnt lgkmcnt(0)
	v_pk_mul_f32 v[2:3], v[2:3], v[0:1] op_sel_hi:[1,0]
	v_pk_mul_f32 v[4:5], v[4:5], v[0:1] op_sel_hi:[1,0]
	v_cvt_pk_bf16_f32 v2, v2, v3
	v_cvt_pk_bf16_f32 v3, v4, v5
	global_store_dwordx2 v[6:7], v[2:3], off offset:32
	v_add_u32_e32 v6, s6, v75
	v_ashrrev_i32_e32 v7, 31, v6
	v_lshl_add_u64 v[2:3], v[6:7], 4, s[46:47]
	v_mad_i64_i32 v[6:7], s[8:9], v6, s12, v[66:67]
	v_add_f32_e32 v0, v160, v161
	v_add_f32_e32 v0, v0, v162
	v_add_f32_e32 v0, v0, v163
	v_fmamk_f32 v0, v0, 0x3a800000, v200
	v_cmp_gt_f32_e32 vcc, s7, v0
	v_mul_f32_e32 v2, 0x4b800000, v0
	s_nop 0
	v_cndmask_b32_e32 v0, v0, v2, vcc
	v_rsq_f32_e32 v0, v0
	s_nop 0
	v_mul_f32_e32 v2, 0x45800000, v0
	v_cndmask_b32_e32 v0, v0, v2, vcc
	ds_read_b128 v[2:5], v76
	s_waitcnt lgkmcnt(0)
	v_pk_mul_f32 v[2:3], v[2:3], v[0:1] op_sel_hi:[1,0]
	v_pk_mul_f32 v[4:5], v[4:5], v[0:1] op_sel_hi:[1,0]
	v_cvt_pk_bf16_f32 v2, v2, v3
	v_cvt_pk_bf16_f32 v3, v4, v5
	global_store_dwordx2 v[6:7], v[2:3], off
	ds_read_b128 v[2:5], v76 offset:64
	s_waitcnt lgkmcnt(0)
	v_pk_mul_f32 v[2:3], v[2:3], v[0:1] op_sel_hi:[1,0]
	v_pk_mul_f32 v[4:5], v[4:5], v[0:1] op_sel_hi:[1,0]
	v_cvt_pk_bf16_f32 v2, v2, v3
	v_cvt_pk_bf16_f32 v3, v4, v5
	global_store_dwordx2 v[6:7], v[2:3], off offset:32
	v_add_u32_e32 v6, s6, v77
	v_ashrrev_i32_e32 v7, 31, v6
	v_lshl_add_u64 v[2:3], v[6:7], 4, s[46:47]
	v_add_f32_e32 v0, v164, v165
	v_add_f32_e32 v0, v0, v166
	v_add_f32_e32 v0, v0, v167
	v_fmamk_f32 v0, v0, 0x3a800000, v200
	v_cmp_gt_f32_e32 vcc, s7, v0
	v_mul_f32_e32 v2, 0x4b800000, v0
	v_mad_i64_i32 v[6:7], s[6:7], v6, s12, v[66:67]
	v_cndmask_b32_e32 v0, v0, v2, vcc
	v_rsq_f32_e32 v0, v0
	s_nop 0
	v_mul_f32_e32 v2, 0x45800000, v0
	v_cndmask_b32_e32 v0, v0, v2, vcc
	ds_read_b128 v[2:5], v78
	s_waitcnt lgkmcnt(0)
	v_pk_mul_f32 v[2:3], v[2:3], v[0:1] op_sel_hi:[1,0]
	v_pk_mul_f32 v[4:5], v[4:5], v[0:1] op_sel_hi:[1,0]
	v_cvt_pk_bf16_f32 v2, v2, v3
	v_cvt_pk_bf16_f32 v3, v4, v5
	global_store_dwordx2 v[6:7], v[2:3], off
	ds_read_b128 v[2:5], v78 offset:64
	s_waitcnt lgkmcnt(0)
	v_pk_mul_f32 v[2:3], v[2:3], v[0:1] op_sel_hi:[1,0]
	v_pk_mul_f32 v[4:5], v[4:5], v[0:1] op_sel_hi:[1,0]
	v_cvt_pk_bf16_f32 v2, v2, v3
	v_cvt_pk_bf16_f32 v3, v4, v5
	global_store_dwordx2 v[6:7], v[2:3], off offset:32
	s_barrier
	s_branch .LBB0_387

.LBB0_1017:
	s_ashr_i32 s14, s17, 31
	s_lshr_b32 s14, s14, 27
	s_add_i32 s15, s17, s14
	s_ashr_i32 s14, s15, 5
	s_ashr_i32 s24, s15, 6
	s_lshl_b32 s22, s14, 6
	s_lshl_b32 s14, s14, 11
	s_ashr_i32 s25, s24, 31
	s_sub_i32 s14, s16, s14
	s_lshl_b64 s[24:25], s[24:25], 20
	v_and_or_b32 v0, s22, 64, v8
	s_add_u32 s24, s28, s24
	v_add_u32_e32 v12, s14, v3
	s_addc_u32 s25, s29, s25
	v_lshlrev_b32_e32 v0, 2, v0
	v_ashrrev_i32_e32 v13, 31, v12
	v_lshl_add_u64 v[6:7], s[24:25], 0, v[0:1]
	v_lshlrev_b64 v[16:17], 9, v[12:13]
	v_lshl_add_u64 v[16:17], v[6:7], 0, v[16:17]
	s_barrier
	global_load_dword v100, v[16:17], off
	v_add_u32_e32 v16, 8, v12
	v_ashrrev_i32_e32 v17, 31, v16
	v_lshlrev_b64 v[16:17], 9, v[16:17]
	v_lshl_add_u64 v[16:17], v[6:7], 0, v[16:17]
	s_ashr_i32 s15, s14, 31
	s_addk_i32 s16, 0x3800
	global_load_dword v101, v[16:17], off
	v_add_u32_e32 v16, 16, v12
	v_ashrrev_i32_e32 v17, 31, v16
	v_lshlrev_b64 v[16:17], 9, v[16:17]
	v_lshl_add_u64 v[16:17], v[6:7], 0, v[16:17]
	global_load_dword v102, v[16:17], off
	v_add_u32_e32 v16, 24, v12
	v_ashrrev_i32_e32 v17, 31, v16
	v_lshlrev_b64 v[16:17], 9, v[16:17]
	v_lshl_add_u64 v[16:17], v[6:7], 0, v[16:17]
	global_load_dword v103, v[16:17], off
	v_add_u32_e32 v16, 32, v12
	v_ashrrev_i32_e32 v17, 31, v16
	v_lshlrev_b64 v[16:17], 9, v[16:17]
	v_lshl_add_u64 v[16:17], v[6:7], 0, v[16:17]
	global_load_dword v104, v[16:17], off
	v_add_u32_e32 v16, 40, v12
	v_ashrrev_i32_e32 v17, 31, v16
	v_lshlrev_b64 v[16:17], 9, v[16:17]
	v_lshl_add_u64 v[16:17], v[6:7], 0, v[16:17]
	global_load_dword v105, v[16:17], off
	v_add_u32_e32 v16, 48, v12
	v_ashrrev_i32_e32 v17, 31, v16
	v_lshlrev_b64 v[16:17], 9, v[16:17]
	v_lshl_add_u64 v[16:17], v[6:7], 0, v[16:17]
	v_add_u32_e32 v12, 56, v12
	v_ashrrev_i32_e32 v13, 31, v12
	v_lshlrev_b64 v[12:13], 9, v[12:13]
	v_lshl_add_u64 v[6:7], v[6:7], 0, v[12:13]
	global_load_dword v106, v[16:17], off
	global_load_dword v107, v[6:7], off
	v_lshl_add_u64 v[6:7], s[14:15], 1, v[4:5]
	s_waitcnt vmcnt(7)
	ds_write_b32 v11, v100
	s_waitcnt vmcnt(6)
	ds_write_b32 v11, v101 offset:2080
	s_waitcnt vmcnt(5)
	ds_write_b32 v11, v102 offset:4160
	s_waitcnt vmcnt(4)
	ds_write_b32 v11, v103 offset:6240
	s_waitcnt vmcnt(3)
	ds_write_b32 v11, v104 offset:8320
	s_waitcnt vmcnt(2)
	ds_write_b32 v11, v105 offset:10400
	s_waitcnt vmcnt(1)
	ds_write_b32 v11, v106 offset:12480
	s_waitcnt vmcnt(0)
	ds_write_b32 v11, v107 offset:14560
	s_waitcnt lgkmcnt(0)
	s_barrier
	ds_read2_b32 v[12:13], v10 offset1:32
	ds_read2_b32 v[16:17], v10 offset0:65 offset1:97
	ds_read2_b32 v[20:21], v10 offset0:130 offset1:162
	ds_read2_b32 v[22:23], v10 offset0:195 offset1:227
	v_add_u32_e32 v0, s22, v9
	v_mad_i64_i32 v[24:25], s[14:15], v0, s20, v[6:7]
	v_add_u32_e32 v0, 32, v0
	v_mad_i64_i32 v[6:7], s[14:15], v0, s20, v[6:7]
	s_add_i32 s14, s17, 0xe0
	s_waitcnt lgkmcnt(2)
	v_cvt_pk_bf16_f32 v18, v12, v16
	s_waitcnt lgkmcnt(0)
	v_cvt_pk_bf16_f32 v19, v20, v22
	v_cvt_pk_bf16_f32 v12, v13, v17
	v_cvt_pk_bf16_f32 v13, v21, v23
	s_cmpk_lt_i32 s17, 0x720
	s_mov_b32 s17, s14
	global_store_dwordx2 v[24:25], v[18:19], off
	global_store_dwordx2 v[6:7], v[12:13], off
	s_cbranch_scc1 .LBB0_1017

.LBB0_1028:
	s_ashr_i32 s12, s14, 31
	s_lshr_b32 s12, s12, 30
	s_add_i32 s12, s14, s12
	s_ashr_i32 s13, s12, 2
	s_lshl_b32 s15, s13, 6
	s_lshl_b32 s22, s13, 8
	s_lshl_b32 s13, s13, 4
	s_and_b32 s16, s15, 0xc0
	s_sub_i32 s12, s7, s22
	s_and_b32 s13, s13, 0xffffff00
	v_or_b32_e32 v0, s16, v7
	s_and_b32 s16, s22, 0xc00
	s_add_u32 s16, s20, s16
	s_addc_u32 s17, s21, 0
	s_sub_i32 s13, s13, s22
	s_add_i32 s13, s13, s7
	v_add_u32_e32 v12, s13, v6
	v_lshlrev_b32_e32 v0, 2, v0
	v_ashrrev_i32_e32 v13, 31, v12
	v_lshl_add_u64 v[4:5], s[16:17], 0, v[0:1]
	v_lshlrev_b64 v[14:15], 12, v[12:13]
	v_lshl_add_u64 v[14:15], v[4:5], 0, v[14:15]
	s_barrier
	global_load_dword v100, v[14:15], off
	v_add_u32_e32 v14, 8, v12
	v_ashrrev_i32_e32 v15, 31, v14
	v_lshlrev_b64 v[14:15], 12, v[14:15]
	v_lshl_add_u64 v[14:15], v[4:5], 0, v[14:15]
	v_add_u32_e32 v22, s15, v8
	s_ashr_i32 s13, s12, 31
	v_ashrrev_i32_e32 v23, 31, v22
	v_lshlrev_b64 v[24:25], 9, v[22:23]
	s_addk_i32 s7, 0x3800
	global_load_dword v101, v[14:15], off
	v_add_u32_e32 v14, 16, v12
	v_ashrrev_i32_e32 v15, 31, v14
	v_lshlrev_b64 v[14:15], 12, v[14:15]
	v_lshl_add_u64 v[14:15], v[4:5], 0, v[14:15]
	global_load_dword v102, v[14:15], off
	v_add_u32_e32 v14, 24, v12
	v_ashrrev_i32_e32 v15, 31, v14
	v_lshlrev_b64 v[14:15], 12, v[14:15]
	v_lshl_add_u64 v[14:15], v[4:5], 0, v[14:15]
	global_load_dword v103, v[14:15], off
	v_add_u32_e32 v14, 32, v12
	v_ashrrev_i32_e32 v15, 31, v14
	v_lshlrev_b64 v[14:15], 12, v[14:15]
	v_lshl_add_u64 v[14:15], v[4:5], 0, v[14:15]
	global_load_dword v104, v[14:15], off
	v_add_u32_e32 v14, 40, v12
	v_ashrrev_i32_e32 v15, 31, v14
	v_lshlrev_b64 v[14:15], 12, v[14:15]
	v_lshl_add_u64 v[14:15], v[4:5], 0, v[14:15]
	global_load_dword v105, v[14:15], off
	v_add_u32_e32 v14, 48, v12
	v_ashrrev_i32_e32 v15, 31, v14
	v_lshlrev_b64 v[14:15], 12, v[14:15]
	v_lshl_add_u64 v[14:15], v[4:5], 0, v[14:15]
	v_add_u32_e32 v12, 56, v12
	v_ashrrev_i32_e32 v13, 31, v12
	v_lshlrev_b64 v[12:13], 12, v[12:13]
	v_lshl_add_u64 v[4:5], v[4:5], 0, v[12:13]
	global_load_dword v106, v[14:15], off
	global_load_dword v107, v[4:5], off
	v_lshl_add_u64 v[4:5], s[12:13], 1, v[2:3]
	s_add_i32 s12, s14, 0xe0
	v_lshl_add_u64 v[24:25], v[4:5], 0, v[24:25]
	s_cmpk_gt_i32 s14, 0x71f
	s_mov_b32 s14, s12
	s_waitcnt vmcnt(7)
	ds_write_b32 v10, v100
	s_waitcnt vmcnt(6)
	ds_write_b32 v10, v101 offset:2080
	s_waitcnt vmcnt(5)
	ds_write_b32 v10, v102 offset:4160
	s_waitcnt vmcnt(4)
	ds_write_b32 v10, v103 offset:6240
	s_waitcnt vmcnt(3)
	ds_write_b32 v10, v104 offset:8320
	s_waitcnt vmcnt(2)
	ds_write_b32 v10, v105 offset:10400
	s_waitcnt vmcnt(1)
	ds_write_b32 v10, v106 offset:12480
	s_waitcnt vmcnt(0)
	ds_write_b32 v10, v107 offset:14560
	s_waitcnt lgkmcnt(0)
	s_barrier
	ds_read2_b32 v[12:13], v9 offset1:32
	ds_read2_b32 v[14:15], v9 offset0:65 offset1:97
	ds_read2_b32 v[18:19], v9 offset0:130 offset1:162
	ds_read2_b32 v[20:21], v9 offset0:195 offset1:227
	s_waitcnt lgkmcnt(2)
	v_cvt_pk_bf16_f32 v16, v12, v14
	v_add_u32_e32 v14, 32, v22
	v_cvt_pk_bf16_f32 v12, v13, v15
	v_ashrrev_i32_e32 v15, 31, v14
	v_lshlrev_b64 v[14:15], 9, v[14:15]
	s_waitcnt lgkmcnt(0)
	v_cvt_pk_bf16_f32 v17, v18, v20
	v_cvt_pk_bf16_f32 v13, v19, v21
	v_lshl_add_u64 v[4:5], v[4:5], 0, v[14:15]
	global_store_dwordx2 v[24:25], v[16:17], off
	global_store_dwordx2 v[4:5], v[12:13], off
	s_cbranch_scc0 .LBB0_1028

.LBB0_1078:
	s_or_b64 exec, exec, s[42:43]
	s_movk_i32 s33, 0x410
	v_lshrrev_b32_e32 v130, 2, v142
	v_lshlrev_b32_e32 v131, 1, v142
	v_and_b32_e32 v0, 15, v142
	v_and_b32_e32 v130, 0xfffffcc, v130
	v_and_b32_e32 v131, 0x180, v131
	v_add_u32_e32 v131, 0, v131
	v_lshlrev_b32_e32 v0, 2, v0
	v_mul_lo_u32 v130, v130, s33
	v_add3_u32 v130, v131, v0, v130
	s_waitcnt vmcnt(0)
	s_barrier
	ds_write2_b32 v130, v114, v126 offset1:16
	v_add_u32_e32 v114, 0x400, v130
	ds_write2_b32 v114, v115, v127 offset0:4 offset1:20
	v_add_u32_e32 v115, 0x800, v130
	ds_write2_b32 v115, v116, v128 offset0:8 offset1:24
	v_add_u32_e32 v116, 0xc00, v130
	ds_write2_b32 v116, v117, v129 offset0:12 offset1:28
	v_add_u32_e32 v117, 0x4000, v130
	ds_write2_b32 v117, v82, v94 offset0:64 offset1:80
	v_add_u32_e32 v94, 0x4400, v130
	ds_write2_b32 v94, v83, v95 offset0:68 offset1:84
	v_add_u32_e32 v95, 0x4800, v130
	ds_write2_b32 v95, v84, v96 offset0:72 offset1:88
	v_add_u32_e32 v96, 0x4c00, v130
	v_add_u32_e32 v133, 0xc000, v130
	ds_write2_b32 v96, v85, v97 offset0:76 offset1:92
	v_add_u32_e32 v132, 0x8000, v130
	v_add_u32_e32 v97, 0x8400, v130
	v_add_u32_e32 v126, 0x8800, v130
	v_add_u32_e32 v127, 0x8c00, v130
	ds_write2_b32 v133, v66, v70 offset0:192 offset1:208
	v_add_u32_e32 v128, 0xc400, v130
	v_add_u32_e32 v129, 0xc800, v130
	v_add_u32_e32 v131, 0xcc00, v130
	v_lshlrev_b32_e32 v0, 3, v142
	v_lshlrev_b32_e32 v66, 2, v142
	ds_write2_b32 v132, v74, v78 offset0:128 offset1:144
	ds_write2_b32 v97, v75, v79 offset0:132 offset1:148
	ds_write2_b32 v126, v76, v80 offset0:136 offset1:152
	ds_write2_b32 v127, v77, v81 offset0:140 offset1:156
	ds_write2_b32 v128, v67, v71 offset0:196 offset1:212
	ds_write2_b32 v129, v68, v72 offset0:200 offset1:216
	ds_write2_b32 v131, v69, v73 offset0:204 offset1:220
	ds_write2_b32 v130, v98, v118 offset0:128 offset1:144
	ds_write2_b32 v114, v99, v119 offset0:132 offset1:148
	ds_write2_b32 v115, v100, v120 offset0:136 offset1:152
	ds_write2_b32 v116, v101, v121 offset0:140 offset1:156
	ds_write2_b32 v117, v102, v122 offset0:192 offset1:208
	ds_write2_b32 v94, v103, v123 offset0:196 offset1:212
	ds_write2_b32 v95, v104, v124 offset0:200 offset1:216
	ds_write2_b32 v96, v105, v125 offset0:204 offset1:220
	ds_write2_b32 v97, v90, v110 offset1:16
	ds_write2_b32 v126, v91, v111 offset0:4 offset1:20
	ds_write2_b32 v127, v92, v112 offset0:8 offset1:24
	v_add_u32_e32 v90, 0x9000, v130
	v_and_b32_e32 v0, 0xe0, v0
	v_and_b32_e32 v68, 12, v66
	ds_write2_b32 v90, v93, v113 offset0:12 offset1:28
	ds_write2_b32 v128, v86, v106 offset0:64 offset1:80
	ds_write2_b32 v129, v87, v107 offset0:68 offset1:84
	ds_write2_b32 v131, v88, v108 offset0:72 offset1:88
	v_lshlrev_b32_e32 v66, 2, v0
	v_lshlrev_b32_e32 v67, 2, v68
	v_or_b32_e32 v0, s60, v0
	v_ashrrev_i32_e32 v88, 5, v142
	v_add3_u32 v74, 0, v66, v67
	v_ashrrev_i32_e32 v66, 1, v0
	v_lshlrev_b32_e32 v0, 1, v68
	v_add_u32_e32 v68, s12, v88
	v_ashrrev_i32_e32 v69, 31, v68
	v_add_u32_e32 v91, 0xd000, v130
	v_lshl_add_u64 v[70:71], v[68:69], 4, s[40:41]
	ds_write2_b32 v91, v89, v109 offset0:76 offset1:92
	s_waitcnt lgkmcnt(0)
	s_barrier
	global_load_dwordx4 v[134:137], v[70:71], off
	global_load_dwordx4 v[138:141], v[70:71], off offset:256
	global_load_dwordx4 v[144:147], v[70:71], off offset:512
	global_load_dwordx4 v[148:151], v[70:71], off offset:768
	global_load_dwordx4 v[152:155], v[70:71], off offset:1024
	global_load_dwordx4 v[156:159], v[70:71], off offset:1280
	global_load_dwordx4 v[160:163], v[70:71], off offset:1536
	global_load_dwordx4 v[164:167], v[70:71], off offset:1792
	v_readlane_b32 s20, v255, 27
	v_ashrrev_i32_e32 v67, 31, v66
	v_readlane_b32 s21, v255, 28
	v_mad_u64_u32 v[82:83], s[36:37], v88, s33, v[74:75]
	s_nop 0
	v_lshl_add_u64 v[66:67], v[66:67], 1, s[20:21]
	v_lshl_add_u64 v[66:67], v[66:67], 0, v[0:1]
	s_mov_b32 s20, 0x800000
	s_movk_i32 s21, 0x1600
	s_or_b32 s42, s60, 0x100
	s_ashr_i32 s43, s42, 31
	s_lshl_b64 s[44:45], s[42:43], 11
	s_waitcnt vmcnt(0)
	v_add_f32_e32 v0, v134, v135
	v_add_f32_e32 v0, v0, v136
	v_add_f32_e32 v0, v0, v137
	v_fmamk_f32 v0, v0, 0x3a800000, v200
	v_cmp_gt_f32_e32 vcc, s20, v0
	v_mul_f32_e32 v69, 0x4b800000, v0
	ds_read_b128 v[70:73], v82
	ds_read_b128 v[76:79], v82 offset:64
	v_cndmask_b32_e32 v0, v0, v69, vcc
	v_rsq_f32_e32 v0, v0
	s_nop 0
	v_mul_f32_e32 v69, 0x45800000, v0
	v_cndmask_b32_e32 v0, v0, v69, vcc
	s_waitcnt lgkmcnt(1)
	v_pk_mul_f32 v[70:71], v[70:71], v[0:1] op_sel_hi:[1,0]
	v_pk_mul_f32 v[72:73], v[72:73], v[0:1] op_sel_hi:[1,0]
	v_mul_f32_e32 v69, 0xbfb8aa3b, v70
	v_exp_f32_e32 v80, v69
	v_mul_f32_e32 v69, 0xbfb8aa3b, v71
	v_exp_f32_e32 v81, v69
	s_waitcnt lgkmcnt(0)
	v_pk_mul_f32 v[76:77], v[76:77], v[0:1] op_sel_hi:[1,0]
	v_pk_mul_f32 v[78:79], v[78:79], v[0:1] op_sel_hi:[1,0]
	v_mul_f32_e32 v0, 0xbfb8aa3b, v73
	v_pk_add_f32 v[80:81], v[80:81], 1.0 op_sel_hi:[1,0]
	s_nop 0
	v_rcp_f32_e32 v75, v81
	s_nop 0
	v_mul_f32_e32 v71, v71, v75
	v_rcp_f32_e32 v75, v80
	s_nop 0
	v_mul_f32_e32 v70, v70, v75
	v_mul_f32_e32 v69, 0xbfb8aa3b, v72
	v_pk_mul_f32 v[70:71], v[76:77], v[70:71]
	v_exp_f32_e32 v76, v69
	v_exp_f32_e32 v77, v0
	v_cvt_pk_bf16_f32 v70, v70, v71
	v_pk_add_f32 v[76:77], v[76:77], 1.0 op_sel_hi:[1,0]
	s_nop 0
	v_rcp_f32_e32 v69, v77
	s_nop 0
	v_mul_f32_e32 v73, v73, v69
	v_rcp_f32_e32 v69, v76
	s_nop 0
	v_mul_f32_e32 v72, v72, v69
	v_pk_mul_f32 v[72:73], v[78:79], v[72:73]
	v_add_u32_e32 v0, 0x200, v142
	v_cvt_pk_bf16_f32 v71, v72, v73
	v_mad_i64_i32 v[68:69], s[36:37], v68, s21, v[66:67]
	v_ashrrev_i32_e32 v83, 5, v0
	global_store_dwordx2 v[68:69], v[70:71], off
	v_add_u32_e32 v68, s12, v83
	v_ashrrev_i32_e32 v69, 31, v68
	v_lshl_add_u64 v[70:71], v[68:69], 4, s[40:41]
	v_mad_u64_u32 v[80:81], s[36:37], v83, s33, v[74:75]
	v_add_f32_e32 v0, v138, v139
	v_add_f32_e32 v0, v0, v140
	v_add_f32_e32 v0, v0, v141
	v_fmamk_f32 v0, v0, 0x3a800000, v200
	v_cmp_gt_f32_e32 vcc, s20, v0
	v_mul_f32_e32 v69, 0x4b800000, v0
	ds_read_b128 v[70:73], v80
	ds_read_b128 v[76:79], v80 offset:64
	v_cndmask_b32_e32 v0, v0, v69, vcc
	v_rsq_f32_e32 v0, v0
	s_nop 0
	v_mul_f32_e32 v69, 0x45800000, v0
	v_cndmask_b32_e32 v0, v0, v69, vcc
	s_waitcnt lgkmcnt(1)
	v_pk_mul_f32 v[70:71], v[70:71], v[0:1] op_sel_hi:[1,0]
	v_pk_mul_f32 v[72:73], v[72:73], v[0:1] op_sel_hi:[1,0]
	v_mul_f32_e32 v69, 0xbfb8aa3b, v70
	v_exp_f32_e32 v84, v69
	v_mul_f32_e32 v69, 0xbfb8aa3b, v71
	v_exp_f32_e32 v85, v69
	s_waitcnt lgkmcnt(0)
	v_pk_mul_f32 v[76:77], v[76:77], v[0:1] op_sel_hi:[1,0]
	v_pk_mul_f32 v[78:79], v[78:79], v[0:1] op_sel_hi:[1,0]
	v_mul_f32_e32 v0, 0xbfb8aa3b, v73
	v_pk_add_f32 v[84:85], v[84:85], 1.0 op_sel_hi:[1,0]
	s_nop 0
	v_rcp_f32_e32 v75, v85
	s_nop 0
	v_mul_f32_e32 v71, v71, v75
	v_rcp_f32_e32 v75, v84
	s_nop 0
	v_mul_f32_e32 v70, v70, v75
	v_mul_f32_e32 v69, 0xbfb8aa3b, v72
	v_pk_mul_f32 v[70:71], v[76:77], v[70:71]
	v_exp_f32_e32 v76, v69
	v_exp_f32_e32 v77, v0
	v_cvt_pk_bf16_f32 v70, v70, v71
	v_pk_add_f32 v[76:77], v[76:77], 1.0 op_sel_hi:[1,0]
	s_nop 0
	v_rcp_f32_e32 v69, v77
	s_nop 0
	v_mul_f32_e32 v73, v73, v69
	v_rcp_f32_e32 v69, v76
	s_nop 0
	v_mul_f32_e32 v72, v72, v69
	v_pk_mul_f32 v[72:73], v[78:79], v[72:73]
	v_add_u32_e32 v0, 0x400, v142
	v_cvt_pk_bf16_f32 v71, v72, v73
	v_mad_i64_i32 v[68:69], s[36:37], v68, s21, v[66:67]
	v_ashrrev_i32_e32 v81, 5, v0
	global_store_dwordx2 v[68:69], v[70:71], off
	v_add_u32_e32 v68, s12, v81
	v_ashrrev_i32_e32 v69, 31, v68
	v_lshl_add_u64 v[70:71], v[68:69], 4, s[40:41]
	v_mad_u64_u32 v[78:79], s[36:37], v81, s33, v[74:75]
	v_add_f32_e32 v0, v144, v145
	v_add_f32_e32 v0, v0, v146
	v_add_f32_e32 v0, v0, v147
	v_fmamk_f32 v0, v0, 0x3a800000, v200
	v_cmp_gt_f32_e32 vcc, s20, v0
	v_mul_f32_e32 v69, 0x4b800000, v0
	ds_read_b128 v[70:73], v78
	ds_read_b128 v[84:87], v78 offset:64
	v_cndmask_b32_e32 v0, v0, v69, vcc
	v_rsq_f32_e32 v0, v0
	s_nop 0
	v_mul_f32_e32 v69, 0x45800000, v0
	v_cndmask_b32_e32 v0, v0, v69, vcc
	s_waitcnt lgkmcnt(1)
	v_pk_mul_f32 v[70:71], v[70:71], v[0:1] op_sel_hi:[1,0]
	v_pk_mul_f32 v[72:73], v[72:73], v[0:1] op_sel_hi:[1,0]
	v_mul_f32_e32 v69, 0xbfb8aa3b, v70
	v_exp_f32_e32 v76, v69
	v_mul_f32_e32 v69, 0xbfb8aa3b, v71
	v_exp_f32_e32 v77, v69
	s_waitcnt lgkmcnt(0)
	v_pk_mul_f32 v[84:85], v[84:85], v[0:1] op_sel_hi:[1,0]
	v_pk_add_f32 v[76:77], v[76:77], 1.0 op_sel_hi:[1,0]
	s_nop 0
	v_rcp_f32_e32 v75, v77
	s_nop 0
	v_mul_f32_e32 v71, v71, v75
	v_rcp_f32_e32 v75, v76
	s_nop 0
	v_mul_f32_e32 v70, v70, v75
	v_mul_f32_e32 v69, 0xbfb8aa3b, v72
	v_pk_mul_f32 v[76:77], v[86:87], v[0:1] op_sel_hi:[1,0]
	v_mul_f32_e32 v0, 0xbfb8aa3b, v73
	v_pk_mul_f32 v[70:71], v[84:85], v[70:71]
	v_exp_f32_e32 v84, v69
	v_exp_f32_e32 v85, v0
	v_cvt_pk_bf16_f32 v70, v70, v71
	v_pk_add_f32 v[84:85], v[84:85], 1.0 op_sel_hi:[1,0]
	s_nop 0
	v_rcp_f32_e32 v69, v85
	s_nop 0
	v_mul_f32_e32 v73, v73, v69
	v_rcp_f32_e32 v69, v84
	s_nop 0
	v_mul_f32_e32 v72, v72, v69
	v_add_u32_e32 v0, 0x600, v142
	v_pk_mul_f32 v[72:73], v[76:77], v[72:73]
	v_ashrrev_i32_e32 v79, 5, v0
	v_cvt_pk_bf16_f32 v71, v72, v73
	v_add_u32_e32 v72, s12, v79
	v_mad_i64_i32 v[68:69], s[36:37], v68, s21, v[66:67]
	v_ashrrev_i32_e32 v73, 31, v72
	global_store_dwordx2 v[68:69], v[70:71], off
	v_lshl_add_u64 v[68:69], v[72:73], 4, s[40:41]
	v_mad_u64_u32 v[76:77], s[36:37], v79, s33, v[74:75]
	v_add_f32_e32 v0, v148, v149
	v_add_f32_e32 v0, v0, v150
	v_add_f32_e32 v0, v0, v151
	v_fmamk_f32 v0, v0, 0x3a800000, v200
	v_cmp_gt_f32_e32 vcc, s20, v0
	v_mul_f32_e32 v68, 0x4b800000, v0
	s_nop 0
	v_cndmask_b32_e32 v0, v0, v68, vcc
	v_rsq_f32_e32 v0, v0
	s_nop 0
	v_mul_f32_e32 v68, 0x45800000, v0
	v_cndmask_b32_e32 v0, v0, v68, vcc
	ds_read_b128 v[68:71], v76
	ds_read_b128 v[84:87], v76 offset:64
	s_waitcnt lgkmcnt(1)
	v_pk_mul_f32 v[68:69], v[68:69], v[0:1] op_sel_hi:[1,0]
	s_nop 0
	v_mul_f32_e32 v73, 0xbfb8aa3b, v68
	v_exp_f32_e32 v92, v73
	v_mul_f32_e32 v73, 0xbfb8aa3b, v69
	v_exp_f32_e32 v93, v73
	v_pk_mul_f32 v[70:71], v[70:71], v[0:1] op_sel_hi:[1,0]
	s_waitcnt lgkmcnt(0)
	v_pk_mul_f32 v[84:85], v[84:85], v[0:1] op_sel_hi:[1,0]
	v_pk_mul_f32 v[86:87], v[86:87], v[0:1] op_sel_hi:[1,0]
	v_pk_add_f32 v[92:93], v[92:93], 1.0 op_sel_hi:[1,0]
	v_mul_f32_e32 v0, 0xbfb8aa3b, v71
	v_rcp_f32_e32 v75, v93
	s_nop 0
	v_mul_f32_e32 v69, v69, v75
	v_rcp_f32_e32 v75, v92
	s_nop 0
	v_mul_f32_e32 v68, v68, v75
	v_mul_f32_e32 v73, 0xbfb8aa3b, v70
	v_pk_mul_f32 v[68:69], v[84:85], v[68:69]
	v_exp_f32_e32 v84, v73
	v_exp_f32_e32 v85, v0
	v_cvt_pk_bf16_f32 v68, v68, v69
	v_pk_add_f32 v[84:85], v[84:85], 1.0 op_sel_hi:[1,0]
	s_nop 0
	v_rcp_f32_e32 v73, v85
	s_nop 0
	v_mul_f32_e32 v71, v71, v73
	v_rcp_f32_e32 v73, v84
	s_nop 0
	v_mul_f32_e32 v70, v70, v73
	v_pk_mul_f32 v[70:71], v[86:87], v[70:71]
	v_add_u32_e32 v0, 0x800, v142
	v_cvt_pk_bf16_f32 v69, v70, v71
	v_mad_i64_i32 v[70:71], s[36:37], v72, s21, v[66:67]
	v_ashrrev_i32_e32 v0, 5, v0
	global_store_dwordx2 v[70:71], v[68:69], off
	v_add_u32_e32 v70, s12, v0
	v_ashrrev_i32_e32 v71, 31, v70
	v_lshl_add_u64 v[72:73], v[70:71], 4, s[40:41]
	v_mad_u64_u32 v[68:69], s[36:37], v0, s33, v[74:75]
	v_add_f32_e32 v69, v152, v153
	v_add_f32_e32 v69, v69, v154
	v_add_f32_e32 v69, v69, v155
	v_fmamk_f32 v69, v69, 0x3a800000, v200
	v_cmp_gt_f32_e32 vcc, s20, v69
	v_mul_f32_e32 v71, 0x4b800000, v69
	ds_read_b128 v[84:87], v68
	ds_read_b128 v[98:101], v68 offset:64
	v_cndmask_b32_e32 v69, v69, v71, vcc
	v_rsq_f32_e32 v69, v69
	s_nop 0
	v_mul_f32_e32 v71, 0x45800000, v69
	v_cndmask_b32_e32 v72, v69, v71, vcc
	s_waitcnt lgkmcnt(1)
	v_pk_mul_f32 v[84:85], v[84:85], v[72:73] op_sel_hi:[1,0]
	s_waitcnt lgkmcnt(0)
	v_pk_mul_f32 v[98:99], v[98:99], v[72:73] op_sel_hi:[1,0]
	v_mul_f32_e32 v69, 0xbfb8aa3b, v84
	v_exp_f32_e32 v92, v69
	v_mul_f32_e32 v69, 0xbfb8aa3b, v85
	v_exp_f32_e32 v93, v69
	s_nop 0
	v_pk_add_f32 v[92:93], v[92:93], 1.0 op_sel_hi:[1,0]
	s_nop 0
	v_rcp_f32_e32 v71, v93
	s_nop 0
	v_mul_f32_e32 v85, v85, v71
	v_div_scale_f32 v69, s[36:37], v92, v92, v84
	v_rcp_f32_e32 v71, v69
	s_nop 0
	v_fma_f32 v73, -v69, v71, 1.0
	v_fmac_f32_e32 v71, v73, v71
	v_div_scale_f32 v73, vcc, v84, v92, v84
	v_mul_f32_e32 v75, v73, v71
	v_fma_f32 v77, -v69, v75, v73
	v_fmac_f32_e32 v75, v77, v71
	v_fma_f32 v69, -v69, v75, v73
	v_div_fmas_f32 v69, v69, v71, v75
	v_pk_mul_f32 v[86:87], v[86:87], v[72:73] op_sel_hi:[1,0]
	v_div_fixup_f32 v84, v69, v92, v84
	v_mul_f32_e32 v69, 0xbfb8aa3b, v86
	v_exp_f32_e32 v92, v69
	v_mul_f32_e32 v69, 0xbfb8aa3b, v87
	v_exp_f32_e32 v93, v69
	v_pk_mul_f32 v[72:73], v[100:101], v[72:73] op_sel_hi:[1,0]
	v_pk_mul_f32 v[84:85], v[98:99], v[84:85]
	v_pk_add_f32 v[92:93], v[92:93], 1.0 op_sel_hi:[1,0]
	s_nop 0
	v_div_scale_f32 v69, s[36:37], v93, v93, v87
	v_rcp_f32_e32 v71, v69
	v_cvt_pk_bf16_f32 v84, v84, v85
	v_fma_f32 v75, -v69, v71, 1.0
	v_fmac_f32_e32 v71, v75, v71
	v_div_scale_f32 v75, vcc, v87, v93, v87
	v_mul_f32_e32 v77, v75, v71
	v_fma_f32 v89, -v69, v77, v75
	v_fmac_f32_e32 v77, v89, v71
	v_fma_f32 v69, -v69, v77, v75
	v_div_fmas_f32 v69, v69, v71, v77
	v_div_fixup_f32 v87, v69, v93, v87
	v_rcp_f32_e32 v71, v92
	s_nop 0
	v_mul_f32_e32 v86, v86, v71
	v_add_u32_e32 v69, 0xa00, v142
	v_pk_mul_f32 v[72:73], v[72:73], v[86:87]
	v_ashrrev_i32_e32 v69, 5, v69
	v_cvt_pk_bf16_f32 v85, v72, v73
	v_add_u32_e32 v72, s12, v69
	v_mad_i64_i32 v[70:71], s[36:37], v70, s21, v[66:67]
	v_ashrrev_i32_e32 v73, 31, v72
	global_store_dwordx2 v[70:71], v[84:85], off
	v_lshl_add_u64 v[84:85], v[72:73], 4, s[40:41]
	v_mad_u64_u32 v[70:71], s[36:37], v69, s33, v[74:75]
	v_add_f32_e32 v71, v156, v157
	v_add_f32_e32 v71, v71, v158
	v_add_f32_e32 v71, v71, v159
	v_fmamk_f32 v71, v71, 0x3a800000, v200
	v_cmp_gt_f32_e32 vcc, s20, v71
	v_mul_f32_e32 v73, 0x4b800000, v71
	ds_read_b128 v[84:87], v70
	ds_read_b128 v[98:101], v70 offset:64
	v_cndmask_b32_e32 v71, v71, v73, vcc
	v_rsq_f32_e32 v71, v71
	s_nop 0
	v_mul_f32_e32 v73, 0x45800000, v71
	v_cndmask_b32_e32 v92, v71, v73, vcc
	s_waitcnt lgkmcnt(1)
	v_pk_mul_f32 v[84:85], v[84:85], v[92:93] op_sel_hi:[1,0]
	v_pk_mul_f32 v[86:87], v[86:87], v[92:93] op_sel_hi:[1,0]
	v_mul_f32_e32 v71, 0xbfb8aa3b, v84
	v_exp_f32_e32 v102, v71
	v_mul_f32_e32 v71, 0xbfb8aa3b, v85
	v_exp_f32_e32 v103, v71
	s_waitcnt lgkmcnt(0)
	v_pk_mul_f32 v[98:99], v[98:99], v[92:93] op_sel_hi:[1,0]
	v_pk_mul_f32 v[92:93], v[100:101], v[92:93] op_sel_hi:[1,0]
	v_pk_add_f32 v[102:103], v[102:103], 1.0 op_sel_hi:[1,0]
	s_nop 0
	v_rcp_f32_e32 v73, v103
	s_nop 0
	v_mul_f32_e32 v85, v85, v73
	v_rcp_f32_e32 v73, v102
	s_nop 0
	v_mul_f32_e32 v84, v84, v73
	v_mul_f32_e32 v71, 0xbfb8aa3b, v86
	v_pk_mul_f32 v[84:85], v[98:99], v[84:85]
	v_exp_f32_e32 v98, v71
	v_mul_f32_e32 v71, 0xbfb8aa3b, v87
	v_exp_f32_e32 v99, v71
	v_cvt_pk_bf16_f32 v84, v84, v85
	v_pk_add_f32 v[98:99], v[98:99], 1.0 op_sel_hi:[1,0]
	s_nop 0
	v_rcp_f32_e32 v73, v99
	s_nop 0
	v_mul_f32_e32 v87, v87, v73
	v_rcp_f32_e32 v73, v98
	s_nop 0
	v_mul_f32_e32 v86, v86, v73
	v_pk_mul_f32 v[86:87], v[92:93], v[86:87]
	v_add_u32_e32 v71, 0xc00, v142
	v_cvt_pk_bf16_f32 v85, v86, v87
	v_mad_i64_i32 v[72:73], s[36:37], v72, s21, v[66:67]
	v_ashrrev_i32_e32 v71, 5, v71
	global_store_dwordx2 v[72:73], v[84:85], off
	v_add_u32_e32 v84, s12, v71
	v_ashrrev_i32_e32 v85, 31, v84
	v_lshl_add_u64 v[86:87], v[84:85], 4, s[40:41]
	v_mad_u64_u32 v[72:73], s[36:37], v71, s33, v[74:75]
	v_add_f32_e32 v73, v160, v161
	v_add_f32_e32 v73, v73, v162
	v_add_f32_e32 v73, v73, v163
	v_fmamk_f32 v73, v73, 0x3a800000, v200
	v_cmp_gt_f32_e32 vcc, s20, v73
	v_mul_f32_e32 v75, 0x4b800000, v73
	ds_read_b128 v[98:101], v72
	ds_read_b128 v[102:105], v72 offset:64
	v_cndmask_b32_e32 v73, v73, v75, vcc
	v_rsq_f32_e32 v73, v73
	s_nop 0
	v_mul_f32_e32 v75, 0x45800000, v73
	v_cndmask_b32_e32 v86, v73, v75, vcc
	s_waitcnt lgkmcnt(1)
	v_pk_mul_f32 v[92:93], v[98:99], v[86:87] op_sel_hi:[1,0]
	s_waitcnt lgkmcnt(0)
	v_pk_mul_f32 v[102:103], v[102:103], v[86:87] op_sel_hi:[1,0]
	v_mul_f32_e32 v73, 0xbfb8aa3b, v92
	v_exp_f32_e32 v98, v73
	v_mul_f32_e32 v73, 0xbfb8aa3b, v93
	v_exp_f32_e32 v99, v73
	s_nop 0
	v_pk_add_f32 v[98:99], v[98:99], 1.0 op_sel_hi:[1,0]
	s_nop 0
	v_rcp_f32_e32 v75, v99
	s_nop 0
	v_mul_f32_e32 v93, v93, v75
	v_rcp_f32_e32 v75, v98
	s_nop 0
	v_mul_f32_e32 v92, v92, v75
	v_pk_mul_f32 v[98:99], v[100:101], v[86:87] op_sel_hi:[1,0]
	v_pk_mul_f32 v[86:87], v[104:105], v[86:87] op_sel_hi:[1,0]
	v_mul_f32_e32 v73, 0xbfb8aa3b, v98
	v_exp_f32_e32 v100, v73
	v_mul_f32_e32 v73, 0xbfb8aa3b, v99
	v_exp_f32_e32 v101, v73
	v_pk_mul_f32 v[92:93], v[102:103], v[92:93]
	v_pk_add_f32 v[100:101], v[100:101], 1.0 op_sel_hi:[1,0]
	s_nop 0
	v_div_scale_f32 v73, s[36:37], v101, v101, v99
	v_rcp_f32_e32 v75, v73
	v_cvt_pk_bf16_f32 v92, v92, v93
	v_fma_f32 v77, -v73, v75, 1.0
	v_fmac_f32_e32 v75, v77, v75
	v_div_scale_f32 v77, vcc, v99, v101, v99
	v_mul_f32_e32 v85, v77, v75
	v_fma_f32 v89, -v73, v85, v77
	v_fmac_f32_e32 v85, v89, v75
	v_fma_f32 v73, -v73, v85, v77
	v_div_fmas_f32 v73, v73, v75, v85
	v_div_fixup_f32 v99, v73, v101, v99
	v_rcp_f32_e32 v75, v100
	s_nop 0
	v_mul_f32_e32 v98, v98, v75
	v_pk_mul_f32 v[86:87], v[86:87], v[98:99]
	v_add_u32_e32 v73, 0xe00, v142
	v_cvt_pk_bf16_f32 v93, v86, v87
	v_mad_i64_i32 v[84:85], s[36:37], v84, s21, v[66:67]
	v_ashrrev_i32_e32 v73, 5, v73
	global_store_dwordx2 v[84:85], v[92:93], off
	v_add_u32_e32 v84, s12, v73
	v_ashrrev_i32_e32 v85, 31, v84
	v_lshl_add_u64 v[86:87], v[84:85], 4, s[40:41]
	v_mad_u64_u32 v[74:75], s[36:37], v73, s33, v[74:75]
	v_mov_b32_e32 v142, v201
	v_add_f32_e32 v75, v164, v165
	v_add_f32_e32 v75, v75, v166
	v_add_f32_e32 v75, v75, v167
	v_fmamk_f32 v75, v75, 0x3a800000, v200
	v_cmp_gt_f32_e32 vcc, s20, v75
	v_mul_f32_e32 v77, 0x4b800000, v75
	ds_read_b128 v[98:101], v74
	ds_read_b128 v[102:105], v74 offset:64
	v_cndmask_b32_e32 v75, v75, v77, vcc
	v_rsq_f32_e32 v75, v75
	s_nop 0
	v_mul_f32_e32 v77, 0x45800000, v75
	v_cndmask_b32_e32 v86, v75, v77, vcc
	s_waitcnt lgkmcnt(1)
	v_pk_mul_f32 v[92:93], v[98:99], v[86:87] op_sel_hi:[1,0]
	s_waitcnt lgkmcnt(0)
	v_pk_mul_f32 v[102:103], v[102:103], v[86:87] op_sel_hi:[1,0]
	v_mul_f32_e32 v75, 0xbfb8aa3b, v92
	v_exp_f32_e32 v98, v75
	v_mul_f32_e32 v75, 0xbfb8aa3b, v93
	v_exp_f32_e32 v99, v75
	s_nop 0
	v_pk_add_f32 v[98:99], v[98:99], 1.0 op_sel_hi:[1,0]
	s_nop 0
	v_rcp_f32_e32 v77, v99
	s_nop 0
	v_mul_f32_e32 v93, v93, v77
	v_rcp_f32_e32 v77, v98
	s_nop 0
	v_mul_f32_e32 v92, v92, v77
	v_pk_mul_f32 v[98:99], v[100:101], v[86:87] op_sel_hi:[1,0]
	v_pk_mul_f32 v[92:93], v[102:103], v[92:93]
	v_mul_f32_e32 v75, 0xbfb8aa3b, v98
	v_exp_f32_e32 v100, v75
	v_mul_f32_e32 v75, 0xbfb8aa3b, v99
	v_exp_f32_e32 v101, v75
	v_pk_mul_f32 v[86:87], v[104:105], v[86:87] op_sel_hi:[1,0]
	v_cvt_pk_bf16_f32 v92, v92, v93
	v_pk_add_f32 v[100:101], v[100:101], 1.0 op_sel_hi:[1,0]
	s_nop 0
	v_rcp_f32_e32 v77, v101
	s_nop 0
	v_mul_f32_e32 v99, v99, v77
	v_rcp_f32_e32 v77, v100
	s_nop 0
	v_mul_f32_e32 v98, v98, v77
	v_pk_mul_f32 v[86:87], v[86:87], v[98:99]
	v_mad_i64_i32 v[84:85], s[36:37], v84, s21, v[66:67]
	v_cvt_pk_bf16_f32 v93, v86, v87
	global_store_dwordx2 v[84:85], v[92:93], off
	s_barrier
	ds_write2_b32 v130, v2, v18 offset1:16
	ds_write2_b32 v114, v3, v19 offset0:4 offset1:20
	ds_write2_b32 v115, v4, v20 offset0:8 offset1:24
	ds_write2_b32 v116, v5, v21 offset0:12 offset1:28
	ds_write2_b32 v117, v6, v22 offset0:64 offset1:80
	ds_write2_b32 v94, v7, v23 offset0:68 offset1:84
	ds_write2_b32 v95, v8, v24 offset0:72 offset1:88
	ds_write2_b32 v96, v9, v25 offset0:76 offset1:92
	ds_write2_b32 v132, v10, v26 offset0:128 offset1:144
	ds_write2_b32 v97, v11, v27 offset0:132 offset1:148
	ds_write2_b32 v126, v12, v28 offset0:136 offset1:152
	ds_write2_b32 v127, v13, v29 offset0:140 offset1:156
	ds_write2_b32 v133, v14, v30 offset0:192 offset1:208
	ds_write2_b32 v128, v15, v31 offset0:196 offset1:212
	ds_write2_b32 v129, v16, v32 offset0:200 offset1:216
	ds_write2_b32 v131, v17, v33 offset0:204 offset1:220
	ds_write2_b32 v130, v34, v50 offset0:128 offset1:144
	ds_write2_b32 v114, v35, v51 offset0:132 offset1:148
	ds_write2_b32 v115, v36, v52 offset0:136 offset1:152
	ds_write2_b32 v116, v37, v53 offset0:140 offset1:156
	ds_write2_b32 v117, v38, v54 offset0:192 offset1:208
	ds_write2_b32 v94, v39, v55 offset0:196 offset1:212
	ds_write2_b32 v95, v40, v56 offset0:200 offset1:216
	ds_write2_b32 v96, v41, v57 offset0:204 offset1:220
	ds_write2_b32 v97, v42, v58 offset1:16
	ds_write2_b32 v126, v43, v59 offset0:4 offset1:20
	ds_write2_b32 v127, v44, v60 offset0:8 offset1:24
	ds_write2_b32 v90, v45, v61 offset0:12 offset1:28
	ds_write2_b32 v128, v46, v62 offset0:64 offset1:80
	ds_write2_b32 v129, v47, v63 offset0:68 offset1:84
	ds_write2_b32 v131, v48, v64 offset0:72 offset1:88
	ds_write2_b32 v91, v49, v65 offset0:76 offset1:92
	v_add_u32_e32 v2, s10, v88
	v_ashrrev_i32_e32 v3, 31, v2
	v_lshl_add_u64 v[4:5], v[2:3], 4, s[40:41]
	s_waitcnt lgkmcnt(0)
	s_barrier
	global_load_dwordx4 v[134:137], v[4:5], off
	global_load_dwordx4 v[138:141], v[4:5], off offset:256
	global_load_dwordx4 v[144:147], v[4:5], off offset:512
	global_load_dwordx4 v[148:151], v[4:5], off offset:768
	global_load_dwordx4 v[152:155], v[4:5], off offset:1024
	global_load_dwordx4 v[156:159], v[4:5], off offset:1280
	global_load_dwordx4 v[160:163], v[4:5], off offset:1536
	global_load_dwordx4 v[164:167], v[4:5], off offset:1792
	s_waitcnt vmcnt(0)
	v_add_f32_e32 v3, v134, v135
	v_add_f32_e32 v3, v3, v136
	v_add_f32_e32 v3, v3, v137
	v_fmamk_f32 v3, v3, 0x3a800000, v200
	v_cmp_gt_f32_e32 vcc, s20, v3
	v_mul_f32_e32 v4, 0x4b800000, v3
	s_nop 0
	v_cndmask_b32_e32 v3, v3, v4, vcc
	v_rsq_f32_e32 v3, v3
	s_nop 0
	v_mul_f32_e32 v4, 0x45800000, v3
	v_cndmask_b32_e32 v12, v3, v4, vcc
	ds_read_b128 v[4:7], v82
	ds_read_b128 v[8:11], v82 offset:64
	s_waitcnt lgkmcnt(1)
	v_pk_mul_f32 v[4:5], v[4:5], v[12:13] op_sel_hi:[1,0]
	s_nop 0
	v_mul_f32_e32 v3, 0xbfb8aa3b, v4
	v_exp_f32_e32 v14, v3
	v_mul_f32_e32 v3, 0xbfb8aa3b, v5
	v_exp_f32_e32 v15, v3
	s_waitcnt lgkmcnt(0)
	v_pk_mul_f32 v[8:9], v[8:9], v[12:13] op_sel_hi:[1,0]
	v_pk_add_f32 v[14:15], v[14:15], 1.0 op_sel_hi:[1,0]
	s_nop 0
	v_rcp_f32_e32 v13, v15
	s_nop 0
	v_mul_f32_e32 v5, v5, v13
	v_div_scale_f32 v3, s[36:37], v14, v14, v4
	v_rcp_f32_e32 v13, v3
	s_nop 0
	v_fma_f32 v15, -v3, v13, 1.0
	v_fmac_f32_e32 v13, v15, v13
	v_div_scale_f32 v15, vcc, v4, v14, v4
	v_mul_f32_e32 v16, v15, v13
	v_fma_f32 v17, -v3, v16, v15
	v_fmac_f32_e32 v16, v17, v13
	v_fma_f32 v3, -v3, v16, v15
	v_div_fmas_f32 v3, v3, v13, v16
	v_pk_mul_f32 v[6:7], v[6:7], v[12:13] op_sel_hi:[1,0]
	v_div_fixup_f32 v4, v3, v14, v4
	v_mul_f32_e32 v3, 0xbfb8aa3b, v6
	v_pk_mul_f32 v[4:5], v[8:9], v[4:5]
	v_exp_f32_e32 v8, v3
	v_mul_f32_e32 v3, 0xbfb8aa3b, v7
	v_exp_f32_e32 v9, v3
	v_pk_mul_f32 v[10:11], v[10:11], v[12:13] op_sel_hi:[1,0]
	v_cvt_pk_bf16_f32 v4, v4, v5
	v_pk_add_f32 v[8:9], v[8:9], 1.0 op_sel_hi:[1,0]
	s_nop 0
	v_rcp_f32_e32 v12, v9
	s_nop 0
	v_mul_f32_e32 v7, v7, v12
	v_rcp_f32_e32 v9, v8
	s_nop 0
	v_mul_f32_e32 v6, v6, v9
	v_pk_mul_f32 v[6:7], v[10:11], v[6:7]
	v_mad_i64_i32 v[2:3], s[36:37], v2, s21, v[66:67]
	v_cvt_pk_bf16_f32 v5, v6, v7
	global_store_dwordx2 v[2:3], v[4:5], off
	v_add_u32_e32 v2, s10, v83
	v_ashrrev_i32_e32 v3, 31, v2
	v_lshl_add_u64 v[4:5], v[2:3], 4, s[40:41]
	v_add_f32_e32 v3, v138, v139
	v_add_f32_e32 v3, v3, v140
	v_add_f32_e32 v3, v3, v141
	v_fmamk_f32 v3, v3, 0x3a800000, v200
	v_cmp_gt_f32_e32 vcc, s20, v3
	v_mul_f32_e32 v4, 0x4b800000, v3
	s_nop 0
	v_cndmask_b32_e32 v3, v3, v4, vcc
	v_rsq_f32_e32 v3, v3
	s_nop 0
	v_mul_f32_e32 v4, 0x45800000, v3
	v_cndmask_b32_e32 v12, v3, v4, vcc
	ds_read_b128 v[4:7], v80
	ds_read_b128 v[8:11], v80 offset:64
	s_waitcnt lgkmcnt(1)
	v_pk_mul_f32 v[4:5], v[4:5], v[12:13] op_sel_hi:[1,0]
	s_nop 0
	v_mul_f32_e32 v3, 0xbfb8aa3b, v4
	v_exp_f32_e32 v14, v3
	v_mul_f32_e32 v3, 0xbfb8aa3b, v5
	v_exp_f32_e32 v15, v3
	s_waitcnt lgkmcnt(0)
	v_pk_mul_f32 v[8:9], v[8:9], v[12:13] op_sel_hi:[1,0]
	v_pk_add_f32 v[14:15], v[14:15], 1.0 op_sel_hi:[1,0]
	s_nop 0
	v_rcp_f32_e32 v13, v15
	s_nop 0
	v_mul_f32_e32 v5, v5, v13
	v_div_scale_f32 v3, s[36:37], v14, v14, v4
	v_rcp_f32_e32 v13, v3
	s_nop 0
	v_fma_f32 v15, -v3, v13, 1.0
	v_fmac_f32_e32 v13, v15, v13
	v_div_scale_f32 v15, vcc, v4, v14, v4
	v_mul_f32_e32 v16, v15, v13
	v_fma_f32 v17, -v3, v16, v15
	v_fmac_f32_e32 v16, v17, v13
	v_fma_f32 v3, -v3, v16, v15
	v_div_fmas_f32 v3, v3, v13, v16
	v_pk_mul_f32 v[6:7], v[6:7], v[12:13] op_sel_hi:[1,0]
	v_div_fixup_f32 v4, v3, v14, v4
	v_mul_f32_e32 v3, 0xbfb8aa3b, v6
	v_pk_mul_f32 v[4:5], v[8:9], v[4:5]
	v_exp_f32_e32 v8, v3
	v_mul_f32_e32 v3, 0xbfb8aa3b, v7
	v_exp_f32_e32 v9, v3
	v_pk_mul_f32 v[10:11], v[10:11], v[12:13] op_sel_hi:[1,0]
	v_cvt_pk_bf16_f32 v4, v4, v5
	v_pk_add_f32 v[8:9], v[8:9], 1.0 op_sel_hi:[1,0]
	s_nop 0
	v_rcp_f32_e32 v12, v9
	s_nop 0
	v_mul_f32_e32 v7, v7, v12
	v_rcp_f32_e32 v9, v8
	s_nop 0
	v_mul_f32_e32 v6, v6, v9
	v_pk_mul_f32 v[6:7], v[10:11], v[6:7]
	v_mad_i64_i32 v[2:3], s[36:37], v2, s21, v[66:67]
	v_cvt_pk_bf16_f32 v5, v6, v7
	global_store_dwordx2 v[2:3], v[4:5], off
	v_add_u32_e32 v2, s10, v81
	v_ashrrev_i32_e32 v3, 31, v2
	v_lshl_add_u64 v[4:5], v[2:3], 4, s[40:41]
	v_add_f32_e32 v3, v144, v145
	v_add_f32_e32 v3, v3, v146
	v_add_f32_e32 v3, v3, v147
	v_fmamk_f32 v3, v3, 0x3a800000, v200
	v_cmp_gt_f32_e32 vcc, s20, v3
	v_mul_f32_e32 v4, 0x4b800000, v3
	s_nop 0
	v_cndmask_b32_e32 v3, v3, v4, vcc
	v_rsq_f32_e32 v3, v3
	s_nop 0
	v_mul_f32_e32 v4, 0x45800000, v3
	v_cndmask_b32_e32 v12, v3, v4, vcc
	ds_read_b128 v[4:7], v78
	ds_read_b128 v[8:11], v78 offset:64
	s_waitcnt lgkmcnt(1)
	v_pk_mul_f32 v[4:5], v[4:5], v[12:13] op_sel_hi:[1,0]
	s_nop 0
	v_mul_f32_e32 v3, 0xbfb8aa3b, v4
	v_exp_f32_e32 v14, v3
	v_mul_f32_e32 v3, 0xbfb8aa3b, v5
	v_exp_f32_e32 v15, v3
	s_waitcnt lgkmcnt(0)
	v_pk_mul_f32 v[8:9], v[8:9], v[12:13] op_sel_hi:[1,0]
	v_pk_add_f32 v[14:15], v[14:15], 1.0 op_sel_hi:[1,0]
	s_nop 0
	v_rcp_f32_e32 v13, v15
	s_nop 0
	v_mul_f32_e32 v5, v5, v13
	v_div_scale_f32 v3, s[36:37], v14, v14, v4
	v_rcp_f32_e32 v13, v3
	s_nop 0
	v_fma_f32 v15, -v3, v13, 1.0
	v_fmac_f32_e32 v13, v15, v13
	v_div_scale_f32 v15, vcc, v4, v14, v4
	v_mul_f32_e32 v16, v15, v13
	v_fma_f32 v17, -v3, v16, v15
	v_fmac_f32_e32 v16, v17, v13
	v_fma_f32 v3, -v3, v16, v15
	v_div_fmas_f32 v3, v3, v13, v16
	v_pk_mul_f32 v[6:7], v[6:7], v[12:13] op_sel_hi:[1,0]
	v_div_fixup_f32 v4, v3, v14, v4
	v_mul_f32_e32 v3, 0xbfb8aa3b, v6
	v_pk_mul_f32 v[4:5], v[8:9], v[4:5]
	v_exp_f32_e32 v8, v3
	v_mul_f32_e32 v3, 0xbfb8aa3b, v7
	v_exp_f32_e32 v9, v3
	v_pk_mul_f32 v[10:11], v[10:11], v[12:13] op_sel_hi:[1,0]
	v_cvt_pk_bf16_f32 v4, v4, v5
	v_pk_add_f32 v[8:9], v[8:9], 1.0 op_sel_hi:[1,0]
	s_nop 0
	v_rcp_f32_e32 v12, v9
	s_nop 0
	v_mul_f32_e32 v7, v7, v12
	v_rcp_f32_e32 v9, v8
	s_nop 0
	v_mul_f32_e32 v6, v6, v9
	v_pk_mul_f32 v[6:7], v[10:11], v[6:7]
	v_mad_i64_i32 v[2:3], s[36:37], v2, s21, v[66:67]
	v_cvt_pk_bf16_f32 v5, v6, v7
	global_store_dwordx2 v[2:3], v[4:5], off
	v_add_u32_e32 v2, s10, v79
	v_ashrrev_i32_e32 v3, 31, v2
	v_lshl_add_u64 v[4:5], v[2:3], 4, s[40:41]
	v_add_f32_e32 v3, v148, v149
	v_add_f32_e32 v3, v3, v150
	v_add_f32_e32 v3, v3, v151
	v_fmamk_f32 v3, v3, 0x3a800000, v200
	v_cmp_gt_f32_e32 vcc, s20, v3
	v_mul_f32_e32 v4, 0x4b800000, v3
	s_nop 0
	v_cndmask_b32_e32 v3, v3, v4, vcc
	v_rsq_f32_e32 v3, v3
	s_nop 0
	v_mul_f32_e32 v4, 0x45800000, v3
	v_cndmask_b32_e32 v12, v3, v4, vcc
	ds_read_b128 v[4:7], v76
	ds_read_b128 v[8:11], v76 offset:64
	s_waitcnt lgkmcnt(1)
	v_pk_mul_f32 v[4:5], v[4:5], v[12:13] op_sel_hi:[1,0]
	s_nop 0
	v_mul_f32_e32 v3, 0xbfb8aa3b, v4
	v_exp_f32_e32 v14, v3
	v_mul_f32_e32 v3, 0xbfb8aa3b, v5
	v_exp_f32_e32 v15, v3
	s_waitcnt lgkmcnt(0)
	v_pk_mul_f32 v[8:9], v[8:9], v[12:13] op_sel_hi:[1,0]
	v_pk_add_f32 v[14:15], v[14:15], 1.0 op_sel_hi:[1,0]
	s_nop 0
	v_rcp_f32_e32 v13, v15
	s_nop 0
	v_mul_f32_e32 v5, v5, v13
	v_div_scale_f32 v3, s[36:37], v14, v14, v4
	v_rcp_f32_e32 v13, v3
	s_nop 0
	v_fma_f32 v15, -v3, v13, 1.0
	v_fmac_f32_e32 v13, v15, v13
	v_div_scale_f32 v15, vcc, v4, v14, v4
	v_mul_f32_e32 v16, v15, v13
	v_fma_f32 v17, -v3, v16, v15
	v_fmac_f32_e32 v16, v17, v13
	v_fma_f32 v3, -v3, v16, v15
	v_div_fmas_f32 v3, v3, v13, v16
	v_pk_mul_f32 v[6:7], v[6:7], v[12:13] op_sel_hi:[1,0]
	v_div_fixup_f32 v4, v3, v14, v4
	v_mul_f32_e32 v3, 0xbfb8aa3b, v6
	v_pk_mul_f32 v[4:5], v[8:9], v[4:5]
	v_exp_f32_e32 v8, v3
	v_mul_f32_e32 v3, 0xbfb8aa3b, v7
	v_exp_f32_e32 v9, v3
	v_pk_mul_f32 v[10:11], v[10:11], v[12:13] op_sel_hi:[1,0]
	v_cvt_pk_bf16_f32 v4, v4, v5
	v_pk_add_f32 v[8:9], v[8:9], 1.0 op_sel_hi:[1,0]
	s_nop 0
	v_rcp_f32_e32 v12, v9
	s_nop 0
	v_mul_f32_e32 v7, v7, v12
	v_rcp_f32_e32 v9, v8
	s_nop 0
	v_mul_f32_e32 v6, v6, v9
	v_pk_mul_f32 v[6:7], v[10:11], v[6:7]
	v_mad_i64_i32 v[2:3], s[36:37], v2, s21, v[66:67]
	v_cvt_pk_bf16_f32 v5, v6, v7
	global_store_dwordx2 v[2:3], v[4:5], off
	v_add_u32_e32 v2, s10, v0
	v_ashrrev_i32_e32 v3, 31, v2
	v_lshl_add_u64 v[4:5], v[2:3], 4, s[40:41]
	v_add_f32_e32 v0, v152, v153
	v_add_f32_e32 v0, v0, v154
	v_add_f32_e32 v0, v0, v155
	v_fmamk_f32 v0, v0, 0x3a800000, v200
	v_cmp_gt_f32_e32 vcc, s20, v0
	v_mul_f32_e32 v3, 0x4b800000, v0
	ds_read_b128 v[4:7], v68
	ds_read_b128 v[8:11], v68 offset:64
	v_cndmask_b32_e32 v0, v0, v3, vcc
	v_rsq_f32_e32 v0, v0
	s_nop 0
	v_mul_f32_e32 v3, 0x45800000, v0
	v_cndmask_b32_e32 v0, v0, v3, vcc
	s_waitcnt lgkmcnt(1)
	v_pk_mul_f32 v[4:5], v[4:5], v[0:1] op_sel_hi:[1,0]
	v_pk_mul_f32 v[6:7], v[6:7], v[0:1] op_sel_hi:[1,0]
	v_mul_f32_e32 v3, 0xbfb8aa3b, v4
	v_exp_f32_e32 v12, v3
	v_mul_f32_e32 v3, 0xbfb8aa3b, v5
	v_exp_f32_e32 v13, v3
	s_waitcnt lgkmcnt(0)
	v_pk_mul_f32 v[8:9], v[8:9], v[0:1] op_sel_hi:[1,0]
	v_pk_mul_f32 v[10:11], v[10:11], v[0:1] op_sel_hi:[1,0]
	v_mul_f32_e32 v0, 0xbfb8aa3b, v7
	v_pk_add_f32 v[12:13], v[12:13], 1.0 op_sel_hi:[1,0]
	s_nop 0
	v_rcp_f32_e32 v14, v13
	s_nop 0
	v_mul_f32_e32 v5, v5, v14
	v_rcp_f32_e32 v13, v12
	s_nop 0
	v_mul_f32_e32 v4, v4, v13
	v_mul_f32_e32 v3, 0xbfb8aa3b, v6
	v_pk_mul_f32 v[4:5], v[8:9], v[4:5]
	v_exp_f32_e32 v8, v3
	v_exp_f32_e32 v9, v0
	v_cvt_pk_bf16_f32 v4, v4, v5
	v_pk_add_f32 v[8:9], v[8:9], 1.0 op_sel_hi:[1,0]
	s_nop 0
	v_rcp_f32_e32 v3, v9
	s_nop 0
	v_mul_f32_e32 v7, v7, v3
	v_rcp_f32_e32 v3, v8
	s_nop 0
	v_mul_f32_e32 v6, v6, v3
	v_pk_mul_f32 v[6:7], v[10:11], v[6:7]
	v_mad_i64_i32 v[2:3], s[36:37], v2, s21, v[66:67]
	v_cvt_pk_bf16_f32 v5, v6, v7
	global_store_dwordx2 v[2:3], v[4:5], off
	v_add_u32_e32 v2, s10, v69
	v_ashrrev_i32_e32 v3, 31, v2
	v_lshl_add_u64 v[4:5], v[2:3], 4, s[40:41]
	v_add_f32_e32 v0, v156, v157
	v_add_f32_e32 v0, v0, v158
	v_add_f32_e32 v0, v0, v159
	v_fmamk_f32 v0, v0, 0x3a800000, v200
	v_cmp_gt_f32_e32 vcc, s20, v0
	v_mul_f32_e32 v3, 0x4b800000, v0
	ds_read_b128 v[4:7], v70
	ds_read_b128 v[8:11], v70 offset:64
	v_cndmask_b32_e32 v0, v0, v3, vcc
	v_rsq_f32_e32 v0, v0
	s_nop 0
	v_mul_f32_e32 v3, 0x45800000, v0
	v_cndmask_b32_e32 v0, v0, v3, vcc
	s_waitcnt lgkmcnt(1)
	v_pk_mul_f32 v[4:5], v[4:5], v[0:1] op_sel_hi:[1,0]
	v_pk_mul_f32 v[6:7], v[6:7], v[0:1] op_sel_hi:[1,0]
	v_mul_f32_e32 v3, 0xbfb8aa3b, v4
	v_exp_f32_e32 v12, v3
	v_mul_f32_e32 v3, 0xbfb8aa3b, v5
	v_exp_f32_e32 v13, v3
	s_waitcnt lgkmcnt(0)
	v_pk_mul_f32 v[8:9], v[8:9], v[0:1] op_sel_hi:[1,0]
	v_pk_mul_f32 v[10:11], v[10:11], v[0:1] op_sel_hi:[1,0]
	v_mul_f32_e32 v0, 0xbfb8aa3b, v7
	v_pk_add_f32 v[12:13], v[12:13], 1.0 op_sel_hi:[1,0]
	s_nop 0
	v_rcp_f32_e32 v14, v13
	s_nop 0
	v_mul_f32_e32 v5, v5, v14
	v_rcp_f32_e32 v13, v12
	s_nop 0
	v_mul_f32_e32 v4, v4, v13
	v_mul_f32_e32 v3, 0xbfb8aa3b, v6
	v_pk_mul_f32 v[4:5], v[8:9], v[4:5]
	v_exp_f32_e32 v8, v3
	v_exp_f32_e32 v9, v0
	v_cvt_pk_bf16_f32 v4, v4, v5
	v_pk_add_f32 v[8:9], v[8:9], 1.0 op_sel_hi:[1,0]
	s_nop 0
	v_rcp_f32_e32 v3, v9
	s_nop 0
	v_mul_f32_e32 v7, v7, v3
	v_rcp_f32_e32 v3, v8
	s_nop 0
	v_mul_f32_e32 v6, v6, v3
	v_pk_mul_f32 v[6:7], v[10:11], v[6:7]
	v_mad_i64_i32 v[2:3], s[36:37], v2, s21, v[66:67]
	v_cvt_pk_bf16_f32 v5, v6, v7
	global_store_dwordx2 v[2:3], v[4:5], off
	v_add_u32_e32 v2, s10, v71
	v_ashrrev_i32_e32 v3, 31, v2
	v_lshl_add_u64 v[4:5], v[2:3], 4, s[40:41]
	v_add_f32_e32 v0, v160, v161
	v_add_f32_e32 v0, v0, v162
	v_add_f32_e32 v0, v0, v163
	v_fmamk_f32 v0, v0, 0x3a800000, v200
	v_cmp_gt_f32_e32 vcc, s20, v0
	v_mul_f32_e32 v3, 0x4b800000, v0
	ds_read_b128 v[4:7], v72
	ds_read_b128 v[8:11], v72 offset:64
	v_cndmask_b32_e32 v0, v0, v3, vcc
	v_rsq_f32_e32 v0, v0
	s_nop 0
	v_mul_f32_e32 v3, 0x45800000, v0
	v_cndmask_b32_e32 v0, v0, v3, vcc
	s_waitcnt lgkmcnt(1)
	v_pk_mul_f32 v[4:5], v[4:5], v[0:1] op_sel_hi:[1,0]
	v_pk_mul_f32 v[6:7], v[6:7], v[0:1] op_sel_hi:[1,0]
	v_mul_f32_e32 v3, 0xbfb8aa3b, v4
	v_exp_f32_e32 v12, v3
	v_mul_f32_e32 v3, 0xbfb8aa3b, v5
	v_exp_f32_e32 v13, v3
	s_waitcnt lgkmcnt(0)
	v_pk_mul_f32 v[8:9], v[8:9], v[0:1] op_sel_hi:[1,0]
	v_pk_mul_f32 v[10:11], v[10:11], v[0:1] op_sel_hi:[1,0]
	v_mul_f32_e32 v0, 0xbfb8aa3b, v7
	v_pk_add_f32 v[12:13], v[12:13], 1.0 op_sel_hi:[1,0]
	s_nop 0
	v_rcp_f32_e32 v14, v13
	s_nop 0
	v_mul_f32_e32 v5, v5, v14
	v_rcp_f32_e32 v13, v12
	s_nop 0
	v_mul_f32_e32 v4, v4, v13
	v_mul_f32_e32 v3, 0xbfb8aa3b, v6
	v_pk_mul_f32 v[4:5], v[8:9], v[4:5]
	v_exp_f32_e32 v8, v3
	v_exp_f32_e32 v9, v0
	v_cvt_pk_bf16_f32 v4, v4, v5
	v_pk_add_f32 v[8:9], v[8:9], 1.0 op_sel_hi:[1,0]
	s_nop 0
	v_rcp_f32_e32 v3, v9
	s_nop 0
	v_mul_f32_e32 v7, v7, v3
	v_rcp_f32_e32 v3, v8
	s_nop 0
	v_mul_f32_e32 v6, v6, v3
	v_pk_mul_f32 v[6:7], v[10:11], v[6:7]
	v_mad_i64_i32 v[2:3], s[36:37], v2, s21, v[66:67]
	v_cvt_pk_bf16_f32 v5, v6, v7
	global_store_dwordx2 v[2:3], v[4:5], off
	v_add_u32_e32 v2, s10, v73
	v_ashrrev_i32_e32 v3, 31, v2
	v_lshl_add_u64 v[4:5], v[2:3], 4, s[40:41]
	v_add_f32_e32 v0, v164, v165
	v_add_f32_e32 v0, v0, v166
	v_add_f32_e32 v0, v0, v167
	v_fmamk_f32 v0, v0, 0x3a800000, v200
	v_cmp_gt_f32_e32 vcc, s20, v0
	v_mul_f32_e32 v3, 0x4b800000, v0
	ds_read_b128 v[4:7], v74
	ds_read_b128 v[8:11], v74 offset:64
	v_cndmask_b32_e32 v0, v0, v3, vcc
	v_rsq_f32_e32 v0, v0
	v_readlane_b32 s20, v255, 9
	v_mul_f32_e32 v3, 0x45800000, v0
	v_cndmask_b32_e32 v0, v0, v3, vcc
	s_waitcnt lgkmcnt(1)
	v_pk_mul_f32 v[4:5], v[4:5], v[0:1] op_sel_hi:[1,0]
	v_pk_mul_f32 v[6:7], v[6:7], v[0:1] op_sel_hi:[1,0]
	v_mul_f32_e32 v3, 0xbfb8aa3b, v4
	v_exp_f32_e32 v12, v3
	v_mul_f32_e32 v3, 0xbfb8aa3b, v5
	v_exp_f32_e32 v13, v3
	s_waitcnt lgkmcnt(0)
	v_pk_mul_f32 v[8:9], v[8:9], v[0:1] op_sel_hi:[1,0]
	v_pk_mul_f32 v[10:11], v[10:11], v[0:1] op_sel_hi:[1,0]
	v_mul_f32_e32 v0, 0xbfb8aa3b, v7
	v_pk_add_f32 v[12:13], v[12:13], 1.0 op_sel_hi:[1,0]
	s_nop 0
	v_rcp_f32_e32 v14, v13
	s_nop 0
	v_mul_f32_e32 v5, v5, v14
	v_rcp_f32_e32 v13, v12
	s_nop 0
	v_mul_f32_e32 v4, v4, v13
	v_mul_f32_e32 v3, 0xbfb8aa3b, v6
	v_pk_mul_f32 v[4:5], v[8:9], v[4:5]
	v_exp_f32_e32 v8, v3
	v_exp_f32_e32 v9, v0
	v_cvt_pk_bf16_f32 v4, v4, v5
	v_pk_add_f32 v[8:9], v[8:9], 1.0 op_sel_hi:[1,0]
	s_nop 0
	v_rcp_f32_e32 v3, v9
	s_nop 0
	v_mul_f32_e32 v7, v7, v3
	v_rcp_f32_e32 v3, v8
	s_nop 0
	v_mul_f32_e32 v6, v6, v3
	v_pk_mul_f32 v[6:7], v[10:11], v[6:7]
	v_mad_i64_i32 v[2:3], s[36:37], v2, s21, v[66:67]
	v_cvt_pk_bf16_f32 v5, v6, v7
	global_store_dwordx2 v[2:3], v[4:5], off
	s_barrier
	v_readlane_b32 s21, v255, 15
	v_ashrrev_i32_e32 v0, 31, v142
	v_lshrrev_b32_e32 v0, 26, v0
	v_add_u32_e32 v0, v142, v0
	v_ashrrev_i32_e32 v16, 6, v0
	v_bfe_i32 v0, v142, 27, 1
	v_lshlrev_b32_e32 v2, 4, v142
	v_lshrrev_b32_e32 v0, 22, v0
	v_add_u32_e32 v0, v2, v0
	v_and_b32_e32 v0, 0xfffffc00, v0
	v_sub_u32_e32 v0, v2, v0
	v_lshrrev_b32_e32 v3, 4, v0
	v_bitop3_b32 v3, v3, v0, 32 bitop3:0x6c
	v_ashrrev_i32_e32 v0, 31, v0
	v_lshrrev_b32_e32 v0, 26, v0
	v_add_u32_e32 v0, v3, v0
	v_ashrrev_i32_e32 v18, 6, v0
	v_mul_i32_i24_e32 v5, 64, v18
	v_sub_u32_e32 v3, v3, v5
	v_lshlrev_b32_e32 v4, 3, v16
	v_lshlrev_b32_e32 v0, 5, v16
	v_ashrrev_i16_sdwa v3, v217, sext(v3) dst_sel:DWORD dst_unused:UNUSED_PAD src0_sel:DWORD src1_sel:BYTE_0
	v_and_b32_e32 v4, 0x1ffff0, v4
	v_and_b32_e32 v0, 32, v0
	v_bfe_i32 v19, v3, 0, 16
	v_add_u32_e32 v0, v0, v19
	v_add_lshl_u32 v3, v18, v4, 11
	v_add_u32_e32 v2, 0x2000, v2
	v_lshl_add_u32 v0, v0, 1, v3
	v_ashrrev_i32_e32 v3, 31, v2
	v_lshrrev_b32_e32 v3, 22, v3
	v_add_u32_e32 v3, v2, v3
	v_ashrrev_i32_e32 v21, 10, v3
	v_mul_i32_i24_e32 v3, 0x400, v21
	v_sub_u32_e32 v2, v2, v3
	v_lshrrev_b32_e32 v3, 4, v2
	v_bitop3_b32 v2, v3, v2, 32 bitop3:0x6c
	v_ashrrev_i32_e32 v4, 31, v2
	v_ashrrev_i32_e32 v20, 6, v142
	v_lshrrev_b32_e32 v4, 26, v4
	v_readfirstlane_b32 s33, v20
	v_add_u32_e32 v4, v2, v4
	s_lshl_b32 s70, s33, 10
	v_ashrrev_i32_e32 v22, 6, v4
	v_and_b32_e32 v4, 0xc0, v4
	v_sub_u32_e32 v2, v2, v4
	s_add_u32 s44, s20, s44
	v_lshlrev_b32_e32 v3, 3, v21
	v_lshlrev_b32_e32 v5, 5, v21
	v_ashrrev_i16_sdwa v2, v217, sext(v2) dst_sel:DWORD dst_unused:UNUSED_PAD src0_sel:DWORD src1_sel:BYTE_0
	s_addc_u32 s45, s21, s45
	s_add_i32 s36, s70, 0
	v_and_b32_e32 v3, 0x1ffff0, v3
	v_and_b32_e32 v5, 32, v5
	v_bfe_i32 v23, v2, 0, 16
	s_add_i32 s37, s36, 0x10000
	v_add_u32_e32 v2, v5, v23
	v_add_lshl_u32 v3, v22, v3, 11
	s_mov_b32 m0, s37
	s_add_i32 s43, s36, 0x12000
	v_lshl_add_u32 v2, v2, 1, v3
	global_load_lds_dwordx4 v0, s[44:45]
	v_mov_b32_e32 v3, v1
	s_mov_b32 m0, s43
	v_lshl_add_u64 v[4:5], s[44:45], 0, v[0:1]
	v_lshl_add_u64 v[8:9], s[44:45], 0, v[2:3]
	global_load_lds_dwordx4 v2, s[44:45]
	s_mov_b32 m0, s36
	s_add_i32 s44, s36, 0x2000
	global_load_lds_dwordx4 v0, s[22:23]
	s_mov_b32 m0, s44
	v_lshl_add_u64 v[10:11], s[22:23], 0, v[0:1]
	v_lshl_add_u64 v[6:7], s[22:23], 0, v[2:3]
	global_load_lds_dwordx4 v2, s[22:23]
	s_or_b32 s22, s60, 0x180
	s_ashr_i32 s23, s22, 31
	s_lshl_b64 s[22:23], s[22:23], 11
	s_add_u32 s22, s20, s22
	s_addc_u32 s23, s21, s23
	s_add_i32 s45, s36, 0x14000
	s_mov_b32 m0, s45
	s_add_i32 s57, s36, 0x16000
	global_load_lds_dwordx4 v0, s[22:23]
	s_mov_b32 m0, s57
	s_add_i32 s60, s36, 0x4000
	global_load_lds_dwordx4 v2, s[22:23]
	s_mov_b32 m0, s60
	s_add_i32 s61, s36, 0x6000
	global_load_lds_dwordx4 v0, s[16:17]
	s_mov_b32 m0, s61
	v_ashrrev_i32_e32 v17, 8, v142
	global_load_lds_dwordx4 v2, s[16:17]
	v_lshl_add_u64 v[12:13], s[22:23], 0, v[0:1]
	v_lshl_add_u64 v[14:15], s[22:23], 0, v[2:3]
	v_cmp_eq_u32_e32 vcc, 1, v17
	s_and_saveexec_b64 s[22:23], vcc
	v_readlane_b32 s62, v253, 50
	s_cbranch_execz .LBB0_1080
	s_barrier

.LBB0_1084:
	s_or_b64 exec, exec, s[14:15]
	s_movk_i32 s11, 0x410
	v_lshrrev_b32_e32 v130, 2, v142
	v_lshlrev_b32_e32 v131, 1, v142
	v_and_b32_e32 v0, 15, v142
	v_and_b32_e32 v130, 0xfffffcc, v130
	v_and_b32_e32 v131, 0x180, v131
	v_add_u32_e32 v131, 0, v131
	v_lshlrev_b32_e32 v0, 2, v0
	v_mul_lo_u32 v130, v130, s11
	v_add3_u32 v130, v131, v0, v130
	s_waitcnt vmcnt(0)
	s_barrier
	ds_write2_b32 v130, v114, v126 offset1:16
	v_add_u32_e32 v114, 0x400, v130
	ds_write2_b32 v114, v115, v127 offset0:4 offset1:20
	v_add_u32_e32 v115, 0x800, v130
	ds_write2_b32 v115, v116, v128 offset0:8 offset1:24
	v_add_u32_e32 v116, 0xc00, v130
	ds_write2_b32 v116, v117, v129 offset0:12 offset1:28
	v_add_u32_e32 v117, 0x4000, v130
	ds_write2_b32 v117, v82, v94 offset0:64 offset1:80
	v_add_u32_e32 v94, 0x4400, v130
	ds_write2_b32 v94, v83, v95 offset0:68 offset1:84
	v_add_u32_e32 v95, 0x4800, v130
	ds_write2_b32 v95, v84, v96 offset0:72 offset1:88
	v_add_u32_e32 v96, 0x4c00, v130
	ds_write2_b32 v96, v85, v97 offset0:76 offset1:92
	v_add_u32_e32 v132, 0x8000, v130
	v_add_u32_e32 v97, 0x8400, v130
	v_add_u32_e32 v126, 0x8800, v130
	v_add_u32_e32 v127, 0x8c00, v130
	v_add_u32_e32 v133, 0xc000, v130
	v_add_u32_e32 v128, 0xc400, v130
	v_add_u32_e32 v129, 0xc800, v130
	v_add_u32_e32 v131, 0xcc00, v130
	ds_write2_b32 v132, v74, v78 offset0:128 offset1:144
	ds_write2_b32 v97, v75, v79 offset0:132 offset1:148
	ds_write2_b32 v126, v76, v80 offset0:136 offset1:152
	ds_write2_b32 v127, v77, v81 offset0:140 offset1:156
	ds_write2_b32 v133, v66, v70 offset0:192 offset1:208
	ds_write2_b32 v128, v67, v71 offset0:196 offset1:212
	ds_write2_b32 v129, v68, v72 offset0:200 offset1:216
	ds_write2_b32 v131, v69, v73 offset0:204 offset1:220
	ds_write2_b32 v130, v98, v118 offset0:128 offset1:144
	ds_write2_b32 v114, v99, v119 offset0:132 offset1:148
	ds_write2_b32 v115, v100, v120 offset0:136 offset1:152
	ds_write2_b32 v116, v101, v121 offset0:140 offset1:156
	ds_write2_b32 v117, v102, v122 offset0:192 offset1:208
	ds_write2_b32 v94, v103, v123 offset0:196 offset1:212
	ds_write2_b32 v95, v104, v124 offset0:200 offset1:216
	ds_write2_b32 v96, v105, v125 offset0:204 offset1:220
	ds_write2_b32 v97, v90, v110 offset1:16
	ds_write2_b32 v126, v91, v111 offset0:4 offset1:20
	ds_write2_b32 v127, v92, v112 offset0:8 offset1:24
	v_add_u32_e32 v90, 0x9000, v130
	ds_write2_b32 v90, v93, v113 offset0:12 offset1:28
	ds_write2_b32 v128, v86, v106 offset0:64 offset1:80
	ds_write2_b32 v129, v87, v107 offset0:68 offset1:84
	ds_write2_b32 v131, v88, v108 offset0:72 offset1:88
	v_ashrrev_i32_e32 v88, 5, v142
	v_add_u32_e32 v70, s12, v88
	v_ashrrev_i32_e32 v71, 31, v70
	v_add_u32_e32 v91, 0xd000, v130
	v_lshl_add_u64 v[72:73], v[70:71], 4, s[40:41]
	ds_write2_b32 v91, v89, v109 offset0:76 offset1:92
	s_waitcnt lgkmcnt(0)
	s_barrier
	global_load_dwordx4 v[134:137], v[72:73], off
	global_load_dwordx4 v[138:141], v[72:73], off offset:256
	global_load_dwordx4 v[144:147], v[72:73], off offset:512
	global_load_dwordx4 v[148:151], v[72:73], off offset:768
	global_load_dwordx4 v[152:155], v[72:73], off offset:1024
	global_load_dwordx4 v[156:159], v[72:73], off offset:1280
	global_load_dwordx4 v[160:163], v[72:73], off offset:1536
	global_load_dwordx4 v[164:167], v[72:73], off offset:1792
	v_lshlrev_b32_e32 v0, 3, v142
	v_lshlrev_b32_e32 v66, 2, v142
	v_and_b32_e32 v0, 0xe0, v0
	v_and_b32_e32 v69, 12, v66
	v_lshlrev_b32_e32 v66, 2, v0
	v_lshlrev_b32_e32 v67, 2, v69
	v_or_b32_e32 v0, s42, v0
	v_add3_u32 v68, 0, v66, v67
	v_ashrrev_i32_e32 v66, 1, v0
	v_readlane_b32 s14, v255, 27
	v_ashrrev_i32_e32 v67, 31, v66
	v_readlane_b32 s15, v255, 28
	v_lshlrev_b32_e32 v0, 1, v69
	s_mov_b32 s7, 0x800000
	v_lshl_add_u64 v[66:67], v[66:67], 1, s[14:15]
	v_lshl_add_u64 v[66:67], v[66:67], 0, v[0:1]
	v_mad_u64_u32 v[82:83], s[14:15], v88, s11, v[68:69]
	s_movk_i32 s16, 0x1600
	s_mov_b64 s[22:23], -1
	s_waitcnt vmcnt(0)
	v_add_f32_e32 v0, v134, v135
	v_add_f32_e32 v0, v0, v136
	v_add_f32_e32 v0, v0, v137
	v_fmamk_f32 v0, v0, 0x3a800000, v200
	v_cmp_gt_f32_e32 vcc, s7, v0
	v_mul_f32_e32 v69, 0x4b800000, v0
	ds_read_b128 v[72:75], v82
	ds_read_b128 v[76:79], v82 offset:64
	v_cndmask_b32_e32 v0, v0, v69, vcc
	v_rsq_f32_e32 v0, v0
	s_nop 0
	v_mul_f32_e32 v69, 0x45800000, v0
	v_cndmask_b32_e32 v0, v0, v69, vcc
	s_waitcnt lgkmcnt(1)
	v_pk_mul_f32 v[72:73], v[72:73], v[0:1] op_sel_hi:[1,0]
	v_pk_mul_f32 v[74:75], v[74:75], v[0:1] op_sel_hi:[1,0]
	v_mul_f32_e32 v69, 0xbfb8aa3b, v72
	v_exp_f32_e32 v80, v69
	v_mul_f32_e32 v69, 0xbfb8aa3b, v73
	v_exp_f32_e32 v81, v69
	s_waitcnt lgkmcnt(0)
	v_pk_mul_f32 v[76:77], v[76:77], v[0:1] op_sel_hi:[1,0]
	v_pk_mul_f32 v[78:79], v[78:79], v[0:1] op_sel_hi:[1,0]
	v_mul_f32_e32 v0, 0xbfb8aa3b, v75
	v_pk_add_f32 v[80:81], v[80:81], 1.0 op_sel_hi:[1,0]
	s_nop 0
	v_rcp_f32_e32 v71, v81
	s_nop 0
	v_mul_f32_e32 v73, v73, v71
	v_rcp_f32_e32 v71, v80
	s_nop 0
	v_mul_f32_e32 v72, v72, v71
	v_mul_f32_e32 v69, 0xbfb8aa3b, v74
	v_pk_mul_f32 v[72:73], v[76:77], v[72:73]
	v_exp_f32_e32 v76, v69
	v_exp_f32_e32 v77, v0
	v_cvt_pk_bf16_f32 v72, v72, v73
	v_pk_add_f32 v[76:77], v[76:77], 1.0 op_sel_hi:[1,0]
	s_nop 0
	v_rcp_f32_e32 v69, v77
	s_nop 0
	v_mul_f32_e32 v75, v75, v69
	v_rcp_f32_e32 v69, v76
	s_nop 0
	v_mul_f32_e32 v74, v74, v69
	v_pk_mul_f32 v[74:75], v[78:79], v[74:75]
	v_add_u32_e32 v0, 0x200, v142
	v_cvt_pk_bf16_f32 v73, v74, v75
	v_mad_i64_i32 v[70:71], s[14:15], v70, s16, v[66:67]
	v_ashrrev_i32_e32 v83, 5, v0
	global_store_dwordx2 v[70:71], v[72:73], off
	v_add_u32_e32 v70, s12, v83
	v_ashrrev_i32_e32 v71, 31, v70
	v_lshl_add_u64 v[72:73], v[70:71], 4, s[40:41]
	v_mad_u64_u32 v[80:81], s[14:15], v83, s11, v[68:69]
	v_add_f32_e32 v0, v138, v139
	v_add_f32_e32 v0, v0, v140
	v_add_f32_e32 v0, v0, v141
	v_fmamk_f32 v0, v0, 0x3a800000, v200
	v_cmp_gt_f32_e32 vcc, s7, v0
	v_mul_f32_e32 v69, 0x4b800000, v0
	ds_read_b128 v[72:75], v80
	ds_read_b128 v[76:79], v80 offset:64
	v_cndmask_b32_e32 v0, v0, v69, vcc
	v_rsq_f32_e32 v0, v0
	s_nop 0
	v_mul_f32_e32 v69, 0x45800000, v0
	v_cndmask_b32_e32 v0, v0, v69, vcc
	s_waitcnt lgkmcnt(1)
	v_pk_mul_f32 v[72:73], v[72:73], v[0:1] op_sel_hi:[1,0]
	v_pk_mul_f32 v[74:75], v[74:75], v[0:1] op_sel_hi:[1,0]
	v_mul_f32_e32 v69, 0xbfb8aa3b, v72
	v_exp_f32_e32 v84, v69
	v_mul_f32_e32 v69, 0xbfb8aa3b, v73
	v_exp_f32_e32 v85, v69
	s_waitcnt lgkmcnt(0)
	v_pk_mul_f32 v[76:77], v[76:77], v[0:1] op_sel_hi:[1,0]
	v_pk_mul_f32 v[78:79], v[78:79], v[0:1] op_sel_hi:[1,0]
	v_mul_f32_e32 v0, 0xbfb8aa3b, v75
	v_pk_add_f32 v[84:85], v[84:85], 1.0 op_sel_hi:[1,0]
	s_nop 0
	v_rcp_f32_e32 v71, v85
	s_nop 0
	v_mul_f32_e32 v73, v73, v71
	v_rcp_f32_e32 v71, v84
	s_nop 0
	v_mul_f32_e32 v72, v72, v71
	v_mul_f32_e32 v69, 0xbfb8aa3b, v74
	v_pk_mul_f32 v[72:73], v[76:77], v[72:73]
	v_exp_f32_e32 v76, v69
	v_exp_f32_e32 v77, v0
	v_cvt_pk_bf16_f32 v72, v72, v73
	v_pk_add_f32 v[76:77], v[76:77], 1.0 op_sel_hi:[1,0]
	s_nop 0
	v_rcp_f32_e32 v69, v77
	s_nop 0
	v_mul_f32_e32 v75, v75, v69
	v_rcp_f32_e32 v69, v76
	s_nop 0
	v_mul_f32_e32 v74, v74, v69
	v_pk_mul_f32 v[74:75], v[78:79], v[74:75]
	v_add_u32_e32 v0, 0x400, v142
	v_cvt_pk_bf16_f32 v73, v74, v75
	v_mad_i64_i32 v[70:71], s[14:15], v70, s16, v[66:67]
	v_ashrrev_i32_e32 v81, 5, v0
	global_store_dwordx2 v[70:71], v[72:73], off
	v_add_u32_e32 v70, s12, v81
	v_ashrrev_i32_e32 v71, 31, v70
	v_lshl_add_u64 v[72:73], v[70:71], 4, s[40:41]
	v_mad_u64_u32 v[78:79], s[14:15], v81, s11, v[68:69]
	v_add_f32_e32 v0, v144, v145
	v_add_f32_e32 v0, v0, v146
	v_add_f32_e32 v0, v0, v147
	v_fmamk_f32 v0, v0, 0x3a800000, v200
	v_cmp_gt_f32_e32 vcc, s7, v0
	v_mul_f32_e32 v69, 0x4b800000, v0
	ds_read_b128 v[72:75], v78
	ds_read_b128 v[84:87], v78 offset:64
	v_cndmask_b32_e32 v0, v0, v69, vcc
	v_rsq_f32_e32 v0, v0
	s_nop 0
	v_mul_f32_e32 v69, 0x45800000, v0
	v_cndmask_b32_e32 v0, v0, v69, vcc
	s_waitcnt lgkmcnt(1)
	v_pk_mul_f32 v[72:73], v[72:73], v[0:1] op_sel_hi:[1,0]
	v_pk_mul_f32 v[74:75], v[74:75], v[0:1] op_sel_hi:[1,0]
	v_mul_f32_e32 v69, 0xbfb8aa3b, v72
	v_exp_f32_e32 v76, v69
	v_mul_f32_e32 v69, 0xbfb8aa3b, v73
	v_exp_f32_e32 v77, v69
	s_waitcnt lgkmcnt(0)
	v_pk_mul_f32 v[84:85], v[84:85], v[0:1] op_sel_hi:[1,0]
	v_pk_add_f32 v[76:77], v[76:77], 1.0 op_sel_hi:[1,0]
	s_nop 0
	v_rcp_f32_e32 v71, v77
	s_nop 0
	v_mul_f32_e32 v73, v73, v71
	v_rcp_f32_e32 v71, v76
	s_nop 0
	v_mul_f32_e32 v72, v72, v71
	v_mul_f32_e32 v69, 0xbfb8aa3b, v74
	v_pk_mul_f32 v[76:77], v[86:87], v[0:1] op_sel_hi:[1,0]
	v_mul_f32_e32 v0, 0xbfb8aa3b, v75
	v_pk_mul_f32 v[72:73], v[84:85], v[72:73]
	v_exp_f32_e32 v84, v69
	v_exp_f32_e32 v85, v0
	v_cvt_pk_bf16_f32 v72, v72, v73
	v_pk_add_f32 v[84:85], v[84:85], 1.0 op_sel_hi:[1,0]
	s_nop 0
	v_rcp_f32_e32 v69, v85
	s_nop 0
	v_mul_f32_e32 v75, v75, v69
	v_rcp_f32_e32 v69, v84
	s_nop 0
	v_mul_f32_e32 v74, v74, v69
	v_add_u32_e32 v0, 0x600, v142
	v_pk_mul_f32 v[74:75], v[76:77], v[74:75]
	v_ashrrev_i32_e32 v79, 5, v0
	v_cvt_pk_bf16_f32 v73, v74, v75
	v_add_u32_e32 v74, s12, v79
	v_mad_i64_i32 v[70:71], s[14:15], v70, s16, v[66:67]
	v_ashrrev_i32_e32 v75, 31, v74
	global_store_dwordx2 v[70:71], v[72:73], off
	v_lshl_add_u64 v[70:71], v[74:75], 4, s[40:41]
	v_mad_u64_u32 v[76:77], s[14:15], v79, s11, v[68:69]
	v_add_f32_e32 v0, v148, v149
	v_add_f32_e32 v0, v0, v150
	v_add_f32_e32 v0, v0, v151
	v_fmamk_f32 v0, v0, 0x3a800000, v200
	v_cmp_gt_f32_e32 vcc, s7, v0
	v_mul_f32_e32 v69, 0x4b800000, v0
	ds_read_b128 v[70:73], v76
	ds_read_b128 v[84:87], v76 offset:64
	v_cndmask_b32_e32 v0, v0, v69, vcc
	v_rsq_f32_e32 v0, v0
	s_nop 0
	v_mul_f32_e32 v69, 0x45800000, v0
	v_cndmask_b32_e32 v0, v0, v69, vcc
	s_waitcnt lgkmcnt(1)
	v_pk_mul_f32 v[70:71], v[70:71], v[0:1] op_sel_hi:[1,0]
	v_pk_mul_f32 v[72:73], v[72:73], v[0:1] op_sel_hi:[1,0]
	v_mul_f32_e32 v69, 0xbfb8aa3b, v70
	v_exp_f32_e32 v92, v69
	v_mul_f32_e32 v69, 0xbfb8aa3b, v71
	v_exp_f32_e32 v93, v69
	s_waitcnt lgkmcnt(0)
	v_pk_mul_f32 v[84:85], v[84:85], v[0:1] op_sel_hi:[1,0]
	v_pk_mul_f32 v[86:87], v[86:87], v[0:1] op_sel_hi:[1,0]
	v_mul_f32_e32 v0, 0xbfb8aa3b, v73
	v_pk_add_f32 v[92:93], v[92:93], 1.0 op_sel_hi:[1,0]
	s_nop 0
	v_rcp_f32_e32 v75, v93
	s_nop 0
	v_mul_f32_e32 v71, v71, v75
	v_rcp_f32_e32 v75, v92
	s_nop 0
	v_mul_f32_e32 v70, v70, v75
	v_mul_f32_e32 v69, 0xbfb8aa3b, v72
	v_pk_mul_f32 v[70:71], v[84:85], v[70:71]
	v_exp_f32_e32 v84, v69
	v_exp_f32_e32 v85, v0
	v_cvt_pk_bf16_f32 v70, v70, v71
	v_pk_add_f32 v[84:85], v[84:85], 1.0 op_sel_hi:[1,0]
	s_nop 0
	v_rcp_f32_e32 v69, v85
	s_nop 0
	v_mul_f32_e32 v73, v73, v69
	v_rcp_f32_e32 v69, v84
	s_nop 0
	v_mul_f32_e32 v72, v72, v69
	v_pk_mul_f32 v[72:73], v[86:87], v[72:73]
	v_add_u32_e32 v0, 0x800, v142
	v_cvt_pk_bf16_f32 v71, v72, v73
	v_mad_i64_i32 v[72:73], s[14:15], v74, s16, v[66:67]
	v_ashrrev_i32_e32 v0, 5, v0
	global_store_dwordx2 v[72:73], v[70:71], off
	v_add_u32_e32 v72, s12, v0
	v_ashrrev_i32_e32 v73, 31, v72
	v_lshl_add_u64 v[74:75], v[72:73], 4, s[40:41]
	v_mad_u64_u32 v[70:71], s[14:15], v0, s11, v[68:69]
	v_add_f32_e32 v69, v152, v153
	v_add_f32_e32 v69, v69, v154
	v_add_f32_e32 v69, v69, v155
	v_fmamk_f32 v69, v69, 0x3a800000, v200
	v_cmp_gt_f32_e32 vcc, s7, v69
	v_mul_f32_e32 v71, 0x4b800000, v69
	ds_read_b128 v[84:87], v70
	ds_read_b128 v[98:101], v70 offset:64
	v_cndmask_b32_e32 v69, v69, v71, vcc
	v_rsq_f32_e32 v69, v69
	s_nop 0
	v_mul_f32_e32 v71, 0x45800000, v69
	v_cndmask_b32_e32 v74, v69, v71, vcc
	s_waitcnt lgkmcnt(1)
	v_pk_mul_f32 v[84:85], v[84:85], v[74:75] op_sel_hi:[1,0]
	s_waitcnt lgkmcnt(0)
	v_pk_mul_f32 v[98:99], v[98:99], v[74:75] op_sel_hi:[1,0]
	v_mul_f32_e32 v69, 0xbfb8aa3b, v84
	v_exp_f32_e32 v92, v69
	v_mul_f32_e32 v69, 0xbfb8aa3b, v85
	v_exp_f32_e32 v93, v69
	s_nop 0
	v_pk_add_f32 v[92:93], v[92:93], 1.0 op_sel_hi:[1,0]
	s_nop 0
	v_rcp_f32_e32 v71, v93
	s_nop 0
	v_mul_f32_e32 v85, v85, v71
	v_div_scale_f32 v69, s[14:15], v92, v92, v84
	v_rcp_f32_e32 v71, v69
	s_nop 0
	v_fma_f32 v73, -v69, v71, 1.0
	v_fmac_f32_e32 v71, v73, v71
	v_div_scale_f32 v73, vcc, v84, v92, v84
	v_mul_f32_e32 v75, v73, v71
	v_fma_f32 v77, -v69, v75, v73
	v_fmac_f32_e32 v75, v77, v71
	v_fma_f32 v69, -v69, v75, v73
	v_div_fmas_f32 v69, v69, v71, v75
	v_pk_mul_f32 v[86:87], v[86:87], v[74:75] op_sel_hi:[1,0]
	v_div_fixup_f32 v84, v69, v92, v84
	v_mul_f32_e32 v69, 0xbfb8aa3b, v86
	v_exp_f32_e32 v92, v69
	v_mul_f32_e32 v69, 0xbfb8aa3b, v87
	v_exp_f32_e32 v93, v69
	v_pk_mul_f32 v[74:75], v[100:101], v[74:75] op_sel_hi:[1,0]
	v_pk_mul_f32 v[84:85], v[98:99], v[84:85]
	v_pk_add_f32 v[92:93], v[92:93], 1.0 op_sel_hi:[1,0]
	s_nop 0
	v_div_scale_f32 v69, s[14:15], v93, v93, v87
	v_rcp_f32_e32 v71, v69
	v_cvt_pk_bf16_f32 v84, v84, v85
	v_fma_f32 v73, -v69, v71, 1.0
	v_fmac_f32_e32 v71, v73, v71
	v_div_scale_f32 v73, vcc, v87, v93, v87
	v_mul_f32_e32 v77, v73, v71
	v_fma_f32 v89, -v69, v77, v73
	v_fmac_f32_e32 v77, v89, v71
	v_fma_f32 v69, -v69, v77, v73
	v_div_fmas_f32 v69, v69, v71, v77
	v_div_fixup_f32 v87, v69, v93, v87
	v_rcp_f32_e32 v71, v92
	s_nop 0
	v_mul_f32_e32 v86, v86, v71
	v_add_u32_e32 v69, 0xa00, v142
	v_pk_mul_f32 v[74:75], v[74:75], v[86:87]
	v_ashrrev_i32_e32 v71, 5, v69
	v_cvt_pk_bf16_f32 v85, v74, v75
	v_add_u32_e32 v74, s12, v71
	v_mad_i64_i32 v[72:73], s[14:15], v72, s16, v[66:67]
	v_ashrrev_i32_e32 v75, 31, v74
	global_store_dwordx2 v[72:73], v[84:85], off
	v_lshl_add_u64 v[84:85], v[74:75], 4, s[40:41]
	v_mad_u64_u32 v[72:73], s[14:15], v71, s11, v[68:69]
	v_add_f32_e32 v69, v156, v157
	v_add_f32_e32 v69, v69, v158
	v_add_f32_e32 v69, v69, v159
	v_fmamk_f32 v69, v69, 0x3a800000, v200
	v_cmp_gt_f32_e32 vcc, s7, v69
	v_mul_f32_e32 v73, 0x4b800000, v69
	ds_read_b128 v[84:87], v72
	ds_read_b128 v[98:101], v72 offset:64
	v_cndmask_b32_e32 v69, v69, v73, vcc
	v_rsq_f32_e32 v69, v69
	s_nop 0
	v_mul_f32_e32 v73, 0x45800000, v69
	v_cndmask_b32_e32 v92, v69, v73, vcc
	s_waitcnt lgkmcnt(1)
	v_pk_mul_f32 v[84:85], v[84:85], v[92:93] op_sel_hi:[1,0]
	v_pk_mul_f32 v[86:87], v[86:87], v[92:93] op_sel_hi:[1,0]
	v_mul_f32_e32 v69, 0xbfb8aa3b, v84
	v_exp_f32_e32 v102, v69
	v_mul_f32_e32 v69, 0xbfb8aa3b, v85
	v_exp_f32_e32 v103, v69
	s_waitcnt lgkmcnt(0)
	v_pk_mul_f32 v[98:99], v[98:99], v[92:93] op_sel_hi:[1,0]
	v_pk_mul_f32 v[92:93], v[100:101], v[92:93] op_sel_hi:[1,0]
	v_pk_add_f32 v[102:103], v[102:103], 1.0 op_sel_hi:[1,0]
	s_nop 0
	v_rcp_f32_e32 v73, v103
	s_nop 0
	v_mul_f32_e32 v85, v85, v73
	v_rcp_f32_e32 v73, v102
	s_nop 0
	v_mul_f32_e32 v84, v84, v73
	v_mul_f32_e32 v69, 0xbfb8aa3b, v86
	v_pk_mul_f32 v[84:85], v[98:99], v[84:85]
	v_exp_f32_e32 v98, v69
	v_mul_f32_e32 v69, 0xbfb8aa3b, v87
	v_exp_f32_e32 v99, v69
	v_cvt_pk_bf16_f32 v84, v84, v85
	v_pk_add_f32 v[98:99], v[98:99], 1.0 op_sel_hi:[1,0]
	s_nop 0
	v_rcp_f32_e32 v73, v99
	s_nop 0
	v_mul_f32_e32 v87, v87, v73
	v_rcp_f32_e32 v73, v98
	s_nop 0
	v_mul_f32_e32 v86, v86, v73
	v_pk_mul_f32 v[86:87], v[92:93], v[86:87]
	v_add_u32_e32 v69, 0xc00, v142
	v_cvt_pk_bf16_f32 v85, v86, v87
	v_mad_i64_i32 v[74:75], s[14:15], v74, s16, v[66:67]
	v_ashrrev_i32_e32 v73, 5, v69
	global_store_dwordx2 v[74:75], v[84:85], off
	v_add_u32_e32 v84, s12, v73
	v_ashrrev_i32_e32 v85, 31, v84
	v_lshl_add_u64 v[86:87], v[84:85], 4, s[40:41]
	v_mad_u64_u32 v[74:75], s[14:15], v73, s11, v[68:69]
	v_add_f32_e32 v69, v160, v161
	v_add_f32_e32 v69, v69, v162
	v_add_f32_e32 v69, v69, v163
	v_fmamk_f32 v69, v69, 0x3a800000, v200
	v_cmp_gt_f32_e32 vcc, s7, v69
	v_mul_f32_e32 v75, 0x4b800000, v69
	ds_read_b128 v[98:101], v74
	ds_read_b128 v[102:105], v74 offset:64
	v_cndmask_b32_e32 v69, v69, v75, vcc
	v_rsq_f32_e32 v69, v69
	s_nop 0
	v_mul_f32_e32 v75, 0x45800000, v69
	v_cndmask_b32_e32 v86, v69, v75, vcc
	s_waitcnt lgkmcnt(1)
	v_pk_mul_f32 v[92:93], v[98:99], v[86:87] op_sel_hi:[1,0]
	s_waitcnt lgkmcnt(0)
	v_pk_mul_f32 v[102:103], v[102:103], v[86:87] op_sel_hi:[1,0]
	v_mul_f32_e32 v69, 0xbfb8aa3b, v92
	v_exp_f32_e32 v98, v69
	v_mul_f32_e32 v69, 0xbfb8aa3b, v93
	v_exp_f32_e32 v99, v69
	s_nop 0
	v_pk_add_f32 v[98:99], v[98:99], 1.0 op_sel_hi:[1,0]
	s_nop 0
	v_rcp_f32_e32 v75, v99
	s_nop 0
	v_mul_f32_e32 v93, v93, v75
	v_rcp_f32_e32 v75, v98
	s_nop 0
	v_mul_f32_e32 v92, v92, v75
	v_pk_mul_f32 v[98:99], v[100:101], v[86:87] op_sel_hi:[1,0]
	v_pk_mul_f32 v[86:87], v[104:105], v[86:87] op_sel_hi:[1,0]
	v_mul_f32_e32 v69, 0xbfb8aa3b, v98
	v_exp_f32_e32 v100, v69
	v_mul_f32_e32 v69, 0xbfb8aa3b, v99
	v_exp_f32_e32 v101, v69
	v_pk_mul_f32 v[92:93], v[102:103], v[92:93]
	v_pk_add_f32 v[100:101], v[100:101], 1.0 op_sel_hi:[1,0]
	s_nop 0
	v_div_scale_f32 v69, s[14:15], v101, v101, v99
	v_rcp_f32_e32 v75, v69
	v_cvt_pk_bf16_f32 v92, v92, v93
	v_fma_f32 v77, -v69, v75, 1.0
	v_fmac_f32_e32 v75, v77, v75
	v_div_scale_f32 v77, vcc, v99, v101, v99
	v_mul_f32_e32 v85, v77, v75
	v_fma_f32 v89, -v69, v85, v77
	v_fmac_f32_e32 v85, v89, v75
	v_fma_f32 v69, -v69, v85, v77
	v_div_fmas_f32 v69, v69, v75, v85
	v_div_fixup_f32 v99, v69, v101, v99
	v_rcp_f32_e32 v75, v100
	s_nop 0
	v_mul_f32_e32 v98, v98, v75
	v_pk_mul_f32 v[86:87], v[86:87], v[98:99]
	v_add_u32_e32 v69, 0xe00, v142
	v_cvt_pk_bf16_f32 v93, v86, v87
	v_mad_i64_i32 v[84:85], s[14:15], v84, s16, v[66:67]
	v_ashrrev_i32_e32 v75, 5, v69
	global_store_dwordx2 v[84:85], v[92:93], off
	v_add_u32_e32 v84, s12, v75
	v_ashrrev_i32_e32 v85, 31, v84
	v_lshl_add_u64 v[86:87], v[84:85], 4, s[40:41]
	v_mad_u64_u32 v[68:69], s[14:15], v75, s11, v[68:69]
	v_add_f32_e32 v69, v164, v165
	v_add_f32_e32 v69, v69, v166
	v_add_f32_e32 v69, v69, v167
	v_fmamk_f32 v69, v69, 0x3a800000, v200
	v_cmp_gt_f32_e32 vcc, s7, v69
	v_mul_f32_e32 v77, 0x4b800000, v69
	ds_read_b128 v[98:101], v68
	ds_read_b128 v[102:105], v68 offset:64
	v_cndmask_b32_e32 v69, v69, v77, vcc
	v_rsq_f32_e32 v69, v69
	s_nop 0
	v_mul_f32_e32 v77, 0x45800000, v69
	v_cndmask_b32_e32 v86, v69, v77, vcc
	s_waitcnt lgkmcnt(1)
	v_pk_mul_f32 v[92:93], v[98:99], v[86:87] op_sel_hi:[1,0]
	s_waitcnt lgkmcnt(0)
	v_pk_mul_f32 v[102:103], v[102:103], v[86:87] op_sel_hi:[1,0]
	v_mul_f32_e32 v69, 0xbfb8aa3b, v92
	v_exp_f32_e32 v98, v69
	v_mul_f32_e32 v69, 0xbfb8aa3b, v93
	v_exp_f32_e32 v99, v69
	s_nop 0
	v_pk_add_f32 v[98:99], v[98:99], 1.0 op_sel_hi:[1,0]
	s_nop 0
	v_rcp_f32_e32 v77, v99
	s_nop 0
	v_mul_f32_e32 v93, v93, v77
	v_rcp_f32_e32 v77, v98
	s_nop 0
	v_mul_f32_e32 v92, v92, v77
	v_pk_mul_f32 v[98:99], v[100:101], v[86:87] op_sel_hi:[1,0]
	v_pk_mul_f32 v[92:93], v[102:103], v[92:93]
	v_mul_f32_e32 v69, 0xbfb8aa3b, v98
	v_exp_f32_e32 v100, v69
	v_mul_f32_e32 v69, 0xbfb8aa3b, v99
	v_exp_f32_e32 v101, v69
	v_pk_mul_f32 v[86:87], v[104:105], v[86:87] op_sel_hi:[1,0]
	v_cvt_pk_bf16_f32 v92, v92, v93
	v_pk_add_f32 v[100:101], v[100:101], 1.0 op_sel_hi:[1,0]
	s_nop 0
	v_rcp_f32_e32 v77, v101
	s_nop 0
	v_mul_f32_e32 v99, v99, v77
	v_rcp_f32_e32 v77, v100
	s_nop 0
	v_mul_f32_e32 v98, v98, v77
	v_pk_mul_f32 v[86:87], v[86:87], v[98:99]
	v_mad_i64_i32 v[84:85], s[12:13], v84, s16, v[66:67]
	v_cvt_pk_bf16_f32 v93, v86, v87
	global_store_dwordx2 v[84:85], v[92:93], off
	s_barrier
	ds_write2_b32 v130, v2, v18 offset1:16
	ds_write2_b32 v114, v3, v19 offset0:4 offset1:20
	ds_write2_b32 v115, v4, v20 offset0:8 offset1:24
	ds_write2_b32 v116, v5, v21 offset0:12 offset1:28
	ds_write2_b32 v117, v6, v22 offset0:64 offset1:80
	ds_write2_b32 v94, v7, v23 offset0:68 offset1:84
	ds_write2_b32 v95, v8, v24 offset0:72 offset1:88
	ds_write2_b32 v96, v9, v25 offset0:76 offset1:92
	ds_write2_b32 v132, v10, v26 offset0:128 offset1:144
	ds_write2_b32 v97, v11, v27 offset0:132 offset1:148
	ds_write2_b32 v126, v12, v28 offset0:136 offset1:152
	ds_write2_b32 v127, v13, v29 offset0:140 offset1:156
	ds_write2_b32 v133, v14, v30 offset0:192 offset1:208
	ds_write2_b32 v128, v15, v31 offset0:196 offset1:212
	ds_write2_b32 v129, v16, v32 offset0:200 offset1:216
	ds_write2_b32 v131, v17, v33 offset0:204 offset1:220
	ds_write2_b32 v130, v34, v50 offset0:128 offset1:144
	ds_write2_b32 v114, v35, v51 offset0:132 offset1:148
	ds_write2_b32 v115, v36, v52 offset0:136 offset1:152
	ds_write2_b32 v116, v37, v53 offset0:140 offset1:156
	ds_write2_b32 v117, v38, v54 offset0:192 offset1:208
	ds_write2_b32 v94, v39, v55 offset0:196 offset1:212
	ds_write2_b32 v95, v40, v56 offset0:200 offset1:216
	ds_write2_b32 v96, v41, v57 offset0:204 offset1:220
	ds_write2_b32 v97, v42, v58 offset1:16
	ds_write2_b32 v126, v43, v59 offset0:4 offset1:20
	ds_write2_b32 v127, v44, v60 offset0:8 offset1:24
	ds_write2_b32 v90, v45, v61 offset0:12 offset1:28
	ds_write2_b32 v128, v46, v62 offset0:64 offset1:80
	ds_write2_b32 v129, v47, v63 offset0:68 offset1:84
	ds_write2_b32 v131, v48, v64 offset0:72 offset1:88
	ds_write2_b32 v91, v49, v65 offset0:76 offset1:92
	v_add_u32_e32 v2, s10, v88
	v_ashrrev_i32_e32 v3, 31, v2
	v_lshl_add_u64 v[4:5], v[2:3], 4, s[40:41]
	s_waitcnt lgkmcnt(0)
	s_barrier
	global_load_dwordx4 v[134:137], v[4:5], off
	global_load_dwordx4 v[138:141], v[4:5], off offset:256
	global_load_dwordx4 v[144:147], v[4:5], off offset:512
	global_load_dwordx4 v[148:151], v[4:5], off offset:768
	global_load_dwordx4 v[152:155], v[4:5], off offset:1024
	global_load_dwordx4 v[156:159], v[4:5], off offset:1280
	global_load_dwordx4 v[160:163], v[4:5], off offset:1536
	global_load_dwordx4 v[164:167], v[4:5], off offset:1792
	s_waitcnt vmcnt(0)
	v_add_f32_e32 v3, v134, v135
	v_add_f32_e32 v3, v3, v136
	v_add_f32_e32 v3, v3, v137
	v_fmamk_f32 v3, v3, 0x3a800000, v200
	v_cmp_gt_f32_e32 vcc, s7, v3
	v_mul_f32_e32 v4, 0x4b800000, v3
	s_nop 0
	v_cndmask_b32_e32 v3, v3, v4, vcc
	v_rsq_f32_e32 v3, v3
	s_nop 0
	v_mul_f32_e32 v4, 0x45800000, v3
	v_cndmask_b32_e32 v12, v3, v4, vcc
	ds_read_b128 v[4:7], v82
	ds_read_b128 v[8:11], v82 offset:64
	s_waitcnt lgkmcnt(1)
	v_pk_mul_f32 v[4:5], v[4:5], v[12:13] op_sel_hi:[1,0]
	s_nop 0
	v_mul_f32_e32 v3, 0xbfb8aa3b, v4
	v_exp_f32_e32 v14, v3
	v_mul_f32_e32 v3, 0xbfb8aa3b, v5
	v_exp_f32_e32 v15, v3
	s_waitcnt lgkmcnt(0)
	v_pk_mul_f32 v[8:9], v[8:9], v[12:13] op_sel_hi:[1,0]
	v_pk_add_f32 v[14:15], v[14:15], 1.0 op_sel_hi:[1,0]
	s_nop 0
	v_rcp_f32_e32 v13, v15
	s_nop 0
	v_mul_f32_e32 v5, v5, v13
	v_div_scale_f32 v3, s[12:13], v14, v14, v4
	v_rcp_f32_e32 v13, v3
	s_nop 0
	v_fma_f32 v15, -v3, v13, 1.0
	v_fmac_f32_e32 v13, v15, v13
	v_div_scale_f32 v15, vcc, v4, v14, v4
	v_mul_f32_e32 v16, v15, v13
	v_fma_f32 v17, -v3, v16, v15
	v_fmac_f32_e32 v16, v17, v13
	v_fma_f32 v3, -v3, v16, v15
	v_div_fmas_f32 v3, v3, v13, v16
	v_pk_mul_f32 v[6:7], v[6:7], v[12:13] op_sel_hi:[1,0]
	v_div_fixup_f32 v4, v3, v14, v4
	v_mul_f32_e32 v3, 0xbfb8aa3b, v6
	v_pk_mul_f32 v[4:5], v[8:9], v[4:5]
	v_exp_f32_e32 v8, v3
	v_mul_f32_e32 v3, 0xbfb8aa3b, v7
	v_exp_f32_e32 v9, v3
	v_pk_mul_f32 v[10:11], v[10:11], v[12:13] op_sel_hi:[1,0]
	v_cvt_pk_bf16_f32 v4, v4, v5
	v_pk_add_f32 v[8:9], v[8:9], 1.0 op_sel_hi:[1,0]
	s_nop 0
	v_rcp_f32_e32 v12, v9
	s_nop 0
	v_mul_f32_e32 v7, v7, v12
	v_rcp_f32_e32 v9, v8
	s_nop 0
	v_mul_f32_e32 v6, v6, v9
	v_pk_mul_f32 v[6:7], v[10:11], v[6:7]
	v_mad_i64_i32 v[2:3], s[12:13], v2, s16, v[66:67]
	v_cvt_pk_bf16_f32 v5, v6, v7
	global_store_dwordx2 v[2:3], v[4:5], off
	v_add_u32_e32 v2, s10, v83
	v_ashrrev_i32_e32 v3, 31, v2
	v_lshl_add_u64 v[4:5], v[2:3], 4, s[40:41]
	v_add_f32_e32 v3, v138, v139
	v_add_f32_e32 v3, v3, v140
	v_add_f32_e32 v3, v3, v141
	v_fmamk_f32 v3, v3, 0x3a800000, v200
	v_cmp_gt_f32_e32 vcc, s7, v3
	v_mul_f32_e32 v4, 0x4b800000, v3
	s_nop 0
	v_cndmask_b32_e32 v3, v3, v4, vcc
	v_rsq_f32_e32 v3, v3
	s_nop 0
	v_mul_f32_e32 v4, 0x45800000, v3
	v_cndmask_b32_e32 v12, v3, v4, vcc
	ds_read_b128 v[4:7], v80
	ds_read_b128 v[8:11], v80 offset:64
	s_waitcnt lgkmcnt(1)
	v_pk_mul_f32 v[4:5], v[4:5], v[12:13] op_sel_hi:[1,0]
	s_nop 0
	v_mul_f32_e32 v3, 0xbfb8aa3b, v4
	v_exp_f32_e32 v14, v3
	v_mul_f32_e32 v3, 0xbfb8aa3b, v5
	v_exp_f32_e32 v15, v3
	s_waitcnt lgkmcnt(0)
	v_pk_mul_f32 v[8:9], v[8:9], v[12:13] op_sel_hi:[1,0]
	v_pk_add_f32 v[14:15], v[14:15], 1.0 op_sel_hi:[1,0]
	s_nop 0
	v_rcp_f32_e32 v13, v15
	s_nop 0
	v_mul_f32_e32 v5, v5, v13
	v_div_scale_f32 v3, s[12:13], v14, v14, v4
	v_rcp_f32_e32 v13, v3
	s_nop 0
	v_fma_f32 v15, -v3, v13, 1.0
	v_fmac_f32_e32 v13, v15, v13
	v_div_scale_f32 v15, vcc, v4, v14, v4
	v_mul_f32_e32 v16, v15, v13
	v_fma_f32 v17, -v3, v16, v15
	v_fmac_f32_e32 v16, v17, v13
	v_fma_f32 v3, -v3, v16, v15
	v_div_fmas_f32 v3, v3, v13, v16
	v_pk_mul_f32 v[6:7], v[6:7], v[12:13] op_sel_hi:[1,0]
	v_div_fixup_f32 v4, v3, v14, v4
	v_mul_f32_e32 v3, 0xbfb8aa3b, v6
	v_pk_mul_f32 v[4:5], v[8:9], v[4:5]
	v_exp_f32_e32 v8, v3
	v_mul_f32_e32 v3, 0xbfb8aa3b, v7
	v_exp_f32_e32 v9, v3
	v_pk_mul_f32 v[10:11], v[10:11], v[12:13] op_sel_hi:[1,0]
	v_cvt_pk_bf16_f32 v4, v4, v5
	v_pk_add_f32 v[8:9], v[8:9], 1.0 op_sel_hi:[1,0]
	s_nop 0
	v_rcp_f32_e32 v12, v9
	s_nop 0
	v_mul_f32_e32 v7, v7, v12
	v_rcp_f32_e32 v9, v8
	s_nop 0
	v_mul_f32_e32 v6, v6, v9
	v_pk_mul_f32 v[6:7], v[10:11], v[6:7]
	v_mad_i64_i32 v[2:3], s[12:13], v2, s16, v[66:67]
	v_cvt_pk_bf16_f32 v5, v6, v7
	global_store_dwordx2 v[2:3], v[4:5], off
	v_add_u32_e32 v2, s10, v81
	v_ashrrev_i32_e32 v3, 31, v2
	v_lshl_add_u64 v[4:5], v[2:3], 4, s[40:41]
	v_add_f32_e32 v3, v144, v145
	v_add_f32_e32 v3, v3, v146
	v_add_f32_e32 v3, v3, v147
	v_fmamk_f32 v3, v3, 0x3a800000, v200
	v_cmp_gt_f32_e32 vcc, s7, v3
	v_mul_f32_e32 v4, 0x4b800000, v3
	s_nop 0
	v_cndmask_b32_e32 v3, v3, v4, vcc
	v_rsq_f32_e32 v3, v3
	s_nop 0
	v_mul_f32_e32 v4, 0x45800000, v3
	v_cndmask_b32_e32 v12, v3, v4, vcc
	ds_read_b128 v[4:7], v78
	ds_read_b128 v[8:11], v78 offset:64
	s_waitcnt lgkmcnt(1)
	v_pk_mul_f32 v[4:5], v[4:5], v[12:13] op_sel_hi:[1,0]
	s_nop 0
	v_mul_f32_e32 v3, 0xbfb8aa3b, v4
	v_exp_f32_e32 v14, v3
	v_mul_f32_e32 v3, 0xbfb8aa3b, v5
	v_exp_f32_e32 v15, v3
	s_waitcnt lgkmcnt(0)
	v_pk_mul_f32 v[8:9], v[8:9], v[12:13] op_sel_hi:[1,0]
	v_pk_add_f32 v[14:15], v[14:15], 1.0 op_sel_hi:[1,0]
	s_nop 0
	v_rcp_f32_e32 v13, v15
	s_nop 0
	v_mul_f32_e32 v5, v5, v13
	v_div_scale_f32 v3, s[12:13], v14, v14, v4
	v_rcp_f32_e32 v13, v3
	s_nop 0
	v_fma_f32 v15, -v3, v13, 1.0
	v_fmac_f32_e32 v13, v15, v13
	v_div_scale_f32 v15, vcc, v4, v14, v4
	v_mul_f32_e32 v16, v15, v13
	v_fma_f32 v17, -v3, v16, v15
	v_fmac_f32_e32 v16, v17, v13
	v_fma_f32 v3, -v3, v16, v15
	v_div_fmas_f32 v3, v3, v13, v16
	v_pk_mul_f32 v[6:7], v[6:7], v[12:13] op_sel_hi:[1,0]
	v_div_fixup_f32 v4, v3, v14, v4
	v_mul_f32_e32 v3, 0xbfb8aa3b, v6
	v_pk_mul_f32 v[4:5], v[8:9], v[4:5]
	v_exp_f32_e32 v8, v3
	v_mul_f32_e32 v3, 0xbfb8aa3b, v7
	v_exp_f32_e32 v9, v3
	v_pk_mul_f32 v[10:11], v[10:11], v[12:13] op_sel_hi:[1,0]
	v_cvt_pk_bf16_f32 v4, v4, v5
	v_pk_add_f32 v[8:9], v[8:9], 1.0 op_sel_hi:[1,0]
	s_nop 0
	v_rcp_f32_e32 v12, v9
	s_nop 0
	v_mul_f32_e32 v7, v7, v12
	v_rcp_f32_e32 v9, v8
	s_nop 0
	v_mul_f32_e32 v6, v6, v9
	v_pk_mul_f32 v[6:7], v[10:11], v[6:7]
	v_mad_i64_i32 v[2:3], s[12:13], v2, s16, v[66:67]
	v_cvt_pk_bf16_f32 v5, v6, v7
	global_store_dwordx2 v[2:3], v[4:5], off
	v_add_u32_e32 v2, s10, v79
	v_ashrrev_i32_e32 v3, 31, v2
	v_lshl_add_u64 v[4:5], v[2:3], 4, s[40:41]
	v_add_f32_e32 v3, v148, v149
	v_add_f32_e32 v3, v3, v150
	v_add_f32_e32 v3, v3, v151
	v_fmamk_f32 v3, v3, 0x3a800000, v200
	v_cmp_gt_f32_e32 vcc, s7, v3
	v_mul_f32_e32 v4, 0x4b800000, v3
	s_nop 0
	v_cndmask_b32_e32 v3, v3, v4, vcc
	v_rsq_f32_e32 v3, v3
	s_nop 0
	v_mul_f32_e32 v4, 0x45800000, v3
	v_cndmask_b32_e32 v12, v3, v4, vcc
	ds_read_b128 v[4:7], v76
	ds_read_b128 v[8:11], v76 offset:64
	s_waitcnt lgkmcnt(1)
	v_pk_mul_f32 v[4:5], v[4:5], v[12:13] op_sel_hi:[1,0]
	s_nop 0
	v_mul_f32_e32 v3, 0xbfb8aa3b, v4
	v_exp_f32_e32 v14, v3
	v_mul_f32_e32 v3, 0xbfb8aa3b, v5
	v_exp_f32_e32 v15, v3
	s_waitcnt lgkmcnt(0)
	v_pk_mul_f32 v[8:9], v[8:9], v[12:13] op_sel_hi:[1,0]
	v_pk_add_f32 v[14:15], v[14:15], 1.0 op_sel_hi:[1,0]
	s_nop 0
	v_rcp_f32_e32 v13, v15
	s_nop 0
	v_mul_f32_e32 v5, v5, v13
	v_div_scale_f32 v3, s[12:13], v14, v14, v4
	v_rcp_f32_e32 v13, v3
	s_nop 0
	v_fma_f32 v15, -v3, v13, 1.0
	v_fmac_f32_e32 v13, v15, v13
	v_div_scale_f32 v15, vcc, v4, v14, v4
	v_mul_f32_e32 v16, v15, v13
	v_fma_f32 v17, -v3, v16, v15
	v_fmac_f32_e32 v16, v17, v13
	v_fma_f32 v3, -v3, v16, v15
	v_div_fmas_f32 v3, v3, v13, v16
	v_pk_mul_f32 v[6:7], v[6:7], v[12:13] op_sel_hi:[1,0]
	v_div_fixup_f32 v4, v3, v14, v4
	v_mul_f32_e32 v3, 0xbfb8aa3b, v6
	v_pk_mul_f32 v[4:5], v[8:9], v[4:5]
	v_exp_f32_e32 v8, v3
	v_mul_f32_e32 v3, 0xbfb8aa3b, v7
	v_exp_f32_e32 v9, v3
	v_pk_mul_f32 v[10:11], v[10:11], v[12:13] op_sel_hi:[1,0]
	v_cvt_pk_bf16_f32 v4, v4, v5
	v_pk_add_f32 v[8:9], v[8:9], 1.0 op_sel_hi:[1,0]
	s_nop 0
	v_rcp_f32_e32 v12, v9
	s_nop 0
	v_mul_f32_e32 v7, v7, v12
	v_rcp_f32_e32 v9, v8
	s_nop 0
	v_mul_f32_e32 v6, v6, v9
	v_pk_mul_f32 v[6:7], v[10:11], v[6:7]
	v_mad_i64_i32 v[2:3], s[12:13], v2, s16, v[66:67]
	v_cvt_pk_bf16_f32 v5, v6, v7
	global_store_dwordx2 v[2:3], v[4:5], off
	v_add_u32_e32 v2, s10, v0
	v_ashrrev_i32_e32 v3, 31, v2
	v_lshl_add_u64 v[4:5], v[2:3], 4, s[40:41]
	v_add_f32_e32 v0, v152, v153
	v_add_f32_e32 v0, v0, v154
	v_add_f32_e32 v0, v0, v155
	v_fmamk_f32 v0, v0, 0x3a800000, v200
	v_cmp_gt_f32_e32 vcc, s7, v0
	v_mul_f32_e32 v3, 0x4b800000, v0
	ds_read_b128 v[4:7], v70
	ds_read_b128 v[8:11], v70 offset:64
	v_cndmask_b32_e32 v0, v0, v3, vcc
	v_rsq_f32_e32 v0, v0
	s_nop 0
	v_mul_f32_e32 v3, 0x45800000, v0
	v_cndmask_b32_e32 v0, v0, v3, vcc
	s_waitcnt lgkmcnt(1)
	v_pk_mul_f32 v[4:5], v[4:5], v[0:1] op_sel_hi:[1,0]
	v_pk_mul_f32 v[6:7], v[6:7], v[0:1] op_sel_hi:[1,0]
	v_mul_f32_e32 v3, 0xbfb8aa3b, v4
	v_exp_f32_e32 v12, v3
	v_mul_f32_e32 v3, 0xbfb8aa3b, v5
	v_exp_f32_e32 v13, v3
	s_waitcnt lgkmcnt(0)
	v_pk_mul_f32 v[8:9], v[8:9], v[0:1] op_sel_hi:[1,0]
	v_pk_mul_f32 v[10:11], v[10:11], v[0:1] op_sel_hi:[1,0]
	v_mul_f32_e32 v0, 0xbfb8aa3b, v7
	v_pk_add_f32 v[12:13], v[12:13], 1.0 op_sel_hi:[1,0]
	s_nop 0
	v_rcp_f32_e32 v14, v13
	s_nop 0
	v_mul_f32_e32 v5, v5, v14
	v_rcp_f32_e32 v13, v12
	s_nop 0
	v_mul_f32_e32 v4, v4, v13
	v_mul_f32_e32 v3, 0xbfb8aa3b, v6
	v_pk_mul_f32 v[4:5], v[8:9], v[4:5]
	v_exp_f32_e32 v8, v3
	v_exp_f32_e32 v9, v0
	v_cvt_pk_bf16_f32 v4, v4, v5
	v_pk_add_f32 v[8:9], v[8:9], 1.0 op_sel_hi:[1,0]
	s_nop 0
	v_rcp_f32_e32 v3, v9
	s_nop 0
	v_mul_f32_e32 v7, v7, v3
	v_rcp_f32_e32 v3, v8
	s_nop 0
	v_mul_f32_e32 v6, v6, v3
	v_pk_mul_f32 v[6:7], v[10:11], v[6:7]
	v_mad_i64_i32 v[2:3], s[12:13], v2, s16, v[66:67]
	v_cvt_pk_bf16_f32 v5, v6, v7
	global_store_dwordx2 v[2:3], v[4:5], off
	v_add_u32_e32 v2, s10, v71
	v_ashrrev_i32_e32 v3, 31, v2
	v_lshl_add_u64 v[4:5], v[2:3], 4, s[40:41]
	v_add_f32_e32 v0, v156, v157
	v_add_f32_e32 v0, v0, v158
	v_add_f32_e32 v0, v0, v159
	v_fmamk_f32 v0, v0, 0x3a800000, v200
	v_cmp_gt_f32_e32 vcc, s7, v0
	v_mul_f32_e32 v3, 0x4b800000, v0
	ds_read_b128 v[4:7], v72
	ds_read_b128 v[8:11], v72 offset:64
	v_cndmask_b32_e32 v0, v0, v3, vcc
	v_rsq_f32_e32 v0, v0
	s_nop 0
	v_mul_f32_e32 v3, 0x45800000, v0
	v_cndmask_b32_e32 v0, v0, v3, vcc
	s_waitcnt lgkmcnt(1)
	v_pk_mul_f32 v[4:5], v[4:5], v[0:1] op_sel_hi:[1,0]
	v_pk_mul_f32 v[6:7], v[6:7], v[0:1] op_sel_hi:[1,0]
	v_mul_f32_e32 v3, 0xbfb8aa3b, v4
	v_exp_f32_e32 v12, v3
	v_mul_f32_e32 v3, 0xbfb8aa3b, v5
	v_exp_f32_e32 v13, v3
	s_waitcnt lgkmcnt(0)
	v_pk_mul_f32 v[8:9], v[8:9], v[0:1] op_sel_hi:[1,0]
	v_pk_mul_f32 v[10:11], v[10:11], v[0:1] op_sel_hi:[1,0]
	v_mul_f32_e32 v0, 0xbfb8aa3b, v7
	v_pk_add_f32 v[12:13], v[12:13], 1.0 op_sel_hi:[1,0]
	s_nop 0
	v_rcp_f32_e32 v14, v13
	s_nop 0
	v_mul_f32_e32 v5, v5, v14
	v_rcp_f32_e32 v13, v12
	s_nop 0
	v_mul_f32_e32 v4, v4, v13
	v_mul_f32_e32 v3, 0xbfb8aa3b, v6
	v_pk_mul_f32 v[4:5], v[8:9], v[4:5]
	v_exp_f32_e32 v8, v3
	v_exp_f32_e32 v9, v0
	v_cvt_pk_bf16_f32 v4, v4, v5
	v_pk_add_f32 v[8:9], v[8:9], 1.0 op_sel_hi:[1,0]
	s_nop 0
	v_rcp_f32_e32 v3, v9
	s_nop 0
	v_mul_f32_e32 v7, v7, v3
	v_rcp_f32_e32 v3, v8
	s_nop 0
	v_mul_f32_e32 v6, v6, v3
	v_pk_mul_f32 v[6:7], v[10:11], v[6:7]
	v_mad_i64_i32 v[2:3], s[12:13], v2, s16, v[66:67]
	v_cvt_pk_bf16_f32 v5, v6, v7
	global_store_dwordx2 v[2:3], v[4:5], off
	v_add_u32_e32 v2, s10, v73
	v_ashrrev_i32_e32 v3, 31, v2
	v_lshl_add_u64 v[4:5], v[2:3], 4, s[40:41]
	v_add_f32_e32 v0, v160, v161
	v_add_f32_e32 v0, v0, v162
	v_add_f32_e32 v0, v0, v163
	v_fmamk_f32 v0, v0, 0x3a800000, v200
	v_cmp_gt_f32_e32 vcc, s7, v0
	v_mul_f32_e32 v3, 0x4b800000, v0
	ds_read_b128 v[4:7], v74
	ds_read_b128 v[8:11], v74 offset:64
	v_cndmask_b32_e32 v0, v0, v3, vcc
	v_rsq_f32_e32 v0, v0
	s_nop 0
	v_mul_f32_e32 v3, 0x45800000, v0
	v_cndmask_b32_e32 v0, v0, v3, vcc
	s_waitcnt lgkmcnt(1)
	v_pk_mul_f32 v[4:5], v[4:5], v[0:1] op_sel_hi:[1,0]
	v_pk_mul_f32 v[6:7], v[6:7], v[0:1] op_sel_hi:[1,0]
	v_mul_f32_e32 v3, 0xbfb8aa3b, v4
	v_exp_f32_e32 v12, v3
	v_mul_f32_e32 v3, 0xbfb8aa3b, v5
	v_exp_f32_e32 v13, v3
	s_waitcnt lgkmcnt(0)
	v_pk_mul_f32 v[8:9], v[8:9], v[0:1] op_sel_hi:[1,0]
	v_pk_mul_f32 v[10:11], v[10:11], v[0:1] op_sel_hi:[1,0]
	v_mul_f32_e32 v0, 0xbfb8aa3b, v7
	v_pk_add_f32 v[12:13], v[12:13], 1.0 op_sel_hi:[1,0]
	s_nop 0
	v_rcp_f32_e32 v14, v13
	s_nop 0
	v_mul_f32_e32 v5, v5, v14
	v_rcp_f32_e32 v13, v12
	s_nop 0
	v_mul_f32_e32 v4, v4, v13
	v_mul_f32_e32 v3, 0xbfb8aa3b, v6
	v_pk_mul_f32 v[4:5], v[8:9], v[4:5]
	v_exp_f32_e32 v8, v3
	v_exp_f32_e32 v9, v0
	v_cvt_pk_bf16_f32 v4, v4, v5
	v_pk_add_f32 v[8:9], v[8:9], 1.0 op_sel_hi:[1,0]
	s_nop 0
	v_rcp_f32_e32 v3, v9
	s_nop 0
	v_mul_f32_e32 v7, v7, v3
	v_rcp_f32_e32 v3, v8
	s_nop 0
	v_mul_f32_e32 v6, v6, v3
	v_pk_mul_f32 v[6:7], v[10:11], v[6:7]
	v_mad_i64_i32 v[2:3], s[12:13], v2, s16, v[66:67]
	v_cvt_pk_bf16_f32 v5, v6, v7
	global_store_dwordx2 v[2:3], v[4:5], off
	v_add_u32_e32 v2, s10, v75
	v_ashrrev_i32_e32 v3, 31, v2
	v_lshl_add_u64 v[4:5], v[2:3], 4, s[40:41]
	v_add_f32_e32 v0, v164, v165
	v_add_f32_e32 v0, v0, v166
	v_add_f32_e32 v0, v0, v167
	v_fmamk_f32 v0, v0, 0x3a800000, v200
	v_cmp_gt_f32_e32 vcc, s7, v0
	v_mul_f32_e32 v3, 0x4b800000, v0
	ds_read_b128 v[4:7], v68
	ds_read_b128 v[8:11], v68 offset:64
	v_cndmask_b32_e32 v0, v0, v3, vcc
	v_rsq_f32_e32 v0, v0
	s_nop 0
	v_mul_f32_e32 v3, 0x45800000, v0
	v_cndmask_b32_e32 v0, v0, v3, vcc
	s_waitcnt lgkmcnt(1)
	v_pk_mul_f32 v[4:5], v[4:5], v[0:1] op_sel_hi:[1,0]
	v_pk_mul_f32 v[6:7], v[6:7], v[0:1] op_sel_hi:[1,0]
	v_mul_f32_e32 v3, 0xbfb8aa3b, v4
	v_exp_f32_e32 v12, v3
	v_mul_f32_e32 v3, 0xbfb8aa3b, v5
	v_exp_f32_e32 v13, v3
	s_waitcnt lgkmcnt(0)
	v_pk_mul_f32 v[8:9], v[8:9], v[0:1] op_sel_hi:[1,0]
	v_pk_mul_f32 v[10:11], v[10:11], v[0:1] op_sel_hi:[1,0]
	v_mul_f32_e32 v0, 0xbfb8aa3b, v7
	v_pk_add_f32 v[12:13], v[12:13], 1.0 op_sel_hi:[1,0]
	s_nop 0
	v_rcp_f32_e32 v14, v13
	s_nop 0
	v_mul_f32_e32 v5, v5, v14
	v_rcp_f32_e32 v13, v12
	s_nop 0
	v_mul_f32_e32 v4, v4, v13
	v_mul_f32_e32 v3, 0xbfb8aa3b, v6
	v_pk_mul_f32 v[4:5], v[8:9], v[4:5]
	v_exp_f32_e32 v8, v3
	v_exp_f32_e32 v9, v0
	v_cvt_pk_bf16_f32 v4, v4, v5
	v_pk_add_f32 v[8:9], v[8:9], 1.0 op_sel_hi:[1,0]
	s_nop 0
	v_rcp_f32_e32 v3, v9
	s_nop 0
	v_mul_f32_e32 v7, v7, v3
	v_rcp_f32_e32 v3, v8
	s_nop 0
	v_mul_f32_e32 v6, v6, v3
	v_pk_mul_f32 v[6:7], v[10:11], v[6:7]
	v_mad_i64_i32 v[2:3], s[10:11], v2, s16, v[66:67]
	v_cvt_pk_bf16_f32 v5, v6, v7
	global_store_dwordx2 v[2:3], v[4:5], off
	s_barrier

.LBB0_1134:
	s_or_b64 exec, exec, s[42:43]
	s_movk_i32 s33, 0x410
	v_lshrrev_b32_e32 v130, 2, v142
	v_lshlrev_b32_e32 v131, 1, v142
	v_and_b32_e32 v0, 15, v142
	v_and_b32_e32 v130, 0xfffffcc, v130
	v_and_b32_e32 v131, 0x180, v131
	v_add_u32_e32 v131, 0, v131
	v_lshlrev_b32_e32 v0, 2, v0
	v_mul_lo_u32 v130, v130, s33
	v_add3_u32 v130, v131, v0, v130
	s_waitcnt vmcnt(0)
	s_barrier
	ds_write2_b32 v130, v114, v126 offset1:16
	v_add_u32_e32 v114, 0x400, v130
	ds_write2_b32 v114, v115, v127 offset0:4 offset1:20
	v_add_u32_e32 v115, 0x800, v130
	ds_write2_b32 v115, v116, v128 offset0:8 offset1:24
	v_add_u32_e32 v116, 0xc00, v130
	ds_write2_b32 v116, v117, v129 offset0:12 offset1:28
	v_add_u32_e32 v117, 0x4000, v130
	ds_write2_b32 v117, v82, v94 offset0:64 offset1:80
	v_add_u32_e32 v94, 0x4400, v130
	ds_write2_b32 v94, v83, v95 offset0:68 offset1:84
	v_add_u32_e32 v95, 0x4800, v130
	ds_write2_b32 v95, v84, v96 offset0:72 offset1:88
	v_add_u32_e32 v96, 0x4c00, v130
	v_add_u32_e32 v133, 0xc000, v130
	ds_write2_b32 v96, v85, v97 offset0:76 offset1:92
	v_add_u32_e32 v132, 0x8000, v130
	v_add_u32_e32 v97, 0x8400, v130
	v_add_u32_e32 v126, 0x8800, v130
	v_add_u32_e32 v127, 0x8c00, v130
	ds_write2_b32 v133, v66, v70 offset0:192 offset1:208
	v_add_u32_e32 v128, 0xc400, v130
	v_add_u32_e32 v129, 0xc800, v130
	v_add_u32_e32 v131, 0xcc00, v130
	v_lshlrev_b32_e32 v0, 3, v142
	v_lshlrev_b32_e32 v66, 2, v142
	ds_write2_b32 v132, v74, v78 offset0:128 offset1:144
	ds_write2_b32 v97, v75, v79 offset0:132 offset1:148
	ds_write2_b32 v126, v76, v80 offset0:136 offset1:152
	ds_write2_b32 v127, v77, v81 offset0:140 offset1:156
	ds_write2_b32 v128, v67, v71 offset0:196 offset1:212
	ds_write2_b32 v129, v68, v72 offset0:200 offset1:216
	ds_write2_b32 v131, v69, v73 offset0:204 offset1:220
	ds_write2_b32 v130, v98, v118 offset0:128 offset1:144
	ds_write2_b32 v114, v99, v119 offset0:132 offset1:148
	ds_write2_b32 v115, v100, v120 offset0:136 offset1:152
	ds_write2_b32 v116, v101, v121 offset0:140 offset1:156
	ds_write2_b32 v117, v102, v122 offset0:192 offset1:208
	ds_write2_b32 v94, v103, v123 offset0:196 offset1:212
	ds_write2_b32 v95, v104, v124 offset0:200 offset1:216
	ds_write2_b32 v96, v105, v125 offset0:204 offset1:220
	ds_write2_b32 v97, v90, v110 offset1:16
	ds_write2_b32 v126, v91, v111 offset0:4 offset1:20
	ds_write2_b32 v127, v92, v112 offset0:8 offset1:24
	v_add_u32_e32 v90, 0x9000, v130
	v_and_b32_e32 v0, 0xe0, v0
	v_and_b32_e32 v68, 12, v66
	ds_write2_b32 v90, v93, v113 offset0:12 offset1:28
	ds_write2_b32 v128, v86, v106 offset0:64 offset1:80
	ds_write2_b32 v129, v87, v107 offset0:68 offset1:84
	ds_write2_b32 v131, v88, v108 offset0:72 offset1:88
	v_lshlrev_b32_e32 v66, 2, v0
	v_lshlrev_b32_e32 v67, 2, v68
	v_or_b32_e32 v0, s60, v0
	v_ashrrev_i32_e32 v88, 5, v142
	v_add3_u32 v74, 0, v66, v67
	v_ashrrev_i32_e32 v66, 1, v0
	v_lshlrev_b32_e32 v0, 1, v68
	v_add_u32_e32 v68, s12, v88
	v_ashrrev_i32_e32 v69, 31, v68
	v_add_u32_e32 v91, 0xd000, v130
	v_lshl_add_u64 v[70:71], v[68:69], 4, s[40:41]
	ds_write2_b32 v91, v89, v109 offset0:76 offset1:92
	s_waitcnt lgkmcnt(0)
	s_barrier
	global_load_dwordx4 v[134:137], v[70:71], off
	global_load_dwordx4 v[138:141], v[70:71], off offset:256
	global_load_dwordx4 v[144:147], v[70:71], off offset:512
	global_load_dwordx4 v[148:151], v[70:71], off offset:768
	global_load_dwordx4 v[152:155], v[70:71], off offset:1024
	global_load_dwordx4 v[156:159], v[70:71], off offset:1280
	global_load_dwordx4 v[160:163], v[70:71], off offset:1536
	global_load_dwordx4 v[164:167], v[70:71], off offset:1792
	v_readlane_b32 s20, v255, 27
	v_ashrrev_i32_e32 v67, 31, v66
	v_readlane_b32 s21, v255, 28
	v_mad_u64_u32 v[82:83], s[36:37], v88, s33, v[74:75]
	s_nop 0
	v_lshl_add_u64 v[66:67], v[66:67], 1, s[20:21]
	v_lshl_add_u64 v[66:67], v[66:67], 0, v[0:1]
	s_mov_b32 s20, 0x800000
	s_movk_i32 s21, 0x1600
	s_or_b32 s42, s60, 0x100
	s_ashr_i32 s43, s42, 31
	s_lshl_b64 s[44:45], s[42:43], 11
	s_waitcnt vmcnt(0)
	v_add_f32_e32 v0, v134, v135
	v_add_f32_e32 v0, v0, v136
	v_add_f32_e32 v0, v0, v137
	v_fmamk_f32 v0, v0, 0x3a800000, v200
	v_cmp_gt_f32_e32 vcc, s20, v0
	v_mul_f32_e32 v69, 0x4b800000, v0
	ds_read_b128 v[70:73], v82
	ds_read_b128 v[76:79], v82 offset:64
	v_cndmask_b32_e32 v0, v0, v69, vcc
	v_rsq_f32_e32 v0, v0
	s_nop 0
	v_mul_f32_e32 v69, 0x45800000, v0
	v_cndmask_b32_e32 v0, v0, v69, vcc
	s_waitcnt lgkmcnt(1)
	v_pk_mul_f32 v[70:71], v[70:71], v[0:1] op_sel_hi:[1,0]
	v_pk_mul_f32 v[72:73], v[72:73], v[0:1] op_sel_hi:[1,0]
	v_mul_f32_e32 v69, 0xbfb8aa3b, v70
	v_exp_f32_e32 v80, v69
	v_mul_f32_e32 v69, 0xbfb8aa3b, v71
	v_exp_f32_e32 v81, v69
	s_waitcnt lgkmcnt(0)
	v_pk_mul_f32 v[76:77], v[76:77], v[0:1] op_sel_hi:[1,0]
	v_pk_mul_f32 v[78:79], v[78:79], v[0:1] op_sel_hi:[1,0]
	v_mul_f32_e32 v0, 0xbfb8aa3b, v73
	v_pk_add_f32 v[80:81], v[80:81], 1.0 op_sel_hi:[1,0]
	s_nop 0
	v_rcp_f32_e32 v75, v81
	s_nop 0
	v_mul_f32_e32 v71, v71, v75
	v_rcp_f32_e32 v75, v80
	s_nop 0
	v_mul_f32_e32 v70, v70, v75
	v_mul_f32_e32 v69, 0xbfb8aa3b, v72
	v_pk_mul_f32 v[70:71], v[76:77], v[70:71]
	v_exp_f32_e32 v76, v69
	v_exp_f32_e32 v77, v0
	v_cvt_pk_bf16_f32 v70, v70, v71
	v_pk_add_f32 v[76:77], v[76:77], 1.0 op_sel_hi:[1,0]
	s_nop 0
	v_rcp_f32_e32 v69, v77
	s_nop 0
	v_mul_f32_e32 v73, v73, v69
	v_rcp_f32_e32 v69, v76
	s_nop 0
	v_mul_f32_e32 v72, v72, v69
	v_pk_mul_f32 v[72:73], v[78:79], v[72:73]
	v_add_u32_e32 v0, 0x200, v142
	v_cvt_pk_bf16_f32 v71, v72, v73
	v_mad_i64_i32 v[68:69], s[36:37], v68, s21, v[66:67]
	v_ashrrev_i32_e32 v83, 5, v0
	global_store_dwordx2 v[68:69], v[70:71], off
	v_add_u32_e32 v68, s12, v83
	v_ashrrev_i32_e32 v69, 31, v68
	v_lshl_add_u64 v[70:71], v[68:69], 4, s[40:41]
	v_mad_u64_u32 v[80:81], s[36:37], v83, s33, v[74:75]
	v_add_f32_e32 v0, v138, v139
	v_add_f32_e32 v0, v0, v140
	v_add_f32_e32 v0, v0, v141
	v_fmamk_f32 v0, v0, 0x3a800000, v200
	v_cmp_gt_f32_e32 vcc, s20, v0
	v_mul_f32_e32 v69, 0x4b800000, v0
	ds_read_b128 v[70:73], v80
	ds_read_b128 v[76:79], v80 offset:64
	v_cndmask_b32_e32 v0, v0, v69, vcc
	v_rsq_f32_e32 v0, v0
	s_nop 0
	v_mul_f32_e32 v69, 0x45800000, v0
	v_cndmask_b32_e32 v0, v0, v69, vcc
	s_waitcnt lgkmcnt(1)
	v_pk_mul_f32 v[70:71], v[70:71], v[0:1] op_sel_hi:[1,0]
	v_pk_mul_f32 v[72:73], v[72:73], v[0:1] op_sel_hi:[1,0]
	v_mul_f32_e32 v69, 0xbfb8aa3b, v70
	v_exp_f32_e32 v84, v69
	v_mul_f32_e32 v69, 0xbfb8aa3b, v71
	v_exp_f32_e32 v85, v69
	s_waitcnt lgkmcnt(0)
	v_pk_mul_f32 v[76:77], v[76:77], v[0:1] op_sel_hi:[1,0]
	v_pk_mul_f32 v[78:79], v[78:79], v[0:1] op_sel_hi:[1,0]
	v_mul_f32_e32 v0, 0xbfb8aa3b, v73
	v_pk_add_f32 v[84:85], v[84:85], 1.0 op_sel_hi:[1,0]
	s_nop 0
	v_rcp_f32_e32 v75, v85
	s_nop 0
	v_mul_f32_e32 v71, v71, v75
	v_rcp_f32_e32 v75, v84
	s_nop 0
	v_mul_f32_e32 v70, v70, v75
	v_mul_f32_e32 v69, 0xbfb8aa3b, v72
	v_pk_mul_f32 v[70:71], v[76:77], v[70:71]
	v_exp_f32_e32 v76, v69
	v_exp_f32_e32 v77, v0
	v_cvt_pk_bf16_f32 v70, v70, v71
	v_pk_add_f32 v[76:77], v[76:77], 1.0 op_sel_hi:[1,0]
	s_nop 0
	v_rcp_f32_e32 v69, v77
	s_nop 0
	v_mul_f32_e32 v73, v73, v69
	v_rcp_f32_e32 v69, v76
	s_nop 0
	v_mul_f32_e32 v72, v72, v69
	v_pk_mul_f32 v[72:73], v[78:79], v[72:73]
	v_add_u32_e32 v0, 0x400, v142
	v_cvt_pk_bf16_f32 v71, v72, v73
	v_mad_i64_i32 v[68:69], s[36:37], v68, s21, v[66:67]
	v_ashrrev_i32_e32 v81, 5, v0
	global_store_dwordx2 v[68:69], v[70:71], off
	v_add_u32_e32 v68, s12, v81
	v_ashrrev_i32_e32 v69, 31, v68
	v_lshl_add_u64 v[70:71], v[68:69], 4, s[40:41]
	v_mad_u64_u32 v[78:79], s[36:37], v81, s33, v[74:75]
	v_add_f32_e32 v0, v144, v145
	v_add_f32_e32 v0, v0, v146
	v_add_f32_e32 v0, v0, v147
	v_fmamk_f32 v0, v0, 0x3a800000, v200
	v_cmp_gt_f32_e32 vcc, s20, v0
	v_mul_f32_e32 v69, 0x4b800000, v0
	ds_read_b128 v[70:73], v78
	ds_read_b128 v[84:87], v78 offset:64
	v_cndmask_b32_e32 v0, v0, v69, vcc
	v_rsq_f32_e32 v0, v0
	s_nop 0
	v_mul_f32_e32 v69, 0x45800000, v0
	v_cndmask_b32_e32 v0, v0, v69, vcc
	s_waitcnt lgkmcnt(1)
	v_pk_mul_f32 v[70:71], v[70:71], v[0:1] op_sel_hi:[1,0]
	v_pk_mul_f32 v[72:73], v[72:73], v[0:1] op_sel_hi:[1,0]
	v_mul_f32_e32 v69, 0xbfb8aa3b, v70
	v_exp_f32_e32 v76, v69
	v_mul_f32_e32 v69, 0xbfb8aa3b, v71
	v_exp_f32_e32 v77, v69
	s_waitcnt lgkmcnt(0)
	v_pk_mul_f32 v[84:85], v[84:85], v[0:1] op_sel_hi:[1,0]
	v_pk_add_f32 v[76:77], v[76:77], 1.0 op_sel_hi:[1,0]
	s_nop 0
	v_rcp_f32_e32 v75, v77
	s_nop 0
	v_mul_f32_e32 v71, v71, v75
	v_rcp_f32_e32 v75, v76
	s_nop 0
	v_mul_f32_e32 v70, v70, v75
	v_mul_f32_e32 v69, 0xbfb8aa3b, v72
	v_pk_mul_f32 v[76:77], v[86:87], v[0:1] op_sel_hi:[1,0]
	v_mul_f32_e32 v0, 0xbfb8aa3b, v73
	v_pk_mul_f32 v[70:71], v[84:85], v[70:71]
	v_exp_f32_e32 v84, v69
	v_exp_f32_e32 v85, v0
	v_cvt_pk_bf16_f32 v70, v70, v71
	v_pk_add_f32 v[84:85], v[84:85], 1.0 op_sel_hi:[1,0]
	s_nop 0
	v_rcp_f32_e32 v69, v85
	s_nop 0
	v_mul_f32_e32 v73, v73, v69
	v_rcp_f32_e32 v69, v84
	s_nop 0
	v_mul_f32_e32 v72, v72, v69
	v_add_u32_e32 v0, 0x600, v142
	v_pk_mul_f32 v[72:73], v[76:77], v[72:73]
	v_ashrrev_i32_e32 v79, 5, v0
	v_cvt_pk_bf16_f32 v71, v72, v73
	v_add_u32_e32 v72, s12, v79
	v_mad_i64_i32 v[68:69], s[36:37], v68, s21, v[66:67]
	v_ashrrev_i32_e32 v73, 31, v72
	global_store_dwordx2 v[68:69], v[70:71], off
	v_lshl_add_u64 v[68:69], v[72:73], 4, s[40:41]
	v_mad_u64_u32 v[76:77], s[36:37], v79, s33, v[74:75]
	v_add_f32_e32 v0, v148, v149
	v_add_f32_e32 v0, v0, v150
	v_add_f32_e32 v0, v0, v151
	v_fmamk_f32 v0, v0, 0x3a800000, v200
	v_cmp_gt_f32_e32 vcc, s20, v0
	v_mul_f32_e32 v68, 0x4b800000, v0
	s_nop 0
	v_cndmask_b32_e32 v0, v0, v68, vcc
	v_rsq_f32_e32 v0, v0
	s_nop 0
	v_mul_f32_e32 v68, 0x45800000, v0
	v_cndmask_b32_e32 v0, v0, v68, vcc
	ds_read_b128 v[68:71], v76
	ds_read_b128 v[84:87], v76 offset:64
	s_waitcnt lgkmcnt(1)
	v_pk_mul_f32 v[68:69], v[68:69], v[0:1] op_sel_hi:[1,0]
	s_nop 0
	v_mul_f32_e32 v73, 0xbfb8aa3b, v68
	v_exp_f32_e32 v92, v73
	v_mul_f32_e32 v73, 0xbfb8aa3b, v69
	v_exp_f32_e32 v93, v73
	v_pk_mul_f32 v[70:71], v[70:71], v[0:1] op_sel_hi:[1,0]
	s_waitcnt lgkmcnt(0)
	v_pk_mul_f32 v[84:85], v[84:85], v[0:1] op_sel_hi:[1,0]
	v_pk_mul_f32 v[86:87], v[86:87], v[0:1] op_sel_hi:[1,0]
	v_pk_add_f32 v[92:93], v[92:93], 1.0 op_sel_hi:[1,0]
	v_mul_f32_e32 v0, 0xbfb8aa3b, v71
	v_rcp_f32_e32 v75, v93
	s_nop 0
	v_mul_f32_e32 v69, v69, v75
	v_rcp_f32_e32 v75, v92
	s_nop 0
	v_mul_f32_e32 v68, v68, v75
	v_mul_f32_e32 v73, 0xbfb8aa3b, v70
	v_pk_mul_f32 v[68:69], v[84:85], v[68:69]
	v_exp_f32_e32 v84, v73
	v_exp_f32_e32 v85, v0
	v_cvt_pk_bf16_f32 v68, v68, v69
	v_pk_add_f32 v[84:85], v[84:85], 1.0 op_sel_hi:[1,0]
	s_nop 0
	v_rcp_f32_e32 v73, v85
	s_nop 0
	v_mul_f32_e32 v71, v71, v73
	v_rcp_f32_e32 v73, v84
	s_nop 0
	v_mul_f32_e32 v70, v70, v73
	v_pk_mul_f32 v[70:71], v[86:87], v[70:71]
	v_add_u32_e32 v0, 0x800, v142
	v_cvt_pk_bf16_f32 v69, v70, v71
	v_mad_i64_i32 v[70:71], s[36:37], v72, s21, v[66:67]
	v_ashrrev_i32_e32 v0, 5, v0
	global_store_dwordx2 v[70:71], v[68:69], off
	v_add_u32_e32 v70, s12, v0
	v_ashrrev_i32_e32 v71, 31, v70
	v_lshl_add_u64 v[72:73], v[70:71], 4, s[40:41]
	v_mad_u64_u32 v[68:69], s[36:37], v0, s33, v[74:75]
	v_add_f32_e32 v69, v152, v153
	v_add_f32_e32 v69, v69, v154
	v_add_f32_e32 v69, v69, v155
	v_fmamk_f32 v69, v69, 0x3a800000, v200
	v_cmp_gt_f32_e32 vcc, s20, v69
	v_mul_f32_e32 v71, 0x4b800000, v69
	ds_read_b128 v[84:87], v68
	ds_read_b128 v[98:101], v68 offset:64
	v_cndmask_b32_e32 v69, v69, v71, vcc
	v_rsq_f32_e32 v69, v69
	s_nop 0
	v_mul_f32_e32 v71, 0x45800000, v69
	v_cndmask_b32_e32 v72, v69, v71, vcc
	s_waitcnt lgkmcnt(1)
	v_pk_mul_f32 v[84:85], v[84:85], v[72:73] op_sel_hi:[1,0]
	s_waitcnt lgkmcnt(0)
	v_pk_mul_f32 v[98:99], v[98:99], v[72:73] op_sel_hi:[1,0]
	v_mul_f32_e32 v69, 0xbfb8aa3b, v84
	v_exp_f32_e32 v92, v69
	v_mul_f32_e32 v69, 0xbfb8aa3b, v85
	v_exp_f32_e32 v93, v69
	s_nop 0
	v_pk_add_f32 v[92:93], v[92:93], 1.0 op_sel_hi:[1,0]
	s_nop 0
	v_rcp_f32_e32 v71, v93
	s_nop 0
	v_mul_f32_e32 v85, v85, v71
	v_div_scale_f32 v69, s[36:37], v92, v92, v84
	v_rcp_f32_e32 v71, v69
	s_nop 0
	v_fma_f32 v73, -v69, v71, 1.0
	v_fmac_f32_e32 v71, v73, v71
	v_div_scale_f32 v73, vcc, v84, v92, v84
	v_mul_f32_e32 v75, v73, v71
	v_fma_f32 v77, -v69, v75, v73
	v_fmac_f32_e32 v75, v77, v71
	v_fma_f32 v69, -v69, v75, v73
	v_div_fmas_f32 v69, v69, v71, v75
	v_pk_mul_f32 v[86:87], v[86:87], v[72:73] op_sel_hi:[1,0]
	v_div_fixup_f32 v84, v69, v92, v84
	v_mul_f32_e32 v69, 0xbfb8aa3b, v86
	v_exp_f32_e32 v92, v69
	v_mul_f32_e32 v69, 0xbfb8aa3b, v87
	v_exp_f32_e32 v93, v69
	v_pk_mul_f32 v[72:73], v[100:101], v[72:73] op_sel_hi:[1,0]
	v_pk_mul_f32 v[84:85], v[98:99], v[84:85]
	v_pk_add_f32 v[92:93], v[92:93], 1.0 op_sel_hi:[1,0]
	s_nop 0
	v_div_scale_f32 v69, s[36:37], v93, v93, v87
	v_rcp_f32_e32 v71, v69
	v_cvt_pk_bf16_f32 v84, v84, v85
	v_fma_f32 v75, -v69, v71, 1.0
	v_fmac_f32_e32 v71, v75, v71
	v_div_scale_f32 v75, vcc, v87, v93, v87
	v_mul_f32_e32 v77, v75, v71
	v_fma_f32 v89, -v69, v77, v75
	v_fmac_f32_e32 v77, v89, v71
	v_fma_f32 v69, -v69, v77, v75
	v_div_fmas_f32 v69, v69, v71, v77
	v_div_fixup_f32 v87, v69, v93, v87
	v_rcp_f32_e32 v71, v92
	s_nop 0
	v_mul_f32_e32 v86, v86, v71
	v_add_u32_e32 v69, 0xa00, v142
	v_pk_mul_f32 v[72:73], v[72:73], v[86:87]
	v_ashrrev_i32_e32 v69, 5, v69
	v_cvt_pk_bf16_f32 v85, v72, v73
	v_add_u32_e32 v72, s12, v69
	v_mad_i64_i32 v[70:71], s[36:37], v70, s21, v[66:67]
	v_ashrrev_i32_e32 v73, 31, v72
	global_store_dwordx2 v[70:71], v[84:85], off
	v_lshl_add_u64 v[84:85], v[72:73], 4, s[40:41]
	v_mad_u64_u32 v[70:71], s[36:37], v69, s33, v[74:75]
	v_add_f32_e32 v71, v156, v157
	v_add_f32_e32 v71, v71, v158
	v_add_f32_e32 v71, v71, v159
	v_fmamk_f32 v71, v71, 0x3a800000, v200
	v_cmp_gt_f32_e32 vcc, s20, v71
	v_mul_f32_e32 v73, 0x4b800000, v71
	ds_read_b128 v[84:87], v70
	ds_read_b128 v[98:101], v70 offset:64
	v_cndmask_b32_e32 v71, v71, v73, vcc
	v_rsq_f32_e32 v71, v71
	s_nop 0
	v_mul_f32_e32 v73, 0x45800000, v71
	v_cndmask_b32_e32 v92, v71, v73, vcc
	s_waitcnt lgkmcnt(1)
	v_pk_mul_f32 v[84:85], v[84:85], v[92:93] op_sel_hi:[1,0]
	v_pk_mul_f32 v[86:87], v[86:87], v[92:93] op_sel_hi:[1,0]
	v_mul_f32_e32 v71, 0xbfb8aa3b, v84
	v_exp_f32_e32 v102, v71
	v_mul_f32_e32 v71, 0xbfb8aa3b, v85
	v_exp_f32_e32 v103, v71
	s_waitcnt lgkmcnt(0)
	v_pk_mul_f32 v[98:99], v[98:99], v[92:93] op_sel_hi:[1,0]
	v_pk_mul_f32 v[92:93], v[100:101], v[92:93] op_sel_hi:[1,0]
	v_pk_add_f32 v[102:103], v[102:103], 1.0 op_sel_hi:[1,0]
	s_nop 0
	v_rcp_f32_e32 v73, v103
	s_nop 0
	v_mul_f32_e32 v85, v85, v73
	v_rcp_f32_e32 v73, v102
	s_nop 0
	v_mul_f32_e32 v84, v84, v73
	v_mul_f32_e32 v71, 0xbfb8aa3b, v86
	v_pk_mul_f32 v[84:85], v[98:99], v[84:85]
	v_exp_f32_e32 v98, v71
	v_mul_f32_e32 v71, 0xbfb8aa3b, v87
	v_exp_f32_e32 v99, v71
	v_cvt_pk_bf16_f32 v84, v84, v85
	v_pk_add_f32 v[98:99], v[98:99], 1.0 op_sel_hi:[1,0]
	s_nop 0
	v_rcp_f32_e32 v73, v99
	s_nop 0
	v_mul_f32_e32 v87, v87, v73
	v_rcp_f32_e32 v73, v98
	s_nop 0
	v_mul_f32_e32 v86, v86, v73
	v_pk_mul_f32 v[86:87], v[92:93], v[86:87]
	v_add_u32_e32 v71, 0xc00, v142
	v_cvt_pk_bf16_f32 v85, v86, v87
	v_mad_i64_i32 v[72:73], s[36:37], v72, s21, v[66:67]
	v_ashrrev_i32_e32 v71, 5, v71
	global_store_dwordx2 v[72:73], v[84:85], off
	v_add_u32_e32 v84, s12, v71
	v_ashrrev_i32_e32 v85, 31, v84
	v_lshl_add_u64 v[86:87], v[84:85], 4, s[40:41]
	v_mad_u64_u32 v[72:73], s[36:37], v71, s33, v[74:75]
	v_add_f32_e32 v73, v160, v161
	v_add_f32_e32 v73, v73, v162
	v_add_f32_e32 v73, v73, v163
	v_fmamk_f32 v73, v73, 0x3a800000, v200
	v_cmp_gt_f32_e32 vcc, s20, v73
	v_mul_f32_e32 v75, 0x4b800000, v73
	ds_read_b128 v[98:101], v72
	ds_read_b128 v[102:105], v72 offset:64
	v_cndmask_b32_e32 v73, v73, v75, vcc
	v_rsq_f32_e32 v73, v73
	s_nop 0
	v_mul_f32_e32 v75, 0x45800000, v73
	v_cndmask_b32_e32 v86, v73, v75, vcc
	s_waitcnt lgkmcnt(1)
	v_pk_mul_f32 v[92:93], v[98:99], v[86:87] op_sel_hi:[1,0]
	s_waitcnt lgkmcnt(0)
	v_pk_mul_f32 v[102:103], v[102:103], v[86:87] op_sel_hi:[1,0]
	v_mul_f32_e32 v73, 0xbfb8aa3b, v92
	v_exp_f32_e32 v98, v73
	v_mul_f32_e32 v73, 0xbfb8aa3b, v93
	v_exp_f32_e32 v99, v73
	s_nop 0
	v_pk_add_f32 v[98:99], v[98:99], 1.0 op_sel_hi:[1,0]
	s_nop 0
	v_rcp_f32_e32 v75, v99
	s_nop 0
	v_mul_f32_e32 v93, v93, v75
	v_rcp_f32_e32 v75, v98
	s_nop 0
	v_mul_f32_e32 v92, v92, v75
	v_pk_mul_f32 v[98:99], v[100:101], v[86:87] op_sel_hi:[1,0]
	v_pk_mul_f32 v[86:87], v[104:105], v[86:87] op_sel_hi:[1,0]
	v_mul_f32_e32 v73, 0xbfb8aa3b, v98
	v_exp_f32_e32 v100, v73
	v_mul_f32_e32 v73, 0xbfb8aa3b, v99
	v_exp_f32_e32 v101, v73
	v_pk_mul_f32 v[92:93], v[102:103], v[92:93]
	v_pk_add_f32 v[100:101], v[100:101], 1.0 op_sel_hi:[1,0]
	s_nop 0
	v_div_scale_f32 v73, s[36:37], v101, v101, v99
	v_rcp_f32_e32 v75, v73
	v_cvt_pk_bf16_f32 v92, v92, v93
	v_fma_f32 v77, -v73, v75, 1.0
	v_fmac_f32_e32 v75, v77, v75
	v_div_scale_f32 v77, vcc, v99, v101, v99
	v_mul_f32_e32 v85, v77, v75
	v_fma_f32 v89, -v73, v85, v77
	v_fmac_f32_e32 v85, v89, v75
	v_fma_f32 v73, -v73, v85, v77
	v_div_fmas_f32 v73, v73, v75, v85
	v_div_fixup_f32 v99, v73, v101, v99
	v_rcp_f32_e32 v75, v100
	s_nop 0
	v_mul_f32_e32 v98, v98, v75
	v_pk_mul_f32 v[86:87], v[86:87], v[98:99]
	v_add_u32_e32 v73, 0xe00, v142
	v_cvt_pk_bf16_f32 v93, v86, v87
	v_mad_i64_i32 v[84:85], s[36:37], v84, s21, v[66:67]
	v_ashrrev_i32_e32 v73, 5, v73
	global_store_dwordx2 v[84:85], v[92:93], off
	v_add_u32_e32 v84, s12, v73
	v_ashrrev_i32_e32 v85, 31, v84
	v_lshl_add_u64 v[86:87], v[84:85], 4, s[40:41]
	v_mad_u64_u32 v[74:75], s[36:37], v73, s33, v[74:75]
	v_mov_b32_e32 v142, v201
	v_add_f32_e32 v75, v164, v165
	v_add_f32_e32 v75, v75, v166
	v_add_f32_e32 v75, v75, v167
	v_fmamk_f32 v75, v75, 0x3a800000, v200
	v_cmp_gt_f32_e32 vcc, s20, v75
	v_mul_f32_e32 v77, 0x4b800000, v75
	ds_read_b128 v[98:101], v74
	ds_read_b128 v[102:105], v74 offset:64
	v_cndmask_b32_e32 v75, v75, v77, vcc
	v_rsq_f32_e32 v75, v75
	s_nop 0
	v_mul_f32_e32 v77, 0x45800000, v75
	v_cndmask_b32_e32 v86, v75, v77, vcc
	s_waitcnt lgkmcnt(1)
	v_pk_mul_f32 v[92:93], v[98:99], v[86:87] op_sel_hi:[1,0]
	s_waitcnt lgkmcnt(0)
	v_pk_mul_f32 v[102:103], v[102:103], v[86:87] op_sel_hi:[1,0]
	v_mul_f32_e32 v75, 0xbfb8aa3b, v92
	v_exp_f32_e32 v98, v75
	v_mul_f32_e32 v75, 0xbfb8aa3b, v93
	v_exp_f32_e32 v99, v75
	s_nop 0
	v_pk_add_f32 v[98:99], v[98:99], 1.0 op_sel_hi:[1,0]
	s_nop 0
	v_rcp_f32_e32 v77, v99
	s_nop 0
	v_mul_f32_e32 v93, v93, v77
	v_rcp_f32_e32 v77, v98
	s_nop 0
	v_mul_f32_e32 v92, v92, v77
	v_pk_mul_f32 v[98:99], v[100:101], v[86:87] op_sel_hi:[1,0]
	v_pk_mul_f32 v[92:93], v[102:103], v[92:93]
	v_mul_f32_e32 v75, 0xbfb8aa3b, v98
	v_exp_f32_e32 v100, v75
	v_mul_f32_e32 v75, 0xbfb8aa3b, v99
	v_exp_f32_e32 v101, v75
	v_pk_mul_f32 v[86:87], v[104:105], v[86:87] op_sel_hi:[1,0]
	v_cvt_pk_bf16_f32 v92, v92, v93
	v_pk_add_f32 v[100:101], v[100:101], 1.0 op_sel_hi:[1,0]
	s_nop 0
	v_rcp_f32_e32 v77, v101
	s_nop 0
	v_mul_f32_e32 v99, v99, v77
	v_rcp_f32_e32 v77, v100
	s_nop 0
	v_mul_f32_e32 v98, v98, v77
	v_pk_mul_f32 v[86:87], v[86:87], v[98:99]
	v_mad_i64_i32 v[84:85], s[36:37], v84, s21, v[66:67]
	v_cvt_pk_bf16_f32 v93, v86, v87
	global_store_dwordx2 v[84:85], v[92:93], off
	s_barrier
	ds_write2_b32 v130, v2, v18 offset1:16
	ds_write2_b32 v114, v3, v19 offset0:4 offset1:20
	ds_write2_b32 v115, v4, v20 offset0:8 offset1:24
	ds_write2_b32 v116, v5, v21 offset0:12 offset1:28
	ds_write2_b32 v117, v6, v22 offset0:64 offset1:80
	ds_write2_b32 v94, v7, v23 offset0:68 offset1:84
	ds_write2_b32 v95, v8, v24 offset0:72 offset1:88
	ds_write2_b32 v96, v9, v25 offset0:76 offset1:92
	ds_write2_b32 v132, v10, v26 offset0:128 offset1:144
	ds_write2_b32 v97, v11, v27 offset0:132 offset1:148
	ds_write2_b32 v126, v12, v28 offset0:136 offset1:152
	ds_write2_b32 v127, v13, v29 offset0:140 offset1:156
	ds_write2_b32 v133, v14, v30 offset0:192 offset1:208
	ds_write2_b32 v128, v15, v31 offset0:196 offset1:212
	ds_write2_b32 v129, v16, v32 offset0:200 offset1:216
	ds_write2_b32 v131, v17, v33 offset0:204 offset1:220
	ds_write2_b32 v130, v34, v50 offset0:128 offset1:144
	ds_write2_b32 v114, v35, v51 offset0:132 offset1:148
	ds_write2_b32 v115, v36, v52 offset0:136 offset1:152
	ds_write2_b32 v116, v37, v53 offset0:140 offset1:156
	ds_write2_b32 v117, v38, v54 offset0:192 offset1:208
	ds_write2_b32 v94, v39, v55 offset0:196 offset1:212
	ds_write2_b32 v95, v40, v56 offset0:200 offset1:216
	ds_write2_b32 v96, v41, v57 offset0:204 offset1:220
	ds_write2_b32 v97, v42, v58 offset1:16
	ds_write2_b32 v126, v43, v59 offset0:4 offset1:20
	ds_write2_b32 v127, v44, v60 offset0:8 offset1:24
	ds_write2_b32 v90, v45, v61 offset0:12 offset1:28
	ds_write2_b32 v128, v46, v62 offset0:64 offset1:80
	ds_write2_b32 v129, v47, v63 offset0:68 offset1:84
	ds_write2_b32 v131, v48, v64 offset0:72 offset1:88
	ds_write2_b32 v91, v49, v65 offset0:76 offset1:92
	v_add_u32_e32 v2, s10, v88
	v_ashrrev_i32_e32 v3, 31, v2
	v_lshl_add_u64 v[4:5], v[2:3], 4, s[40:41]
	s_waitcnt lgkmcnt(0)
	s_barrier
	global_load_dwordx4 v[134:137], v[4:5], off
	global_load_dwordx4 v[138:141], v[4:5], off offset:256
	global_load_dwordx4 v[144:147], v[4:5], off offset:512
	global_load_dwordx4 v[148:151], v[4:5], off offset:768
	global_load_dwordx4 v[152:155], v[4:5], off offset:1024
	global_load_dwordx4 v[156:159], v[4:5], off offset:1280
	global_load_dwordx4 v[160:163], v[4:5], off offset:1536
	global_load_dwordx4 v[164:167], v[4:5], off offset:1792
	s_waitcnt vmcnt(0)
	v_add_f32_e32 v3, v134, v135
	v_add_f32_e32 v3, v3, v136
	v_add_f32_e32 v3, v3, v137
	v_fmamk_f32 v3, v3, 0x3a800000, v200
	v_cmp_gt_f32_e32 vcc, s20, v3
	v_mul_f32_e32 v4, 0x4b800000, v3
	s_nop 0
	v_cndmask_b32_e32 v3, v3, v4, vcc
	v_rsq_f32_e32 v3, v3
	s_nop 0
	v_mul_f32_e32 v4, 0x45800000, v3
	v_cndmask_b32_e32 v12, v3, v4, vcc
	ds_read_b128 v[4:7], v82
	ds_read_b128 v[8:11], v82 offset:64
	s_waitcnt lgkmcnt(1)
	v_pk_mul_f32 v[4:5], v[4:5], v[12:13] op_sel_hi:[1,0]
	s_nop 0
	v_mul_f32_e32 v3, 0xbfb8aa3b, v4
	v_exp_f32_e32 v14, v3
	v_mul_f32_e32 v3, 0xbfb8aa3b, v5
	v_exp_f32_e32 v15, v3
	s_waitcnt lgkmcnt(0)
	v_pk_mul_f32 v[8:9], v[8:9], v[12:13] op_sel_hi:[1,0]
	v_pk_add_f32 v[14:15], v[14:15], 1.0 op_sel_hi:[1,0]
	s_nop 0
	v_rcp_f32_e32 v13, v15
	s_nop 0
	v_mul_f32_e32 v5, v5, v13
	v_div_scale_f32 v3, s[36:37], v14, v14, v4
	v_rcp_f32_e32 v13, v3
	s_nop 0
	v_fma_f32 v15, -v3, v13, 1.0
	v_fmac_f32_e32 v13, v15, v13
	v_div_scale_f32 v15, vcc, v4, v14, v4
	v_mul_f32_e32 v16, v15, v13
	v_fma_f32 v17, -v3, v16, v15
	v_fmac_f32_e32 v16, v17, v13
	v_fma_f32 v3, -v3, v16, v15
	v_div_fmas_f32 v3, v3, v13, v16
	v_pk_mul_f32 v[6:7], v[6:7], v[12:13] op_sel_hi:[1,0]
	v_div_fixup_f32 v4, v3, v14, v4
	v_mul_f32_e32 v3, 0xbfb8aa3b, v6
	v_pk_mul_f32 v[4:5], v[8:9], v[4:5]
	v_exp_f32_e32 v8, v3
	v_mul_f32_e32 v3, 0xbfb8aa3b, v7
	v_exp_f32_e32 v9, v3
	v_pk_mul_f32 v[10:11], v[10:11], v[12:13] op_sel_hi:[1,0]
	v_cvt_pk_bf16_f32 v4, v4, v5
	v_pk_add_f32 v[8:9], v[8:9], 1.0 op_sel_hi:[1,0]
	s_nop 0
	v_rcp_f32_e32 v12, v9
	s_nop 0
	v_mul_f32_e32 v7, v7, v12
	v_rcp_f32_e32 v9, v8
	s_nop 0
	v_mul_f32_e32 v6, v6, v9
	v_pk_mul_f32 v[6:7], v[10:11], v[6:7]
	v_mad_i64_i32 v[2:3], s[36:37], v2, s21, v[66:67]
	v_cvt_pk_bf16_f32 v5, v6, v7
	global_store_dwordx2 v[2:3], v[4:5], off
	v_add_u32_e32 v2, s10, v83
	v_ashrrev_i32_e32 v3, 31, v2
	v_lshl_add_u64 v[4:5], v[2:3], 4, s[40:41]
	v_add_f32_e32 v3, v138, v139
	v_add_f32_e32 v3, v3, v140
	v_add_f32_e32 v3, v3, v141
	v_fmamk_f32 v3, v3, 0x3a800000, v200
	v_cmp_gt_f32_e32 vcc, s20, v3
	v_mul_f32_e32 v4, 0x4b800000, v3
	s_nop 0
	v_cndmask_b32_e32 v3, v3, v4, vcc
	v_rsq_f32_e32 v3, v3
	s_nop 0
	v_mul_f32_e32 v4, 0x45800000, v3
	v_cndmask_b32_e32 v12, v3, v4, vcc
	ds_read_b128 v[4:7], v80
	ds_read_b128 v[8:11], v80 offset:64
	s_waitcnt lgkmcnt(1)
	v_pk_mul_f32 v[4:5], v[4:5], v[12:13] op_sel_hi:[1,0]
	s_nop 0
	v_mul_f32_e32 v3, 0xbfb8aa3b, v4
	v_exp_f32_e32 v14, v3
	v_mul_f32_e32 v3, 0xbfb8aa3b, v5
	v_exp_f32_e32 v15, v3
	s_waitcnt lgkmcnt(0)
	v_pk_mul_f32 v[8:9], v[8:9], v[12:13] op_sel_hi:[1,0]
	v_pk_add_f32 v[14:15], v[14:15], 1.0 op_sel_hi:[1,0]
	s_nop 0
	v_rcp_f32_e32 v13, v15
	s_nop 0
	v_mul_f32_e32 v5, v5, v13
	v_div_scale_f32 v3, s[36:37], v14, v14, v4
	v_rcp_f32_e32 v13, v3
	s_nop 0
	v_fma_f32 v15, -v3, v13, 1.0
	v_fmac_f32_e32 v13, v15, v13
	v_div_scale_f32 v15, vcc, v4, v14, v4
	v_mul_f32_e32 v16, v15, v13
	v_fma_f32 v17, -v3, v16, v15
	v_fmac_f32_e32 v16, v17, v13
	v_fma_f32 v3, -v3, v16, v15
	v_div_fmas_f32 v3, v3, v13, v16
	v_pk_mul_f32 v[6:7], v[6:7], v[12:13] op_sel_hi:[1,0]
	v_div_fixup_f32 v4, v3, v14, v4
	v_mul_f32_e32 v3, 0xbfb8aa3b, v6
	v_pk_mul_f32 v[4:5], v[8:9], v[4:5]
	v_exp_f32_e32 v8, v3
	v_mul_f32_e32 v3, 0xbfb8aa3b, v7
	v_exp_f32_e32 v9, v3
	v_pk_mul_f32 v[10:11], v[10:11], v[12:13] op_sel_hi:[1,0]
	v_cvt_pk_bf16_f32 v4, v4, v5
	v_pk_add_f32 v[8:9], v[8:9], 1.0 op_sel_hi:[1,0]
	s_nop 0
	v_rcp_f32_e32 v12, v9
	s_nop 0
	v_mul_f32_e32 v7, v7, v12
	v_rcp_f32_e32 v9, v8
	s_nop 0
	v_mul_f32_e32 v6, v6, v9
	v_pk_mul_f32 v[6:7], v[10:11], v[6:7]
	v_mad_i64_i32 v[2:3], s[36:37], v2, s21, v[66:67]
	v_cvt_pk_bf16_f32 v5, v6, v7
	global_store_dwordx2 v[2:3], v[4:5], off
	v_add_u32_e32 v2, s10, v81
	v_ashrrev_i32_e32 v3, 31, v2
	v_lshl_add_u64 v[4:5], v[2:3], 4, s[40:41]
	v_add_f32_e32 v3, v144, v145
	v_add_f32_e32 v3, v3, v146
	v_add_f32_e32 v3, v3, v147
	v_fmamk_f32 v3, v3, 0x3a800000, v200
	v_cmp_gt_f32_e32 vcc, s20, v3
	v_mul_f32_e32 v4, 0x4b800000, v3
	s_nop 0
	v_cndmask_b32_e32 v3, v3, v4, vcc
	v_rsq_f32_e32 v3, v3
	s_nop 0
	v_mul_f32_e32 v4, 0x45800000, v3
	v_cndmask_b32_e32 v12, v3, v4, vcc
	ds_read_b128 v[4:7], v78
	ds_read_b128 v[8:11], v78 offset:64
	s_waitcnt lgkmcnt(1)
	v_pk_mul_f32 v[4:5], v[4:5], v[12:13] op_sel_hi:[1,0]
	s_nop 0
	v_mul_f32_e32 v3, 0xbfb8aa3b, v4
	v_exp_f32_e32 v14, v3
	v_mul_f32_e32 v3, 0xbfb8aa3b, v5
	v_exp_f32_e32 v15, v3
	s_waitcnt lgkmcnt(0)
	v_pk_mul_f32 v[8:9], v[8:9], v[12:13] op_sel_hi:[1,0]
	v_pk_add_f32 v[14:15], v[14:15], 1.0 op_sel_hi:[1,0]
	s_nop 0
	v_rcp_f32_e32 v13, v15
	s_nop 0
	v_mul_f32_e32 v5, v5, v13
	v_div_scale_f32 v3, s[36:37], v14, v14, v4
	v_rcp_f32_e32 v13, v3
	s_nop 0
	v_fma_f32 v15, -v3, v13, 1.0
	v_fmac_f32_e32 v13, v15, v13
	v_div_scale_f32 v15, vcc, v4, v14, v4
	v_mul_f32_e32 v16, v15, v13
	v_fma_f32 v17, -v3, v16, v15
	v_fmac_f32_e32 v16, v17, v13
	v_fma_f32 v3, -v3, v16, v15
	v_div_fmas_f32 v3, v3, v13, v16
	v_pk_mul_f32 v[6:7], v[6:7], v[12:13] op_sel_hi:[1,0]
	v_div_fixup_f32 v4, v3, v14, v4
	v_mul_f32_e32 v3, 0xbfb8aa3b, v6
	v_pk_mul_f32 v[4:5], v[8:9], v[4:5]
	v_exp_f32_e32 v8, v3
	v_mul_f32_e32 v3, 0xbfb8aa3b, v7
	v_exp_f32_e32 v9, v3
	v_pk_mul_f32 v[10:11], v[10:11], v[12:13] op_sel_hi:[1,0]
	v_cvt_pk_bf16_f32 v4, v4, v5
	v_pk_add_f32 v[8:9], v[8:9], 1.0 op_sel_hi:[1,0]
	s_nop 0
	v_rcp_f32_e32 v12, v9
	s_nop 0
	v_mul_f32_e32 v7, v7, v12
	v_rcp_f32_e32 v9, v8
	s_nop 0
	v_mul_f32_e32 v6, v6, v9
	v_pk_mul_f32 v[6:7], v[10:11], v[6:7]
	v_mad_i64_i32 v[2:3], s[36:37], v2, s21, v[66:67]
	v_cvt_pk_bf16_f32 v5, v6, v7
	global_store_dwordx2 v[2:3], v[4:5], off
	v_add_u32_e32 v2, s10, v79
	v_ashrrev_i32_e32 v3, 31, v2
	v_lshl_add_u64 v[4:5], v[2:3], 4, s[40:41]
	v_add_f32_e32 v3, v148, v149
	v_add_f32_e32 v3, v3, v150
	v_add_f32_e32 v3, v3, v151
	v_fmamk_f32 v3, v3, 0x3a800000, v200
	v_cmp_gt_f32_e32 vcc, s20, v3
	v_mul_f32_e32 v4, 0x4b800000, v3
	s_nop 0
	v_cndmask_b32_e32 v3, v3, v4, vcc
	v_rsq_f32_e32 v3, v3
	s_nop 0
	v_mul_f32_e32 v4, 0x45800000, v3
	v_cndmask_b32_e32 v12, v3, v4, vcc
	ds_read_b128 v[4:7], v76
	ds_read_b128 v[8:11], v76 offset:64
	s_waitcnt lgkmcnt(1)
	v_pk_mul_f32 v[4:5], v[4:5], v[12:13] op_sel_hi:[1,0]
	s_nop 0
	v_mul_f32_e32 v3, 0xbfb8aa3b, v4
	v_exp_f32_e32 v14, v3
	v_mul_f32_e32 v3, 0xbfb8aa3b, v5
	v_exp_f32_e32 v15, v3
	s_waitcnt lgkmcnt(0)
	v_pk_mul_f32 v[8:9], v[8:9], v[12:13] op_sel_hi:[1,0]
	v_pk_add_f32 v[14:15], v[14:15], 1.0 op_sel_hi:[1,0]
	s_nop 0
	v_rcp_f32_e32 v13, v15
	s_nop 0
	v_mul_f32_e32 v5, v5, v13
	v_div_scale_f32 v3, s[36:37], v14, v14, v4
	v_rcp_f32_e32 v13, v3
	s_nop 0
	v_fma_f32 v15, -v3, v13, 1.0
	v_fmac_f32_e32 v13, v15, v13
	v_div_scale_f32 v15, vcc, v4, v14, v4
	v_mul_f32_e32 v16, v15, v13
	v_fma_f32 v17, -v3, v16, v15
	v_fmac_f32_e32 v16, v17, v13
	v_fma_f32 v3, -v3, v16, v15
	v_div_fmas_f32 v3, v3, v13, v16
	v_pk_mul_f32 v[6:7], v[6:7], v[12:13] op_sel_hi:[1,0]
	v_div_fixup_f32 v4, v3, v14, v4
	v_mul_f32_e32 v3, 0xbfb8aa3b, v6
	v_pk_mul_f32 v[4:5], v[8:9], v[4:5]
	v_exp_f32_e32 v8, v3
	v_mul_f32_e32 v3, 0xbfb8aa3b, v7
	v_exp_f32_e32 v9, v3
	v_pk_mul_f32 v[10:11], v[10:11], v[12:13] op_sel_hi:[1,0]
	v_cvt_pk_bf16_f32 v4, v4, v5
	v_pk_add_f32 v[8:9], v[8:9], 1.0 op_sel_hi:[1,0]
	s_nop 0
	v_rcp_f32_e32 v12, v9
	s_nop 0
	v_mul_f32_e32 v7, v7, v12
	v_rcp_f32_e32 v9, v8
	s_nop 0
	v_mul_f32_e32 v6, v6, v9
	v_pk_mul_f32 v[6:7], v[10:11], v[6:7]
	v_mad_i64_i32 v[2:3], s[36:37], v2, s21, v[66:67]
	v_cvt_pk_bf16_f32 v5, v6, v7
	global_store_dwordx2 v[2:3], v[4:5], off
	v_add_u32_e32 v2, s10, v0
	v_ashrrev_i32_e32 v3, 31, v2
	v_lshl_add_u64 v[4:5], v[2:3], 4, s[40:41]
	v_add_f32_e32 v0, v152, v153
	v_add_f32_e32 v0, v0, v154
	v_add_f32_e32 v0, v0, v155
	v_fmamk_f32 v0, v0, 0x3a800000, v200
	v_cmp_gt_f32_e32 vcc, s20, v0
	v_mul_f32_e32 v3, 0x4b800000, v0
	ds_read_b128 v[4:7], v68
	ds_read_b128 v[8:11], v68 offset:64
	v_cndmask_b32_e32 v0, v0, v3, vcc
	v_rsq_f32_e32 v0, v0
	s_nop 0
	v_mul_f32_e32 v3, 0x45800000, v0
	v_cndmask_b32_e32 v0, v0, v3, vcc
	s_waitcnt lgkmcnt(1)
	v_pk_mul_f32 v[4:5], v[4:5], v[0:1] op_sel_hi:[1,0]
	v_pk_mul_f32 v[6:7], v[6:7], v[0:1] op_sel_hi:[1,0]
	v_mul_f32_e32 v3, 0xbfb8aa3b, v4
	v_exp_f32_e32 v12, v3
	v_mul_f32_e32 v3, 0xbfb8aa3b, v5
	v_exp_f32_e32 v13, v3
	s_waitcnt lgkmcnt(0)
	v_pk_mul_f32 v[8:9], v[8:9], v[0:1] op_sel_hi:[1,0]
	v_pk_mul_f32 v[10:11], v[10:11], v[0:1] op_sel_hi:[1,0]
	v_mul_f32_e32 v0, 0xbfb8aa3b, v7
	v_pk_add_f32 v[12:13], v[12:13], 1.0 op_sel_hi:[1,0]
	s_nop 0
	v_rcp_f32_e32 v14, v13
	s_nop 0
	v_mul_f32_e32 v5, v5, v14
	v_rcp_f32_e32 v13, v12
	s_nop 0
	v_mul_f32_e32 v4, v4, v13
	v_mul_f32_e32 v3, 0xbfb8aa3b, v6
	v_pk_mul_f32 v[4:5], v[8:9], v[4:5]
	v_exp_f32_e32 v8, v3
	v_exp_f32_e32 v9, v0
	v_cvt_pk_bf16_f32 v4, v4, v5
	v_pk_add_f32 v[8:9], v[8:9], 1.0 op_sel_hi:[1,0]
	s_nop 0
	v_rcp_f32_e32 v3, v9
	s_nop 0
	v_mul_f32_e32 v7, v7, v3
	v_rcp_f32_e32 v3, v8
	s_nop 0
	v_mul_f32_e32 v6, v6, v3
	v_pk_mul_f32 v[6:7], v[10:11], v[6:7]
	v_mad_i64_i32 v[2:3], s[36:37], v2, s21, v[66:67]
	v_cvt_pk_bf16_f32 v5, v6, v7
	global_store_dwordx2 v[2:3], v[4:5], off
	v_add_u32_e32 v2, s10, v69
	v_ashrrev_i32_e32 v3, 31, v2
	v_lshl_add_u64 v[4:5], v[2:3], 4, s[40:41]
	v_add_f32_e32 v0, v156, v157
	v_add_f32_e32 v0, v0, v158
	v_add_f32_e32 v0, v0, v159
	v_fmamk_f32 v0, v0, 0x3a800000, v200
	v_cmp_gt_f32_e32 vcc, s20, v0
	v_mul_f32_e32 v3, 0x4b800000, v0
	ds_read_b128 v[4:7], v70
	ds_read_b128 v[8:11], v70 offset:64
	v_cndmask_b32_e32 v0, v0, v3, vcc
	v_rsq_f32_e32 v0, v0
	s_nop 0
	v_mul_f32_e32 v3, 0x45800000, v0
	v_cndmask_b32_e32 v0, v0, v3, vcc
	s_waitcnt lgkmcnt(1)
	v_pk_mul_f32 v[4:5], v[4:5], v[0:1] op_sel_hi:[1,0]
	v_pk_mul_f32 v[6:7], v[6:7], v[0:1] op_sel_hi:[1,0]
	v_mul_f32_e32 v3, 0xbfb8aa3b, v4
	v_exp_f32_e32 v12, v3
	v_mul_f32_e32 v3, 0xbfb8aa3b, v5
	v_exp_f32_e32 v13, v3
	s_waitcnt lgkmcnt(0)
	v_pk_mul_f32 v[8:9], v[8:9], v[0:1] op_sel_hi:[1,0]
	v_pk_mul_f32 v[10:11], v[10:11], v[0:1] op_sel_hi:[1,0]
	v_mul_f32_e32 v0, 0xbfb8aa3b, v7
	v_pk_add_f32 v[12:13], v[12:13], 1.0 op_sel_hi:[1,0]
	s_nop 0
	v_rcp_f32_e32 v14, v13
	s_nop 0
	v_mul_f32_e32 v5, v5, v14
	v_rcp_f32_e32 v13, v12
	s_nop 0
	v_mul_f32_e32 v4, v4, v13
	v_mul_f32_e32 v3, 0xbfb8aa3b, v6
	v_pk_mul_f32 v[4:5], v[8:9], v[4:5]
	v_exp_f32_e32 v8, v3
	v_exp_f32_e32 v9, v0
	v_cvt_pk_bf16_f32 v4, v4, v5
	v_pk_add_f32 v[8:9], v[8:9], 1.0 op_sel_hi:[1,0]
	s_nop 0
	v_rcp_f32_e32 v3, v9
	s_nop 0
	v_mul_f32_e32 v7, v7, v3
	v_rcp_f32_e32 v3, v8
	s_nop 0
	v_mul_f32_e32 v6, v6, v3
	v_pk_mul_f32 v[6:7], v[10:11], v[6:7]
	v_mad_i64_i32 v[2:3], s[36:37], v2, s21, v[66:67]
	v_cvt_pk_bf16_f32 v5, v6, v7
	global_store_dwordx2 v[2:3], v[4:5], off
	v_add_u32_e32 v2, s10, v71
	v_ashrrev_i32_e32 v3, 31, v2
	v_lshl_add_u64 v[4:5], v[2:3], 4, s[40:41]
	v_add_f32_e32 v0, v160, v161
	v_add_f32_e32 v0, v0, v162
	v_add_f32_e32 v0, v0, v163
	v_fmamk_f32 v0, v0, 0x3a800000, v200
	v_cmp_gt_f32_e32 vcc, s20, v0
	v_mul_f32_e32 v3, 0x4b800000, v0
	ds_read_b128 v[4:7], v72
	ds_read_b128 v[8:11], v72 offset:64
	v_cndmask_b32_e32 v0, v0, v3, vcc
	v_rsq_f32_e32 v0, v0
	s_nop 0
	v_mul_f32_e32 v3, 0x45800000, v0
	v_cndmask_b32_e32 v0, v0, v3, vcc
	s_waitcnt lgkmcnt(1)
	v_pk_mul_f32 v[4:5], v[4:5], v[0:1] op_sel_hi:[1,0]
	v_pk_mul_f32 v[6:7], v[6:7], v[0:1] op_sel_hi:[1,0]
	v_mul_f32_e32 v3, 0xbfb8aa3b, v4
	v_exp_f32_e32 v12, v3
	v_mul_f32_e32 v3, 0xbfb8aa3b, v5
	v_exp_f32_e32 v13, v3
	s_waitcnt lgkmcnt(0)
	v_pk_mul_f32 v[8:9], v[8:9], v[0:1] op_sel_hi:[1,0]
	v_pk_mul_f32 v[10:11], v[10:11], v[0:1] op_sel_hi:[1,0]
	v_mul_f32_e32 v0, 0xbfb8aa3b, v7
	v_pk_add_f32 v[12:13], v[12:13], 1.0 op_sel_hi:[1,0]
	s_nop 0
	v_rcp_f32_e32 v14, v13
	s_nop 0
	v_mul_f32_e32 v5, v5, v14
	v_rcp_f32_e32 v13, v12
	s_nop 0
	v_mul_f32_e32 v4, v4, v13
	v_mul_f32_e32 v3, 0xbfb8aa3b, v6
	v_pk_mul_f32 v[4:5], v[8:9], v[4:5]
	v_exp_f32_e32 v8, v3
	v_exp_f32_e32 v9, v0
	v_cvt_pk_bf16_f32 v4, v4, v5
	v_pk_add_f32 v[8:9], v[8:9], 1.0 op_sel_hi:[1,0]
	s_nop 0
	v_rcp_f32_e32 v3, v9
	s_nop 0
	v_mul_f32_e32 v7, v7, v3
	v_rcp_f32_e32 v3, v8
	s_nop 0
	v_mul_f32_e32 v6, v6, v3
	v_pk_mul_f32 v[6:7], v[10:11], v[6:7]
	v_mad_i64_i32 v[2:3], s[36:37], v2, s21, v[66:67]
	v_cvt_pk_bf16_f32 v5, v6, v7
	global_store_dwordx2 v[2:3], v[4:5], off
	v_add_u32_e32 v2, s10, v73
	v_ashrrev_i32_e32 v3, 31, v2
	v_lshl_add_u64 v[4:5], v[2:3], 4, s[40:41]
	v_add_f32_e32 v0, v164, v165
	v_add_f32_e32 v0, v0, v166
	v_add_f32_e32 v0, v0, v167
	v_fmamk_f32 v0, v0, 0x3a800000, v200
	v_cmp_gt_f32_e32 vcc, s20, v0
	v_mul_f32_e32 v3, 0x4b800000, v0
	ds_read_b128 v[4:7], v74
	ds_read_b128 v[8:11], v74 offset:64
	v_cndmask_b32_e32 v0, v0, v3, vcc
	v_rsq_f32_e32 v0, v0
	v_readlane_b32 s20, v255, 16
	v_mul_f32_e32 v3, 0x45800000, v0
	v_cndmask_b32_e32 v0, v0, v3, vcc
	s_waitcnt lgkmcnt(1)
	v_pk_mul_f32 v[4:5], v[4:5], v[0:1] op_sel_hi:[1,0]
	v_pk_mul_f32 v[6:7], v[6:7], v[0:1] op_sel_hi:[1,0]
	v_mul_f32_e32 v3, 0xbfb8aa3b, v4
	v_exp_f32_e32 v12, v3
	v_mul_f32_e32 v3, 0xbfb8aa3b, v5
	v_exp_f32_e32 v13, v3
	s_waitcnt lgkmcnt(0)
	v_pk_mul_f32 v[8:9], v[8:9], v[0:1] op_sel_hi:[1,0]
	v_pk_mul_f32 v[10:11], v[10:11], v[0:1] op_sel_hi:[1,0]
	v_mul_f32_e32 v0, 0xbfb8aa3b, v7
	v_pk_add_f32 v[12:13], v[12:13], 1.0 op_sel_hi:[1,0]
	s_nop 0
	v_rcp_f32_e32 v14, v13
	s_nop 0
	v_mul_f32_e32 v5, v5, v14
	v_rcp_f32_e32 v13, v12
	s_nop 0
	v_mul_f32_e32 v4, v4, v13
	v_mul_f32_e32 v3, 0xbfb8aa3b, v6
	v_pk_mul_f32 v[4:5], v[8:9], v[4:5]
	v_exp_f32_e32 v8, v3
	v_exp_f32_e32 v9, v0
	v_cvt_pk_bf16_f32 v4, v4, v5
	v_pk_add_f32 v[8:9], v[8:9], 1.0 op_sel_hi:[1,0]
	s_nop 0
	v_rcp_f32_e32 v3, v9
	s_nop 0
	v_mul_f32_e32 v7, v7, v3
	v_rcp_f32_e32 v3, v8
	s_nop 0
	v_mul_f32_e32 v6, v6, v3
	v_pk_mul_f32 v[6:7], v[10:11], v[6:7]
	v_mad_i64_i32 v[2:3], s[36:37], v2, s21, v[66:67]
	v_cvt_pk_bf16_f32 v5, v6, v7
	global_store_dwordx2 v[2:3], v[4:5], off
	s_barrier
	v_readlane_b32 s21, v255, 25
	v_ashrrev_i32_e32 v0, 31, v142
	v_lshrrev_b32_e32 v0, 26, v0
	v_add_u32_e32 v0, v142, v0
	v_ashrrev_i32_e32 v16, 6, v0
	v_bfe_i32 v0, v142, 27, 1
	v_lshlrev_b32_e32 v2, 4, v142
	v_lshrrev_b32_e32 v0, 22, v0
	v_add_u32_e32 v0, v2, v0
	v_and_b32_e32 v0, 0xfffffc00, v0
	v_sub_u32_e32 v0, v2, v0
	v_lshrrev_b32_e32 v3, 4, v0
	v_bitop3_b32 v3, v3, v0, 32 bitop3:0x6c
	v_ashrrev_i32_e32 v0, 31, v0
	v_lshrrev_b32_e32 v0, 26, v0
	v_add_u32_e32 v0, v3, v0
	v_ashrrev_i32_e32 v18, 6, v0
	v_mul_i32_i24_e32 v5, 64, v18
	v_sub_u32_e32 v3, v3, v5
	v_lshlrev_b32_e32 v4, 3, v16
	v_lshlrev_b32_e32 v0, 5, v16
	v_ashrrev_i16_sdwa v3, v217, sext(v3) dst_sel:DWORD dst_unused:UNUSED_PAD src0_sel:DWORD src1_sel:BYTE_0
	v_and_b32_e32 v4, 0x1ffff0, v4
	v_and_b32_e32 v0, 32, v0
	v_bfe_i32 v19, v3, 0, 16
	v_add_u32_e32 v0, v0, v19
	v_add_lshl_u32 v3, v18, v4, 11
	v_add_u32_e32 v2, 0x2000, v2
	v_lshl_add_u32 v0, v0, 1, v3
	v_ashrrev_i32_e32 v3, 31, v2
	v_lshrrev_b32_e32 v3, 22, v3
	v_add_u32_e32 v3, v2, v3
	v_ashrrev_i32_e32 v21, 10, v3
	v_mul_i32_i24_e32 v3, 0x400, v21
	v_sub_u32_e32 v2, v2, v3
	v_lshrrev_b32_e32 v3, 4, v2
	v_bitop3_b32 v2, v3, v2, 32 bitop3:0x6c
	v_ashrrev_i32_e32 v4, 31, v2
	v_ashrrev_i32_e32 v20, 6, v142
	v_lshrrev_b32_e32 v4, 26, v4
	v_readfirstlane_b32 s33, v20
	v_add_u32_e32 v4, v2, v4
	s_lshl_b32 s70, s33, 10
	v_ashrrev_i32_e32 v22, 6, v4
	v_and_b32_e32 v4, 0xc0, v4
	v_sub_u32_e32 v2, v2, v4
	s_add_u32 s44, s20, s44
	v_lshlrev_b32_e32 v3, 3, v21
	v_lshlrev_b32_e32 v5, 5, v21
	v_ashrrev_i16_sdwa v2, v217, sext(v2) dst_sel:DWORD dst_unused:UNUSED_PAD src0_sel:DWORD src1_sel:BYTE_0
	s_addc_u32 s45, s21, s45
	s_add_i32 s36, s70, 0
	v_and_b32_e32 v3, 0x1ffff0, v3
	v_and_b32_e32 v5, 32, v5
	v_bfe_i32 v23, v2, 0, 16
	s_add_i32 s37, s36, 0x10000
	v_add_u32_e32 v2, v5, v23
	v_add_lshl_u32 v3, v22, v3, 11
	s_mov_b32 m0, s37
	s_add_i32 s43, s36, 0x12000
	v_lshl_add_u32 v2, v2, 1, v3
	global_load_lds_dwordx4 v0, s[44:45]
	v_mov_b32_e32 v3, v1
	s_mov_b32 m0, s43
	v_lshl_add_u64 v[4:5], s[44:45], 0, v[0:1]
	v_lshl_add_u64 v[8:9], s[44:45], 0, v[2:3]
	global_load_lds_dwordx4 v2, s[44:45]
	s_mov_b32 m0, s36
	s_add_i32 s44, s36, 0x2000
	global_load_lds_dwordx4 v0, s[22:23]
	s_mov_b32 m0, s44
	v_lshl_add_u64 v[10:11], s[22:23], 0, v[0:1]
	v_lshl_add_u64 v[6:7], s[22:23], 0, v[2:3]
	global_load_lds_dwordx4 v2, s[22:23]
	s_or_b32 s22, s60, 0x180
	s_ashr_i32 s23, s22, 31
	s_lshl_b64 s[22:23], s[22:23], 11
	s_add_u32 s22, s20, s22
	s_addc_u32 s23, s21, s23
	s_add_i32 s45, s36, 0x14000
	s_mov_b32 m0, s45
	s_add_i32 s57, s36, 0x16000
	global_load_lds_dwordx4 v0, s[22:23]
	s_mov_b32 m0, s57
	s_add_i32 s60, s36, 0x4000
	global_load_lds_dwordx4 v2, s[22:23]
	s_mov_b32 m0, s60
	s_add_i32 s61, s36, 0x6000
	global_load_lds_dwordx4 v0, s[16:17]
	s_mov_b32 m0, s61
	v_ashrrev_i32_e32 v17, 8, v142
	global_load_lds_dwordx4 v2, s[16:17]
	v_lshl_add_u64 v[12:13], s[22:23], 0, v[0:1]
	v_lshl_add_u64 v[14:15], s[22:23], 0, v[2:3]
	v_cmp_eq_u32_e32 vcc, 1, v17
	s_and_saveexec_b64 s[22:23], vcc
	v_readlane_b32 s62, v253, 50
	s_cbranch_execz .LBB0_1136
	s_barrier

.LBB0_1140:
	s_or_b64 exec, exec, s[14:15]
	s_movk_i32 s11, 0x410
	v_lshrrev_b32_e32 v130, 2, v142
	v_lshlrev_b32_e32 v131, 1, v142
	v_and_b32_e32 v0, 15, v142
	v_and_b32_e32 v130, 0xfffffcc, v130
	v_and_b32_e32 v131, 0x180, v131
	v_add_u32_e32 v131, 0, v131
	v_lshlrev_b32_e32 v0, 2, v0
	v_mul_lo_u32 v130, v130, s11
	v_add3_u32 v130, v131, v0, v130
	s_waitcnt vmcnt(0)
	s_barrier
	ds_write2_b32 v130, v114, v126 offset1:16
	v_add_u32_e32 v114, 0x400, v130
	ds_write2_b32 v114, v115, v127 offset0:4 offset1:20
	v_add_u32_e32 v115, 0x800, v130
	ds_write2_b32 v115, v116, v128 offset0:8 offset1:24
	v_add_u32_e32 v116, 0xc00, v130
	ds_write2_b32 v116, v117, v129 offset0:12 offset1:28
	v_add_u32_e32 v117, 0x4000, v130
	ds_write2_b32 v117, v82, v94 offset0:64 offset1:80
	v_add_u32_e32 v94, 0x4400, v130
	ds_write2_b32 v94, v83, v95 offset0:68 offset1:84
	v_add_u32_e32 v95, 0x4800, v130
	ds_write2_b32 v95, v84, v96 offset0:72 offset1:88
	v_add_u32_e32 v96, 0x4c00, v130
	ds_write2_b32 v96, v85, v97 offset0:76 offset1:92
	v_add_u32_e32 v132, 0x8000, v130
	v_add_u32_e32 v97, 0x8400, v130
	v_add_u32_e32 v126, 0x8800, v130
	v_add_u32_e32 v127, 0x8c00, v130
	v_add_u32_e32 v133, 0xc000, v130
	v_add_u32_e32 v128, 0xc400, v130
	v_add_u32_e32 v129, 0xc800, v130
	v_add_u32_e32 v131, 0xcc00, v130
	ds_write2_b32 v132, v74, v78 offset0:128 offset1:144
	ds_write2_b32 v97, v75, v79 offset0:132 offset1:148
	ds_write2_b32 v126, v76, v80 offset0:136 offset1:152
	ds_write2_b32 v127, v77, v81 offset0:140 offset1:156
	ds_write2_b32 v133, v66, v70 offset0:192 offset1:208
	ds_write2_b32 v128, v67, v71 offset0:196 offset1:212
	ds_write2_b32 v129, v68, v72 offset0:200 offset1:216
	ds_write2_b32 v131, v69, v73 offset0:204 offset1:220
	ds_write2_b32 v130, v98, v118 offset0:128 offset1:144
	ds_write2_b32 v114, v99, v119 offset0:132 offset1:148
	ds_write2_b32 v115, v100, v120 offset0:136 offset1:152
	ds_write2_b32 v116, v101, v121 offset0:140 offset1:156
	ds_write2_b32 v117, v102, v122 offset0:192 offset1:208
	ds_write2_b32 v94, v103, v123 offset0:196 offset1:212
	ds_write2_b32 v95, v104, v124 offset0:200 offset1:216
	ds_write2_b32 v96, v105, v125 offset0:204 offset1:220
	ds_write2_b32 v97, v90, v110 offset1:16
	ds_write2_b32 v126, v91, v111 offset0:4 offset1:20
	ds_write2_b32 v127, v92, v112 offset0:8 offset1:24
	v_add_u32_e32 v90, 0x9000, v130
	ds_write2_b32 v90, v93, v113 offset0:12 offset1:28
	ds_write2_b32 v128, v86, v106 offset0:64 offset1:80
	ds_write2_b32 v129, v87, v107 offset0:68 offset1:84
	ds_write2_b32 v131, v88, v108 offset0:72 offset1:88
	v_ashrrev_i32_e32 v88, 5, v142
	v_add_u32_e32 v70, s12, v88
	v_ashrrev_i32_e32 v71, 31, v70
	v_add_u32_e32 v91, 0xd000, v130
	v_lshl_add_u64 v[72:73], v[70:71], 4, s[40:41]
	ds_write2_b32 v91, v89, v109 offset0:76 offset1:92
	s_waitcnt lgkmcnt(0)
	s_barrier
	global_load_dwordx4 v[134:137], v[72:73], off
	global_load_dwordx4 v[138:141], v[72:73], off offset:256
	global_load_dwordx4 v[144:147], v[72:73], off offset:512
	global_load_dwordx4 v[148:151], v[72:73], off offset:768
	global_load_dwordx4 v[152:155], v[72:73], off offset:1024
	global_load_dwordx4 v[156:159], v[72:73], off offset:1280
	global_load_dwordx4 v[160:163], v[72:73], off offset:1536
	global_load_dwordx4 v[164:167], v[72:73], off offset:1792
	v_lshlrev_b32_e32 v0, 3, v142
	v_lshlrev_b32_e32 v66, 2, v142
	v_and_b32_e32 v0, 0xe0, v0
	v_and_b32_e32 v69, 12, v66
	v_lshlrev_b32_e32 v66, 2, v0
	v_lshlrev_b32_e32 v67, 2, v69
	v_or_b32_e32 v0, s42, v0
	v_add3_u32 v68, 0, v66, v67
	v_ashrrev_i32_e32 v66, 1, v0
	v_readlane_b32 s14, v255, 27
	v_ashrrev_i32_e32 v67, 31, v66
	v_readlane_b32 s15, v255, 28
	v_lshlrev_b32_e32 v0, 1, v69
	s_mov_b32 s7, 0x800000
	v_lshl_add_u64 v[66:67], v[66:67], 1, s[14:15]
	v_lshl_add_u64 v[66:67], v[66:67], 0, v[0:1]
	v_mad_u64_u32 v[82:83], s[14:15], v88, s11, v[68:69]
	s_movk_i32 s16, 0x1600
	s_waitcnt vmcnt(0)
	v_add_f32_e32 v0, v134, v135
	v_add_f32_e32 v0, v0, v136
	v_add_f32_e32 v0, v0, v137
	v_fmamk_f32 v0, v0, 0x3a800000, v200
	v_cmp_gt_f32_e32 vcc, s7, v0
	v_mul_f32_e32 v69, 0x4b800000, v0
	ds_read_b128 v[72:75], v82
	ds_read_b128 v[76:79], v82 offset:64
	v_cndmask_b32_e32 v0, v0, v69, vcc
	v_rsq_f32_e32 v0, v0
	s_nop 0
	v_mul_f32_e32 v69, 0x45800000, v0
	v_cndmask_b32_e32 v0, v0, v69, vcc
	s_waitcnt lgkmcnt(1)
	v_pk_mul_f32 v[72:73], v[72:73], v[0:1] op_sel_hi:[1,0]
	v_pk_mul_f32 v[74:75], v[74:75], v[0:1] op_sel_hi:[1,0]
	v_mul_f32_e32 v69, 0xbfb8aa3b, v72
	v_exp_f32_e32 v80, v69
	v_mul_f32_e32 v69, 0xbfb8aa3b, v73
	v_exp_f32_e32 v81, v69
	s_waitcnt lgkmcnt(0)
	v_pk_mul_f32 v[76:77], v[76:77], v[0:1] op_sel_hi:[1,0]
	v_pk_mul_f32 v[78:79], v[78:79], v[0:1] op_sel_hi:[1,0]
	v_mul_f32_e32 v0, 0xbfb8aa3b, v75
	v_pk_add_f32 v[80:81], v[80:81], 1.0 op_sel_hi:[1,0]
	s_nop 0
	v_rcp_f32_e32 v71, v81
	s_nop 0
	v_mul_f32_e32 v73, v73, v71
	v_rcp_f32_e32 v71, v80
	s_nop 0
	v_mul_f32_e32 v72, v72, v71
	v_mul_f32_e32 v69, 0xbfb8aa3b, v74
	v_pk_mul_f32 v[72:73], v[76:77], v[72:73]
	v_exp_f32_e32 v76, v69
	v_exp_f32_e32 v77, v0
	v_cvt_pk_bf16_f32 v72, v72, v73
	v_pk_add_f32 v[76:77], v[76:77], 1.0 op_sel_hi:[1,0]
	s_nop 0
	v_rcp_f32_e32 v69, v77
	s_nop 0
	v_mul_f32_e32 v75, v75, v69
	v_rcp_f32_e32 v69, v76
	s_nop 0
	v_mul_f32_e32 v74, v74, v69
	v_pk_mul_f32 v[74:75], v[78:79], v[74:75]
	v_add_u32_e32 v0, 0x200, v142
	v_cvt_pk_bf16_f32 v73, v74, v75
	v_mad_i64_i32 v[70:71], s[14:15], v70, s16, v[66:67]
	v_ashrrev_i32_e32 v83, 5, v0
	global_store_dwordx2 v[70:71], v[72:73], off
	v_add_u32_e32 v70, s12, v83
	v_ashrrev_i32_e32 v71, 31, v70
	v_lshl_add_u64 v[72:73], v[70:71], 4, s[40:41]
	v_mad_u64_u32 v[80:81], s[14:15], v83, s11, v[68:69]
	v_add_f32_e32 v0, v138, v139
	v_add_f32_e32 v0, v0, v140
	v_add_f32_e32 v0, v0, v141
	v_fmamk_f32 v0, v0, 0x3a800000, v200
	v_cmp_gt_f32_e32 vcc, s7, v0
	v_mul_f32_e32 v69, 0x4b800000, v0
	ds_read_b128 v[72:75], v80
	ds_read_b128 v[76:79], v80 offset:64
	v_cndmask_b32_e32 v0, v0, v69, vcc
	v_rsq_f32_e32 v0, v0
	s_nop 0
	v_mul_f32_e32 v69, 0x45800000, v0
	v_cndmask_b32_e32 v0, v0, v69, vcc
	s_waitcnt lgkmcnt(1)
	v_pk_mul_f32 v[72:73], v[72:73], v[0:1] op_sel_hi:[1,0]
	v_pk_mul_f32 v[74:75], v[74:75], v[0:1] op_sel_hi:[1,0]
	v_mul_f32_e32 v69, 0xbfb8aa3b, v72
	v_exp_f32_e32 v84, v69
	v_mul_f32_e32 v69, 0xbfb8aa3b, v73
	v_exp_f32_e32 v85, v69
	s_waitcnt lgkmcnt(0)
	v_pk_mul_f32 v[76:77], v[76:77], v[0:1] op_sel_hi:[1,0]
	v_pk_mul_f32 v[78:79], v[78:79], v[0:1] op_sel_hi:[1,0]
	v_mul_f32_e32 v0, 0xbfb8aa3b, v75
	v_pk_add_f32 v[84:85], v[84:85], 1.0 op_sel_hi:[1,0]
	s_nop 0
	v_rcp_f32_e32 v71, v85
	s_nop 0
	v_mul_f32_e32 v73, v73, v71
	v_rcp_f32_e32 v71, v84
	s_nop 0
	v_mul_f32_e32 v72, v72, v71
	v_mul_f32_e32 v69, 0xbfb8aa3b, v74
	v_pk_mul_f32 v[72:73], v[76:77], v[72:73]
	v_exp_f32_e32 v76, v69
	v_exp_f32_e32 v77, v0
	v_cvt_pk_bf16_f32 v72, v72, v73
	v_pk_add_f32 v[76:77], v[76:77], 1.0 op_sel_hi:[1,0]
	s_nop 0
	v_rcp_f32_e32 v69, v77
	s_nop 0
	v_mul_f32_e32 v75, v75, v69
	v_rcp_f32_e32 v69, v76
	s_nop 0
	v_mul_f32_e32 v74, v74, v69
	v_pk_mul_f32 v[74:75], v[78:79], v[74:75]
	v_add_u32_e32 v0, 0x400, v142
	v_cvt_pk_bf16_f32 v73, v74, v75
	v_mad_i64_i32 v[70:71], s[14:15], v70, s16, v[66:67]
	v_ashrrev_i32_e32 v81, 5, v0
	global_store_dwordx2 v[70:71], v[72:73], off
	v_add_u32_e32 v70, s12, v81
	v_ashrrev_i32_e32 v71, 31, v70
	v_lshl_add_u64 v[72:73], v[70:71], 4, s[40:41]
	v_mad_u64_u32 v[78:79], s[14:15], v81, s11, v[68:69]
	v_add_f32_e32 v0, v144, v145
	v_add_f32_e32 v0, v0, v146
	v_add_f32_e32 v0, v0, v147
	v_fmamk_f32 v0, v0, 0x3a800000, v200
	v_cmp_gt_f32_e32 vcc, s7, v0
	v_mul_f32_e32 v69, 0x4b800000, v0
	ds_read_b128 v[72:75], v78
	ds_read_b128 v[84:87], v78 offset:64
	v_cndmask_b32_e32 v0, v0, v69, vcc
	v_rsq_f32_e32 v0, v0
	s_nop 0
	v_mul_f32_e32 v69, 0x45800000, v0
	v_cndmask_b32_e32 v0, v0, v69, vcc
	s_waitcnt lgkmcnt(1)
	v_pk_mul_f32 v[72:73], v[72:73], v[0:1] op_sel_hi:[1,0]
	v_pk_mul_f32 v[74:75], v[74:75], v[0:1] op_sel_hi:[1,0]
	v_mul_f32_e32 v69, 0xbfb8aa3b, v72
	v_exp_f32_e32 v76, v69
	v_mul_f32_e32 v69, 0xbfb8aa3b, v73
	v_exp_f32_e32 v77, v69
	s_waitcnt lgkmcnt(0)
	v_pk_mul_f32 v[84:85], v[84:85], v[0:1] op_sel_hi:[1,0]
	v_pk_add_f32 v[76:77], v[76:77], 1.0 op_sel_hi:[1,0]
	s_nop 0
	v_rcp_f32_e32 v71, v77
	s_nop 0
	v_mul_f32_e32 v73, v73, v71
	v_rcp_f32_e32 v71, v76
	s_nop 0
	v_mul_f32_e32 v72, v72, v71
	v_mul_f32_e32 v69, 0xbfb8aa3b, v74
	v_pk_mul_f32 v[76:77], v[86:87], v[0:1] op_sel_hi:[1,0]
	v_mul_f32_e32 v0, 0xbfb8aa3b, v75
	v_pk_mul_f32 v[72:73], v[84:85], v[72:73]
	v_exp_f32_e32 v84, v69
	v_exp_f32_e32 v85, v0
	v_cvt_pk_bf16_f32 v72, v72, v73
	v_pk_add_f32 v[84:85], v[84:85], 1.0 op_sel_hi:[1,0]
	s_nop 0
	v_rcp_f32_e32 v69, v85
	s_nop 0
	v_mul_f32_e32 v75, v75, v69
	v_rcp_f32_e32 v69, v84
	s_nop 0
	v_mul_f32_e32 v74, v74, v69
	v_add_u32_e32 v0, 0x600, v142
	v_pk_mul_f32 v[74:75], v[76:77], v[74:75]
	v_ashrrev_i32_e32 v79, 5, v0
	v_cvt_pk_bf16_f32 v73, v74, v75
	v_add_u32_e32 v74, s12, v79
	v_mad_i64_i32 v[70:71], s[14:15], v70, s16, v[66:67]
	v_ashrrev_i32_e32 v75, 31, v74
	global_store_dwordx2 v[70:71], v[72:73], off
	v_lshl_add_u64 v[70:71], v[74:75], 4, s[40:41]
	v_mad_u64_u32 v[76:77], s[14:15], v79, s11, v[68:69]
	v_add_f32_e32 v0, v148, v149
	v_add_f32_e32 v0, v0, v150
	v_add_f32_e32 v0, v0, v151
	v_fmamk_f32 v0, v0, 0x3a800000, v200
	v_cmp_gt_f32_e32 vcc, s7, v0
	v_mul_f32_e32 v69, 0x4b800000, v0
	ds_read_b128 v[70:73], v76
	ds_read_b128 v[84:87], v76 offset:64
	v_cndmask_b32_e32 v0, v0, v69, vcc
	v_rsq_f32_e32 v0, v0
	s_nop 0
	v_mul_f32_e32 v69, 0x45800000, v0
	v_cndmask_b32_e32 v0, v0, v69, vcc
	s_waitcnt lgkmcnt(1)
	v_pk_mul_f32 v[70:71], v[70:71], v[0:1] op_sel_hi:[1,0]
	v_pk_mul_f32 v[72:73], v[72:73], v[0:1] op_sel_hi:[1,0]
	v_mul_f32_e32 v69, 0xbfb8aa3b, v70
	v_exp_f32_e32 v92, v69
	v_mul_f32_e32 v69, 0xbfb8aa3b, v71
	v_exp_f32_e32 v93, v69
	s_waitcnt lgkmcnt(0)
	v_pk_mul_f32 v[84:85], v[84:85], v[0:1] op_sel_hi:[1,0]
	v_pk_mul_f32 v[86:87], v[86:87], v[0:1] op_sel_hi:[1,0]
	v_mul_f32_e32 v0, 0xbfb8aa3b, v73
	v_pk_add_f32 v[92:93], v[92:93], 1.0 op_sel_hi:[1,0]
	s_nop 0
	v_rcp_f32_e32 v75, v93
	s_nop 0
	v_mul_f32_e32 v71, v71, v75
	v_rcp_f32_e32 v75, v92
	s_nop 0
	v_mul_f32_e32 v70, v70, v75
	v_mul_f32_e32 v69, 0xbfb8aa3b, v72
	v_pk_mul_f32 v[70:71], v[84:85], v[70:71]
	v_exp_f32_e32 v84, v69
	v_exp_f32_e32 v85, v0
	v_cvt_pk_bf16_f32 v70, v70, v71
	v_pk_add_f32 v[84:85], v[84:85], 1.0 op_sel_hi:[1,0]
	s_nop 0
	v_rcp_f32_e32 v69, v85
	s_nop 0
	v_mul_f32_e32 v73, v73, v69
	v_rcp_f32_e32 v69, v84
	s_nop 0
	v_mul_f32_e32 v72, v72, v69
	v_pk_mul_f32 v[72:73], v[86:87], v[72:73]
	v_add_u32_e32 v0, 0x800, v142
	v_cvt_pk_bf16_f32 v71, v72, v73
	v_mad_i64_i32 v[72:73], s[14:15], v74, s16, v[66:67]
	v_ashrrev_i32_e32 v0, 5, v0
	global_store_dwordx2 v[72:73], v[70:71], off
	v_add_u32_e32 v72, s12, v0
	v_ashrrev_i32_e32 v73, 31, v72
	v_lshl_add_u64 v[74:75], v[72:73], 4, s[40:41]
	v_mad_u64_u32 v[70:71], s[14:15], v0, s11, v[68:69]
	v_add_f32_e32 v69, v152, v153
	v_add_f32_e32 v69, v69, v154
	v_add_f32_e32 v69, v69, v155
	v_fmamk_f32 v69, v69, 0x3a800000, v200
	v_cmp_gt_f32_e32 vcc, s7, v69
	v_mul_f32_e32 v71, 0x4b800000, v69
	ds_read_b128 v[84:87], v70
	ds_read_b128 v[98:101], v70 offset:64
	v_cndmask_b32_e32 v69, v69, v71, vcc
	v_rsq_f32_e32 v69, v69
	s_nop 0
	v_mul_f32_e32 v71, 0x45800000, v69
	v_cndmask_b32_e32 v74, v69, v71, vcc
	s_waitcnt lgkmcnt(1)
	v_pk_mul_f32 v[84:85], v[84:85], v[74:75] op_sel_hi:[1,0]
	s_waitcnt lgkmcnt(0)
	v_pk_mul_f32 v[98:99], v[98:99], v[74:75] op_sel_hi:[1,0]
	v_mul_f32_e32 v69, 0xbfb8aa3b, v84
	v_exp_f32_e32 v92, v69
	v_mul_f32_e32 v69, 0xbfb8aa3b, v85
	v_exp_f32_e32 v93, v69
	s_nop 0
	v_pk_add_f32 v[92:93], v[92:93], 1.0 op_sel_hi:[1,0]
	s_nop 0
	v_rcp_f32_e32 v71, v93
	s_nop 0
	v_mul_f32_e32 v85, v85, v71
	v_div_scale_f32 v69, s[14:15], v92, v92, v84
	v_rcp_f32_e32 v71, v69
	s_nop 0
	v_fma_f32 v73, -v69, v71, 1.0
	v_fmac_f32_e32 v71, v73, v71
	v_div_scale_f32 v73, vcc, v84, v92, v84
	v_mul_f32_e32 v75, v73, v71
	v_fma_f32 v77, -v69, v75, v73
	v_fmac_f32_e32 v75, v77, v71
	v_fma_f32 v69, -v69, v75, v73
	v_div_fmas_f32 v69, v69, v71, v75
	v_pk_mul_f32 v[86:87], v[86:87], v[74:75] op_sel_hi:[1,0]
	v_div_fixup_f32 v84, v69, v92, v84
	v_mul_f32_e32 v69, 0xbfb8aa3b, v86
	v_exp_f32_e32 v92, v69
	v_mul_f32_e32 v69, 0xbfb8aa3b, v87
	v_exp_f32_e32 v93, v69
	v_pk_mul_f32 v[74:75], v[100:101], v[74:75] op_sel_hi:[1,0]
	v_pk_mul_f32 v[84:85], v[98:99], v[84:85]
	v_pk_add_f32 v[92:93], v[92:93], 1.0 op_sel_hi:[1,0]
	s_nop 0
	v_div_scale_f32 v69, s[14:15], v93, v93, v87
	v_rcp_f32_e32 v71, v69
	v_cvt_pk_bf16_f32 v84, v84, v85
	v_fma_f32 v73, -v69, v71, 1.0
	v_fmac_f32_e32 v71, v73, v71
	v_div_scale_f32 v73, vcc, v87, v93, v87
	v_mul_f32_e32 v77, v73, v71
	v_fma_f32 v89, -v69, v77, v73
	v_fmac_f32_e32 v77, v89, v71
	v_fma_f32 v69, -v69, v77, v73
	v_div_fmas_f32 v69, v69, v71, v77
	v_div_fixup_f32 v87, v69, v93, v87
	v_rcp_f32_e32 v71, v92
	s_nop 0
	v_mul_f32_e32 v86, v86, v71
	v_add_u32_e32 v69, 0xa00, v142
	v_pk_mul_f32 v[74:75], v[74:75], v[86:87]
	v_ashrrev_i32_e32 v71, 5, v69
	v_cvt_pk_bf16_f32 v85, v74, v75
	v_add_u32_e32 v74, s12, v71
	v_mad_i64_i32 v[72:73], s[14:15], v72, s16, v[66:67]
	v_ashrrev_i32_e32 v75, 31, v74
	global_store_dwordx2 v[72:73], v[84:85], off
	v_lshl_add_u64 v[84:85], v[74:75], 4, s[40:41]
	v_mad_u64_u32 v[72:73], s[14:15], v71, s11, v[68:69]
	v_add_f32_e32 v69, v156, v157
	v_add_f32_e32 v69, v69, v158
	v_add_f32_e32 v69, v69, v159
	v_fmamk_f32 v69, v69, 0x3a800000, v200
	v_cmp_gt_f32_e32 vcc, s7, v69
	v_mul_f32_e32 v73, 0x4b800000, v69
	ds_read_b128 v[84:87], v72
	ds_read_b128 v[98:101], v72 offset:64
	v_cndmask_b32_e32 v69, v69, v73, vcc
	v_rsq_f32_e32 v69, v69
	s_nop 0
	v_mul_f32_e32 v73, 0x45800000, v69
	v_cndmask_b32_e32 v92, v69, v73, vcc
	s_waitcnt lgkmcnt(1)
	v_pk_mul_f32 v[84:85], v[84:85], v[92:93] op_sel_hi:[1,0]
	v_pk_mul_f32 v[86:87], v[86:87], v[92:93] op_sel_hi:[1,0]
	v_mul_f32_e32 v69, 0xbfb8aa3b, v84
	v_exp_f32_e32 v102, v69
	v_mul_f32_e32 v69, 0xbfb8aa3b, v85
	v_exp_f32_e32 v103, v69
	s_waitcnt lgkmcnt(0)
	v_pk_mul_f32 v[98:99], v[98:99], v[92:93] op_sel_hi:[1,0]
	v_pk_mul_f32 v[92:93], v[100:101], v[92:93] op_sel_hi:[1,0]
	v_pk_add_f32 v[102:103], v[102:103], 1.0 op_sel_hi:[1,0]
	s_nop 0
	v_rcp_f32_e32 v73, v103
	s_nop 0
	v_mul_f32_e32 v85, v85, v73
	v_rcp_f32_e32 v73, v102
	s_nop 0
	v_mul_f32_e32 v84, v84, v73
	v_mul_f32_e32 v69, 0xbfb8aa3b, v86
	v_pk_mul_f32 v[84:85], v[98:99], v[84:85]
	v_exp_f32_e32 v98, v69
	v_mul_f32_e32 v69, 0xbfb8aa3b, v87
	v_exp_f32_e32 v99, v69
	v_cvt_pk_bf16_f32 v84, v84, v85
	v_pk_add_f32 v[98:99], v[98:99], 1.0 op_sel_hi:[1,0]
	s_nop 0
	v_rcp_f32_e32 v73, v99
	s_nop 0
	v_mul_f32_e32 v87, v87, v73
	v_rcp_f32_e32 v73, v98
	s_nop 0
	v_mul_f32_e32 v86, v86, v73
	v_pk_mul_f32 v[86:87], v[92:93], v[86:87]
	v_add_u32_e32 v69, 0xc00, v142
	v_cvt_pk_bf16_f32 v85, v86, v87
	v_mad_i64_i32 v[74:75], s[14:15], v74, s16, v[66:67]
	v_ashrrev_i32_e32 v73, 5, v69
	global_store_dwordx2 v[74:75], v[84:85], off
	v_add_u32_e32 v84, s12, v73
	v_ashrrev_i32_e32 v85, 31, v84
	v_lshl_add_u64 v[86:87], v[84:85], 4, s[40:41]
	v_mad_u64_u32 v[74:75], s[14:15], v73, s11, v[68:69]
	v_add_f32_e32 v69, v160, v161
	v_add_f32_e32 v69, v69, v162
	v_add_f32_e32 v69, v69, v163
	v_fmamk_f32 v69, v69, 0x3a800000, v200
	v_cmp_gt_f32_e32 vcc, s7, v69
	v_mul_f32_e32 v75, 0x4b800000, v69
	ds_read_b128 v[98:101], v74
	ds_read_b128 v[102:105], v74 offset:64
	v_cndmask_b32_e32 v69, v69, v75, vcc
	v_rsq_f32_e32 v69, v69
	s_nop 0
	v_mul_f32_e32 v75, 0x45800000, v69
	v_cndmask_b32_e32 v86, v69, v75, vcc
	s_waitcnt lgkmcnt(1)
	v_pk_mul_f32 v[92:93], v[98:99], v[86:87] op_sel_hi:[1,0]
	s_waitcnt lgkmcnt(0)
	v_pk_mul_f32 v[102:103], v[102:103], v[86:87] op_sel_hi:[1,0]
	v_mul_f32_e32 v69, 0xbfb8aa3b, v92
	v_exp_f32_e32 v98, v69
	v_mul_f32_e32 v69, 0xbfb8aa3b, v93
	v_exp_f32_e32 v99, v69
	s_nop 0
	v_pk_add_f32 v[98:99], v[98:99], 1.0 op_sel_hi:[1,0]
	s_nop 0
	v_rcp_f32_e32 v75, v99
	s_nop 0
	v_mul_f32_e32 v93, v93, v75
	v_rcp_f32_e32 v75, v98
	s_nop 0
	v_mul_f32_e32 v92, v92, v75
	v_pk_mul_f32 v[98:99], v[100:101], v[86:87] op_sel_hi:[1,0]
	v_pk_mul_f32 v[86:87], v[104:105], v[86:87] op_sel_hi:[1,0]
	v_mul_f32_e32 v69, 0xbfb8aa3b, v98
	v_exp_f32_e32 v100, v69
	v_mul_f32_e32 v69, 0xbfb8aa3b, v99
	v_exp_f32_e32 v101, v69
	v_pk_mul_f32 v[92:93], v[102:103], v[92:93]
	v_pk_add_f32 v[100:101], v[100:101], 1.0 op_sel_hi:[1,0]
	s_nop 0
	v_div_scale_f32 v69, s[14:15], v101, v101, v99
	v_rcp_f32_e32 v75, v69
	v_cvt_pk_bf16_f32 v92, v92, v93
	v_fma_f32 v77, -v69, v75, 1.0
	v_fmac_f32_e32 v75, v77, v75
	v_div_scale_f32 v77, vcc, v99, v101, v99
	v_mul_f32_e32 v85, v77, v75
	v_fma_f32 v89, -v69, v85, v77
	v_fmac_f32_e32 v85, v89, v75
	v_fma_f32 v69, -v69, v85, v77
	v_div_fmas_f32 v69, v69, v75, v85
	v_div_fixup_f32 v99, v69, v101, v99
	v_rcp_f32_e32 v75, v100
	s_nop 0
	v_mul_f32_e32 v98, v98, v75
	v_pk_mul_f32 v[86:87], v[86:87], v[98:99]
	v_add_u32_e32 v69, 0xe00, v142
	v_cvt_pk_bf16_f32 v93, v86, v87
	v_mad_i64_i32 v[84:85], s[14:15], v84, s16, v[66:67]
	v_ashrrev_i32_e32 v75, 5, v69
	global_store_dwordx2 v[84:85], v[92:93], off
	v_add_u32_e32 v84, s12, v75
	v_ashrrev_i32_e32 v85, 31, v84
	v_lshl_add_u64 v[86:87], v[84:85], 4, s[40:41]
	v_mad_u64_u32 v[68:69], s[14:15], v75, s11, v[68:69]
	v_add_f32_e32 v69, v164, v165
	v_add_f32_e32 v69, v69, v166
	v_add_f32_e32 v69, v69, v167
	v_fmamk_f32 v69, v69, 0x3a800000, v200
	v_cmp_gt_f32_e32 vcc, s7, v69
	v_mul_f32_e32 v77, 0x4b800000, v69
	ds_read_b128 v[98:101], v68
	ds_read_b128 v[102:105], v68 offset:64
	v_cndmask_b32_e32 v69, v69, v77, vcc
	v_rsq_f32_e32 v69, v69
	s_nop 0
	v_mul_f32_e32 v77, 0x45800000, v69
	v_cndmask_b32_e32 v86, v69, v77, vcc
	s_waitcnt lgkmcnt(1)
	v_pk_mul_f32 v[92:93], v[98:99], v[86:87] op_sel_hi:[1,0]
	s_waitcnt lgkmcnt(0)
	v_pk_mul_f32 v[102:103], v[102:103], v[86:87] op_sel_hi:[1,0]
	v_mul_f32_e32 v69, 0xbfb8aa3b, v92
	v_exp_f32_e32 v98, v69
	v_mul_f32_e32 v69, 0xbfb8aa3b, v93
	v_exp_f32_e32 v99, v69
	s_nop 0
	v_pk_add_f32 v[98:99], v[98:99], 1.0 op_sel_hi:[1,0]
	s_nop 0
	v_rcp_f32_e32 v77, v99
	s_nop 0
	v_mul_f32_e32 v93, v93, v77
	v_rcp_f32_e32 v77, v98
	s_nop 0
	v_mul_f32_e32 v92, v92, v77
	v_pk_mul_f32 v[98:99], v[100:101], v[86:87] op_sel_hi:[1,0]
	v_pk_mul_f32 v[92:93], v[102:103], v[92:93]
	v_mul_f32_e32 v69, 0xbfb8aa3b, v98
	v_exp_f32_e32 v100, v69
	v_mul_f32_e32 v69, 0xbfb8aa3b, v99
	v_exp_f32_e32 v101, v69
	v_pk_mul_f32 v[86:87], v[104:105], v[86:87] op_sel_hi:[1,0]
	v_cvt_pk_bf16_f32 v92, v92, v93
	v_pk_add_f32 v[100:101], v[100:101], 1.0 op_sel_hi:[1,0]
	s_nop 0
	v_rcp_f32_e32 v77, v101
	s_nop 0
	v_mul_f32_e32 v99, v99, v77
	v_rcp_f32_e32 v77, v100
	s_nop 0
	v_mul_f32_e32 v98, v98, v77
	v_pk_mul_f32 v[86:87], v[86:87], v[98:99]
	v_mad_i64_i32 v[84:85], s[12:13], v84, s16, v[66:67]
	v_cvt_pk_bf16_f32 v93, v86, v87
	global_store_dwordx2 v[84:85], v[92:93], off
	s_barrier
	ds_write2_b32 v130, v2, v18 offset1:16
	ds_write2_b32 v114, v3, v19 offset0:4 offset1:20
	ds_write2_b32 v115, v4, v20 offset0:8 offset1:24
	ds_write2_b32 v116, v5, v21 offset0:12 offset1:28
	ds_write2_b32 v117, v6, v22 offset0:64 offset1:80
	ds_write2_b32 v94, v7, v23 offset0:68 offset1:84
	ds_write2_b32 v95, v8, v24 offset0:72 offset1:88
	ds_write2_b32 v96, v9, v25 offset0:76 offset1:92
	ds_write2_b32 v132, v10, v26 offset0:128 offset1:144
	ds_write2_b32 v97, v11, v27 offset0:132 offset1:148
	ds_write2_b32 v126, v12, v28 offset0:136 offset1:152
	ds_write2_b32 v127, v13, v29 offset0:140 offset1:156
	ds_write2_b32 v133, v14, v30 offset0:192 offset1:208
	ds_write2_b32 v128, v15, v31 offset0:196 offset1:212
	ds_write2_b32 v129, v16, v32 offset0:200 offset1:216
	ds_write2_b32 v131, v17, v33 offset0:204 offset1:220
	ds_write2_b32 v130, v34, v50 offset0:128 offset1:144
	ds_write2_b32 v114, v35, v51 offset0:132 offset1:148
	ds_write2_b32 v115, v36, v52 offset0:136 offset1:152
	ds_write2_b32 v116, v37, v53 offset0:140 offset1:156
	ds_write2_b32 v117, v38, v54 offset0:192 offset1:208
	ds_write2_b32 v94, v39, v55 offset0:196 offset1:212
	ds_write2_b32 v95, v40, v56 offset0:200 offset1:216
	ds_write2_b32 v96, v41, v57 offset0:204 offset1:220
	ds_write2_b32 v97, v42, v58 offset1:16
	ds_write2_b32 v126, v43, v59 offset0:4 offset1:20
	ds_write2_b32 v127, v44, v60 offset0:8 offset1:24
	ds_write2_b32 v90, v45, v61 offset0:12 offset1:28
	ds_write2_b32 v128, v46, v62 offset0:64 offset1:80
	ds_write2_b32 v129, v47, v63 offset0:68 offset1:84
	ds_write2_b32 v131, v48, v64 offset0:72 offset1:88
	ds_write2_b32 v91, v49, v65 offset0:76 offset1:92
	v_add_u32_e32 v2, s10, v88
	v_ashrrev_i32_e32 v3, 31, v2
	v_lshl_add_u64 v[4:5], v[2:3], 4, s[40:41]
	s_waitcnt lgkmcnt(0)
	s_barrier
	global_load_dwordx4 v[134:137], v[4:5], off
	global_load_dwordx4 v[138:141], v[4:5], off offset:256
	global_load_dwordx4 v[144:147], v[4:5], off offset:512
	global_load_dwordx4 v[148:151], v[4:5], off offset:768
	global_load_dwordx4 v[152:155], v[4:5], off offset:1024
	global_load_dwordx4 v[156:159], v[4:5], off offset:1280
	global_load_dwordx4 v[160:163], v[4:5], off offset:1536
	global_load_dwordx4 v[164:167], v[4:5], off offset:1792
	s_waitcnt vmcnt(0)
	v_add_f32_e32 v3, v134, v135
	v_add_f32_e32 v3, v3, v136
	v_add_f32_e32 v3, v3, v137
	v_fmamk_f32 v3, v3, 0x3a800000, v200
	v_cmp_gt_f32_e32 vcc, s7, v3
	v_mul_f32_e32 v4, 0x4b800000, v3
	s_nop 0
	v_cndmask_b32_e32 v3, v3, v4, vcc
	v_rsq_f32_e32 v3, v3
	s_nop 0
	v_mul_f32_e32 v4, 0x45800000, v3
	v_cndmask_b32_e32 v12, v3, v4, vcc
	ds_read_b128 v[4:7], v82
	ds_read_b128 v[8:11], v82 offset:64
	s_waitcnt lgkmcnt(1)
	v_pk_mul_f32 v[4:5], v[4:5], v[12:13] op_sel_hi:[1,0]
	s_nop 0
	v_mul_f32_e32 v3, 0xbfb8aa3b, v4
	v_exp_f32_e32 v14, v3
	v_mul_f32_e32 v3, 0xbfb8aa3b, v5
	v_exp_f32_e32 v15, v3
	s_waitcnt lgkmcnt(0)
	v_pk_mul_f32 v[8:9], v[8:9], v[12:13] op_sel_hi:[1,0]
	v_pk_add_f32 v[14:15], v[14:15], 1.0 op_sel_hi:[1,0]
	s_nop 0
	v_rcp_f32_e32 v13, v15
	s_nop 0
	v_mul_f32_e32 v5, v5, v13
	v_div_scale_f32 v3, s[12:13], v14, v14, v4
	v_rcp_f32_e32 v13, v3
	s_nop 0
	v_fma_f32 v15, -v3, v13, 1.0
	v_fmac_f32_e32 v13, v15, v13
	v_div_scale_f32 v15, vcc, v4, v14, v4
	v_mul_f32_e32 v16, v15, v13
	v_fma_f32 v17, -v3, v16, v15
	v_fmac_f32_e32 v16, v17, v13
	v_fma_f32 v3, -v3, v16, v15
	v_div_fmas_f32 v3, v3, v13, v16
	v_pk_mul_f32 v[6:7], v[6:7], v[12:13] op_sel_hi:[1,0]
	v_div_fixup_f32 v4, v3, v14, v4
	v_mul_f32_e32 v3, 0xbfb8aa3b, v6
	v_pk_mul_f32 v[4:5], v[8:9], v[4:5]
	v_exp_f32_e32 v8, v3
	v_mul_f32_e32 v3, 0xbfb8aa3b, v7
	v_exp_f32_e32 v9, v3
	v_pk_mul_f32 v[10:11], v[10:11], v[12:13] op_sel_hi:[1,0]
	v_cvt_pk_bf16_f32 v4, v4, v5
	v_pk_add_f32 v[8:9], v[8:9], 1.0 op_sel_hi:[1,0]
	s_nop 0
	v_rcp_f32_e32 v12, v9
	s_nop 0
	v_mul_f32_e32 v7, v7, v12
	v_rcp_f32_e32 v9, v8
	s_nop 0
	v_mul_f32_e32 v6, v6, v9
	v_pk_mul_f32 v[6:7], v[10:11], v[6:7]
	v_mad_i64_i32 v[2:3], s[12:13], v2, s16, v[66:67]
	v_cvt_pk_bf16_f32 v5, v6, v7
	global_store_dwordx2 v[2:3], v[4:5], off
	v_add_u32_e32 v2, s10, v83
	v_ashrrev_i32_e32 v3, 31, v2
	v_lshl_add_u64 v[4:5], v[2:3], 4, s[40:41]
	v_add_f32_e32 v3, v138, v139
	v_add_f32_e32 v3, v3, v140
	v_add_f32_e32 v3, v3, v141
	v_fmamk_f32 v3, v3, 0x3a800000, v200
	v_cmp_gt_f32_e32 vcc, s7, v3
	v_mul_f32_e32 v4, 0x4b800000, v3
	s_nop 0
	v_cndmask_b32_e32 v3, v3, v4, vcc
	v_rsq_f32_e32 v3, v3
	s_nop 0
	v_mul_f32_e32 v4, 0x45800000, v3
	v_cndmask_b32_e32 v12, v3, v4, vcc
	ds_read_b128 v[4:7], v80
	ds_read_b128 v[8:11], v80 offset:64
	s_waitcnt lgkmcnt(1)
	v_pk_mul_f32 v[4:5], v[4:5], v[12:13] op_sel_hi:[1,0]
	s_nop 0
	v_mul_f32_e32 v3, 0xbfb8aa3b, v4
	v_exp_f32_e32 v14, v3
	v_mul_f32_e32 v3, 0xbfb8aa3b, v5
	v_exp_f32_e32 v15, v3
	s_waitcnt lgkmcnt(0)
	v_pk_mul_f32 v[8:9], v[8:9], v[12:13] op_sel_hi:[1,0]
	v_pk_add_f32 v[14:15], v[14:15], 1.0 op_sel_hi:[1,0]
	s_nop 0
	v_rcp_f32_e32 v13, v15
	s_nop 0
	v_mul_f32_e32 v5, v5, v13
	v_div_scale_f32 v3, s[12:13], v14, v14, v4
	v_rcp_f32_e32 v13, v3
	s_nop 0
	v_fma_f32 v15, -v3, v13, 1.0
	v_fmac_f32_e32 v13, v15, v13
	v_div_scale_f32 v15, vcc, v4, v14, v4
	v_mul_f32_e32 v16, v15, v13
	v_fma_f32 v17, -v3, v16, v15
	v_fmac_f32_e32 v16, v17, v13
	v_fma_f32 v3, -v3, v16, v15
	v_div_fmas_f32 v3, v3, v13, v16
	v_pk_mul_f32 v[6:7], v[6:7], v[12:13] op_sel_hi:[1,0]
	v_div_fixup_f32 v4, v3, v14, v4
	v_mul_f32_e32 v3, 0xbfb8aa3b, v6
	v_pk_mul_f32 v[4:5], v[8:9], v[4:5]
	v_exp_f32_e32 v8, v3
	v_mul_f32_e32 v3, 0xbfb8aa3b, v7
	v_exp_f32_e32 v9, v3
	v_pk_mul_f32 v[10:11], v[10:11], v[12:13] op_sel_hi:[1,0]
	v_cvt_pk_bf16_f32 v4, v4, v5
	v_pk_add_f32 v[8:9], v[8:9], 1.0 op_sel_hi:[1,0]
	s_nop 0
	v_rcp_f32_e32 v12, v9
	s_nop 0
	v_mul_f32_e32 v7, v7, v12
	v_rcp_f32_e32 v9, v8
	s_nop 0
	v_mul_f32_e32 v6, v6, v9
	v_pk_mul_f32 v[6:7], v[10:11], v[6:7]
	v_mad_i64_i32 v[2:3], s[12:13], v2, s16, v[66:67]
	v_cvt_pk_bf16_f32 v5, v6, v7
	global_store_dwordx2 v[2:3], v[4:5], off
	v_add_u32_e32 v2, s10, v81
	v_ashrrev_i32_e32 v3, 31, v2
	v_lshl_add_u64 v[4:5], v[2:3], 4, s[40:41]
	v_add_f32_e32 v3, v144, v145
	v_add_f32_e32 v3, v3, v146
	v_add_f32_e32 v3, v3, v147
	v_fmamk_f32 v3, v3, 0x3a800000, v200
	v_cmp_gt_f32_e32 vcc, s7, v3
	v_mul_f32_e32 v4, 0x4b800000, v3
	s_nop 0
	v_cndmask_b32_e32 v3, v3, v4, vcc
	v_rsq_f32_e32 v3, v3
	s_nop 0
	v_mul_f32_e32 v4, 0x45800000, v3
	v_cndmask_b32_e32 v12, v3, v4, vcc
	ds_read_b128 v[4:7], v78
	ds_read_b128 v[8:11], v78 offset:64
	s_waitcnt lgkmcnt(1)
	v_pk_mul_f32 v[4:5], v[4:5], v[12:13] op_sel_hi:[1,0]
	s_nop 0
	v_mul_f32_e32 v3, 0xbfb8aa3b, v4
	v_exp_f32_e32 v14, v3
	v_mul_f32_e32 v3, 0xbfb8aa3b, v5
	v_exp_f32_e32 v15, v3
	s_waitcnt lgkmcnt(0)
	v_pk_mul_f32 v[8:9], v[8:9], v[12:13] op_sel_hi:[1,0]
	v_pk_add_f32 v[14:15], v[14:15], 1.0 op_sel_hi:[1,0]
	s_nop 0
	v_rcp_f32_e32 v13, v15
	s_nop 0
	v_mul_f32_e32 v5, v5, v13
	v_div_scale_f32 v3, s[12:13], v14, v14, v4
	v_rcp_f32_e32 v13, v3
	s_nop 0
	v_fma_f32 v15, -v3, v13, 1.0
	v_fmac_f32_e32 v13, v15, v13
	v_div_scale_f32 v15, vcc, v4, v14, v4
	v_mul_f32_e32 v16, v15, v13
	v_fma_f32 v17, -v3, v16, v15
	v_fmac_f32_e32 v16, v17, v13
	v_fma_f32 v3, -v3, v16, v15
	v_div_fmas_f32 v3, v3, v13, v16
	v_pk_mul_f32 v[6:7], v[6:7], v[12:13] op_sel_hi:[1,0]
	v_div_fixup_f32 v4, v3, v14, v4
	v_mul_f32_e32 v3, 0xbfb8aa3b, v6
	v_pk_mul_f32 v[4:5], v[8:9], v[4:5]
	v_exp_f32_e32 v8, v3
	v_mul_f32_e32 v3, 0xbfb8aa3b, v7
	v_exp_f32_e32 v9, v3
	v_pk_mul_f32 v[10:11], v[10:11], v[12:13] op_sel_hi:[1,0]
	v_cvt_pk_bf16_f32 v4, v4, v5
	v_pk_add_f32 v[8:9], v[8:9], 1.0 op_sel_hi:[1,0]
	s_nop 0
	v_rcp_f32_e32 v12, v9
	s_nop 0
	v_mul_f32_e32 v7, v7, v12
	v_rcp_f32_e32 v9, v8
	s_nop 0
	v_mul_f32_e32 v6, v6, v9
	v_pk_mul_f32 v[6:7], v[10:11], v[6:7]
	v_mad_i64_i32 v[2:3], s[12:13], v2, s16, v[66:67]
	v_cvt_pk_bf16_f32 v5, v6, v7
	global_store_dwordx2 v[2:3], v[4:5], off
	v_add_u32_e32 v2, s10, v79
	v_ashrrev_i32_e32 v3, 31, v2
	v_lshl_add_u64 v[4:5], v[2:3], 4, s[40:41]
	v_add_f32_e32 v3, v148, v149
	v_add_f32_e32 v3, v3, v150
	v_add_f32_e32 v3, v3, v151
	v_fmamk_f32 v3, v3, 0x3a800000, v200
	v_cmp_gt_f32_e32 vcc, s7, v3
	v_mul_f32_e32 v4, 0x4b800000, v3
	s_nop 0
	v_cndmask_b32_e32 v3, v3, v4, vcc
	v_rsq_f32_e32 v3, v3
	s_nop 0
	v_mul_f32_e32 v4, 0x45800000, v3
	v_cndmask_b32_e32 v12, v3, v4, vcc
	ds_read_b128 v[4:7], v76
	ds_read_b128 v[8:11], v76 offset:64
	s_waitcnt lgkmcnt(1)
	v_pk_mul_f32 v[4:5], v[4:5], v[12:13] op_sel_hi:[1,0]
	s_nop 0
	v_mul_f32_e32 v3, 0xbfb8aa3b, v4
	v_exp_f32_e32 v14, v3
	v_mul_f32_e32 v3, 0xbfb8aa3b, v5
	v_exp_f32_e32 v15, v3
	s_waitcnt lgkmcnt(0)
	v_pk_mul_f32 v[8:9], v[8:9], v[12:13] op_sel_hi:[1,0]
	v_pk_add_f32 v[14:15], v[14:15], 1.0 op_sel_hi:[1,0]
	s_nop 0
	v_rcp_f32_e32 v13, v15
	s_nop 0
	v_mul_f32_e32 v5, v5, v13
	v_div_scale_f32 v3, s[12:13], v14, v14, v4
	v_rcp_f32_e32 v13, v3
	s_nop 0
	v_fma_f32 v15, -v3, v13, 1.0
	v_fmac_f32_e32 v13, v15, v13
	v_div_scale_f32 v15, vcc, v4, v14, v4
	v_mul_f32_e32 v16, v15, v13
	v_fma_f32 v17, -v3, v16, v15
	v_fmac_f32_e32 v16, v17, v13
	v_fma_f32 v3, -v3, v16, v15
	v_div_fmas_f32 v3, v3, v13, v16
	v_pk_mul_f32 v[6:7], v[6:7], v[12:13] op_sel_hi:[1,0]
	v_div_fixup_f32 v4, v3, v14, v4
	v_mul_f32_e32 v3, 0xbfb8aa3b, v6
	v_pk_mul_f32 v[4:5], v[8:9], v[4:5]
	v_exp_f32_e32 v8, v3
	v_mul_f32_e32 v3, 0xbfb8aa3b, v7
	v_exp_f32_e32 v9, v3
	v_pk_mul_f32 v[10:11], v[10:11], v[12:13] op_sel_hi:[1,0]
	v_cvt_pk_bf16_f32 v4, v4, v5
	v_pk_add_f32 v[8:9], v[8:9], 1.0 op_sel_hi:[1,0]
	s_nop 0
	v_rcp_f32_e32 v12, v9
	s_nop 0
	v_mul_f32_e32 v7, v7, v12
	v_rcp_f32_e32 v9, v8
	s_nop 0
	v_mul_f32_e32 v6, v6, v9
	v_pk_mul_f32 v[6:7], v[10:11], v[6:7]
	v_mad_i64_i32 v[2:3], s[12:13], v2, s16, v[66:67]
	v_cvt_pk_bf16_f32 v5, v6, v7
	global_store_dwordx2 v[2:3], v[4:5], off
	v_add_u32_e32 v2, s10, v0
	v_ashrrev_i32_e32 v3, 31, v2
	v_lshl_add_u64 v[4:5], v[2:3], 4, s[40:41]
	v_add_f32_e32 v0, v152, v153
	v_add_f32_e32 v0, v0, v154
	v_add_f32_e32 v0, v0, v155
	v_fmamk_f32 v0, v0, 0x3a800000, v200
	v_cmp_gt_f32_e32 vcc, s7, v0
	v_mul_f32_e32 v3, 0x4b800000, v0
	ds_read_b128 v[4:7], v70
	ds_read_b128 v[8:11], v70 offset:64
	v_cndmask_b32_e32 v0, v0, v3, vcc
	v_rsq_f32_e32 v0, v0
	s_nop 0
	v_mul_f32_e32 v3, 0x45800000, v0
	v_cndmask_b32_e32 v0, v0, v3, vcc
	s_waitcnt lgkmcnt(1)
	v_pk_mul_f32 v[4:5], v[4:5], v[0:1] op_sel_hi:[1,0]
	v_pk_mul_f32 v[6:7], v[6:7], v[0:1] op_sel_hi:[1,0]
	v_mul_f32_e32 v3, 0xbfb8aa3b, v4
	v_exp_f32_e32 v12, v3
	v_mul_f32_e32 v3, 0xbfb8aa3b, v5
	v_exp_f32_e32 v13, v3
	s_waitcnt lgkmcnt(0)
	v_pk_mul_f32 v[8:9], v[8:9], v[0:1] op_sel_hi:[1,0]
	v_pk_mul_f32 v[10:11], v[10:11], v[0:1] op_sel_hi:[1,0]
	v_mul_f32_e32 v0, 0xbfb8aa3b, v7
	v_pk_add_f32 v[12:13], v[12:13], 1.0 op_sel_hi:[1,0]
	s_nop 0
	v_rcp_f32_e32 v14, v13
	s_nop 0
	v_mul_f32_e32 v5, v5, v14
	v_rcp_f32_e32 v13, v12
	s_nop 0
	v_mul_f32_e32 v4, v4, v13
	v_mul_f32_e32 v3, 0xbfb8aa3b, v6
	v_pk_mul_f32 v[4:5], v[8:9], v[4:5]
	v_exp_f32_e32 v8, v3
	v_exp_f32_e32 v9, v0
	v_cvt_pk_bf16_f32 v4, v4, v5
	v_pk_add_f32 v[8:9], v[8:9], 1.0 op_sel_hi:[1,0]
	s_nop 0
	v_rcp_f32_e32 v3, v9
	s_nop 0
	v_mul_f32_e32 v7, v7, v3
	v_rcp_f32_e32 v3, v8
	s_nop 0
	v_mul_f32_e32 v6, v6, v3
	v_pk_mul_f32 v[6:7], v[10:11], v[6:7]
	v_mad_i64_i32 v[2:3], s[12:13], v2, s16, v[66:67]
	v_cvt_pk_bf16_f32 v5, v6, v7
	global_store_dwordx2 v[2:3], v[4:5], off
	v_add_u32_e32 v2, s10, v71
	v_ashrrev_i32_e32 v3, 31, v2
	v_lshl_add_u64 v[4:5], v[2:3], 4, s[40:41]
	v_add_f32_e32 v0, v156, v157
	v_add_f32_e32 v0, v0, v158
	v_add_f32_e32 v0, v0, v159
	v_fmamk_f32 v0, v0, 0x3a800000, v200
	v_cmp_gt_f32_e32 vcc, s7, v0
	v_mul_f32_e32 v3, 0x4b800000, v0
	ds_read_b128 v[4:7], v72
	ds_read_b128 v[8:11], v72 offset:64
	v_cndmask_b32_e32 v0, v0, v3, vcc
	v_rsq_f32_e32 v0, v0
	s_nop 0
	v_mul_f32_e32 v3, 0x45800000, v0
	v_cndmask_b32_e32 v0, v0, v3, vcc
	s_waitcnt lgkmcnt(1)
	v_pk_mul_f32 v[4:5], v[4:5], v[0:1] op_sel_hi:[1,0]
	v_pk_mul_f32 v[6:7], v[6:7], v[0:1] op_sel_hi:[1,0]
	v_mul_f32_e32 v3, 0xbfb8aa3b, v4
	v_exp_f32_e32 v12, v3
	v_mul_f32_e32 v3, 0xbfb8aa3b, v5
	v_exp_f32_e32 v13, v3
	s_waitcnt lgkmcnt(0)
	v_pk_mul_f32 v[8:9], v[8:9], v[0:1] op_sel_hi:[1,0]
	v_pk_mul_f32 v[10:11], v[10:11], v[0:1] op_sel_hi:[1,0]
	v_mul_f32_e32 v0, 0xbfb8aa3b, v7
	v_pk_add_f32 v[12:13], v[12:13], 1.0 op_sel_hi:[1,0]
	s_nop 0
	v_rcp_f32_e32 v14, v13
	s_nop 0
	v_mul_f32_e32 v5, v5, v14
	v_rcp_f32_e32 v13, v12
	s_nop 0
	v_mul_f32_e32 v4, v4, v13
	v_mul_f32_e32 v3, 0xbfb8aa3b, v6
	v_pk_mul_f32 v[4:5], v[8:9], v[4:5]
	v_exp_f32_e32 v8, v3
	v_exp_f32_e32 v9, v0
	v_cvt_pk_bf16_f32 v4, v4, v5
	v_pk_add_f32 v[8:9], v[8:9], 1.0 op_sel_hi:[1,0]
	s_nop 0
	v_rcp_f32_e32 v3, v9
	s_nop 0
	v_mul_f32_e32 v7, v7, v3
	v_rcp_f32_e32 v3, v8
	s_nop 0
	v_mul_f32_e32 v6, v6, v3
	v_pk_mul_f32 v[6:7], v[10:11], v[6:7]
	v_mad_i64_i32 v[2:3], s[12:13], v2, s16, v[66:67]
	v_cvt_pk_bf16_f32 v5, v6, v7
	global_store_dwordx2 v[2:3], v[4:5], off
	v_add_u32_e32 v2, s10, v73
	v_ashrrev_i32_e32 v3, 31, v2
	v_lshl_add_u64 v[4:5], v[2:3], 4, s[40:41]
	v_add_f32_e32 v0, v160, v161
	v_add_f32_e32 v0, v0, v162
	v_add_f32_e32 v0, v0, v163
	v_fmamk_f32 v0, v0, 0x3a800000, v200
	v_cmp_gt_f32_e32 vcc, s7, v0
	v_mul_f32_e32 v3, 0x4b800000, v0
	ds_read_b128 v[4:7], v74
	ds_read_b128 v[8:11], v74 offset:64
	v_cndmask_b32_e32 v0, v0, v3, vcc
	v_rsq_f32_e32 v0, v0
	s_nop 0
	v_mul_f32_e32 v3, 0x45800000, v0
	v_cndmask_b32_e32 v0, v0, v3, vcc
	s_waitcnt lgkmcnt(1)
	v_pk_mul_f32 v[4:5], v[4:5], v[0:1] op_sel_hi:[1,0]
	v_pk_mul_f32 v[6:7], v[6:7], v[0:1] op_sel_hi:[1,0]
	v_mul_f32_e32 v3, 0xbfb8aa3b, v4
	v_exp_f32_e32 v12, v3
	v_mul_f32_e32 v3, 0xbfb8aa3b, v5
	v_exp_f32_e32 v13, v3
	s_waitcnt lgkmcnt(0)
	v_pk_mul_f32 v[8:9], v[8:9], v[0:1] op_sel_hi:[1,0]
	v_pk_mul_f32 v[10:11], v[10:11], v[0:1] op_sel_hi:[1,0]
	v_mul_f32_e32 v0, 0xbfb8aa3b, v7
	v_pk_add_f32 v[12:13], v[12:13], 1.0 op_sel_hi:[1,0]
	s_nop 0
	v_rcp_f32_e32 v14, v13
	s_nop 0
	v_mul_f32_e32 v5, v5, v14
	v_rcp_f32_e32 v13, v12
	s_nop 0
	v_mul_f32_e32 v4, v4, v13
	v_mul_f32_e32 v3, 0xbfb8aa3b, v6
	v_pk_mul_f32 v[4:5], v[8:9], v[4:5]
	v_exp_f32_e32 v8, v3
	v_exp_f32_e32 v9, v0
	v_cvt_pk_bf16_f32 v4, v4, v5
	v_pk_add_f32 v[8:9], v[8:9], 1.0 op_sel_hi:[1,0]
	s_nop 0
	v_rcp_f32_e32 v3, v9
	s_nop 0
	v_mul_f32_e32 v7, v7, v3
	v_rcp_f32_e32 v3, v8
	s_nop 0
	v_mul_f32_e32 v6, v6, v3
	v_pk_mul_f32 v[6:7], v[10:11], v[6:7]
	v_mad_i64_i32 v[2:3], s[12:13], v2, s16, v[66:67]
	v_cvt_pk_bf16_f32 v5, v6, v7
	global_store_dwordx2 v[2:3], v[4:5], off
	v_add_u32_e32 v2, s10, v75
	v_ashrrev_i32_e32 v3, 31, v2
	v_lshl_add_u64 v[4:5], v[2:3], 4, s[40:41]
	v_add_f32_e32 v0, v164, v165
	v_add_f32_e32 v0, v0, v166
	v_add_f32_e32 v0, v0, v167
	v_fmamk_f32 v0, v0, 0x3a800000, v200
	v_cmp_gt_f32_e32 vcc, s7, v0
	v_mul_f32_e32 v3, 0x4b800000, v0
	ds_read_b128 v[4:7], v68
	ds_read_b128 v[8:11], v68 offset:64
	v_cndmask_b32_e32 v0, v0, v3, vcc
	v_rsq_f32_e32 v0, v0
	s_nop 0
	v_mul_f32_e32 v3, 0x45800000, v0
	v_cndmask_b32_e32 v0, v0, v3, vcc
	s_waitcnt lgkmcnt(1)
	v_pk_mul_f32 v[4:5], v[4:5], v[0:1] op_sel_hi:[1,0]
	v_pk_mul_f32 v[6:7], v[6:7], v[0:1] op_sel_hi:[1,0]
	v_mul_f32_e32 v3, 0xbfb8aa3b, v4
	v_exp_f32_e32 v12, v3
	v_mul_f32_e32 v3, 0xbfb8aa3b, v5
	v_exp_f32_e32 v13, v3
	s_waitcnt lgkmcnt(0)
	v_pk_mul_f32 v[8:9], v[8:9], v[0:1] op_sel_hi:[1,0]
	v_pk_mul_f32 v[10:11], v[10:11], v[0:1] op_sel_hi:[1,0]
	v_mul_f32_e32 v0, 0xbfb8aa3b, v7
	v_pk_add_f32 v[12:13], v[12:13], 1.0 op_sel_hi:[1,0]
	s_nop 0
	v_rcp_f32_e32 v14, v13
	s_nop 0
	v_mul_f32_e32 v5, v5, v14
	v_rcp_f32_e32 v13, v12
	s_nop 0
	v_mul_f32_e32 v4, v4, v13
	v_mul_f32_e32 v3, 0xbfb8aa3b, v6
	v_pk_mul_f32 v[4:5], v[8:9], v[4:5]
	v_exp_f32_e32 v8, v3
	v_exp_f32_e32 v9, v0
	v_cvt_pk_bf16_f32 v4, v4, v5
	v_pk_add_f32 v[8:9], v[8:9], 1.0 op_sel_hi:[1,0]
	s_nop 0
	v_rcp_f32_e32 v3, v9
	s_nop 0
	v_mul_f32_e32 v7, v7, v3
	v_rcp_f32_e32 v3, v8
	s_nop 0
	v_mul_f32_e32 v6, v6, v3
	v_pk_mul_f32 v[6:7], v[10:11], v[6:7]
	v_mad_i64_i32 v[2:3], s[10:11], v2, s16, v[66:67]
	v_cvt_pk_bf16_f32 v5, v6, v7
	global_store_dwordx2 v[2:3], v[4:5], off
	s_barrier

.LBB0_1302:
	s_or_b64 exec, exec, s[14:15]
	s_movk_i32 s9, 0x410
	v_lshrrev_b32_e32 v130, 2, v142
	v_lshlrev_b32_e32 v131, 1, v142
	v_and_b32_e32 v0, 15, v142
	v_and_b32_e32 v130, 0xfffffcc, v130
	v_and_b32_e32 v131, 0x180, v131
	v_add_u32_e32 v131, 0, v131
	v_lshlrev_b32_e32 v0, 2, v0
	v_mul_lo_u32 v130, v130, s9
	v_add3_u32 v130, v131, v0, v130
	s_waitcnt vmcnt(0)
	s_barrier
	ds_write2_b32 v130, v114, v126 offset1:16
	v_add_u32_e32 v114, 0x400, v130
	ds_write2_b32 v114, v115, v127 offset0:4 offset1:20
	v_add_u32_e32 v115, 0x800, v130
	ds_write2_b32 v115, v116, v128 offset0:8 offset1:24
	v_add_u32_e32 v116, 0xc00, v130
	ds_write2_b32 v116, v117, v129 offset0:12 offset1:28
	v_add_u32_e32 v117, 0x4000, v130
	ds_write2_b32 v117, v82, v94 offset0:64 offset1:80
	v_add_u32_e32 v94, 0x4400, v130
	ds_write2_b32 v94, v83, v95 offset0:68 offset1:84
	v_add_u32_e32 v95, 0x4800, v130
	ds_write2_b32 v95, v84, v96 offset0:72 offset1:88
	v_add_u32_e32 v96, 0x4c00, v130
	v_add_u32_e32 v128, 0xc800, v130
	v_ashrrev_i32_e32 v84, 5, v142
	ds_write2_b32 v96, v85, v97 offset0:76 offset1:92
	v_add_u32_e32 v131, 0x8000, v130
	v_add_u32_e32 v85, 0x8400, v130
	v_add_u32_e32 v97, 0x8800, v130
	v_add_u32_e32 v126, 0x8c00, v130
	v_add_u32_e32 v132, 0xc000, v130
	v_add_u32_e32 v127, 0xc400, v130
	ds_write2_b32 v128, v68, v72 offset0:200 offset1:216
	v_add_u32_e32 v129, 0xcc00, v130
	v_add_u32_e32 v72, s10, v84
	ds_write2_b32 v131, v74, v78 offset0:128 offset1:144
	ds_write2_b32 v85, v75, v79 offset0:132 offset1:148
	ds_write2_b32 v97, v76, v80 offset0:136 offset1:152
	ds_write2_b32 v126, v77, v81 offset0:140 offset1:156
	ds_write2_b32 v132, v66, v70 offset0:192 offset1:208
	ds_write2_b32 v127, v67, v71 offset0:196 offset1:212
	ds_write2_b32 v129, v69, v73 offset0:204 offset1:220
	ds_write2_b32 v130, v98, v118 offset0:128 offset1:144
	ds_write2_b32 v114, v99, v119 offset0:132 offset1:148
	ds_write2_b32 v115, v100, v120 offset0:136 offset1:152
	ds_write2_b32 v116, v101, v121 offset0:140 offset1:156
	ds_write2_b32 v117, v102, v122 offset0:192 offset1:208
	ds_write2_b32 v94, v103, v123 offset0:196 offset1:212
	ds_write2_b32 v95, v104, v124 offset0:200 offset1:216
	ds_write2_b32 v96, v105, v125 offset0:204 offset1:220
	ds_write2_b32 v85, v90, v110 offset1:16
	ds_write2_b32 v97, v91, v111 offset0:4 offset1:20
	ds_write2_b32 v126, v92, v112 offset0:8 offset1:24
	v_add_u32_e32 v90, 0x9000, v130
	v_ashrrev_i32_e32 v73, 31, v72
	ds_write2_b32 v90, v93, v113 offset0:12 offset1:28
	ds_write2_b32 v127, v86, v106 offset0:64 offset1:80
	ds_write2_b32 v128, v87, v107 offset0:68 offset1:84
	ds_write2_b32 v129, v88, v108 offset0:72 offset1:88
	v_add_u32_e32 v86, 0xd000, v130
	v_lshl_add_u64 v[68:69], v[72:73], 4, s[40:41]
	ds_write2_b32 v86, v89, v109 offset0:76 offset1:92
	s_waitcnt lgkmcnt(0)
	s_barrier
	global_load_dwordx4 v[134:137], v[68:69], off
	global_load_dwordx4 v[138:141], v[68:69], off offset:256
	global_load_dwordx4 v[144:147], v[68:69], off offset:512
	global_load_dwordx4 v[148:151], v[68:69], off offset:768
	global_load_dwordx4 v[152:155], v[68:69], off offset:1024
	global_load_dwordx4 v[156:159], v[68:69], off offset:1280
	global_load_dwordx4 v[160:163], v[68:69], off offset:1536
	global_load_dwordx4 v[164:167], v[68:69], off offset:1792
	v_lshlrev_b32_e32 v66, 2, v142
	v_lshlrev_b32_e32 v0, 3, v142
	v_and_b32_e32 v66, 12, v66
	s_movk_i32 s7, 0xe0
	v_and_or_b32 v66, v0, s7, v66
	s_mov_b32 s7, 0x800000
	v_lshl_add_u32 v0, v66, 2, 0
	v_or_b32_e32 v66, s12, v66
	v_readlane_b32 s12, v253, 62
	v_ashrrev_i32_e32 v67, 31, v66
	v_readlane_b32 s13, v253, 63
	s_movk_i32 s14, 0x1200
	s_mov_b64 s[22:23], -1
	v_lshl_add_u64 v[66:67], v[66:67], 1, s[12:13]
	v_mad_u64_u32 v[82:83], s[12:13], v84, s9, v[0:1]
	v_mad_i64_i32 v[72:73], s[12:13], v72, s14, v[66:67]
	s_waitcnt vmcnt(0)
	v_add_f32_e32 v68, v134, v135
	v_add_f32_e32 v68, v68, v136
	v_add_f32_e32 v68, v68, v137
	v_fmamk_f32 v68, v68, 0x3a800000, v200
	v_cmp_gt_f32_e32 vcc, s7, v68
	v_mul_f32_e32 v69, 0x4b800000, v68
	s_nop 0
	v_cndmask_b32_e32 v68, v68, v69, vcc
	v_rsq_f32_e32 v68, v68
	s_nop 0
	v_mul_f32_e32 v69, 0x45800000, v68
	v_cndmask_b32_e32 v74, v68, v69, vcc
	ds_read_b128 v[68:71], v82
	s_waitcnt lgkmcnt(0)
	v_pk_mul_f32 v[68:69], v[68:69], v[74:75] op_sel_hi:[1,0]
	v_pk_mul_f32 v[70:71], v[70:71], v[74:75] op_sel_hi:[1,0]
	v_cvt_pk_bf16_f32 v68, v68, v69
	v_cvt_pk_bf16_f32 v69, v70, v71
	global_store_dwordx2 v[72:73], v[68:69], off
	ds_read_b128 v[68:71], v82 offset:64
	s_waitcnt lgkmcnt(0)
	v_pk_mul_f32 v[68:69], v[68:69], v[74:75] op_sel_hi:[1,0]
	v_pk_mul_f32 v[70:71], v[70:71], v[74:75] op_sel_hi:[1,0]
	v_cvt_pk_bf16_f32 v68, v68, v69
	v_cvt_pk_bf16_f32 v69, v70, v71
	global_store_dwordx2 v[72:73], v[68:69], off offset:32
	v_add_u32_e32 v68, 0x200, v142
	v_ashrrev_i32_e32 v83, 5, v68
	v_add_u32_e32 v72, s10, v83
	v_ashrrev_i32_e32 v73, 31, v72
	v_lshl_add_u64 v[68:69], v[72:73], 4, s[40:41]
	v_mad_u64_u32 v[80:81], s[12:13], v83, s9, v[0:1]
	v_mad_i64_i32 v[72:73], s[12:13], v72, s14, v[66:67]
	v_add_f32_e32 v68, v138, v139
	v_add_f32_e32 v68, v68, v140
	v_add_f32_e32 v68, v68, v141
	v_fmamk_f32 v68, v68, 0x3a800000, v200
	v_cmp_gt_f32_e32 vcc, s7, v68
	v_mul_f32_e32 v69, 0x4b800000, v68
	s_nop 0
	v_cndmask_b32_e32 v68, v68, v69, vcc
	v_rsq_f32_e32 v68, v68
	s_nop 0
	v_mul_f32_e32 v69, 0x45800000, v68
	v_cndmask_b32_e32 v74, v68, v69, vcc
	ds_read_b128 v[68:71], v80
	s_waitcnt lgkmcnt(0)
	v_pk_mul_f32 v[68:69], v[68:69], v[74:75] op_sel_hi:[1,0]
	v_pk_mul_f32 v[70:71], v[70:71], v[74:75] op_sel_hi:[1,0]
	v_cvt_pk_bf16_f32 v68, v68, v69
	v_cvt_pk_bf16_f32 v69, v70, v71
	global_store_dwordx2 v[72:73], v[68:69], off
	ds_read_b128 v[68:71], v80 offset:64
	s_waitcnt lgkmcnt(0)
	v_pk_mul_f32 v[68:69], v[68:69], v[74:75] op_sel_hi:[1,0]
	v_pk_mul_f32 v[70:71], v[70:71], v[74:75] op_sel_hi:[1,0]
	v_cvt_pk_bf16_f32 v68, v68, v69
	v_cvt_pk_bf16_f32 v69, v70, v71
	global_store_dwordx2 v[72:73], v[68:69], off offset:32
	v_add_u32_e32 v68, 0x400, v142
	v_ashrrev_i32_e32 v81, 5, v68
	v_add_u32_e32 v74, s10, v81
	v_ashrrev_i32_e32 v75, 31, v74
	v_lshl_add_u64 v[70:71], v[74:75], 4, s[40:41]
	v_mad_u64_u32 v[68:69], s[12:13], v81, s9, v[0:1]
	v_mad_i64_i32 v[74:75], s[12:13], v74, s14, v[66:67]
	v_add_f32_e32 v69, v144, v145
	v_add_f32_e32 v69, v69, v146
	v_add_f32_e32 v69, v69, v147
	v_fmamk_f32 v69, v69, 0x3a800000, v200
	v_cmp_gt_f32_e32 vcc, s7, v69
	v_mul_f32_e32 v70, 0x4b800000, v69
	s_nop 0
	v_cndmask_b32_e32 v69, v69, v70, vcc
	v_rsq_f32_e32 v69, v69
	s_nop 0
	v_mul_f32_e32 v70, 0x45800000, v69
	v_cndmask_b32_e32 v76, v69, v70, vcc
	ds_read_b128 v[70:73], v68
	v_add_u32_e32 v69, 0x600, v142
	v_ashrrev_i32_e32 v69, 5, v69
	s_waitcnt lgkmcnt(0)
	v_pk_mul_f32 v[70:71], v[70:71], v[76:77] op_sel_hi:[1,0]
	v_pk_mul_f32 v[72:73], v[72:73], v[76:77] op_sel_hi:[1,0]
	v_cvt_pk_bf16_f32 v70, v70, v71
	v_cvt_pk_bf16_f32 v71, v72, v73
	global_store_dwordx2 v[74:75], v[70:71], off
	ds_read_b128 v[70:73], v68 offset:64
	s_waitcnt lgkmcnt(0)
	v_pk_mul_f32 v[70:71], v[70:71], v[76:77] op_sel_hi:[1,0]
	v_pk_mul_f32 v[72:73], v[72:73], v[76:77] op_sel_hi:[1,0]
	v_add_u32_e32 v76, s10, v69
	v_cvt_pk_bf16_f32 v70, v70, v71
	v_cvt_pk_bf16_f32 v71, v72, v73
	v_ashrrev_i32_e32 v77, 31, v76
	global_store_dwordx2 v[74:75], v[70:71], off offset:32
	v_lshl_add_u64 v[72:73], v[76:77], 4, s[40:41]
	v_mad_u64_u32 v[70:71], s[12:13], v69, s9, v[0:1]
	v_mad_i64_i32 v[76:77], s[12:13], v76, s14, v[66:67]
	v_add_f32_e32 v71, v148, v149
	v_add_f32_e32 v71, v71, v150
	v_add_f32_e32 v71, v71, v151
	v_fmamk_f32 v71, v71, 0x3a800000, v200
	v_cmp_gt_f32_e32 vcc, s7, v71
	v_mul_f32_e32 v72, 0x4b800000, v71
	s_nop 0
	v_cndmask_b32_e32 v71, v71, v72, vcc
	v_rsq_f32_e32 v71, v71
	s_nop 0
	v_mul_f32_e32 v72, 0x45800000, v71
	v_cndmask_b32_e32 v78, v71, v72, vcc
	ds_read_b128 v[72:75], v70
	v_add_u32_e32 v71, 0x800, v142
	v_ashrrev_i32_e32 v71, 5, v71
	s_waitcnt lgkmcnt(0)
	v_pk_mul_f32 v[72:73], v[72:73], v[78:79] op_sel_hi:[1,0]
	v_pk_mul_f32 v[74:75], v[74:75], v[78:79] op_sel_hi:[1,0]
	v_cvt_pk_bf16_f32 v72, v72, v73
	v_cvt_pk_bf16_f32 v73, v74, v75
	global_store_dwordx2 v[76:77], v[72:73], off
	ds_read_b128 v[72:75], v70 offset:64
	s_waitcnt lgkmcnt(0)
	v_pk_mul_f32 v[72:73], v[72:73], v[78:79] op_sel_hi:[1,0]
	v_pk_mul_f32 v[74:75], v[74:75], v[78:79] op_sel_hi:[1,0]
	v_add_u32_e32 v78, s10, v71
	v_cvt_pk_bf16_f32 v72, v72, v73
	v_cvt_pk_bf16_f32 v73, v74, v75
	v_ashrrev_i32_e32 v79, 31, v78
	global_store_dwordx2 v[76:77], v[72:73], off offset:32
	v_lshl_add_u64 v[74:75], v[78:79], 4, s[40:41]
	v_mad_u64_u32 v[72:73], s[12:13], v71, s9, v[0:1]
	v_mad_i64_i32 v[78:79], s[12:13], v78, s14, v[66:67]
	v_add_f32_e32 v73, v152, v153
	v_add_f32_e32 v73, v73, v154
	v_add_f32_e32 v73, v73, v155
	v_fmamk_f32 v73, v73, 0x3a800000, v200
	v_cmp_gt_f32_e32 vcc, s7, v73
	v_mul_f32_e32 v74, 0x4b800000, v73
	s_nop 0
	v_cndmask_b32_e32 v73, v73, v74, vcc
	v_rsq_f32_e32 v73, v73
	s_nop 0
	v_mul_f32_e32 v74, 0x45800000, v73
	v_cndmask_b32_e32 v88, v73, v74, vcc
	ds_read_b128 v[74:77], v72
	v_add_u32_e32 v73, 0xa00, v142
	v_ashrrev_i32_e32 v73, 5, v73
	s_waitcnt lgkmcnt(0)
	v_pk_mul_f32 v[74:75], v[74:75], v[88:89] op_sel_hi:[1,0]
	v_pk_mul_f32 v[76:77], v[76:77], v[88:89] op_sel_hi:[1,0]
	v_cvt_pk_bf16_f32 v74, v74, v75
	v_cvt_pk_bf16_f32 v75, v76, v77
	global_store_dwordx2 v[78:79], v[74:75], off
	ds_read_b128 v[74:77], v72 offset:64
	s_waitcnt lgkmcnt(0)
	v_pk_mul_f32 v[74:75], v[74:75], v[88:89] op_sel_hi:[1,0]
	v_pk_mul_f32 v[76:77], v[76:77], v[88:89] op_sel_hi:[1,0]
	v_add_u32_e32 v88, s10, v73
	v_cvt_pk_bf16_f32 v74, v74, v75
	v_cvt_pk_bf16_f32 v75, v76, v77
	v_ashrrev_i32_e32 v89, 31, v88
	global_store_dwordx2 v[78:79], v[74:75], off offset:32
	v_lshl_add_u64 v[76:77], v[88:89], 4, s[40:41]
	v_mad_u64_u32 v[74:75], s[12:13], v73, s9, v[0:1]
	v_mad_i64_i32 v[88:89], s[12:13], v88, s14, v[66:67]
	v_add_f32_e32 v75, v156, v157
	v_add_f32_e32 v75, v75, v158
	v_add_f32_e32 v75, v75, v159
	v_fmamk_f32 v75, v75, 0x3a800000, v200
	v_cmp_gt_f32_e32 vcc, s7, v75
	v_mul_f32_e32 v76, 0x4b800000, v75
	s_nop 0
	v_cndmask_b32_e32 v75, v75, v76, vcc
	v_rsq_f32_e32 v75, v75
	s_nop 0
	v_mul_f32_e32 v76, 0x45800000, v75
	v_cndmask_b32_e32 v92, v75, v76, vcc
	ds_read_b128 v[76:79], v74
	v_add_u32_e32 v75, 0xc00, v142
	v_ashrrev_i32_e32 v75, 5, v75
	s_waitcnt lgkmcnt(0)
	v_pk_mul_f32 v[76:77], v[76:77], v[92:93] op_sel_hi:[1,0]
	v_pk_mul_f32 v[78:79], v[78:79], v[92:93] op_sel_hi:[1,0]
	v_cvt_pk_bf16_f32 v76, v76, v77
	v_cvt_pk_bf16_f32 v77, v78, v79
	global_store_dwordx2 v[88:89], v[76:77], off
	ds_read_b128 v[76:79], v74 offset:64
	s_waitcnt lgkmcnt(0)
	v_pk_mul_f32 v[76:77], v[76:77], v[92:93] op_sel_hi:[1,0]
	v_pk_mul_f32 v[78:79], v[78:79], v[92:93] op_sel_hi:[1,0]
	v_cvt_pk_bf16_f32 v76, v76, v77
	v_cvt_pk_bf16_f32 v77, v78, v79
	v_add_u32_e32 v78, s10, v75
	v_ashrrev_i32_e32 v79, 31, v78
	global_store_dwordx2 v[88:89], v[76:77], off offset:32
	v_lshl_add_u64 v[88:89], v[78:79], 4, s[40:41]
	v_mad_u64_u32 v[76:77], s[12:13], v75, s9, v[0:1]
	v_add_f32_e32 v77, v160, v161
	v_add_f32_e32 v77, v77, v162
	v_add_f32_e32 v77, v77, v163
	v_fmamk_f32 v77, v77, 0x3a800000, v200
	v_cmp_gt_f32_e32 vcc, s7, v77
	v_mul_f32_e32 v79, 0x4b800000, v77
	ds_read_b128 v[98:101], v76
	v_cndmask_b32_e32 v77, v77, v79, vcc
	v_rsq_f32_e32 v77, v77
	s_nop 0
	v_mul_f32_e32 v79, 0x45800000, v77
	v_cndmask_b32_e32 v88, v77, v79, vcc
	s_waitcnt lgkmcnt(0)
	v_pk_mul_f32 v[92:93], v[98:99], v[88:89] op_sel_hi:[1,0]
	v_pk_mul_f32 v[98:99], v[100:101], v[88:89] op_sel_hi:[1,0]
	v_cvt_pk_bf16_f32 v92, v92, v93
	v_cvt_pk_bf16_f32 v93, v98, v99
	ds_read_b128 v[98:101], v76 offset:64
	v_mad_i64_i32 v[78:79], s[12:13], v78, s14, v[66:67]
	v_add_u32_e32 v77, 0xe00, v142
	global_store_dwordx2 v[78:79], v[92:93], off
	s_waitcnt lgkmcnt(0)
	v_pk_mul_f32 v[92:93], v[98:99], v[88:89] op_sel_hi:[1,0]
	v_pk_mul_f32 v[88:89], v[100:101], v[88:89] op_sel_hi:[1,0]
	v_ashrrev_i32_e32 v77, 5, v77
	v_cvt_pk_bf16_f32 v92, v92, v93
	v_cvt_pk_bf16_f32 v93, v88, v89
	v_add_u32_e32 v88, s10, v77
	v_ashrrev_i32_e32 v89, 31, v88
	global_store_dwordx2 v[78:79], v[92:93], off offset:32
	v_lshl_add_u64 v[92:93], v[88:89], 4, s[40:41]
	v_mad_u64_u32 v[78:79], s[12:13], v77, s9, v[0:1]
	v_mad_i64_i32 v[88:89], s[10:11], v88, s14, v[66:67]
	v_add_f32_e32 v0, v164, v165
	v_add_f32_e32 v0, v0, v166
	v_add_f32_e32 v0, v0, v167
	v_fmamk_f32 v0, v0, 0x3a800000, v200
	v_cmp_gt_f32_e32 vcc, s7, v0
	v_mul_f32_e32 v79, 0x4b800000, v0
	ds_read_b128 v[98:101], v78
	v_cndmask_b32_e32 v0, v0, v79, vcc
	v_rsq_f32_e32 v0, v0
	s_nop 0
	v_mul_f32_e32 v79, 0x45800000, v0
	v_cndmask_b32_e32 v0, v0, v79, vcc
	s_waitcnt lgkmcnt(0)
	v_pk_mul_f32 v[92:93], v[98:99], v[0:1] op_sel_hi:[1,0]
	v_pk_mul_f32 v[98:99], v[100:101], v[0:1] op_sel_hi:[1,0]
	v_cvt_pk_bf16_f32 v92, v92, v93
	v_cvt_pk_bf16_f32 v93, v98, v99
	ds_read_b128 v[98:101], v78 offset:64
	global_store_dwordx2 v[88:89], v[92:93], off
	s_waitcnt lgkmcnt(0)
	v_pk_mul_f32 v[92:93], v[98:99], v[0:1] op_sel_hi:[1,0]
	v_pk_mul_f32 v[98:99], v[100:101], v[0:1] op_sel_hi:[1,0]
	v_cvt_pk_bf16_f32 v92, v92, v93
	v_cvt_pk_bf16_f32 v93, v98, v99
	global_store_dwordx2 v[88:89], v[92:93], off offset:32
	s_barrier
	ds_write2_b32 v130, v2, v18 offset1:16
	ds_write2_b32 v114, v3, v19 offset0:4 offset1:20
	ds_write2_b32 v115, v4, v20 offset0:8 offset1:24
	ds_write2_b32 v116, v5, v21 offset0:12 offset1:28
	ds_write2_b32 v117, v6, v22 offset0:64 offset1:80
	ds_write2_b32 v94, v7, v23 offset0:68 offset1:84
	ds_write2_b32 v95, v8, v24 offset0:72 offset1:88
	ds_write2_b32 v96, v9, v25 offset0:76 offset1:92
	ds_write2_b32 v131, v10, v26 offset0:128 offset1:144
	ds_write2_b32 v85, v11, v27 offset0:132 offset1:148
	ds_write2_b32 v97, v12, v28 offset0:136 offset1:152
	ds_write2_b32 v126, v13, v29 offset0:140 offset1:156
	ds_write2_b32 v132, v14, v30 offset0:192 offset1:208
	ds_write2_b32 v127, v15, v31 offset0:196 offset1:212
	ds_write2_b32 v128, v16, v32 offset0:200 offset1:216
	ds_write2_b32 v129, v17, v33 offset0:204 offset1:220
	ds_write2_b32 v130, v34, v50 offset0:128 offset1:144
	ds_write2_b32 v114, v35, v51 offset0:132 offset1:148
	ds_write2_b32 v115, v36, v52 offset0:136 offset1:152
	ds_write2_b32 v116, v37, v53 offset0:140 offset1:156
	ds_write2_b32 v117, v38, v54 offset0:192 offset1:208
	ds_write2_b32 v94, v39, v55 offset0:196 offset1:212
	ds_write2_b32 v95, v40, v56 offset0:200 offset1:216
	ds_write2_b32 v96, v41, v57 offset0:204 offset1:220
	ds_write2_b32 v85, v42, v58 offset1:16
	ds_write2_b32 v97, v43, v59 offset0:4 offset1:20
	ds_write2_b32 v126, v44, v60 offset0:8 offset1:24
	ds_write2_b32 v90, v45, v61 offset0:12 offset1:28
	ds_write2_b32 v127, v46, v62 offset0:64 offset1:80
	ds_write2_b32 v128, v47, v63 offset0:68 offset1:84
	ds_write2_b32 v129, v48, v64 offset0:72 offset1:88
	ds_write2_b32 v86, v49, v65 offset0:76 offset1:92
	v_add_u32_e32 v2, s8, v84
	v_ashrrev_i32_e32 v3, 31, v2
	v_lshl_add_u64 v[4:5], v[2:3], 4, s[40:41]
	s_waitcnt lgkmcnt(0)
	s_barrier
	global_load_dwordx4 v[134:137], v[4:5], off
	global_load_dwordx4 v[138:141], v[4:5], off offset:256
	global_load_dwordx4 v[144:147], v[4:5], off offset:512
	global_load_dwordx4 v[148:151], v[4:5], off offset:768
	global_load_dwordx4 v[152:155], v[4:5], off offset:1024
	global_load_dwordx4 v[156:159], v[4:5], off offset:1280
	global_load_dwordx4 v[160:163], v[4:5], off offset:1536
	global_load_dwordx4 v[164:167], v[4:5], off offset:1792
	s_waitcnt vmcnt(0)
	v_add_f32_e32 v0, v134, v135
	v_add_f32_e32 v0, v0, v136
	v_add_f32_e32 v0, v0, v137
	v_fmamk_f32 v0, v0, 0x3a800000, v200
	v_cmp_gt_f32_e32 vcc, s7, v0
	v_mul_f32_e32 v3, 0x4b800000, v0
	ds_read_b128 v[4:7], v82
	v_cndmask_b32_e32 v0, v0, v3, vcc
	v_rsq_f32_e32 v0, v0
	s_nop 0
	v_mul_f32_e32 v3, 0x45800000, v0
	v_cndmask_b32_e32 v0, v0, v3, vcc
	s_waitcnt lgkmcnt(0)
	v_pk_mul_f32 v[4:5], v[4:5], v[0:1] op_sel_hi:[1,0]
	v_pk_mul_f32 v[6:7], v[6:7], v[0:1] op_sel_hi:[1,0]
	v_cvt_pk_bf16_f32 v4, v4, v5
	v_cvt_pk_bf16_f32 v5, v6, v7
	v_mad_i64_i32 v[6:7], s[10:11], v2, s14, v[66:67]
	global_store_dwordx2 v[6:7], v[4:5], off
	ds_read_b128 v[2:5], v82 offset:64
	s_waitcnt lgkmcnt(0)
	v_pk_mul_f32 v[2:3], v[2:3], v[0:1] op_sel_hi:[1,0]
	v_pk_mul_f32 v[4:5], v[4:5], v[0:1] op_sel_hi:[1,0]
	v_cvt_pk_bf16_f32 v2, v2, v3
	v_cvt_pk_bf16_f32 v3, v4, v5
	global_store_dwordx2 v[6:7], v[2:3], off offset:32
	v_add_u32_e32 v6, s8, v83
	v_ashrrev_i32_e32 v7, 31, v6
	v_lshl_add_u64 v[2:3], v[6:7], 4, s[40:41]
	v_mad_i64_i32 v[6:7], s[10:11], v6, s14, v[66:67]
	v_add_f32_e32 v0, v138, v139
	v_add_f32_e32 v0, v0, v140
	v_add_f32_e32 v0, v0, v141
	v_fmamk_f32 v0, v0, 0x3a800000, v200
	v_cmp_gt_f32_e32 vcc, s7, v0
	v_mul_f32_e32 v2, 0x4b800000, v0
	s_nop 0
	v_cndmask_b32_e32 v0, v0, v2, vcc
	v_rsq_f32_e32 v0, v0
	s_nop 0
	v_mul_f32_e32 v2, 0x45800000, v0
	v_cndmask_b32_e32 v0, v0, v2, vcc
	ds_read_b128 v[2:5], v80
	s_waitcnt lgkmcnt(0)
	v_pk_mul_f32 v[2:3], v[2:3], v[0:1] op_sel_hi:[1,0]
	v_pk_mul_f32 v[4:5], v[4:5], v[0:1] op_sel_hi:[1,0]
	v_cvt_pk_bf16_f32 v2, v2, v3
	v_cvt_pk_bf16_f32 v3, v4, v5
	global_store_dwordx2 v[6:7], v[2:3], off
	ds_read_b128 v[2:5], v80 offset:64
	s_waitcnt lgkmcnt(0)
	v_pk_mul_f32 v[2:3], v[2:3], v[0:1] op_sel_hi:[1,0]
	v_pk_mul_f32 v[4:5], v[4:5], v[0:1] op_sel_hi:[1,0]
	v_cvt_pk_bf16_f32 v2, v2, v3
	v_cvt_pk_bf16_f32 v3, v4, v5
	global_store_dwordx2 v[6:7], v[2:3], off offset:32
	v_add_u32_e32 v6, s8, v81
	v_ashrrev_i32_e32 v7, 31, v6
	v_lshl_add_u64 v[2:3], v[6:7], 4, s[40:41]
	v_mad_i64_i32 v[6:7], s[10:11], v6, s14, v[66:67]
	v_add_f32_e32 v0, v144, v145
	v_add_f32_e32 v0, v0, v146
	v_add_f32_e32 v0, v0, v147
	v_fmamk_f32 v0, v0, 0x3a800000, v200
	v_cmp_gt_f32_e32 vcc, s7, v0
	v_mul_f32_e32 v2, 0x4b800000, v0
	s_nop 0
	v_cndmask_b32_e32 v0, v0, v2, vcc
	v_rsq_f32_e32 v0, v0
	s_nop 0
	v_mul_f32_e32 v2, 0x45800000, v0
	v_cndmask_b32_e32 v0, v0, v2, vcc
	ds_read_b128 v[2:5], v68
	s_waitcnt lgkmcnt(0)
	v_pk_mul_f32 v[2:3], v[2:3], v[0:1] op_sel_hi:[1,0]
	v_pk_mul_f32 v[4:5], v[4:5], v[0:1] op_sel_hi:[1,0]
	v_cvt_pk_bf16_f32 v2, v2, v3
	v_cvt_pk_bf16_f32 v3, v4, v5
	global_store_dwordx2 v[6:7], v[2:3], off
	ds_read_b128 v[2:5], v68 offset:64
	s_waitcnt lgkmcnt(0)
	v_pk_mul_f32 v[2:3], v[2:3], v[0:1] op_sel_hi:[1,0]
	v_pk_mul_f32 v[4:5], v[4:5], v[0:1] op_sel_hi:[1,0]
	v_cvt_pk_bf16_f32 v2, v2, v3
	v_cvt_pk_bf16_f32 v3, v4, v5
	global_store_dwordx2 v[6:7], v[2:3], off offset:32
	v_add_u32_e32 v6, s8, v69
	v_ashrrev_i32_e32 v7, 31, v6
	v_lshl_add_u64 v[2:3], v[6:7], 4, s[40:41]
	v_mad_i64_i32 v[6:7], s[10:11], v6, s14, v[66:67]
	v_add_f32_e32 v0, v148, v149
	v_add_f32_e32 v0, v0, v150
	v_add_f32_e32 v0, v0, v151
	v_fmamk_f32 v0, v0, 0x3a800000, v200
	v_cmp_gt_f32_e32 vcc, s7, v0
	v_mul_f32_e32 v2, 0x4b800000, v0
	s_nop 0
	v_cndmask_b32_e32 v0, v0, v2, vcc
	v_rsq_f32_e32 v0, v0
	s_nop 0
	v_mul_f32_e32 v2, 0x45800000, v0
	v_cndmask_b32_e32 v0, v0, v2, vcc
	ds_read_b128 v[2:5], v70
	s_waitcnt lgkmcnt(0)
	v_pk_mul_f32 v[2:3], v[2:3], v[0:1] op_sel_hi:[1,0]
	v_pk_mul_f32 v[4:5], v[4:5], v[0:1] op_sel_hi:[1,0]
	v_cvt_pk_bf16_f32 v2, v2, v3
	v_cvt_pk_bf16_f32 v3, v4, v5
	global_store_dwordx2 v[6:7], v[2:3], off
	ds_read_b128 v[2:5], v70 offset:64
	s_waitcnt lgkmcnt(0)
	v_pk_mul_f32 v[2:3], v[2:3], v[0:1] op_sel_hi:[1,0]
	v_pk_mul_f32 v[4:5], v[4:5], v[0:1] op_sel_hi:[1,0]
	v_cvt_pk_bf16_f32 v2, v2, v3
	v_cvt_pk_bf16_f32 v3, v4, v5
	global_store_dwordx2 v[6:7], v[2:3], off offset:32
	v_add_u32_e32 v6, s8, v71
	v_ashrrev_i32_e32 v7, 31, v6
	v_lshl_add_u64 v[2:3], v[6:7], 4, s[40:41]
	v_mad_i64_i32 v[6:7], s[10:11], v6, s14, v[66:67]
	v_add_f32_e32 v0, v152, v153
	v_add_f32_e32 v0, v0, v154
	v_add_f32_e32 v0, v0, v155
	v_fmamk_f32 v0, v0, 0x3a800000, v200
	v_cmp_gt_f32_e32 vcc, s7, v0
	v_mul_f32_e32 v2, 0x4b800000, v0
	s_nop 0
	v_cndmask_b32_e32 v0, v0, v2, vcc
	v_rsq_f32_e32 v0, v0
	s_nop 0
	v_mul_f32_e32 v2, 0x45800000, v0
	v_cndmask_b32_e32 v0, v0, v2, vcc
	ds_read_b128 v[2:5], v72
	s_waitcnt lgkmcnt(0)
	v_pk_mul_f32 v[2:3], v[2:3], v[0:1] op_sel_hi:[1,0]
	v_pk_mul_f32 v[4:5], v[4:5], v[0:1] op_sel_hi:[1,0]
	v_cvt_pk_bf16_f32 v2, v2, v3
	v_cvt_pk_bf16_f32 v3, v4, v5
	global_store_dwordx2 v[6:7], v[2:3], off
	ds_read_b128 v[2:5], v72 offset:64
	s_waitcnt lgkmcnt(0)
	v_pk_mul_f32 v[2:3], v[2:3], v[0:1] op_sel_hi:[1,0]
	v_pk_mul_f32 v[4:5], v[4:5], v[0:1] op_sel_hi:[1,0]
	v_cvt_pk_bf16_f32 v2, v2, v3
	v_cvt_pk_bf16_f32 v3, v4, v5
	global_store_dwordx2 v[6:7], v[2:3], off offset:32
	v_add_u32_e32 v6, s8, v73
	v_ashrrev_i32_e32 v7, 31, v6
	v_lshl_add_u64 v[2:3], v[6:7], 4, s[40:41]
	v_mad_i64_i32 v[6:7], s[10:11], v6, s14, v[66:67]
	v_add_f32_e32 v0, v156, v157
	v_add_f32_e32 v0, v0, v158
	v_add_f32_e32 v0, v0, v159
	v_fmamk_f32 v0, v0, 0x3a800000, v200
	v_cmp_gt_f32_e32 vcc, s7, v0
	v_mul_f32_e32 v2, 0x4b800000, v0
	s_nop 0
	v_cndmask_b32_e32 v0, v0, v2, vcc
	v_rsq_f32_e32 v0, v0
	s_nop 0
	v_mul_f32_e32 v2, 0x45800000, v0
	v_cndmask_b32_e32 v0, v0, v2, vcc
	ds_read_b128 v[2:5], v74
	s_waitcnt lgkmcnt(0)
	v_pk_mul_f32 v[2:3], v[2:3], v[0:1] op_sel_hi:[1,0]
	v_pk_mul_f32 v[4:5], v[4:5], v[0:1] op_sel_hi:[1,0]
	v_cvt_pk_bf16_f32 v2, v2, v3
	v_cvt_pk_bf16_f32 v3, v4, v5
	global_store_dwordx2 v[6:7], v[2:3], off
	ds_read_b128 v[2:5], v74 offset:64
	s_waitcnt lgkmcnt(0)
	v_pk_mul_f32 v[2:3], v[2:3], v[0:1] op_sel_hi:[1,0]
	v_pk_mul_f32 v[4:5], v[4:5], v[0:1] op_sel_hi:[1,0]
	v_cvt_pk_bf16_f32 v2, v2, v3
	v_cvt_pk_bf16_f32 v3, v4, v5
	global_store_dwordx2 v[6:7], v[2:3], off offset:32
	v_add_u32_e32 v6, s8, v75
	v_ashrrev_i32_e32 v7, 31, v6
	v_lshl_add_u64 v[2:3], v[6:7], 4, s[40:41]
	v_mad_i64_i32 v[6:7], s[10:11], v6, s14, v[66:67]
	v_add_f32_e32 v0, v160, v161
	v_add_f32_e32 v0, v0, v162
	v_add_f32_e32 v0, v0, v163
	v_fmamk_f32 v0, v0, 0x3a800000, v200
	v_cmp_gt_f32_e32 vcc, s7, v0
	v_mul_f32_e32 v2, 0x4b800000, v0
	s_nop 0
	v_cndmask_b32_e32 v0, v0, v2, vcc
	v_rsq_f32_e32 v0, v0
	s_nop 0
	v_mul_f32_e32 v2, 0x45800000, v0
	v_cndmask_b32_e32 v0, v0, v2, vcc
	ds_read_b128 v[2:5], v76
	s_waitcnt lgkmcnt(0)
	v_pk_mul_f32 v[2:3], v[2:3], v[0:1] op_sel_hi:[1,0]
	v_pk_mul_f32 v[4:5], v[4:5], v[0:1] op_sel_hi:[1,0]
	v_cvt_pk_bf16_f32 v2, v2, v3
	v_cvt_pk_bf16_f32 v3, v4, v5
	global_store_dwordx2 v[6:7], v[2:3], off
	ds_read_b128 v[2:5], v76 offset:64
	s_waitcnt lgkmcnt(0)
	v_pk_mul_f32 v[2:3], v[2:3], v[0:1] op_sel_hi:[1,0]
	v_pk_mul_f32 v[4:5], v[4:5], v[0:1] op_sel_hi:[1,0]
	v_cvt_pk_bf16_f32 v2, v2, v3
	v_cvt_pk_bf16_f32 v3, v4, v5
	global_store_dwordx2 v[6:7], v[2:3], off offset:32
	v_add_u32_e32 v6, s8, v77
	v_ashrrev_i32_e32 v7, 31, v6
	v_lshl_add_u64 v[2:3], v[6:7], 4, s[40:41]
	v_mad_i64_i32 v[6:7], s[8:9], v6, s14, v[66:67]
	v_add_f32_e32 v0, v164, v165
	v_add_f32_e32 v0, v0, v166
	v_add_f32_e32 v0, v0, v167
	v_fmamk_f32 v0, v0, 0x3a800000, v200
	v_cmp_gt_f32_e32 vcc, s7, v0
	v_mul_f32_e32 v2, 0x4b800000, v0
	s_nop 0
	v_cndmask_b32_e32 v0, v0, v2, vcc
	v_rsq_f32_e32 v0, v0
	s_nop 0
	v_mul_f32_e32 v2, 0x45800000, v0
	v_cndmask_b32_e32 v0, v0, v2, vcc
	ds_read_b128 v[2:5], v78
	s_waitcnt lgkmcnt(0)
	v_pk_mul_f32 v[2:3], v[2:3], v[0:1] op_sel_hi:[1,0]
	v_pk_mul_f32 v[4:5], v[4:5], v[0:1] op_sel_hi:[1,0]
	v_cvt_pk_bf16_f32 v2, v2, v3
	v_cvt_pk_bf16_f32 v3, v4, v5
	global_store_dwordx2 v[6:7], v[2:3], off
	ds_read_b128 v[2:5], v78 offset:64
	s_waitcnt lgkmcnt(0)
	v_pk_mul_f32 v[2:3], v[2:3], v[0:1] op_sel_hi:[1,0]
	v_pk_mul_f32 v[4:5], v[4:5], v[0:1] op_sel_hi:[1,0]
	v_cvt_pk_bf16_f32 v2, v2, v3
	v_cvt_pk_bf16_f32 v3, v4, v5
	global_store_dwordx2 v[6:7], v[2:3], off offset:32
	s_barrier
	s_branch .LBB0_1279
